# write-through (sc1) stores only in the single-round EpiResid phases (FFN-out x4, wout x2): residual f32 tile + panel-norm outputs
# speedup vs baseline: 1.0057x; 1.0057x over previous
.LBB0_411:
	v_lshl_or_b32 v168, s76, 8, v198
	v_add_u32_e32 v156, 0x800, v168
	v_ashrrev_i32_e32 v157, 31, v156
	v_lshlrev_b64 v[160:161], 2, v[156:157]
	s_ashr_i32 s49, s46, 3
	v_lshl_add_u64 v[164:165], s[18:19], 0, v[160:161]
	v_lshl_add_u64 v[156:157], s[12:13], 0, v[160:161]
	v_mad_i64_i32 v[160:161], s[38:39], s49, v211, v[164:165]
	global_load_dwordx4 v[156:159], v[156:157], off
	s_add_i32 s50, s49, 8
	s_add_i32 s48, s49, 16
	s_add_i32 s47, s49, 24
	s_add_i32 s81, s49, 32
	s_add_i32 s80, s49, 40
	s_add_i32 s79, s49, 48
	s_add_i32 s78, s49, 56
	s_lshl_b32 s77, s46, 8
	global_load_dwordx4 v[160:163], v[160:161], off
	v_mad_i64_i32 v[212:213], s[38:39], s50, v211, v[164:165]
	global_load_dwordx4 v[212:215], v[212:213], off
	v_mad_i64_i32 v[216:217], s[38:39], s48, v211, v[164:165]
	global_load_dwordx4 v[216:219], v[216:217], off
	v_mad_i64_i32 v[220:221], s[38:39], s47, v211, v[164:165]
	global_load_dwordx4 v[220:223], v[220:221], off
	v_mad_i64_i32 v[230:231], s[38:39], s81, v211, v[164:165]
	global_load_dwordx4 v[230:233], v[230:231], off
	v_mad_i64_i32 v[234:235], s[38:39], s80, v211, v[164:165]
	global_load_dwordx4 v[234:237], v[234:235], off
	v_mad_i64_i32 v[238:239], s[38:39], s79, v211, v[164:165]
	global_load_dwordx4 v[238:241], v[238:239], off
	v_mad_i64_i32 v[246:247], s[38:39], s78, v211, v[164:165]
	global_load_dwordx4 v[246:249], v[246:247], off
	v_ashrrev_i32_e32 v169, 31, v168
	v_readfirstlane_b32 s82, v180
	s_waitcnt vmcnt(7)
	v_pk_add_f32 v[160:161], v[156:157], v[160:161]
	v_pk_add_f32 v[162:163], v[158:159], v[162:163]
	s_waitcnt vmcnt(6)
	v_pk_add_f32 v[160:161], v[160:161], v[212:213]
	v_pk_add_f32 v[162:163], v[162:163], v[214:215]
	s_waitcnt vmcnt(5)
	v_pk_add_f32 v[160:161], v[160:161], v[216:217]
	v_pk_add_f32 v[162:163], v[162:163], v[218:219]
	s_waitcnt vmcnt(4)
	v_pk_add_f32 v[160:161], v[160:161], v[220:221]
	v_pk_add_f32 v[162:163], v[162:163], v[222:223]
	s_waitcnt vmcnt(3)
	v_pk_add_f32 v[160:161], v[160:161], v[230:231]
	v_pk_add_f32 v[162:163], v[162:163], v[232:233]
	s_waitcnt vmcnt(2)
	v_pk_add_f32 v[160:161], v[160:161], v[234:235]
	v_pk_add_f32 v[162:163], v[162:163], v[236:237]
	s_waitcnt vmcnt(1)
	v_pk_add_f32 v[160:161], v[160:161], v[238:239]
	v_pk_add_f32 v[162:163], v[162:163], v[240:241]
	s_waitcnt vmcnt(0)
	v_pk_add_f32 v[158:159], v[162:163], v[248:249]
	v_pk_add_f32 v[160:161], v[160:161], v[246:247]
	v_pk_mul_f32 v[156:157], v[158:159], 0.5 op_sel_hi:[1, 0]
	v_pk_mul_f32 v[158:159], v[160:161], 0.5 op_sel_hi:[1, 0]
	v_add_u32_e32 v160, 0x810, v168
	v_ashrrev_i32_e32 v161, 31, v160
	v_lshlrev_b64 v[164:165], 2, v[160:161]
	v_lshl_add_u64 v[170:171], s[18:19], 0, v[164:165]
	v_lshl_add_u64 v[160:161], s[12:13], 0, v[164:165]
	v_mad_i64_i32 v[164:165], s[38:39], s49, v211, v[170:171]
	global_load_dwordx4 v[160:163], v[160:161], off
	global_load_dwordx4 v[164:167], v[164:165], off
	v_mad_i64_i32 v[212:213], s[38:39], s50, v211, v[170:171]
	global_load_dwordx4 v[212:215], v[212:213], off
	v_mad_i64_i32 v[216:217], s[38:39], s48, v211, v[170:171]
	global_load_dwordx4 v[216:219], v[216:217], off
	v_mad_i64_i32 v[220:221], s[38:39], s47, v211, v[170:171]
	global_load_dwordx4 v[220:223], v[220:221], off
	v_mad_i64_i32 v[230:231], s[38:39], s81, v211, v[170:171]
	global_load_dwordx4 v[230:233], v[230:231], off
	v_mad_i64_i32 v[234:235], s[38:39], s80, v211, v[170:171]
	global_load_dwordx4 v[234:237], v[234:235], off
	v_mad_i64_i32 v[238:239], s[38:39], s79, v211, v[170:171]
	global_load_dwordx4 v[238:241], v[238:239], off
	v_mad_i64_i32 v[246:247], s[38:39], s78, v211, v[170:171]
	global_load_dwordx4 v[246:249], v[246:247], off
	s_waitcnt vmcnt(7)
	v_pk_add_f32 v[164:165], v[160:161], v[164:165]
	v_pk_add_f32 v[166:167], v[162:163], v[166:167]
	s_waitcnt vmcnt(6)
	v_pk_add_f32 v[164:165], v[164:165], v[212:213]
	v_pk_add_f32 v[166:167], v[166:167], v[214:215]
	s_waitcnt vmcnt(5)
	v_pk_add_f32 v[164:165], v[164:165], v[216:217]
	v_pk_add_f32 v[166:167], v[166:167], v[218:219]
	s_waitcnt vmcnt(4)
	v_pk_add_f32 v[164:165], v[164:165], v[220:221]
	v_pk_add_f32 v[166:167], v[166:167], v[222:223]
	s_waitcnt vmcnt(3)
	v_pk_add_f32 v[164:165], v[164:165], v[230:231]
	v_pk_add_f32 v[166:167], v[166:167], v[232:233]
	s_waitcnt vmcnt(2)
	v_pk_add_f32 v[164:165], v[164:165], v[234:235]
	v_pk_add_f32 v[166:167], v[166:167], v[236:237]
	s_waitcnt vmcnt(1)
	v_pk_add_f32 v[164:165], v[164:165], v[238:239]
	v_pk_add_f32 v[166:167], v[166:167], v[240:241]
	s_waitcnt vmcnt(0)
	v_pk_add_f32 v[162:163], v[166:167], v[248:249]
	v_pk_add_f32 v[164:165], v[164:165], v[246:247]
	v_pk_mul_f32 v[160:161], v[162:163], 0.5 op_sel_hi:[1, 0]
	v_pk_mul_f32 v[162:163], v[164:165], 0.5 op_sel_hi:[1, 0]
	v_add_u32_e32 v164, 0x880, v168
	v_ashrrev_i32_e32 v165, 31, v164
	v_lshlrev_b64 v[170:171], 2, v[164:165]
	v_lshl_add_u64 v[174:175], s[18:19], 0, v[170:171]
	v_lshl_add_u64 v[164:165], s[12:13], 0, v[170:171]
	v_mad_i64_i32 v[170:171], s[38:39], s49, v211, v[174:175]
	global_load_dwordx4 v[164:167], v[164:165], off
	global_load_dwordx4 v[170:173], v[170:171], off
	v_mad_i64_i32 v[212:213], s[38:39], s50, v211, v[174:175]
	global_load_dwordx4 v[212:215], v[212:213], off
	v_mad_i64_i32 v[216:217], s[38:39], s48, v211, v[174:175]
	global_load_dwordx4 v[216:219], v[216:217], off
	v_mad_i64_i32 v[220:221], s[38:39], s47, v211, v[174:175]
	global_load_dwordx4 v[220:223], v[220:221], off
	v_mad_i64_i32 v[230:231], s[38:39], s81, v211, v[174:175]
	global_load_dwordx4 v[230:233], v[230:231], off
	v_mad_i64_i32 v[234:235], s[38:39], s80, v211, v[174:175]
	global_load_dwordx4 v[234:237], v[234:235], off
	v_mad_i64_i32 v[238:239], s[38:39], s79, v211, v[174:175]
	global_load_dwordx4 v[238:241], v[238:239], off
	v_mad_i64_i32 v[246:247], s[38:39], s78, v211, v[174:175]
	global_load_dwordx4 v[246:249], v[246:247], off
	s_waitcnt vmcnt(7)
	v_pk_add_f32 v[170:171], v[164:165], v[170:171]
	v_pk_add_f32 v[172:173], v[166:167], v[172:173]
	s_waitcnt vmcnt(6)
	v_pk_add_f32 v[170:171], v[170:171], v[212:213]
	v_pk_add_f32 v[172:173], v[172:173], v[214:215]
	s_waitcnt vmcnt(5)
	v_pk_add_f32 v[170:171], v[170:171], v[216:217]
	v_pk_add_f32 v[172:173], v[172:173], v[218:219]
	s_waitcnt vmcnt(4)
	v_pk_add_f32 v[170:171], v[170:171], v[220:221]
	v_pk_add_f32 v[172:173], v[172:173], v[222:223]
	s_waitcnt vmcnt(3)
	v_pk_add_f32 v[170:171], v[170:171], v[230:231]
	v_pk_add_f32 v[172:173], v[172:173], v[232:233]
	s_waitcnt vmcnt(2)
	v_pk_add_f32 v[170:171], v[170:171], v[234:235]
	v_pk_add_f32 v[172:173], v[172:173], v[236:237]
	s_waitcnt vmcnt(1)
	v_pk_add_f32 v[170:171], v[170:171], v[238:239]
	v_pk_add_f32 v[172:173], v[172:173], v[240:241]
	s_waitcnt vmcnt(0)
	v_pk_add_f32 v[166:167], v[172:173], v[248:249]
	v_pk_add_f32 v[170:171], v[170:171], v[246:247]
	v_pk_mul_f32 v[164:165], v[166:167], 0.5 op_sel_hi:[1, 0]
	v_pk_mul_f32 v[166:167], v[170:171], 0.5 op_sel_hi:[1, 0]
	v_add_u32_e32 v170, 0x890, v168
	v_ashrrev_i32_e32 v171, 31, v170
	v_lshlrev_b64 v[174:175], 2, v[170:171]
	v_lshl_add_u64 v[178:179], s[18:19], 0, v[174:175]
	v_lshl_add_u64 v[170:171], s[12:13], 0, v[174:175]
	v_mad_i64_i32 v[174:175], s[38:39], s49, v211, v[178:179]
	global_load_dwordx4 v[170:173], v[170:171], off
	global_load_dwordx4 v[174:177], v[174:175], off
	v_mad_i64_i32 v[212:213], s[38:39], s50, v211, v[178:179]
	global_load_dwordx4 v[212:215], v[212:213], off
	v_mad_i64_i32 v[216:217], s[38:39], s48, v211, v[178:179]
	global_load_dwordx4 v[216:219], v[216:217], off
	v_mad_i64_i32 v[220:221], s[38:39], s47, v211, v[178:179]
	global_load_dwordx4 v[220:223], v[220:221], off
	v_mad_i64_i32 v[230:231], s[38:39], s81, v211, v[178:179]
	global_load_dwordx4 v[230:233], v[230:231], off
	v_mad_i64_i32 v[234:235], s[38:39], s80, v211, v[178:179]
	global_load_dwordx4 v[234:237], v[234:235], off
	v_mad_i64_i32 v[238:239], s[38:39], s79, v211, v[178:179]
	global_load_dwordx4 v[238:241], v[238:239], off
	v_mad_i64_i32 v[246:247], s[38:39], s78, v211, v[178:179]
	global_load_dwordx4 v[246:249], v[246:247], off
	v_lshlrev_b64 v[168:169], 2, v[168:169]
	s_waitcnt vmcnt(7)
	v_pk_add_f32 v[174:175], v[170:171], v[174:175]
	v_pk_add_f32 v[176:177], v[172:173], v[176:177]
	s_waitcnt vmcnt(6)
	v_pk_add_f32 v[174:175], v[174:175], v[212:213]
	v_pk_add_f32 v[176:177], v[176:177], v[214:215]
	s_waitcnt vmcnt(5)
	v_pk_add_f32 v[174:175], v[174:175], v[216:217]
	v_pk_add_f32 v[176:177], v[176:177], v[218:219]
	s_waitcnt vmcnt(4)
	v_pk_add_f32 v[174:175], v[174:175], v[220:221]
	v_pk_add_f32 v[176:177], v[176:177], v[222:223]
	s_waitcnt vmcnt(3)
	v_pk_add_f32 v[174:175], v[174:175], v[230:231]
	v_pk_add_f32 v[176:177], v[176:177], v[232:233]
	s_waitcnt vmcnt(2)
	v_pk_add_f32 v[174:175], v[174:175], v[234:235]
	v_pk_add_f32 v[176:177], v[176:177], v[236:237]
	s_waitcnt vmcnt(1)
	v_pk_add_f32 v[174:175], v[174:175], v[238:239]
	v_pk_add_f32 v[176:177], v[176:177], v[240:241]
	v_add_u32_e32 v178, s77, v181
	v_ashrrev_i32_e32 v179, 31, v178
	v_or_b32_e32 v228, 16, v178
	v_ashrrev_i32_e32 v229, 31, v228
	v_lshlrev_b64 v[244:245], 12, v[228:229]
	s_waitcnt vmcnt(0)
	v_pk_add_f32 v[172:173], v[176:177], v[248:249]
	v_pk_add_f32 v[174:175], v[174:175], v[246:247]
	v_pk_mul_f32 v[170:171], v[172:173], 0.5 op_sel_hi:[1, 0]
	v_pk_mul_f32 v[172:173], v[174:175], 0.5 op_sel_hi:[1, 0]
	v_lshl_add_u64 v[174:175], s[2:3], 0, v[168:169]
	v_lshlrev_b64 v[176:177], 12, v[178:179]
	v_lshl_add_u64 v[224:225], v[174:175], 0, v[176:177]
	global_load_dwordx4 v[212:215], v[224:225], off
	global_load_dwordx4 v[216:219], v[224:225], off offset:64
	global_load_dwordx4 v[220:223], v[224:225], off offset:512
	s_nop 0
	global_load_dwordx4 v[224:227], v[224:225], off offset:576
	v_lshl_add_u64 v[240:241], v[174:175], 0, v[244:245]
	global_load_dwordx4 v[228:231], v[240:241], off
	global_load_dwordx4 v[232:235], v[240:241], off offset:64
	global_load_dwordx4 v[236:239], v[240:241], off offset:512
	s_nop 0
	global_load_dwordx4 v[240:243], v[240:241], off offset:576
	s_waitcnt vmcnt(7)
	v_pk_fma_f32 v[124:125], v[124:125], v[158:159], v[212:213]
	v_lshl_add_u64 v[212:213], s[16:17], 0, v[176:177]
	v_lshl_add_u64 v[212:213], v[212:213], 0, v[168:169]
	s_waitcnt vmcnt(5)
	v_pk_fma_f32 v[114:115], v[114:115], v[164:165], v[222:223]
	v_pk_fma_f32 v[112:113], v[112:113], v[166:167], v[220:221]
	global_store_dwordx4 v[212:213], v[112:115], off offset:512 sc1
	s_waitcnt vmcnt(5)
	v_pk_fma_f32 v[106:107], v[106:107], v[170:171], v[226:227]
	v_pk_fma_f32 v[104:105], v[104:105], v[172:173], v[224:225]
	v_lshl_add_u64 v[112:113], s[16:17], 0, v[244:245]
	v_lshl_add_u64 v[112:113], v[112:113], 0, v[168:169]
	s_waitcnt vmcnt(1)
	v_pk_fma_f32 v[98:99], v[98:99], v[170:171], v[242:243]
	v_pk_fma_f32 v[96:97], v[96:97], v[172:173], v[240:241]
	global_store_dwordx4 v[212:213], v[104:107], off offset:576 sc1
	global_store_dwordx4 v[112:113], v[96:99], off offset:576 sc1
	v_pk_fma_f32 v[126:127], v[126:127], v[156:157], v[214:215]
	v_pk_fma_f32 v[106:107], v[118:119], v[156:157], v[230:231]
	v_pk_fma_f32 v[104:105], v[116:117], v[158:159], v[228:229]
	v_or_b32_e32 v96, 32, v178
	v_pk_fma_f32 v[122:123], v[122:123], v[160:161], v[218:219]
	v_pk_fma_f32 v[120:121], v[120:121], v[162:163], v[216:217]
	global_store_dwordx4 v[112:113], v[104:107], off sc1
	v_pk_fma_f32 v[102:103], v[102:103], v[164:165], v[238:239]
	v_pk_fma_f32 v[100:101], v[100:101], v[166:167], v[236:237]
	v_pk_fma_f32 v[106:107], v[110:111], v[160:161], v[234:235]
	v_pk_fma_f32 v[104:105], v[108:109], v[162:163], v[232:233]
	v_ashrrev_i32_e32 v97, 31, v96
	global_store_dwordx4 v[212:213], v[124:127], off sc1
	global_store_dwordx4 v[212:213], v[120:123], off offset:64 sc1
	global_store_dwordx4 v[112:113], v[104:107], off offset:64 sc1
	global_store_dwordx4 v[112:113], v[100:103], off offset:512 sc1
	v_lshlrev_b64 v[212:213], 12, v[96:97]
	v_or_b32_e32 v112, 48, v178
	v_lshl_add_u64 v[108:109], v[174:175], 0, v[212:213]
	v_ashrrev_i32_e32 v113, 31, v112
	global_load_dwordx4 v[96:99], v[108:109], off
	global_load_dwordx4 v[100:103], v[108:109], off offset:64
	global_load_dwordx4 v[104:107], v[108:109], off offset:512
	s_nop 0
	global_load_dwordx4 v[108:111], v[108:109], off offset:576
	v_lshlrev_b64 v[178:179], 12, v[112:113]
	v_lshl_add_u64 v[124:125], v[174:175], 0, v[178:179]
	global_load_dwordx4 v[112:115], v[124:125], off
	global_load_dwordx4 v[116:119], v[124:125], off offset:64
	global_load_dwordx4 v[120:123], v[124:125], off offset:512
	s_nop 0
	global_load_dwordx4 v[124:127], v[124:125], off offset:576
	s_waitcnt vmcnt(7)
	v_pk_fma_f32 v[92:93], v[92:93], v[158:159], v[96:97]
	v_lshl_add_u64 v[96:97], s[16:17], 0, v[212:213]
	v_lshl_add_u64 v[96:97], v[96:97], 0, v[168:169]
	s_waitcnt vmcnt(5)
	v_pk_fma_f32 v[82:83], v[82:83], v[164:165], v[106:107]
	v_pk_fma_f32 v[80:81], v[80:81], v[166:167], v[104:105]
	global_store_dwordx4 v[96:97], v[80:83], off offset:512 sc1
	s_waitcnt vmcnt(5)
	v_pk_fma_f32 v[74:75], v[74:75], v[170:171], v[110:111]
	v_pk_fma_f32 v[72:73], v[72:73], v[172:173], v[108:109]
	v_lshl_add_u64 v[80:81], s[16:17], 0, v[178:179]
	v_pk_fma_f32 v[94:95], v[94:95], v[156:157], v[98:99]
	v_pk_fma_f32 v[90:91], v[90:91], v[160:161], v[102:103]
	v_pk_fma_f32 v[88:89], v[88:89], v[162:163], v[100:101]
	global_store_dwordx4 v[96:97], v[72:75], off offset:576 sc1
	v_lshl_add_u64 v[80:81], v[80:81], 0, v[168:169]
	global_store_dwordx4 v[96:97], v[92:95], off sc1
	s_waitcnt vmcnt(6)
	v_pk_fma_f32 v[74:75], v[86:87], v[156:157], v[114:115]
	v_pk_fma_f32 v[72:73], v[84:85], v[158:159], v[112:113]
	global_store_dwordx4 v[96:97], v[88:91], off offset:64 sc1
	global_store_dwordx4 v[80:81], v[72:75], off sc1
	s_waitcnt vmcnt(6)
	v_pk_fma_f32 v[70:71], v[70:71], v[164:165], v[122:123]
	v_pk_fma_f32 v[68:69], v[68:69], v[166:167], v[120:121]
	v_pk_fma_f32 v[74:75], v[78:79], v[160:161], v[118:119]
	v_pk_fma_f32 v[72:73], v[76:77], v[162:163], v[116:117]
	s_waitcnt vmcnt(5)
	v_pk_fma_f32 v[66:67], v[66:67], v[170:171], v[126:127]
	v_pk_fma_f32 v[64:65], v[64:65], v[172:173], v[124:125]
	v_lshl_add_u64 v[96:97], v[176:177], 0, s[22:23]
	global_store_dwordx4 v[80:81], v[72:75], off offset:64 sc1
	global_store_dwordx4 v[80:81], v[68:71], off offset:512 sc1
	global_store_dwordx4 v[80:81], v[64:67], off offset:576 sc1
	v_lshl_add_u64 v[76:77], v[174:175], 0, v[96:97]
	global_load_dwordx4 v[64:67], v[76:77], off
	global_load_dwordx4 v[68:71], v[76:77], off offset:64
	global_load_dwordx4 v[72:75], v[76:77], off offset:512
	s_nop 0
	global_load_dwordx4 v[76:79], v[76:77], off offset:576
	v_lshl_add_u64 v[98:99], v[176:177], 0, s[24:25]
	v_lshl_add_u64 v[92:93], v[174:175], 0, v[98:99]
	global_load_dwordx4 v[80:83], v[92:93], off
	global_load_dwordx4 v[84:87], v[92:93], off offset:64
	global_load_dwordx4 v[88:91], v[92:93], off offset:512
	s_nop 0
	global_load_dwordx4 v[92:95], v[92:93], off offset:576
	s_waitcnt vmcnt(7)
	v_pk_fma_f32 v[60:61], v[60:61], v[158:159], v[64:65]
	v_lshl_add_u64 v[64:65], s[16:17], 0, v[96:97]
	v_lshl_add_u64 v[64:65], v[64:65], 0, v[168:169]
	s_waitcnt vmcnt(5)
	v_pk_fma_f32 v[50:51], v[50:51], v[164:165], v[74:75]
	v_pk_fma_f32 v[48:49], v[48:49], v[166:167], v[72:73]
	global_store_dwordx4 v[64:65], v[48:51], off offset:512 sc1
	s_waitcnt vmcnt(5)
	v_pk_fma_f32 v[42:43], v[42:43], v[170:171], v[78:79]
	v_pk_fma_f32 v[40:41], v[40:41], v[172:173], v[76:77]
	v_lshl_add_u64 v[48:49], s[16:17], 0, v[98:99]
	v_pk_fma_f32 v[62:63], v[62:63], v[156:157], v[66:67]
	v_pk_fma_f32 v[58:59], v[58:59], v[160:161], v[70:71]
	v_pk_fma_f32 v[56:57], v[56:57], v[162:163], v[68:69]
	global_store_dwordx4 v[64:65], v[40:43], off offset:576 sc1
	v_lshl_add_u64 v[48:49], v[48:49], 0, v[168:169]
	global_store_dwordx4 v[64:65], v[60:63], off sc1
	s_waitcnt vmcnt(6)
	v_pk_fma_f32 v[42:43], v[54:55], v[156:157], v[82:83]
	v_pk_fma_f32 v[40:41], v[52:53], v[158:159], v[80:81]
	global_store_dwordx4 v[64:65], v[56:59], off offset:64 sc1
	global_store_dwordx4 v[48:49], v[40:43], off sc1
	s_waitcnt vmcnt(6)
	v_pk_fma_f32 v[38:39], v[38:39], v[164:165], v[90:91]
	v_pk_fma_f32 v[36:37], v[36:37], v[166:167], v[88:89]
	v_pk_fma_f32 v[42:43], v[46:47], v[160:161], v[86:87]
	v_pk_fma_f32 v[40:41], v[44:45], v[162:163], v[84:85]
	s_waitcnt vmcnt(5)
	v_pk_fma_f32 v[30:31], v[30:31], v[170:171], v[94:95]
	v_pk_fma_f32 v[28:29], v[28:29], v[172:173], v[92:93]
	v_lshl_add_u64 v[64:65], v[176:177], 0, s[26:27]
	global_store_dwordx4 v[48:49], v[40:43], off offset:64 sc1
	global_store_dwordx4 v[48:49], v[36:39], off offset:512 sc1
	global_store_dwordx4 v[48:49], v[28:31], off offset:576 sc1
	v_lshl_add_u64 v[44:45], v[174:175], 0, v[64:65]
	global_load_dwordx4 v[28:31], v[44:45], off
	global_load_dwordx4 v[36:39], v[44:45], off offset:64
	global_load_dwordx4 v[40:43], v[44:45], off offset:512
	s_nop 0
	global_load_dwordx4 v[44:47], v[44:45], off offset:576
	v_lshl_add_u64 v[66:67], v[176:177], 0, s[28:29]
	v_lshl_add_u64 v[60:61], v[174:175], 0, v[66:67]
	global_load_dwordx4 v[48:51], v[60:61], off
	global_load_dwordx4 v[52:55], v[60:61], off offset:64
	global_load_dwordx4 v[56:59], v[60:61], off offset:512
	s_nop 0
	global_load_dwordx4 v[60:63], v[60:61], off offset:576
	s_waitcnt vmcnt(7)
	v_pk_fma_f32 v[28:29], v[32:33], v[158:159], v[28:29]
	v_lshl_add_u64 v[32:33], s[16:17], 0, v[64:65]
	v_lshl_add_u64 v[32:33], v[32:33], 0, v[168:169]
	s_waitcnt vmcnt(5)
	v_pk_fma_f32 v[18:19], v[18:19], v[164:165], v[42:43]
	v_pk_fma_f32 v[16:17], v[16:17], v[166:167], v[40:41]
	global_store_dwordx4 v[32:33], v[16:19], off offset:512 sc1
	s_waitcnt vmcnt(5)
	v_pk_fma_f32 v[10:11], v[10:11], v[170:171], v[46:47]
	v_pk_fma_f32 v[8:9], v[8:9], v[172:173], v[44:45]
	v_lshl_add_u64 v[16:17], s[16:17], 0, v[66:67]
	global_store_dwordx4 v[32:33], v[8:11], off offset:576 sc1
	v_lshl_add_u64 v[16:17], v[16:17], 0, v[168:169]
	v_pk_fma_f32 v[30:31], v[34:35], v[156:157], v[30:31]
	s_waitcnt vmcnt(5)
	v_pk_fma_f32 v[10:11], v[22:23], v[156:157], v[50:51]
	v_pk_fma_f32 v[8:9], v[20:21], v[158:159], v[48:49]
	v_pk_fma_f32 v[26:27], v[26:27], v[160:161], v[38:39]
	v_pk_fma_f32 v[24:25], v[24:25], v[162:163], v[36:37]
	global_store_dwordx4 v[16:17], v[8:11], off sc1
	s_waitcnt vmcnt(4)
	v_pk_fma_f32 v[6:7], v[6:7], v[164:165], v[58:59]
	v_pk_fma_f32 v[4:5], v[4:5], v[166:167], v[56:57]
	v_pk_fma_f32 v[10:11], v[14:15], v[160:161], v[54:55]
	v_pk_fma_f32 v[8:9], v[12:13], v[162:163], v[52:53]
	s_waitcnt vmcnt(3)
	v_pk_fma_f32 v[2:3], v[2:3], v[170:171], v[62:63]
	v_pk_fma_f32 v[0:1], v[0:1], v[172:173], v[60:61]
	global_store_dwordx4 v[32:33], v[28:31], off sc1
	global_store_dwordx4 v[32:33], v[24:27], off offset:64 sc1
	global_store_dwordx4 v[16:17], v[8:11], off offset:64 sc1
	global_store_dwordx4 v[16:17], v[4:7], off offset:512 sc1
	global_store_dwordx4 v[16:17], v[0:3], off offset:576 sc1
	s_waitcnt vmcnt(0)
	s_barrier
	s_and_saveexec_b64 s[38:39], s[4:5]
	s_cbranch_execz .LBB0_425
	s_lshl_b32 s40, s46, 2
	s_ashr_i32 s41, s40, 31
	s_lshl_b64 s[40:41], s[40:41], 2
	s_add_u32 s40, s65, s40
	s_addc_u32 s41, s66, s41
	s_getreg_b32 s42, hwreg(HW_REG_XCC_ID, 0, 4)
	global_load_dwordx4 v[0:3], v129, s[40:41]
	s_and_b32 s40, s42, 15
	s_add_i32 s40, s40, 1
	s_waitcnt vmcnt(0)
	v_cmp_ne_u32_e32 vcc, s40, v2
	s_nop 1
	v_cndmask_b32_e64 v2, 0, 1, vcc
	v_cmp_ne_u32_e32 vcc, s40, v3
	v_lshlrev_b32_e32 v2, 2, v2
	s_nop 0
	v_cndmask_b32_e64 v3, 0, 1, vcc
	v_cmp_ne_u32_e32 vcc, s40, v1
	v_lshlrev_b32_e32 v3, 3, v3
	v_or_b32_e32 v2, v3, v2
	v_cndmask_b32_e64 v1, 0, 1, vcc
	v_cmp_ne_u32_e32 vcc, s40, v0
	v_lshlrev_b32_e32 v1, 1, v1
	s_nop 0
	v_cndmask_b32_e64 v0, 0, 1, vcc
	v_or_b32_e32 v0, v0, v1
	v_and_b32_e32 v0, 3, v0
	v_or_b32_e32 v0, v0, v2
	v_and_b32_e32 v0, 15, v0
	v_cmp_eq_u32_e32 vcc, 0, v0
	s_cbranch_vccnz .LBB0_414
	buffer_wbl2 sc1
	s_waitcnt vmcnt(0)

.LBB0_425:
	s_or_b64 exec, exec, s[38:39]
	s_mul_hi_i32 s53, s49, 0x9000
	s_mul_i32 s52, s49, 0x9000
	s_mul_hi_i32 s51, s50, 0x9000
	s_add_i32 s50, s52, 0x48000
	v_lshl_add_u64 v[4:5], v[134:135], 0, s[52:53]
	s_mul_hi_i32 s49, s48, 0x9000
	s_add_i32 s48, s52, 0x90000
	s_barrier
	global_load_dwordx4 v[0:3], v[132:133], off
	v_lshl_add_u64 v[8:9], v[134:135], 0, s[50:51]
	global_load_dwordx4 v[4:7], v[4:5], off
	s_mul_hi_i32 s47, s47, 0x9000
	s_add_i32 s46, s52, 0xd8000
	global_load_dwordx4 v[8:11], v[8:9], off
	v_lshl_add_u64 v[12:13], v[134:135], 0, s[48:49]
	s_mul_hi_i32 s45, s81, 0x9000
	s_add_i32 s44, s52, 0x120000
	global_load_dwordx4 v[12:15], v[12:13], off
	v_lshl_add_u64 v[16:17], v[134:135], 0, s[46:47]
	s_mul_hi_i32 s43, s80, 0x9000
	s_add_i32 s42, s52, 0x168000
	global_load_dwordx4 v[16:19], v[16:17], off
	v_lshl_add_u64 v[20:21], v[134:135], 0, s[44:45]
	s_mul_hi_i32 s41, s79, 0x9000
	s_add_i32 s40, s52, 0x1b0000
	global_load_dwordx4 v[20:23], v[20:21], off
	v_lshl_add_u64 v[24:25], v[134:135], 0, s[42:43]
	s_mul_hi_i32 s39, s78, 0x9000
	s_add_i32 s38, s52, 0x1f8000
	global_load_dwordx4 v[24:27], v[24:25], off
	v_lshl_add_u64 v[28:29], v[134:135], 0, s[40:41]
	global_load_dwordx4 v[28:31], v[28:29], off
	v_lshl_add_u64 v[32:33], v[134:135], 0, s[38:39]
	global_load_dwordx4 v[32:35], v[32:33], off
	s_lshl_b32 s38, s76, 6
	s_ashr_i32 s39, s82, 3
	s_add_i32 s38, s77, s38
	s_and_b32 s39, s39, -8
	s_add_i32 s38, s38, s39
	s_ashr_i32 s39, s38, 31
	s_lshl_b64 s[40:41], s[38:39], 12
	v_lshl_add_u64 v[36:37], v[136:137], 0, s[40:41]
	s_or_b32 s44, s38, 1
	s_ashr_i32 s45, s44, 31
	s_lshl_b64 s[40:41], s[44:45], 12
	v_mov_b64_e32 v[88:89], s[34:35]
	s_or_b32 s42, s38, 2
	s_ashr_i32 s43, s42, 31
	s_lshl_b64 s[48:49], s[42:43], 12
	s_lshl_b64 s[46:47], s[38:39], 11
	s_waitcnt vmcnt(7)
	v_pk_add_f32 v[2:3], v[2:3], v[6:7]
	v_pk_add_f32 v[0:1], v[0:1], v[4:5]
	s_waitcnt vmcnt(6)
	v_pk_add_f32 v[2:3], v[2:3], v[10:11]
	v_pk_add_f32 v[0:1], v[0:1], v[8:9]
	v_lshl_add_u64 v[8:9], v[136:137], 0, s[40:41]
	s_or_b32 s40, s38, 3
	s_waitcnt vmcnt(5)
	v_pk_add_f32 v[2:3], v[2:3], v[14:15]
	v_pk_add_f32 v[0:1], v[0:1], v[12:13]
	s_ashr_i32 s41, s40, 31
	s_lshl_b64 s[50:51], s[40:41], 12
	s_waitcnt vmcnt(4)
	v_pk_add_f32 v[2:3], v[2:3], v[18:19]
	v_pk_add_f32 v[0:1], v[0:1], v[16:17]
	s_waitcnt vmcnt(3)
	v_pk_add_f32 v[2:3], v[2:3], v[22:23]
	v_pk_add_f32 v[0:1], v[0:1], v[20:21]
	s_waitcnt vmcnt(2)
	v_pk_add_f32 v[2:3], v[2:3], v[26:27]
	v_pk_add_f32 v[0:1], v[0:1], v[24:25]
	s_waitcnt vmcnt(1)
	v_pk_add_f32 v[2:3], v[2:3], v[30:31]
	v_pk_add_f32 v[0:1], v[0:1], v[28:29]
	s_waitcnt vmcnt(0)
	v_pk_add_f32 v[2:3], v[2:3], v[34:35]
	v_pk_add_f32 v[0:1], v[0:1], v[32:33]
	v_pk_add_f32 v[4:5], v[2:3], 1.0 op_sel_hi:[1,0]
	v_pk_add_f32 v[6:7], v[0:1], 1.0 op_sel_hi:[1,0]
	v_cndmask_b32_e64 v3, v5, v3, s[6:7]
	v_cndmask_b32_e64 v2, v4, v2, s[6:7]
	v_cndmask_b32_e64 v1, v7, v1, s[6:7]
	v_cndmask_b32_e64 v0, v6, v0, s[6:7]
	ds_write_b128 v183, v[0:3]
	s_waitcnt lgkmcnt(0)
	s_barrier
	global_load_dwordx4 v[108:111], v[138:139], off
	global_load_dwordx4 v[112:115], v[142:143], off
	global_load_dwordx4 v[116:119], v[144:145], off
	global_load_dwordx4 v[120:123], v[146:147], off
	global_load_dwordx4 v[16:19], v[36:37], off
	global_load_dwordx4 v[4:7], v[36:37], off offset:1024
	global_load_dwordx4 v[80:83], v[36:37], off offset:3072
	global_load_dwordx4 v[0:3], v[36:37], off offset:2048
	global_load_dwordx4 v[76:79], v[8:9], off
	global_load_dwordx4 v[68:71], v[8:9], off offset:1024
	s_nop 0
	global_load_dwordx4 v[36:39], v[8:9], off offset:3072
	global_load_dwordx4 v[64:67], v[8:9], off offset:2048
	s_waitcnt vmcnt(3)
	v_pk_mul_f32 v[28:29], v[78:79], v[78:79]
	v_pk_mul_f32 v[8:9], v[18:19], v[18:19]
	v_pk_mul_f32 v[10:11], v[16:17], v[16:17]
	v_pk_mul_f32 v[12:13], v[6:7], v[6:7]
	v_pk_mul_f32 v[14:15], v[4:5], v[4:5]
	v_mul_f32_e32 v24, v1, v1
	v_mul_f32_e32 v26, v3, v3
	v_pk_mul_f32 v[30:31], v[76:77], v[76:77]
	s_waitcnt vmcnt(2)
	v_pk_mul_f32 v[32:33], v[70:71], v[70:71]
	v_pk_mul_f32 v[34:35], v[68:69], v[68:69]
	v_mul_f32_e32 v47, v82, v82
	v_mul_f32_e32 v48, v83, v83
	v_pk_mov_b32 v[44:45], v[10:11], v[8:9] op_sel:[1, 0]
	v_mov_b32_e32 v11, v9
	v_pk_mov_b32 v[8:9], v[14:15], v[12:13] op_sel:[1, 0]
	v_mov_b32_e32 v15, v13
	v_pk_fma_f32 v[12:13], v[0:1], v[0:1], v[24:25] op_sel_hi:[1, 1, 0]
	v_pk_fma_f32 v[24:25], v[2:3], v[2:3], v[26:27] op_sel_hi:[1, 1, 0]
	v_pk_mov_b32 v[26:27], v[30:31], v[28:29] op_sel:[1, 0]
	v_mov_b32_e32 v31, v29
	v_pk_mov_b32 v[28:29], v[34:35], v[32:33] op_sel:[1, 0]
	v_mov_b32_e32 v35, v33
	v_mul_f32_e32 v43, v80, v80
	s_waitcnt vmcnt(0)
	v_mul_f32_e32 v40, v65, v65
	v_mul_f32_e32 v42, v67, v67
	v_pk_add_f32 v[10:11], v[44:45], v[10:11]
	v_pk_add_f32 v[8:9], v[8:9], v[14:15]
	v_mov_b32_e32 v13, v47
	v_mov_b32_e32 v25, v48
	v_pk_add_f32 v[14:15], v[26:27], v[30:31]
	v_pk_add_f32 v[26:27], v[28:29], v[34:35]
	v_mul_f32_e32 v46, v81, v81
	v_mul_f32_e32 v49, v36, v36
	v_mul_f32_e32 v50, v37, v37
	v_mul_f32_e32 v51, v38, v38
	v_mul_f32_e32 v52, v39, v39
	v_pk_fma_f32 v[32:33], v[64:65], v[64:65], v[40:41] op_sel_hi:[1, 1, 0]
	v_pk_fma_f32 v[40:41], v[66:67], v[66:67], v[42:43] op_sel_hi:[1, 1, 0]
	v_pk_add_f32 v[10:11], v[10:11], v[10:11] op_sel:[0, 1] op_sel_hi:[1, 0]
	v_pk_add_f32 v[8:9], v[8:9], v[8:9] op_sel:[0, 1] op_sel_hi:[1, 0]
	v_pk_add_f32 v[12:13], v[12:13], v[24:25]
	v_pk_add_f32 v[14:15], v[14:15], v[14:15] op_sel:[0, 1] op_sel_hi:[1, 0]
	v_pk_add_f32 v[24:25], v[26:27], v[26:27] op_sel:[0, 1] op_sel_hi:[1, 0]
	v_mov_b32_e32 v33, v51
	v_mov_b32_e32 v41, v52
	v_mov_b32_e32 v11, v43
	v_mov_b32_e32 v9, v46
	v_mov_b32_e32 v15, v49
	v_mov_b32_e32 v25, v50
	v_pk_add_f32 v[26:27], v[32:33], v[40:41]
	v_pk_add_f32 v[8:9], v[10:11], v[8:9]
	v_pk_add_f32 v[10:11], v[14:15], v[24:25]
	v_pk_add_f32 v[8:9], v[8:9], v[12:13]
	v_pk_add_f32 v[10:11], v[10:11], v[26:27]
	v_mov_b32_e32 v13, v8
	v_mov_b32_e32 v12, v10
	v_mov_b32_e32 v8, v11
	v_pk_add_f32 v[8:9], v[12:13], v[8:9]
	v_lshl_add_u64 v[12:13], v[136:137], 0, s[48:49]
	v_lshl_add_u64 v[14:15], v[136:137], 0, s[50:51]
	global_load_dwordx4 v[72:75], v[12:13], off
	global_load_dwordx4 v[60:63], v[12:13], off offset:1024
	global_load_dwordx4 v[56:59], v[12:13], off offset:2048
	global_load_dwordx4 v[52:55], v[12:13], off offset:3072
	global_load_dwordx4 v[48:51], v[14:15], off
	global_load_dwordx4 v[44:47], v[14:15], off offset:1024
	s_waitcnt lgkmcnt(0)
	s_nop 1
	v_add_f32_dpp v8, v8, v8 quad_perm:[1,0,3,2] row_mask:0xf bank_mask:0xf
	v_add_f32_dpp v9, v9, v9 quad_perm:[1,0,3,2] row_mask:0xf bank_mask:0xf
	global_load_dwordx4 v[40:43], v[14:15], off offset:2048
	global_load_dwordx4 v[32:35], v[14:15], off offset:3072
	v_lshl_add_u64 v[24:25], v[140:141], 0, s[46:47]
	s_add_u32 s46, s20, s46
	s_addc_u32 s47, s21, s47
	s_waitcnt lgkmcnt(0)
	s_nop 1
	v_add_f32_dpp v8, v8, v8 quad_perm:[2,3,0,1] row_mask:0xf bank_mask:0xf
	v_add_f32_dpp v9, v9, v9 quad_perm:[2,3,0,1] row_mask:0xf bank_mask:0xf
	s_lshl_b64 s[44:45], s[44:45], 11
	s_waitcnt lgkmcnt(0)
	s_nop 1
	v_add_f32_dpp v8, v8, v8 row_half_mirror row_mask:0xf bank_mask:0xf
	v_add_f32_dpp v9, v9, v9 row_half_mirror row_mask:0xf bank_mask:0xf
	s_waitcnt lgkmcnt(0)
	s_nop 1
	v_add_f32_dpp v8, v8, v8 row_mirror row_mask:0xf bank_mask:0xf
	v_add_f32_dpp v9, v9, v9 row_mirror row_mask:0xf bank_mask:0xf
	ds_bpermute_b32 v11, v188, v9
	ds_bpermute_b32 v10, v188, v8
	s_waitcnt lgkmcnt(0)
	v_pk_add_f32 v[8:9], v[8:9], v[10:11]
	s_waitcnt lgkmcnt(0)
	v_mov_b32_e32 v10, v8
	v_mov_b32_e32 v11, v9
	s_nop 1
	v_permlane32_swap_b32_e32 v10, v8
	v_permlane32_swap_b32_e32 v11, v9
	v_pk_add_f32 v[8:9], v[8:9], v[10:11]
	s_nop 0
	v_pk_fma_f32 v[90:91], v[8:9], s[30:31], v[88:89] op_sel_hi:[1, 0, 0]
	s_waitcnt vmcnt(4)
	v_mul_f32_e32 v99, v53, v53
	v_mul_f32_e32 v8, 0x4b800000, v91
	v_cmp_gt_f32_e32 vcc, s73, v91
	s_waitcnt vmcnt(2)
	v_pk_mul_f32 v[94:95], v[44:45], v[44:45]
	v_mul_f32_e32 v102, v54, v54
	v_cndmask_b32_e32 v8, v91, v8, vcc
	v_rsq_f32_e32 v26, v8
	ds_read_b128 v[8:11], v190
	ds_read_b128 v[12:15], v191
	s_waitcnt vmcnt(1)
	v_mul_f32_e32 v96, v41, v41
	v_mul_f32_e32 v98, v43, v43
	v_mul_f32_e32 v27, 0x45800000, v26
	v_cndmask_b32_e32 v92, v26, v27, vcc
	v_pk_mul_f32 v[18:19], v[18:19], v[92:93] op_sel_hi:[1, 0]
	v_pk_mul_f32 v[16:17], v[16:17], v[92:93] op_sel_hi:[1, 0]
	v_pk_mul_f32 v[18:19], v[110:111], v[18:19]
	v_pk_mul_f32 v[16:17], v[108:109], v[16:17]
	s_waitcnt lgkmcnt(0)
	v_pk_fma_f32 v[18:19], v[14:15], v[18:19], v[10:11]
	v_pk_fma_f32 v[16:17], v[12:13], v[16:17], v[8:9]
	v_pk_mul_f32 v[6:7], v[6:7], v[92:93] op_sel_hi:[1, 0]
	v_cvt_pk_bf16_f32 v16, v16, v17
	v_cvt_pk_bf16_f32 v17, v18, v19
	global_store_dwordx2 v[24:25], v[16:17], off sc1
	ds_read_b128 v[16:19], v192
	ds_read_b128 v[20:23], v193
	v_pk_mul_f32 v[4:5], v[4:5], v[92:93] op_sel_hi:[1, 0]
	v_pk_mul_f32 v[2:3], v[2:3], v[92:93] op_sel_hi:[1, 0]
	v_pk_mul_f32 v[0:1], v[0:1], v[92:93] op_sel_hi:[1, 0]
	v_pk_mul_f32 v[82:83], v[82:83], v[92:93] op_sel_hi:[1, 0]
	v_pk_mul_f32 v[80:81], v[80:81], v[92:93] op_sel_hi:[1, 0]
	v_cmp_gt_f32_e32 vcc, s73, v90
	v_pk_mul_f32 v[92:93], v[46:47], v[46:47]
	v_mul_f32_e32 v103, v55, v55
	s_waitcnt vmcnt(1)
	v_mul_f32_e32 v104, v32, v32
	v_mul_f32_e32 v105, v33, v33
	v_mul_f32_e32 v106, v34, v34
	v_mul_f32_e32 v107, v35, v35
	v_pk_mul_f32 v[4:5], v[112:113], v[4:5]
	v_pk_mul_f32 v[6:7], v[114:115], v[6:7]
	s_waitcnt lgkmcnt(0)
	v_pk_fma_f32 v[4:5], v[20:21], v[4:5], v[16:17]
	v_pk_fma_f32 v[6:7], v[22:23], v[6:7], v[18:19]
	v_cvt_pk_bf16_f32 v4, v4, v5
	v_cvt_pk_bf16_f32 v5, v6, v7
	global_store_dwordx2 v200, v[4:5], s[46:47] sc1
	ds_read_b128 v[24:27], v194
	ds_read_b128 v[28:31], v195
	v_pk_mul_f32 v[0:1], v[116:117], v[0:1]
	v_pk_mul_f32 v[2:3], v[118:119], v[2:3]
	s_waitcnt lgkmcnt(0)
	v_pk_fma_f32 v[0:1], v[28:29], v[0:1], v[24:25]
	v_pk_fma_f32 v[2:3], v[30:31], v[2:3], v[26:27]
	v_cvt_pk_bf16_f32 v0, v0, v1
	v_cvt_pk_bf16_f32 v1, v2, v3
	global_store_dwordx2 v201, v[0:1], s[46:47] sc1
	ds_read_b128 v[0:3], v196
	ds_read_b128 v[4:7], v197
	v_pk_mul_f32 v[80:81], v[80:81], v[120:121]
	v_pk_mul_f32 v[82:83], v[82:83], v[122:123]
	s_waitcnt lgkmcnt(0)
	v_pk_fma_f32 v[80:81], v[80:81], v[4:5], v[0:1]
	v_pk_fma_f32 v[82:83], v[82:83], v[6:7], v[2:3]
	v_cvt_pk_bf16_f32 v80, v80, v81
	v_cvt_pk_bf16_f32 v81, v82, v83
	global_store_dwordx2 v210, v[80:81], s[46:47] sc1
	v_mul_f32_e32 v84, 0x4b800000, v90
	v_cndmask_b32_e32 v84, v90, v84, vcc
	v_rsq_f32_e32 v86, v84
	v_lshl_add_u64 v[84:85], v[140:141], 0, s[44:45]
	s_add_u32 s44, s20, s44
	s_addc_u32 s45, s21, s45
	v_mul_f32_e32 v87, 0x45800000, v86
	v_cndmask_b32_e32 v86, v86, v87, vcc
	v_pk_mul_f32 v[78:79], v[78:79], v[86:87] op_sel_hi:[1, 0]
	v_pk_mul_f32 v[76:77], v[76:77], v[86:87] op_sel_hi:[1, 0]
	v_pk_mul_f32 v[70:71], v[70:71], v[86:87] op_sel_hi:[1, 0]
	v_pk_mul_f32 v[68:69], v[68:69], v[86:87] op_sel_hi:[1, 0]
	v_pk_mul_f32 v[66:67], v[66:67], v[86:87] op_sel_hi:[1, 0]
	v_pk_mul_f32 v[64:65], v[64:65], v[86:87] op_sel_hi:[1, 0]
	v_mul_f32_e32 v87, v52, v52
	v_pk_mul_f32 v[38:39], v[38:39], v[86:87] op_sel_hi:[1, 0]
	v_pk_mul_f32 v[36:37], v[36:37], v[86:87] op_sel_hi:[1, 0]
	v_pk_mul_f32 v[90:91], v[48:49], v[48:49]
	s_lshl_b64 s[42:43], s[42:43], 11
	v_pk_mul_f32 v[76:77], v[108:109], v[76:77]
	v_pk_mul_f32 v[78:79], v[110:111], v[78:79]
	v_pk_fma_f32 v[76:77], v[12:13], v[76:77], v[8:9]
	v_pk_fma_f32 v[78:79], v[14:15], v[78:79], v[10:11]
	v_cvt_pk_bf16_f32 v76, v76, v77
	v_cvt_pk_bf16_f32 v77, v78, v79
	global_store_dwordx2 v[84:85], v[76:77], off sc1
	v_mul_f32_e32 v80, v57, v57
	v_mul_f32_e32 v82, v59, v59
	v_pk_mul_f32 v[84:85], v[50:51], v[50:51]
	v_pk_mul_f32 v[68:69], v[112:113], v[68:69]
	v_pk_mul_f32 v[70:71], v[114:115], v[70:71]
	v_pk_fma_f32 v[68:69], v[20:21], v[68:69], v[16:17]
	v_pk_fma_f32 v[70:71], v[22:23], v[70:71], v[18:19]
	v_cvt_pk_bf16_f32 v68, v68, v69
	v_cvt_pk_bf16_f32 v69, v70, v71
	global_store_dwordx2 v200, v[68:69], s[44:45] sc1
	v_pk_mul_f32 v[76:77], v[62:63], v[62:63]
	v_pk_mul_f32 v[78:79], v[60:61], v[60:61]
	v_pk_mul_f32 v[64:65], v[116:117], v[64:65]
	v_pk_mul_f32 v[66:67], v[118:119], v[66:67]
	v_pk_fma_f32 v[64:65], v[28:29], v[64:65], v[24:25]
	v_pk_fma_f32 v[66:67], v[30:31], v[66:67], v[26:27]
	v_cvt_pk_bf16_f32 v64, v64, v65
	v_cvt_pk_bf16_f32 v65, v66, v67
	global_store_dwordx2 v201, v[64:65], s[44:45] sc1
	v_pk_mul_f32 v[68:69], v[74:75], v[74:75]
	v_pk_mul_f32 v[70:71], v[72:73], v[72:73]
	v_pk_mul_f32 v[36:37], v[120:121], v[36:37]
	v_pk_mul_f32 v[38:39], v[122:123], v[38:39]
	v_pk_fma_f32 v[36:37], v[4:5], v[36:37], v[0:1]
	v_pk_fma_f32 v[38:39], v[6:7], v[38:39], v[2:3]
	v_cvt_pk_bf16_f32 v36, v36, v37
	v_cvt_pk_bf16_f32 v37, v38, v39
	global_store_dwordx2 v210, v[36:37], s[44:45] sc1
	v_pk_mov_b32 v[100:101], v[70:71], v[68:69] op_sel:[1, 0]
	v_mov_b32_e32 v71, v69
	v_pk_mov_b32 v[68:69], v[78:79], v[76:77] op_sel:[1, 0]
	v_mov_b32_e32 v79, v77
	v_pk_fma_f32 v[76:77], v[56:57], v[56:57], v[80:81] op_sel_hi:[1, 1, 0]
	v_pk_fma_f32 v[80:81], v[58:59], v[58:59], v[82:83] op_sel_hi:[1, 1, 0]
	v_pk_mov_b32 v[82:83], v[90:91], v[84:85] op_sel:[1, 0]
	v_mov_b32_e32 v91, v85
	v_pk_mov_b32 v[84:85], v[94:95], v[92:93] op_sel:[1, 0]
	v_mov_b32_e32 v95, v93
	v_pk_add_f32 v[70:71], v[100:101], v[70:71]
	v_pk_add_f32 v[64:65], v[68:69], v[78:79]
	v_pk_add_f32 v[66:67], v[82:83], v[90:91]
	v_pk_add_f32 v[68:69], v[84:85], v[94:95]
	v_pk_fma_f32 v[92:93], v[40:41], v[40:41], v[96:97] op_sel_hi:[1, 1, 0]
	v_pk_fma_f32 v[96:97], v[42:43], v[42:43], v[98:99] op_sel_hi:[1, 1, 0]
	v_pk_add_f32 v[70:71], v[70:71], v[70:71] op_sel:[0, 1] op_sel_hi:[1, 0]
	v_pk_add_f32 v[64:65], v[64:65], v[64:65] op_sel:[0, 1] op_sel_hi:[1, 0]
	v_pk_add_f32 v[66:67], v[66:67], v[66:67] op_sel:[0, 1] op_sel_hi:[1, 0]
	v_pk_add_f32 v[68:69], v[68:69], v[68:69] op_sel:[0, 1] op_sel_hi:[1, 0]
	v_mov_b32_e32 v77, v102
	v_mov_b32_e32 v81, v103
	v_mov_b32_e32 v93, v106
	v_mov_b32_e32 v97, v107
	v_mov_b32_e32 v71, v87
	v_mov_b32_e32 v65, v99
	v_mov_b32_e32 v67, v104
	v_mov_b32_e32 v69, v105
	v_pk_add_f32 v[76:77], v[76:77], v[80:81]
	v_pk_add_f32 v[78:79], v[92:93], v[96:97]
	v_pk_add_f32 v[64:65], v[70:71], v[64:65]
	v_pk_add_f32 v[66:67], v[66:67], v[68:69]
	v_pk_add_f32 v[64:65], v[64:65], v[76:77]
	v_pk_add_f32 v[66:67], v[66:67], v[78:79]
	v_mov_b32_e32 v69, v64
	v_mov_b32_e32 v68, v66
	v_mov_b32_e32 v64, v67
	v_pk_add_f32 v[64:65], v[68:69], v[64:65]
	s_waitcnt lgkmcnt(0)
	s_nop 1
	v_add_f32_dpp v64, v64, v64 quad_perm:[1,0,3,2] row_mask:0xf bank_mask:0xf
	v_add_f32_dpp v65, v65, v65 quad_perm:[1,0,3,2] row_mask:0xf bank_mask:0xf
	s_waitcnt lgkmcnt(0)
	s_nop 1
	v_add_f32_dpp v64, v64, v64 quad_perm:[2,3,0,1] row_mask:0xf bank_mask:0xf
	v_add_f32_dpp v65, v65, v65 quad_perm:[2,3,0,1] row_mask:0xf bank_mask:0xf
	s_waitcnt lgkmcnt(0)
	s_nop 1
	v_add_f32_dpp v64, v64, v64 row_half_mirror row_mask:0xf bank_mask:0xf
	v_add_f32_dpp v65, v65, v65 row_half_mirror row_mask:0xf bank_mask:0xf
	s_waitcnt lgkmcnt(0)
	s_nop 1
	v_add_f32_dpp v64, v64, v64 row_mirror row_mask:0xf bank_mask:0xf
	v_add_f32_dpp v65, v65, v65 row_mirror row_mask:0xf bank_mask:0xf
	ds_bpermute_b32 v67, v188, v65
	ds_bpermute_b32 v66, v188, v64
	s_waitcnt lgkmcnt(0)
	v_pk_add_f32 v[64:65], v[64:65], v[66:67]
	s_waitcnt lgkmcnt(0)
	v_mov_b32_e32 v66, v64
	v_mov_b32_e32 v67, v65
	s_nop 1
	v_permlane32_swap_b32_e32 v66, v64
	v_permlane32_swap_b32_e32 v67, v65
	v_pk_add_f32 v[64:65], v[64:65], v[66:67]
	s_nop 0
	v_pk_fma_f32 v[64:65], v[64:65], s[30:31], v[88:89] op_sel_hi:[1, 0, 0]
	s_nop 0
	v_mul_f32_e32 v66, 0x4b800000, v65
	v_cmp_gt_f32_e32 vcc, s73, v65
	s_nop 1
	v_cndmask_b32_e32 v65, v65, v66, vcc
	v_rsq_f32_e32 v65, v65
	v_lshl_add_u64 v[66:67], v[140:141], 0, s[42:43]
	s_add_u32 s42, s20, s42
	s_addc_u32 s43, s21, s43
	v_mul_f32_e32 v68, 0x45800000, v65
	v_cndmask_b32_e32 v68, v65, v68, vcc
	v_pk_mul_f32 v[70:71], v[74:75], v[68:69] op_sel_hi:[1, 0]
	v_pk_mul_f32 v[72:73], v[72:73], v[68:69] op_sel_hi:[1, 0]
	v_pk_mul_f32 v[38:39], v[110:111], v[70:71]
	v_pk_mul_f32 v[36:37], v[108:109], v[72:73]
	v_pk_fma_f32 v[38:39], v[14:15], v[38:39], v[10:11]
	v_pk_fma_f32 v[36:37], v[12:13], v[36:37], v[8:9]
	v_pk_mul_f32 v[62:63], v[62:63], v[68:69] op_sel_hi:[1, 0]
	v_cvt_pk_bf16_f32 v36, v36, v37
	v_cvt_pk_bf16_f32 v37, v38, v39
	global_store_dwordx2 v[66:67], v[36:37], off sc1
	v_pk_mul_f32 v[60:61], v[60:61], v[68:69] op_sel_hi:[1, 0]
	v_pk_mul_f32 v[58:59], v[58:59], v[68:69] op_sel_hi:[1, 0]
	v_pk_mul_f32 v[56:57], v[56:57], v[68:69] op_sel_hi:[1, 0]
	v_pk_mul_f32 v[54:55], v[54:55], v[68:69] op_sel_hi:[1, 0]
	v_pk_mul_f32 v[52:53], v[52:53], v[68:69] op_sel_hi:[1, 0]
	v_cmp_gt_f32_e32 vcc, s73, v64
	s_lshl_b64 s[40:41], s[40:41], 11
	v_pk_mul_f32 v[36:37], v[112:113], v[60:61]
	v_pk_mul_f32 v[38:39], v[114:115], v[62:63]
	v_pk_fma_f32 v[36:37], v[20:21], v[36:37], v[16:17]
	v_pk_fma_f32 v[38:39], v[22:23], v[38:39], v[18:19]
	v_cvt_pk_bf16_f32 v36, v36, v37
	v_cvt_pk_bf16_f32 v37, v38, v39
	global_store_dwordx2 v200, v[36:37], s[42:43] sc1
	v_pk_mul_f32 v[36:37], v[116:117], v[56:57]
	v_pk_mul_f32 v[38:39], v[118:119], v[58:59]
	v_pk_fma_f32 v[36:37], v[28:29], v[36:37], v[24:25]
	v_pk_fma_f32 v[38:39], v[30:31], v[38:39], v[26:27]
	v_cvt_pk_bf16_f32 v36, v36, v37
	v_cvt_pk_bf16_f32 v37, v38, v39
	global_store_dwordx2 v201, v[36:37], s[42:43] sc1
	v_pk_mul_f32 v[36:37], v[120:121], v[52:53]
	v_pk_mul_f32 v[38:39], v[122:123], v[54:55]
	v_pk_fma_f32 v[36:37], v[4:5], v[36:37], v[0:1]
	v_pk_fma_f32 v[38:39], v[6:7], v[38:39], v[2:3]
	v_cvt_pk_bf16_f32 v36, v36, v37
	v_cvt_pk_bf16_f32 v37, v38, v39
	global_store_dwordx2 v210, v[36:37], s[42:43] sc1
	v_mul_f32_e32 v52, 0x4b800000, v64
	v_cndmask_b32_e32 v52, v64, v52, vcc
	v_rsq_f32_e32 v54, v52
	v_lshl_add_u64 v[52:53], v[140:141], 0, s[40:41]
	s_add_u32 s40, s20, s40
	s_addc_u32 s41, s21, s41
	v_mul_f32_e32 v55, 0x45800000, v54
	v_cndmask_b32_e32 v54, v54, v55, vcc
	v_pk_mul_f32 v[50:51], v[50:51], v[54:55] op_sel_hi:[1, 0]
	v_pk_mul_f32 v[48:49], v[48:49], v[54:55] op_sel_hi:[1, 0]
	v_pk_mul_f32 v[46:47], v[46:47], v[54:55] op_sel_hi:[1, 0]
	v_pk_mul_f32 v[44:45], v[44:45], v[54:55] op_sel_hi:[1, 0]
	v_pk_mul_f32 v[42:43], v[42:43], v[54:55] op_sel_hi:[1, 0]
	v_pk_mul_f32 v[40:41], v[40:41], v[54:55] op_sel_hi:[1, 0]
	v_pk_mul_f32 v[34:35], v[34:35], v[54:55] op_sel_hi:[1, 0]
	v_pk_mul_f32 v[32:33], v[32:33], v[54:55] op_sel_hi:[1, 0]
	s_or_b32 s44, s38, 4
	s_ashr_i32 s45, s44, 31
	s_lshl_b64 s[42:43], s[44:45], 12
	s_lshl_b64 s[44:45], s[44:45], 11
	v_lshl_add_u64 v[104:105], v[140:141], 0, s[44:45]
	v_pk_mul_f32 v[36:37], v[108:109], v[48:49]
	v_pk_mul_f32 v[38:39], v[110:111], v[50:51]
	v_pk_fma_f32 v[36:37], v[12:13], v[36:37], v[8:9]
	v_pk_fma_f32 v[38:39], v[14:15], v[38:39], v[10:11]
	v_cvt_pk_bf16_f32 v36, v36, v37
	v_cvt_pk_bf16_f32 v37, v38, v39
	global_store_dwordx2 v[52:53], v[36:37], off sc1
	v_pk_mul_f32 v[36:37], v[112:113], v[44:45]
	v_pk_mul_f32 v[38:39], v[114:115], v[46:47]
	v_pk_fma_f32 v[36:37], v[20:21], v[36:37], v[16:17]
	v_pk_fma_f32 v[38:39], v[22:23], v[38:39], v[18:19]
	v_cvt_pk_bf16_f32 v36, v36, v37
	v_cvt_pk_bf16_f32 v37, v38, v39
	global_store_dwordx2 v200, v[36:37], s[40:41] sc1
	v_pk_mul_f32 v[36:37], v[116:117], v[40:41]
	v_pk_mul_f32 v[38:39], v[118:119], v[42:43]
	v_pk_fma_f32 v[36:37], v[28:29], v[36:37], v[24:25]
	v_pk_fma_f32 v[38:39], v[30:31], v[38:39], v[26:27]
	v_cvt_pk_bf16_f32 v36, v36, v37
	v_cvt_pk_bf16_f32 v37, v38, v39
	global_store_dwordx2 v201, v[36:37], s[40:41] sc1
	v_lshl_add_u64 v[40:41], v[136:137], 0, s[42:43]
	s_or_b32 s42, s38, 5
	s_ashr_i32 s43, s42, 31
	v_pk_mul_f32 v[32:33], v[120:121], v[32:33]
	v_pk_mul_f32 v[34:35], v[122:123], v[34:35]
	v_pk_fma_f32 v[32:33], v[4:5], v[32:33], v[0:1]
	v_pk_fma_f32 v[34:35], v[6:7], v[34:35], v[2:3]
	v_cvt_pk_bf16_f32 v32, v32, v33
	v_cvt_pk_bf16_f32 v33, v34, v35
	global_store_dwordx2 v210, v[32:33], s[40:41] sc1
	global_load_dwordx4 v[90:93], v[40:41], off
	global_load_dwordx4 v[94:97], v[40:41], off offset:1024
	global_load_dwordx4 v[80:83], v[40:41], off offset:3072
	global_load_dwordx4 v[84:87], v[40:41], off offset:2048
	s_lshl_b64 s[40:41], s[42:43], 12
	v_lshl_add_u64 v[32:33], v[136:137], 0, s[40:41]
	global_load_dwordx4 v[76:79], v[32:33], off
	global_load_dwordx4 v[72:75], v[32:33], off offset:1024
	global_load_dwordx4 v[36:39], v[32:33], off offset:3072
	global_load_dwordx4 v[68:71], v[32:33], off offset:2048
	s_or_b32 s40, s38, 6
	s_or_b32 s38, s38, 7
	s_ashr_i32 s41, s40, 31
	s_ashr_i32 s39, s38, 31
	s_lshl_b64 s[46:47], s[40:41], 12
	s_lshl_b64 s[48:49], s[38:39], 12
	s_add_u32 s44, s20, s44
	s_addc_u32 s45, s21, s45
	s_lshl_b64 s[42:43], s[42:43], 11
	s_waitcnt vmcnt(7)
	v_pk_mul_f32 v[32:33], v[92:93], v[92:93]
	v_pk_mul_f32 v[34:35], v[90:91], v[90:91]
	s_waitcnt vmcnt(6)
	v_pk_mul_f32 v[40:41], v[96:97], v[96:97]
	v_pk_mul_f32 v[42:43], v[94:95], v[94:95]
	s_waitcnt vmcnt(4)
	v_mul_f32_e32 v44, v85, v85
	v_mul_f32_e32 v46, v87, v87
	s_waitcnt vmcnt(3)
	v_pk_mul_f32 v[48:49], v[78:79], v[78:79]
	v_pk_mul_f32 v[50:51], v[76:77], v[76:77]
	s_waitcnt vmcnt(2)
	v_pk_mul_f32 v[52:53], v[74:75], v[74:75]
	v_pk_mul_f32 v[54:55], v[72:73], v[72:73]
	v_mul_f32_e32 v63, v82, v82
	v_mul_f32_e32 v64, v83, v83
	v_pk_mov_b32 v[60:61], v[34:35], v[32:33] op_sel:[1, 0]
	v_mov_b32_e32 v35, v33
	v_pk_mov_b32 v[32:33], v[42:43], v[40:41] op_sel:[1, 0]
	v_mov_b32_e32 v43, v41
	v_pk_fma_f32 v[40:41], v[84:85], v[84:85], v[44:45] op_sel_hi:[1, 1, 0]
	v_pk_fma_f32 v[44:45], v[86:87], v[86:87], v[46:47] op_sel_hi:[1, 1, 0]
	v_pk_mov_b32 v[46:47], v[50:51], v[48:49] op_sel:[1, 0]
	v_mov_b32_e32 v51, v49
	v_pk_mov_b32 v[48:49], v[54:55], v[52:53] op_sel:[1, 0]
	v_mov_b32_e32 v55, v53
	v_mul_f32_e32 v59, v80, v80
	s_waitcnt vmcnt(0)
	v_mul_f32_e32 v56, v69, v69
	v_mul_f32_e32 v58, v71, v71
	v_pk_add_f32 v[34:35], v[60:61], v[34:35]
	v_pk_add_f32 v[32:33], v[32:33], v[42:43]
	v_mov_b32_e32 v41, v63
	v_mov_b32_e32 v45, v64
	v_pk_add_f32 v[42:43], v[46:47], v[50:51]
	v_pk_add_f32 v[46:47], v[48:49], v[54:55]
	v_mul_f32_e32 v62, v81, v81
	v_mul_f32_e32 v65, v36, v36
	v_mul_f32_e32 v66, v37, v37
	v_mul_f32_e32 v67, v38, v38
	v_mul_f32_e32 v102, v39, v39
	v_pk_fma_f32 v[52:53], v[68:69], v[68:69], v[56:57] op_sel_hi:[1, 1, 0]
	v_pk_fma_f32 v[56:57], v[70:71], v[70:71], v[58:59] op_sel_hi:[1, 1, 0]
	v_pk_add_f32 v[34:35], v[34:35], v[34:35] op_sel:[0, 1] op_sel_hi:[1, 0]
	v_pk_add_f32 v[32:33], v[32:33], v[32:33] op_sel:[0, 1] op_sel_hi:[1, 0]
	v_pk_add_f32 v[40:41], v[40:41], v[44:45]
	v_pk_add_f32 v[42:43], v[42:43], v[42:43] op_sel:[0, 1] op_sel_hi:[1, 0]
	v_pk_add_f32 v[44:45], v[46:47], v[46:47] op_sel:[0, 1] op_sel_hi:[1, 0]
	v_mov_b32_e32 v53, v67
	v_mov_b32_e32 v57, v102
	v_mov_b32_e32 v35, v59
	v_mov_b32_e32 v33, v62
	v_mov_b32_e32 v43, v65
	v_mov_b32_e32 v45, v66
	v_pk_add_f32 v[46:47], v[52:53], v[56:57]
	v_pk_add_f32 v[32:33], v[34:35], v[32:33]
	v_pk_add_f32 v[34:35], v[42:43], v[44:45]
	v_pk_add_f32 v[32:33], v[32:33], v[40:41]
	v_pk_add_f32 v[34:35], v[34:35], v[46:47]
	v_mov_b32_e32 v41, v32
	v_mov_b32_e32 v40, v34
	v_mov_b32_e32 v32, v35
	v_pk_add_f32 v[32:33], v[40:41], v[32:33]
	v_lshl_add_u64 v[40:41], v[136:137], 0, s[46:47]
	v_lshl_add_u64 v[102:103], v[136:137], 0, s[48:49]
	global_load_dwordx4 v[64:67], v[40:41], off
	global_load_dwordx4 v[60:63], v[40:41], off offset:1024
	global_load_dwordx4 v[56:59], v[40:41], off offset:2048
	global_load_dwordx4 v[52:55], v[40:41], off offset:3072
	s_waitcnt lgkmcnt(0)
	s_nop 1
	v_add_f32_dpp v32, v32, v32 quad_perm:[1,0,3,2] row_mask:0xf bank_mask:0xf
	v_add_f32_dpp v33, v33, v33 quad_perm:[1,0,3,2] row_mask:0xf bank_mask:0xf
	s_waitcnt lgkmcnt(0)
	s_nop 1
	v_add_f32_dpp v32, v32, v32 quad_perm:[2,3,0,1] row_mask:0xf bank_mask:0xf
	v_add_f32_dpp v33, v33, v33 quad_perm:[2,3,0,1] row_mask:0xf bank_mask:0xf
	s_waitcnt lgkmcnt(0)
	s_nop 1
	v_add_f32_dpp v32, v32, v32 row_half_mirror row_mask:0xf bank_mask:0xf
	v_add_f32_dpp v33, v33, v33 row_half_mirror row_mask:0xf bank_mask:0xf
	s_waitcnt lgkmcnt(0)
	s_nop 1
	v_add_f32_dpp v32, v32, v32 row_mirror row_mask:0xf bank_mask:0xf
	v_add_f32_dpp v33, v33, v33 row_mirror row_mask:0xf bank_mask:0xf
	ds_bpermute_b32 v35, v188, v33
	ds_bpermute_b32 v34, v188, v32
	s_waitcnt lgkmcnt(0)
	v_pk_add_f32 v[32:33], v[32:33], v[34:35]
	s_waitcnt lgkmcnt(0)
	v_mov_b32_e32 v34, v32
	v_mov_b32_e32 v35, v33
	s_nop 1
	v_permlane32_swap_b32_e32 v34, v32
	v_permlane32_swap_b32_e32 v35, v33
	v_pk_add_f32 v[32:33], v[32:33], v[34:35]
	s_nop 0
	v_pk_fma_f32 v[106:107], v[32:33], s[30:31], v[88:89] op_sel_hi:[1, 0, 0]
	s_nop 0
	v_mul_f32_e32 v32, 0x4b800000, v107
	v_cmp_gt_f32_e32 vcc, s73, v107
	s_nop 1
	v_cndmask_b32_e32 v32, v107, v32, vcc
	v_rsq_f32_e32 v107, v32
	global_load_dwordx4 v[48:51], v[102:103], off
	global_load_dwordx4 v[44:47], v[102:103], off offset:1024
	global_load_dwordx4 v[40:43], v[102:103], off offset:2048
	global_load_dwordx4 v[32:35], v[102:103], off offset:3072
	v_mul_f32_e32 v102, 0x45800000, v107
	v_cndmask_b32_e32 v102, v107, v102, vcc
	v_pk_mul_f32 v[92:93], v[92:93], v[102:103] op_sel_hi:[1, 0]
	v_pk_mul_f32 v[90:91], v[90:91], v[102:103] op_sel_hi:[1, 0]
	v_pk_mul_f32 v[92:93], v[110:111], v[92:93]
	v_pk_mul_f32 v[90:91], v[108:109], v[90:91]
	v_pk_fma_f32 v[92:93], v[14:15], v[92:93], v[10:11]
	v_pk_fma_f32 v[90:91], v[12:13], v[90:91], v[8:9]
	v_pk_mul_f32 v[96:97], v[96:97], v[102:103] op_sel_hi:[1, 0]
	v_cvt_pk_bf16_f32 v90, v90, v91
	v_cvt_pk_bf16_f32 v91, v92, v93
	global_store_dwordx2 v[104:105], v[90:91], off sc1
	v_pk_mul_f32 v[94:95], v[94:95], v[102:103] op_sel_hi:[1, 0]
	v_pk_mul_f32 v[86:87], v[86:87], v[102:103] op_sel_hi:[1, 0]
	v_pk_mul_f32 v[84:85], v[84:85], v[102:103] op_sel_hi:[1, 0]
	v_pk_mul_f32 v[82:83], v[82:83], v[102:103] op_sel_hi:[1, 0]
	v_pk_mul_f32 v[80:81], v[80:81], v[102:103] op_sel_hi:[1, 0]
	v_cmp_gt_f32_e32 vcc, s73, v106
	s_waitcnt vmcnt(5)
	v_mul_f32_e32 v99, v53, v53
	v_mul_f32_e32 v102, v54, v54
	v_mul_f32_e32 v103, v55, v55
	s_waitcnt vmcnt(2)
	v_mul_f32_e32 v98, v43, v43
	s_waitcnt vmcnt(1)
	v_mul_f32_e32 v104, v32, v32
	v_mul_f32_e32 v105, v33, v33
	v_mul_f32_e32 v107, v35, v35
	v_pk_mul_f32 v[90:91], v[112:113], v[94:95]
	v_pk_mul_f32 v[92:93], v[114:115], v[96:97]
	v_pk_fma_f32 v[90:91], v[20:21], v[90:91], v[16:17]
	v_pk_fma_f32 v[92:93], v[22:23], v[92:93], v[18:19]
	v_cvt_pk_bf16_f32 v90, v90, v91
	v_cvt_pk_bf16_f32 v91, v92, v93
	global_store_dwordx2 v200, v[90:91], s[44:45] sc1
	v_pk_mul_f32 v[94:95], v[44:45], v[44:45]
	v_mul_f32_e32 v96, v41, v41
	v_pk_mul_f32 v[84:85], v[116:117], v[84:85]
	v_pk_mul_f32 v[86:87], v[118:119], v[86:87]
	v_pk_fma_f32 v[84:85], v[28:29], v[84:85], v[24:25]
	v_pk_fma_f32 v[86:87], v[30:31], v[86:87], v[26:27]
	v_cvt_pk_bf16_f32 v84, v84, v85
	v_cvt_pk_bf16_f32 v85, v86, v87
	global_store_dwordx2 v201, v[84:85], s[44:45] sc1
	v_pk_mul_f32 v[90:91], v[48:49], v[48:49]
	v_pk_mul_f32 v[92:93], v[46:47], v[46:47]
	v_pk_mul_f32 v[80:81], v[120:121], v[80:81]
	v_pk_mul_f32 v[82:83], v[122:123], v[82:83]
	v_pk_fma_f32 v[80:81], v[4:5], v[80:81], v[0:1]
	v_pk_fma_f32 v[82:83], v[6:7], v[82:83], v[2:3]
	v_cvt_pk_bf16_f32 v80, v80, v81
	v_cvt_pk_bf16_f32 v81, v82, v83
	global_store_dwordx2 v210, v[80:81], s[44:45] sc1
	v_mul_f32_e32 v84, 0x4b800000, v106
	v_cndmask_b32_e32 v84, v106, v84, vcc
	v_rsq_f32_e32 v86, v84
	v_lshl_add_u64 v[84:85], v[140:141], 0, s[42:43]
	s_add_u32 s42, s20, s42
	s_addc_u32 s43, s21, s43
	v_mul_f32_e32 v87, 0x45800000, v86
	v_cndmask_b32_e32 v86, v86, v87, vcc
	v_pk_mul_f32 v[78:79], v[78:79], v[86:87] op_sel_hi:[1, 0]
	v_pk_mul_f32 v[76:77], v[76:77], v[86:87] op_sel_hi:[1, 0]
	v_pk_mul_f32 v[74:75], v[74:75], v[86:87] op_sel_hi:[1, 0]
	v_pk_mul_f32 v[72:73], v[72:73], v[86:87] op_sel_hi:[1, 0]
	v_pk_mul_f32 v[70:71], v[70:71], v[86:87] op_sel_hi:[1, 0]
	v_pk_mul_f32 v[68:69], v[68:69], v[86:87] op_sel_hi:[1, 0]
	v_mul_f32_e32 v87, v52, v52
	v_pk_mul_f32 v[38:39], v[38:39], v[86:87] op_sel_hi:[1, 0]
	v_pk_mul_f32 v[36:37], v[36:37], v[86:87] op_sel_hi:[1, 0]
	v_mul_f32_e32 v106, v34, v34
	s_lshl_b64 s[40:41], s[40:41], 11
	v_pk_mul_f32 v[76:77], v[108:109], v[76:77]
	v_pk_mul_f32 v[78:79], v[110:111], v[78:79]
	v_pk_fma_f32 v[76:77], v[12:13], v[76:77], v[8:9]
	v_pk_fma_f32 v[78:79], v[14:15], v[78:79], v[10:11]
	v_cvt_pk_bf16_f32 v76, v76, v77
	v_cvt_pk_bf16_f32 v77, v78, v79
	global_store_dwordx2 v[84:85], v[76:77], off sc1
	v_mul_f32_e32 v80, v57, v57
	v_mul_f32_e32 v82, v59, v59
	v_pk_mul_f32 v[84:85], v[50:51], v[50:51]
	v_pk_mul_f32 v[72:73], v[112:113], v[72:73]
	v_pk_mul_f32 v[74:75], v[114:115], v[74:75]
	v_pk_fma_f32 v[72:73], v[20:21], v[72:73], v[16:17]
	v_pk_fma_f32 v[74:75], v[22:23], v[74:75], v[18:19]
	v_cvt_pk_bf16_f32 v72, v72, v73
	v_cvt_pk_bf16_f32 v73, v74, v75
	global_store_dwordx2 v200, v[72:73], s[42:43] sc1
	v_pk_mul_f32 v[76:77], v[62:63], v[62:63]
	v_pk_mul_f32 v[78:79], v[60:61], v[60:61]
	v_pk_mul_f32 v[68:69], v[116:117], v[68:69]
	v_pk_mul_f32 v[70:71], v[118:119], v[70:71]
	v_pk_fma_f32 v[68:69], v[28:29], v[68:69], v[24:25]
	v_pk_fma_f32 v[70:71], v[30:31], v[70:71], v[26:27]
	v_cvt_pk_bf16_f32 v68, v68, v69
	v_cvt_pk_bf16_f32 v69, v70, v71
	global_store_dwordx2 v201, v[68:69], s[42:43] sc1
	v_pk_mul_f32 v[72:73], v[66:67], v[66:67]
	v_pk_mul_f32 v[74:75], v[64:65], v[64:65]
	v_pk_mul_f32 v[36:37], v[120:121], v[36:37]
	v_pk_mul_f32 v[38:39], v[122:123], v[38:39]
	v_pk_fma_f32 v[36:37], v[4:5], v[36:37], v[0:1]
	v_pk_fma_f32 v[38:39], v[6:7], v[38:39], v[2:3]
	v_cvt_pk_bf16_f32 v36, v36, v37
	v_cvt_pk_bf16_f32 v37, v38, v39
	global_store_dwordx2 v210, v[36:37], s[42:43] sc1
	v_pk_mov_b32 v[100:101], v[74:75], v[72:73] op_sel:[1, 0]
	v_mov_b32_e32 v75, v73
	v_pk_mov_b32 v[72:73], v[78:79], v[76:77] op_sel:[1, 0]
	v_mov_b32_e32 v79, v77
	v_pk_fma_f32 v[76:77], v[56:57], v[56:57], v[80:81] op_sel_hi:[1, 1, 0]
	v_pk_fma_f32 v[80:81], v[58:59], v[58:59], v[82:83] op_sel_hi:[1, 1, 0]
	v_pk_mov_b32 v[82:83], v[90:91], v[84:85] op_sel:[1, 0]
	v_mov_b32_e32 v91, v85
	v_pk_mov_b32 v[84:85], v[94:95], v[92:93] op_sel:[1, 0]
	v_mov_b32_e32 v95, v93
	v_pk_add_f32 v[74:75], v[100:101], v[74:75]
	v_pk_add_f32 v[68:69], v[72:73], v[78:79]
	v_pk_add_f32 v[70:71], v[82:83], v[90:91]
	v_pk_add_f32 v[72:73], v[84:85], v[94:95]
	v_pk_fma_f32 v[92:93], v[40:41], v[40:41], v[96:97] op_sel_hi:[1, 1, 0]
	v_pk_fma_f32 v[96:97], v[42:43], v[42:43], v[98:99] op_sel_hi:[1, 1, 0]
	v_pk_add_f32 v[74:75], v[74:75], v[74:75] op_sel:[0, 1] op_sel_hi:[1, 0]
	v_pk_add_f32 v[68:69], v[68:69], v[68:69] op_sel:[0, 1] op_sel_hi:[1, 0]
	v_pk_add_f32 v[70:71], v[70:71], v[70:71] op_sel:[0, 1] op_sel_hi:[1, 0]
	v_pk_add_f32 v[72:73], v[72:73], v[72:73] op_sel:[0, 1] op_sel_hi:[1, 0]
	v_mov_b32_e32 v77, v102
	v_mov_b32_e32 v81, v103
	v_mov_b32_e32 v93, v106
	v_mov_b32_e32 v97, v107
	v_mov_b32_e32 v75, v87
	v_mov_b32_e32 v69, v99
	v_mov_b32_e32 v71, v104
	v_mov_b32_e32 v73, v105
	v_pk_add_f32 v[76:77], v[76:77], v[80:81]
	v_pk_add_f32 v[78:79], v[92:93], v[96:97]
	v_pk_add_f32 v[68:69], v[74:75], v[68:69]
	v_pk_add_f32 v[70:71], v[70:71], v[72:73]
	v_pk_add_f32 v[68:69], v[68:69], v[76:77]
	v_pk_add_f32 v[70:71], v[70:71], v[78:79]
	v_mov_b32_e32 v73, v68
	v_mov_b32_e32 v72, v70
	v_mov_b32_e32 v68, v71
	v_pk_add_f32 v[68:69], v[72:73], v[68:69]
	s_waitcnt lgkmcnt(0)
	s_nop 1
	v_add_f32_dpp v68, v68, v68 quad_perm:[1,0,3,2] row_mask:0xf bank_mask:0xf
	v_add_f32_dpp v69, v69, v69 quad_perm:[1,0,3,2] row_mask:0xf bank_mask:0xf
	s_waitcnt lgkmcnt(0)
	s_nop 1
	v_add_f32_dpp v68, v68, v68 quad_perm:[2,3,0,1] row_mask:0xf bank_mask:0xf
	v_add_f32_dpp v69, v69, v69 quad_perm:[2,3,0,1] row_mask:0xf bank_mask:0xf
	s_waitcnt lgkmcnt(0)
	s_nop 1
	v_add_f32_dpp v68, v68, v68 row_half_mirror row_mask:0xf bank_mask:0xf
	v_add_f32_dpp v69, v69, v69 row_half_mirror row_mask:0xf bank_mask:0xf
	s_waitcnt lgkmcnt(0)
	s_nop 1
	v_add_f32_dpp v68, v68, v68 row_mirror row_mask:0xf bank_mask:0xf
	v_add_f32_dpp v69, v69, v69 row_mirror row_mask:0xf bank_mask:0xf
	ds_bpermute_b32 v71, v188, v69
	ds_bpermute_b32 v70, v188, v68
	s_waitcnt lgkmcnt(0)
	v_pk_add_f32 v[68:69], v[68:69], v[70:71]
	s_waitcnt lgkmcnt(0)
	v_mov_b32_e32 v70, v68
	v_mov_b32_e32 v71, v69
	s_nop 1
	v_permlane32_swap_b32_e32 v70, v68
	v_permlane32_swap_b32_e32 v71, v69
	v_pk_add_f32 v[68:69], v[68:69], v[70:71]
	s_nop 0
	v_pk_fma_f32 v[68:69], v[68:69], s[30:31], v[88:89] op_sel_hi:[1, 0, 0]
	s_nop 0
	v_mul_f32_e32 v70, 0x4b800000, v69
	v_cmp_gt_f32_e32 vcc, s73, v69
	s_nop 1
	v_cndmask_b32_e32 v69, v69, v70, vcc
	v_rsq_f32_e32 v69, v69
	v_lshl_add_u64 v[70:71], v[140:141], 0, s[40:41]
	s_add_u32 s40, s20, s40
	s_addc_u32 s41, s21, s41
	v_mul_f32_e32 v72, 0x45800000, v69
	v_cndmask_b32_e32 v72, v69, v72, vcc
	v_pk_mul_f32 v[66:67], v[66:67], v[72:73] op_sel_hi:[1, 0]
	v_pk_mul_f32 v[64:65], v[64:65], v[72:73] op_sel_hi:[1, 0]
	v_pk_mul_f32 v[38:39], v[110:111], v[66:67]
	v_pk_mul_f32 v[36:37], v[108:109], v[64:65]
	v_pk_fma_f32 v[38:39], v[14:15], v[38:39], v[10:11]
	v_pk_fma_f32 v[36:37], v[12:13], v[36:37], v[8:9]
	v_pk_mul_f32 v[62:63], v[62:63], v[72:73] op_sel_hi:[1, 0]
	v_cvt_pk_bf16_f32 v36, v36, v37
	v_cvt_pk_bf16_f32 v37, v38, v39
	global_store_dwordx2 v[70:71], v[36:37], off sc1
	v_pk_mul_f32 v[60:61], v[60:61], v[72:73] op_sel_hi:[1, 0]
	v_pk_mul_f32 v[58:59], v[58:59], v[72:73] op_sel_hi:[1, 0]
	v_pk_mul_f32 v[56:57], v[56:57], v[72:73] op_sel_hi:[1, 0]
	v_pk_mul_f32 v[54:55], v[54:55], v[72:73] op_sel_hi:[1, 0]
	v_pk_mul_f32 v[52:53], v[52:53], v[72:73] op_sel_hi:[1, 0]
	v_cmp_gt_f32_e32 vcc, s73, v68
	s_lshl_b64 s[38:39], s[38:39], 11
	v_pk_mul_f32 v[36:37], v[112:113], v[60:61]
	v_pk_mul_f32 v[38:39], v[114:115], v[62:63]
	v_pk_fma_f32 v[36:37], v[20:21], v[36:37], v[16:17]
	v_pk_fma_f32 v[38:39], v[22:23], v[38:39], v[18:19]
	v_cvt_pk_bf16_f32 v36, v36, v37
	v_cvt_pk_bf16_f32 v37, v38, v39
	global_store_dwordx2 v200, v[36:37], s[40:41] sc1
	v_pk_mul_f32 v[36:37], v[116:117], v[56:57]
	v_pk_mul_f32 v[38:39], v[118:119], v[58:59]
	v_pk_fma_f32 v[36:37], v[28:29], v[36:37], v[24:25]
	v_pk_fma_f32 v[38:39], v[30:31], v[38:39], v[26:27]
	v_cvt_pk_bf16_f32 v36, v36, v37
	v_cvt_pk_bf16_f32 v37, v38, v39
	global_store_dwordx2 v201, v[36:37], s[40:41] sc1
	v_pk_mul_f32 v[36:37], v[120:121], v[52:53]
	v_pk_mul_f32 v[38:39], v[122:123], v[54:55]
	v_pk_fma_f32 v[36:37], v[4:5], v[36:37], v[0:1]
	v_pk_fma_f32 v[38:39], v[6:7], v[38:39], v[2:3]
	v_cvt_pk_bf16_f32 v36, v36, v37
	v_cvt_pk_bf16_f32 v37, v38, v39
	global_store_dwordx2 v210, v[36:37], s[40:41] sc1
	v_mul_f32_e32 v52, 0x4b800000, v68
	v_cndmask_b32_e32 v52, v68, v52, vcc
	v_rsq_f32_e32 v54, v52
	v_lshl_add_u64 v[52:53], v[140:141], 0, s[38:39]
	s_add_u32 s38, s20, s38
	s_addc_u32 s39, s21, s39
	v_mul_f32_e32 v55, 0x45800000, v54
	v_cndmask_b32_e32 v54, v54, v55, vcc
	v_pk_mul_f32 v[50:51], v[50:51], v[54:55] op_sel_hi:[1, 0]
	v_pk_mul_f32 v[48:49], v[48:49], v[54:55] op_sel_hi:[1, 0]
	s_and_b64 vcc, exec, s[8:9]
	s_mov_b64 s[8:9], -1
	v_pk_mul_f32 v[36:37], v[108:109], v[48:49]
	v_pk_mul_f32 v[38:39], v[110:111], v[50:51]
	v_pk_fma_f32 v[8:9], v[12:13], v[36:37], v[8:9]
	v_pk_fma_f32 v[10:11], v[14:15], v[38:39], v[10:11]
	v_cvt_pk_bf16_f32 v8, v8, v9
	v_cvt_pk_bf16_f32 v9, v10, v11
	global_store_dwordx2 v[52:53], v[8:9], off sc1
	v_pk_mul_f32 v[12:13], v[46:47], v[54:55] op_sel_hi:[1, 0]
	v_pk_mul_f32 v[14:15], v[44:45], v[54:55] op_sel_hi:[1, 0]
	v_pk_mul_f32 v[10:11], v[114:115], v[12:13]
	v_pk_mul_f32 v[8:9], v[112:113], v[14:15]
	v_pk_fma_f32 v[10:11], v[22:23], v[10:11], v[18:19]
	v_pk_fma_f32 v[8:9], v[20:21], v[8:9], v[16:17]
	v_pk_mul_f32 v[12:13], v[42:43], v[54:55] op_sel_hi:[1, 0]
	v_cvt_pk_bf16_f32 v8, v8, v9
	v_cvt_pk_bf16_f32 v9, v10, v11
	global_store_dwordx2 v200, v[8:9], s[38:39] sc1
	v_pk_mul_f32 v[14:15], v[40:41], v[54:55] op_sel_hi:[1, 0]
	v_pk_mul_f32 v[10:11], v[118:119], v[12:13]
	v_pk_mul_f32 v[8:9], v[116:117], v[14:15]
	v_pk_fma_f32 v[10:11], v[30:31], v[10:11], v[26:27]
	v_pk_fma_f32 v[8:9], v[28:29], v[8:9], v[24:25]
	v_pk_mul_f32 v[12:13], v[34:35], v[54:55] op_sel_hi:[1, 0]
	v_cvt_pk_bf16_f32 v8, v8, v9
	v_cvt_pk_bf16_f32 v9, v10, v11
	global_store_dwordx2 v201, v[8:9], s[38:39] sc1
	v_pk_mul_f32 v[14:15], v[32:33], v[54:55] op_sel_hi:[1, 0]
	v_pk_mul_f32 v[10:11], v[122:123], v[12:13]
	v_pk_mul_f32 v[8:9], v[120:121], v[14:15]
	v_pk_fma_f32 v[2:3], v[6:7], v[10:11], v[2:3]
	v_pk_fma_f32 v[0:1], v[4:5], v[8:9], v[0:1]
	s_nop 0
	v_cvt_pk_bf16_f32 v0, v0, v1
	v_cvt_pk_bf16_f32 v1, v2, v3
	global_store_dwordx2 v210, v[0:1], s[38:39] sc1
	s_cbranch_vccnz .LBB0_396
	s_andn2_b64 vcc, exec, s[10:11]
	s_cbranch_vccnz .LBB0_395
	s_barrier
	s_branch .LBB0_395

.LBB0_1174:
	v_lshl_or_b32 v172, s42, 8, v198
	v_add_u32_e32 v156, 0x1400, v172
	v_ashrrev_i32_e32 v157, 31, v156
	v_lshlrev_b64 v[160:161], 2, v[156:157]
	s_ashr_i32 s54, s44, 3
	v_lshl_add_u64 v[164:165], s[2:3], 0, v[160:161]
	v_lshl_add_u64 v[156:157], s[12:13], 0, v[160:161]
	v_mad_i64_i32 v[160:161], s[46:47], s54, v211, v[164:165]
	global_load_dwordx4 v[156:159], v[156:157], off
	s_add_i32 s55, s54, 8
	s_add_i32 s53, s54, 16
	s_add_i32 s52, s54, 24
	s_add_i32 s81, s54, 32
	s_add_i32 s80, s54, 40
	s_add_i32 s43, s54, 48
	s_add_i32 s37, s54, 56
	s_lshl_b32 s35, s44, 8
	global_load_dwordx4 v[160:163], v[160:161], off
	v_mad_i64_i32 v[212:213], s[46:47], s55, v211, v[164:165]
	global_load_dwordx4 v[212:215], v[212:213], off
	v_mad_i64_i32 v[216:217], s[46:47], s53, v211, v[164:165]
	global_load_dwordx4 v[216:219], v[216:217], off
	v_mad_i64_i32 v[220:221], s[46:47], s52, v211, v[164:165]
	global_load_dwordx4 v[220:223], v[220:221], off
	v_mad_i64_i32 v[224:225], s[46:47], s81, v211, v[164:165]
	global_load_dwordx4 v[224:227], v[224:225], off
	v_mad_i64_i32 v[228:229], s[46:47], s80, v211, v[164:165]
	global_load_dwordx4 v[228:231], v[228:229], off
	v_mad_i64_i32 v[232:233], s[46:47], s43, v211, v[164:165]
	global_load_dwordx4 v[232:235], v[232:233], off
	v_mad_i64_i32 v[236:237], s[46:47], s37, v211, v[164:165]
	global_load_dwordx4 v[236:239], v[236:237], off
	v_ashrrev_i32_e32 v173, 31, v172
	v_readfirstlane_b32 s82, v180
	s_waitcnt vmcnt(7)
	v_pk_add_f32 v[160:161], v[156:157], v[160:161]
	v_pk_add_f32 v[162:163], v[158:159], v[162:163]
	s_waitcnt vmcnt(6)
	v_pk_add_f32 v[160:161], v[160:161], v[212:213]
	v_pk_add_f32 v[162:163], v[162:163], v[214:215]
	s_waitcnt vmcnt(5)
	v_pk_add_f32 v[160:161], v[160:161], v[216:217]
	v_pk_add_f32 v[162:163], v[162:163], v[218:219]
	s_waitcnt vmcnt(4)
	v_pk_add_f32 v[160:161], v[160:161], v[220:221]
	v_pk_add_f32 v[162:163], v[162:163], v[222:223]
	s_waitcnt vmcnt(3)
	v_pk_add_f32 v[160:161], v[160:161], v[224:225]
	v_pk_add_f32 v[162:163], v[162:163], v[226:227]
	s_waitcnt vmcnt(2)
	v_pk_add_f32 v[160:161], v[160:161], v[228:229]
	v_pk_add_f32 v[162:163], v[162:163], v[230:231]
	s_waitcnt vmcnt(1)
	v_pk_add_f32 v[166:167], v[160:161], v[232:233]
	v_pk_add_f32 v[162:163], v[162:163], v[234:235]
	s_waitcnt vmcnt(0)
	v_pk_add_f32 v[156:157], v[162:163], v[238:239]
	v_add_u32_e32 v160, 0x1410, v172
	v_ashrrev_i32_e32 v161, 31, v160
	v_lshlrev_b64 v[164:165], 2, v[160:161]
	v_lshl_add_u64 v[168:169], s[2:3], 0, v[164:165]
	v_lshl_add_u64 v[160:161], s[12:13], 0, v[164:165]
	v_mad_i64_i32 v[164:165], s[46:47], s54, v211, v[168:169]
	v_pk_add_f32 v[158:159], v[166:167], v[236:237]
	global_load_dwordx4 v[160:163], v[160:161], off
	global_load_dwordx4 v[164:167], v[164:165], off
	v_mad_i64_i32 v[212:213], s[46:47], s55, v211, v[168:169]
	global_load_dwordx4 v[212:215], v[212:213], off
	v_mad_i64_i32 v[216:217], s[46:47], s53, v211, v[168:169]
	global_load_dwordx4 v[216:219], v[216:217], off
	v_mad_i64_i32 v[220:221], s[46:47], s52, v211, v[168:169]
	global_load_dwordx4 v[220:223], v[220:221], off
	v_mad_i64_i32 v[224:225], s[46:47], s81, v211, v[168:169]
	global_load_dwordx4 v[224:227], v[224:225], off
	v_mad_i64_i32 v[228:229], s[46:47], s80, v211, v[168:169]
	global_load_dwordx4 v[228:231], v[228:229], off
	v_mad_i64_i32 v[232:233], s[46:47], s43, v211, v[168:169]
	global_load_dwordx4 v[232:235], v[232:233], off
	v_mad_i64_i32 v[236:237], s[46:47], s37, v211, v[168:169]
	global_load_dwordx4 v[236:239], v[236:237], off
	s_waitcnt vmcnt(7)
	v_pk_add_f32 v[164:165], v[160:161], v[164:165]
	v_pk_add_f32 v[166:167], v[162:163], v[166:167]
	s_waitcnt vmcnt(6)
	v_pk_add_f32 v[164:165], v[164:165], v[212:213]
	v_pk_add_f32 v[166:167], v[166:167], v[214:215]
	s_waitcnt vmcnt(5)
	v_pk_add_f32 v[164:165], v[164:165], v[216:217]
	v_pk_add_f32 v[166:167], v[166:167], v[218:219]
	s_waitcnt vmcnt(4)
	v_pk_add_f32 v[164:165], v[164:165], v[220:221]
	v_pk_add_f32 v[166:167], v[166:167], v[222:223]
	s_waitcnt vmcnt(3)
	v_pk_add_f32 v[164:165], v[164:165], v[224:225]
	v_pk_add_f32 v[166:167], v[166:167], v[226:227]
	s_waitcnt vmcnt(2)
	v_pk_add_f32 v[164:165], v[164:165], v[228:229]
	v_pk_add_f32 v[166:167], v[166:167], v[230:231]
	s_waitcnt vmcnt(1)
	v_pk_add_f32 v[170:171], v[164:165], v[232:233]
	v_pk_add_f32 v[166:167], v[166:167], v[234:235]
	s_waitcnt vmcnt(0)
	v_pk_add_f32 v[160:161], v[166:167], v[238:239]
	v_add_u32_e32 v164, 0x1480, v172
	v_ashrrev_i32_e32 v165, 31, v164
	v_lshlrev_b64 v[168:169], 2, v[164:165]
	v_lshl_add_u64 v[174:175], s[2:3], 0, v[168:169]
	v_lshl_add_u64 v[164:165], s[12:13], 0, v[168:169]
	v_mad_i64_i32 v[168:169], s[46:47], s54, v211, v[174:175]
	v_pk_add_f32 v[162:163], v[170:171], v[236:237]
	global_load_dwordx4 v[164:167], v[164:165], off
	global_load_dwordx4 v[168:171], v[168:169], off
	v_mad_i64_i32 v[212:213], s[46:47], s55, v211, v[174:175]
	global_load_dwordx4 v[212:215], v[212:213], off
	v_mad_i64_i32 v[216:217], s[46:47], s53, v211, v[174:175]
	global_load_dwordx4 v[216:219], v[216:217], off
	v_mad_i64_i32 v[220:221], s[46:47], s52, v211, v[174:175]
	global_load_dwordx4 v[220:223], v[220:221], off
	v_mad_i64_i32 v[224:225], s[46:47], s81, v211, v[174:175]
	global_load_dwordx4 v[224:227], v[224:225], off
	v_mad_i64_i32 v[228:229], s[46:47], s80, v211, v[174:175]
	global_load_dwordx4 v[228:231], v[228:229], off
	v_mad_i64_i32 v[232:233], s[46:47], s43, v211, v[174:175]
	global_load_dwordx4 v[232:235], v[232:233], off
	v_mad_i64_i32 v[236:237], s[46:47], s37, v211, v[174:175]
	global_load_dwordx4 v[236:239], v[236:237], off
	s_waitcnt vmcnt(7)
	v_pk_add_f32 v[168:169], v[164:165], v[168:169]
	v_pk_add_f32 v[170:171], v[166:167], v[170:171]
	s_waitcnt vmcnt(6)
	v_pk_add_f32 v[168:169], v[168:169], v[212:213]
	v_pk_add_f32 v[170:171], v[170:171], v[214:215]
	s_waitcnt vmcnt(5)
	v_pk_add_f32 v[168:169], v[168:169], v[216:217]
	v_pk_add_f32 v[170:171], v[170:171], v[218:219]
	s_waitcnt vmcnt(4)
	v_pk_add_f32 v[168:169], v[168:169], v[220:221]
	v_pk_add_f32 v[170:171], v[170:171], v[222:223]
	s_waitcnt vmcnt(3)
	v_pk_add_f32 v[168:169], v[168:169], v[224:225]
	v_pk_add_f32 v[170:171], v[170:171], v[226:227]
	s_waitcnt vmcnt(2)
	v_pk_add_f32 v[168:169], v[168:169], v[228:229]
	v_pk_add_f32 v[170:171], v[170:171], v[230:231]
	s_waitcnt vmcnt(1)
	v_pk_add_f32 v[176:177], v[168:169], v[232:233]
	v_pk_add_f32 v[170:171], v[170:171], v[234:235]
	s_waitcnt vmcnt(0)
	v_pk_add_f32 v[164:165], v[170:171], v[238:239]
	v_add_u32_e32 v168, 0x1490, v172
	v_ashrrev_i32_e32 v169, 31, v168
	v_lshlrev_b64 v[174:175], 2, v[168:169]
	v_lshl_add_u64 v[178:179], s[2:3], 0, v[174:175]
	v_lshl_add_u64 v[168:169], s[12:13], 0, v[174:175]
	v_mad_i64_i32 v[174:175], s[46:47], s54, v211, v[178:179]
	v_pk_add_f32 v[166:167], v[176:177], v[236:237]
	global_load_dwordx4 v[168:171], v[168:169], off
	global_load_dwordx4 v[174:177], v[174:175], off
	v_mad_i64_i32 v[212:213], s[46:47], s55, v211, v[178:179]
	global_load_dwordx4 v[212:215], v[212:213], off
	v_mad_i64_i32 v[216:217], s[46:47], s53, v211, v[178:179]
	global_load_dwordx4 v[216:219], v[216:217], off
	v_mad_i64_i32 v[220:221], s[46:47], s52, v211, v[178:179]
	global_load_dwordx4 v[220:223], v[220:221], off
	v_mad_i64_i32 v[224:225], s[46:47], s81, v211, v[178:179]
	global_load_dwordx4 v[224:227], v[224:225], off
	v_mad_i64_i32 v[228:229], s[46:47], s80, v211, v[178:179]
	global_load_dwordx4 v[228:231], v[228:229], off
	v_mad_i64_i32 v[232:233], s[46:47], s43, v211, v[178:179]
	global_load_dwordx4 v[232:235], v[232:233], off
	v_mad_i64_i32 v[236:237], s[46:47], s37, v211, v[178:179]
	global_load_dwordx4 v[236:239], v[236:237], off
	v_lshlrev_b64 v[172:173], 2, v[172:173]
	s_waitcnt vmcnt(7)
	v_pk_add_f32 v[174:175], v[168:169], v[174:175]
	v_pk_add_f32 v[176:177], v[170:171], v[176:177]
	s_waitcnt vmcnt(6)
	v_pk_add_f32 v[174:175], v[174:175], v[212:213]
	v_pk_add_f32 v[176:177], v[176:177], v[214:215]
	s_waitcnt vmcnt(5)
	v_pk_add_f32 v[174:175], v[174:175], v[216:217]
	v_pk_add_f32 v[176:177], v[176:177], v[218:219]
	s_waitcnt vmcnt(4)
	v_pk_add_f32 v[174:175], v[174:175], v[220:221]
	v_pk_add_f32 v[176:177], v[176:177], v[222:223]
	s_waitcnt vmcnt(3)
	v_pk_add_f32 v[174:175], v[174:175], v[224:225]
	v_pk_add_f32 v[176:177], v[176:177], v[226:227]
	s_waitcnt vmcnt(2)
	v_pk_add_f32 v[174:175], v[174:175], v[228:229]
	v_pk_add_f32 v[176:177], v[176:177], v[230:231]
	s_waitcnt vmcnt(1)
	v_pk_add_f32 v[204:205], v[174:175], v[232:233]
	v_pk_add_f32 v[170:171], v[176:177], v[234:235]
	v_add_u32_e32 v178, s35, v181
	v_ashrrev_i32_e32 v179, 31, v178
	s_waitcnt vmcnt(0)
	v_pk_add_f32 v[168:169], v[170:171], v[238:239]
	v_pk_add_f32 v[170:171], v[204:205], v[236:237]
	v_lshl_add_u64 v[174:175], s[0:1], 0, v[172:173]
	v_lshlrev_b64 v[176:177], 12, v[178:179]
	v_lshl_add_u64 v[204:205], v[174:175], 0, v[176:177]
	global_load_dwordx4 v[212:215], v[204:205], off
	global_load_dwordx4 v[216:219], v[204:205], off offset:64
	global_load_dwordx4 v[220:223], v[204:205], off offset:512
	global_load_dwordx4 v[224:227], v[204:205], off offset:576
	v_or_b32_e32 v204, 16, v178
	v_ashrrev_i32_e32 v205, 31, v204
	v_lshlrev_b64 v[204:205], 12, v[204:205]
	v_lshl_add_u64 v[206:207], v[174:175], 0, v[204:205]
	global_load_dwordx4 v[228:231], v[206:207], off
	global_load_dwordx4 v[232:235], v[206:207], off offset:64
	global_load_dwordx4 v[236:239], v[206:207], off offset:512
	global_load_dwordx4 v[240:243], v[206:207], off offset:576
	v_lshl_add_u64 v[206:207], s[0:1], 0, v[176:177]
	v_lshl_add_u64 v[206:207], v[206:207], 0, v[172:173]
	s_waitcnt vmcnt(7)
	v_pk_fma_f32 v[126:127], v[126:127], v[156:157], v[214:215]
	v_pk_fma_f32 v[124:125], v[124:125], v[158:159], v[212:213]
	s_waitcnt vmcnt(5)
	v_pk_fma_f32 v[110:111], v[110:111], v[164:165], v[222:223]
	v_pk_fma_f32 v[108:109], v[108:109], v[166:167], v[220:221]
	global_store_dwordx4 v[206:207], v[108:111], off offset:512 sc1
	s_waitcnt vmcnt(5)
	v_pk_fma_f32 v[106:107], v[106:107], v[168:169], v[226:227]
	v_pk_fma_f32 v[104:105], v[104:105], v[170:171], v[224:225]
	v_lshl_add_u64 v[108:109], s[0:1], 0, v[204:205]
	v_lshl_add_u64 v[108:109], v[108:109], 0, v[172:173]
	s_waitcnt vmcnt(1)
	v_pk_fma_f32 v[98:99], v[98:99], v[168:169], v[242:243]
	v_pk_fma_f32 v[96:97], v[96:97], v[170:171], v[240:241]
	global_store_dwordx4 v[108:109], v[96:99], off offset:576 sc1
	global_store_dwordx4 v[206:207], v[104:107], off offset:576 sc1
	v_pk_fma_f32 v[122:123], v[122:123], v[160:161], v[218:219]
	v_or_b32_e32 v96, 32, v178
	v_pk_fma_f32 v[106:107], v[118:119], v[156:157], v[230:231]
	v_pk_fma_f32 v[104:105], v[116:117], v[158:159], v[228:229]
	v_ashrrev_i32_e32 v97, 31, v96
	v_pk_fma_f32 v[120:121], v[120:121], v[162:163], v[216:217]
	global_store_dwordx4 v[108:109], v[104:107], off sc1
	v_pk_fma_f32 v[102:103], v[102:103], v[164:165], v[238:239]
	v_pk_fma_f32 v[100:101], v[100:101], v[166:167], v[236:237]
	v_pk_fma_f32 v[106:107], v[114:115], v[160:161], v[234:235]
	v_pk_fma_f32 v[104:105], v[112:113], v[162:163], v[232:233]
	v_lshlrev_b64 v[204:205], 12, v[96:97]
	v_or_b32_e32 v112, 48, v178
	global_store_dwordx4 v[206:207], v[124:127], off sc1
	global_store_dwordx4 v[206:207], v[120:123], off offset:64 sc1
	global_store_dwordx4 v[108:109], v[104:107], off offset:64 sc1
	global_store_dwordx4 v[108:109], v[100:103], off offset:512 sc1
	v_lshl_add_u64 v[108:109], v[174:175], 0, v[204:205]
	v_ashrrev_i32_e32 v113, 31, v112
	global_load_dwordx4 v[96:99], v[108:109], off
	global_load_dwordx4 v[100:103], v[108:109], off offset:64
	global_load_dwordx4 v[104:107], v[108:109], off offset:512
	s_nop 0
	global_load_dwordx4 v[108:111], v[108:109], off offset:576
	v_lshlrev_b64 v[178:179], 12, v[112:113]
	v_lshl_add_u64 v[124:125], v[174:175], 0, v[178:179]
	global_load_dwordx4 v[112:115], v[124:125], off
	global_load_dwordx4 v[116:119], v[124:125], off offset:64
	global_load_dwordx4 v[120:123], v[124:125], off offset:512
	s_nop 0
	global_load_dwordx4 v[124:127], v[124:125], off offset:576
	s_waitcnt vmcnt(7)
	v_pk_fma_f32 v[92:93], v[92:93], v[158:159], v[96:97]
	v_lshl_add_u64 v[96:97], s[0:1], 0, v[204:205]
	v_lshl_add_u64 v[96:97], v[96:97], 0, v[172:173]
	s_waitcnt vmcnt(5)
	v_pk_fma_f32 v[78:79], v[78:79], v[164:165], v[106:107]
	v_pk_fma_f32 v[76:77], v[76:77], v[166:167], v[104:105]
	global_store_dwordx4 v[96:97], v[76:79], off offset:512 sc1
	s_waitcnt vmcnt(5)
	v_pk_fma_f32 v[74:75], v[74:75], v[168:169], v[110:111]
	v_pk_fma_f32 v[72:73], v[72:73], v[170:171], v[108:109]
	v_lshl_add_u64 v[76:77], s[0:1], 0, v[178:179]
	v_pk_fma_f32 v[94:95], v[94:95], v[156:157], v[98:99]
	v_pk_fma_f32 v[90:91], v[90:91], v[160:161], v[102:103]
	v_pk_fma_f32 v[88:89], v[88:89], v[162:163], v[100:101]
	global_store_dwordx4 v[96:97], v[72:75], off offset:576 sc1
	v_lshl_add_u64 v[76:77], v[76:77], 0, v[172:173]
	global_store_dwordx4 v[96:97], v[92:95], off sc1
	s_waitcnt vmcnt(6)
	v_pk_fma_f32 v[74:75], v[86:87], v[156:157], v[114:115]
	v_pk_fma_f32 v[72:73], v[84:85], v[158:159], v[112:113]
	global_store_dwordx4 v[96:97], v[88:91], off offset:64 sc1
	global_store_dwordx4 v[76:77], v[72:75], off sc1
	s_waitcnt vmcnt(6)
	v_pk_fma_f32 v[70:71], v[70:71], v[164:165], v[122:123]
	v_pk_fma_f32 v[68:69], v[68:69], v[166:167], v[120:121]
	v_pk_fma_f32 v[74:75], v[82:83], v[160:161], v[118:119]
	v_pk_fma_f32 v[72:73], v[80:81], v[162:163], v[116:117]
	s_waitcnt vmcnt(5)
	v_pk_fma_f32 v[66:67], v[66:67], v[168:169], v[126:127]
	v_pk_fma_f32 v[64:65], v[64:65], v[170:171], v[124:125]
	v_lshl_add_u64 v[96:97], v[176:177], 0, s[20:21]
	global_store_dwordx4 v[76:77], v[72:75], off offset:64 sc1
	global_store_dwordx4 v[76:77], v[68:71], off offset:512 sc1
	global_store_dwordx4 v[76:77], v[64:67], off offset:576 sc1
	v_lshl_add_u64 v[76:77], v[174:175], 0, v[96:97]
	global_load_dwordx4 v[64:67], v[76:77], off
	global_load_dwordx4 v[68:71], v[76:77], off offset:64
	global_load_dwordx4 v[72:75], v[76:77], off offset:512
	s_nop 0
	global_load_dwordx4 v[76:79], v[76:77], off offset:576
	v_lshl_add_u64 v[98:99], v[176:177], 0, s[22:23]
	v_lshl_add_u64 v[92:93], v[174:175], 0, v[98:99]
	global_load_dwordx4 v[80:83], v[92:93], off
	global_load_dwordx4 v[84:87], v[92:93], off offset:64
	global_load_dwordx4 v[88:91], v[92:93], off offset:512
	s_nop 0
	global_load_dwordx4 v[92:95], v[92:93], off offset:576
	s_waitcnt vmcnt(7)
	v_pk_fma_f32 v[60:61], v[60:61], v[158:159], v[64:65]
	v_lshl_add_u64 v[64:65], s[0:1], 0, v[96:97]
	v_lshl_add_u64 v[64:65], v[64:65], 0, v[172:173]
	s_waitcnt vmcnt(5)
	v_pk_fma_f32 v[46:47], v[46:47], v[164:165], v[74:75]
	v_pk_fma_f32 v[44:45], v[44:45], v[166:167], v[72:73]
	global_store_dwordx4 v[64:65], v[44:47], off offset:512 sc1
	s_waitcnt vmcnt(5)
	v_pk_fma_f32 v[42:43], v[42:43], v[168:169], v[78:79]
	v_pk_fma_f32 v[40:41], v[40:41], v[170:171], v[76:77]
	v_lshl_add_u64 v[44:45], s[0:1], 0, v[98:99]
	global_store_dwordx4 v[64:65], v[40:43], off offset:576 sc1
	v_lshl_add_u64 v[44:45], v[44:45], 0, v[172:173]
	v_pk_fma_f32 v[62:63], v[62:63], v[156:157], v[66:67]
	s_waitcnt vmcnt(5)
	v_pk_fma_f32 v[42:43], v[54:55], v[156:157], v[82:83]
	v_pk_fma_f32 v[40:41], v[52:53], v[158:159], v[80:81]
	v_pk_fma_f32 v[58:59], v[58:59], v[160:161], v[70:71]
	v_pk_fma_f32 v[56:57], v[56:57], v[162:163], v[68:69]
	global_store_dwordx4 v[44:45], v[40:43], off sc1
	s_waitcnt vmcnt(4)
	v_pk_fma_f32 v[38:39], v[38:39], v[164:165], v[90:91]
	v_pk_fma_f32 v[36:37], v[36:37], v[166:167], v[88:89]
	v_pk_fma_f32 v[42:43], v[50:51], v[160:161], v[86:87]
	v_pk_fma_f32 v[40:41], v[48:49], v[162:163], v[84:85]
	s_waitcnt vmcnt(3)
	v_pk_fma_f32 v[34:35], v[34:35], v[168:169], v[94:95]
	v_pk_fma_f32 v[32:33], v[32:33], v[170:171], v[92:93]
	v_lshl_add_u64 v[66:67], v[176:177], 0, s[24:25]
	global_store_dwordx4 v[64:65], v[60:63], off sc1
	global_store_dwordx4 v[64:65], v[56:59], off offset:64 sc1
	global_store_dwordx4 v[44:45], v[40:43], off offset:64 sc1
	global_store_dwordx4 v[44:45], v[36:39], off offset:512 sc1
	global_store_dwordx4 v[44:45], v[32:35], off offset:576 sc1
	v_lshl_add_u64 v[64:65], v[176:177], 0, s[26:27]
	v_lshl_add_u64 v[36:37], v[174:175], 0, v[64:65]
	v_lshl_add_u64 v[32:33], v[174:175], 0, v[66:67]
	global_load_dwordx4 v[48:51], v[32:33], off
	global_load_dwordx4 v[60:63], v[32:33], off offset:64
	global_load_dwordx4 v[56:59], v[32:33], off offset:512
	global_load_dwordx4 v[52:55], v[32:33], off offset:576
	s_nop 0
	global_load_dwordx4 v[32:35], v[36:37], off
	global_load_dwordx4 v[44:47], v[36:37], off offset:64
	global_load_dwordx4 v[40:43], v[36:37], off offset:512
	s_nop 0
	global_load_dwordx4 v[36:39], v[36:37], off offset:576
	s_waitcnt vmcnt(7)
	v_pk_fma_f32 v[28:29], v[28:29], v[158:159], v[48:49]
	v_lshl_add_u64 v[48:49], s[0:1], 0, v[66:67]
	v_lshl_add_u64 v[48:49], v[48:49], 0, v[172:173]
	s_waitcnt vmcnt(5)
	v_pk_fma_f32 v[18:19], v[18:19], v[164:165], v[58:59]
	v_pk_fma_f32 v[16:17], v[16:17], v[166:167], v[56:57]
	global_store_dwordx4 v[48:49], v[16:19], off offset:512 sc1
	s_waitcnt vmcnt(5)
	v_pk_fma_f32 v[10:11], v[10:11], v[168:169], v[54:55]
	v_pk_fma_f32 v[8:9], v[8:9], v[170:171], v[52:53]
	v_lshl_add_u64 v[16:17], s[0:1], 0, v[64:65]
	global_store_dwordx4 v[48:49], v[8:11], off offset:576 sc1
	v_lshl_add_u64 v[16:17], v[16:17], 0, v[172:173]
	v_pk_fma_f32 v[30:31], v[30:31], v[156:157], v[50:51]
	s_waitcnt vmcnt(5)
	v_pk_fma_f32 v[10:11], v[22:23], v[156:157], v[34:35]
	v_pk_fma_f32 v[8:9], v[20:21], v[158:159], v[32:33]
	v_pk_fma_f32 v[26:27], v[26:27], v[160:161], v[62:63]
	v_pk_fma_f32 v[24:25], v[24:25], v[162:163], v[60:61]
	global_store_dwordx4 v[16:17], v[8:11], off sc1
	s_waitcnt vmcnt(4)
	v_pk_fma_f32 v[6:7], v[6:7], v[164:165], v[42:43]
	v_pk_fma_f32 v[4:5], v[4:5], v[166:167], v[40:41]
	v_pk_fma_f32 v[10:11], v[14:15], v[160:161], v[46:47]
	v_pk_fma_f32 v[8:9], v[12:13], v[162:163], v[44:45]
	s_waitcnt vmcnt(3)
	v_pk_fma_f32 v[2:3], v[2:3], v[168:169], v[38:39]
	v_pk_fma_f32 v[0:1], v[0:1], v[170:171], v[36:37]
	global_store_dwordx4 v[48:49], v[28:31], off sc1
	global_store_dwordx4 v[48:49], v[24:27], off offset:64 sc1
	global_store_dwordx4 v[16:17], v[8:11], off offset:64 sc1
	global_store_dwordx4 v[16:17], v[4:7], off offset:512 sc1
	global_store_dwordx4 v[16:17], v[0:3], off offset:576 sc1
	s_waitcnt vmcnt(0)
	s_barrier
	s_and_saveexec_b64 s[46:47], s[4:5]
	s_cbranch_execz .LBB0_1188
	s_lshl_b32 s48, s44, 2
	s_ashr_i32 s49, s48, 31
	s_lshl_b64 s[48:49], s[48:49], 2
	s_add_u32 s48, s72, s48
	s_addc_u32 s49, s73, s49
	s_getreg_b32 s45, hwreg(HW_REG_XCC_ID, 0, 4)
	global_load_dwordx4 v[0:3], v131, s[48:49]
	s_and_b32 s45, s45, 15
	s_add_i32 s45, s45, 1
	s_waitcnt vmcnt(0)
	v_cmp_ne_u32_e32 vcc, s45, v2
	s_nop 1
	v_cndmask_b32_e64 v2, 0, 1, vcc
	v_cmp_ne_u32_e32 vcc, s45, v3
	v_lshlrev_b32_e32 v2, 2, v2
	s_nop 0
	v_cndmask_b32_e64 v3, 0, 1, vcc
	v_cmp_ne_u32_e32 vcc, s45, v1
	v_lshlrev_b32_e32 v3, 3, v3
	v_or_b32_e32 v2, v3, v2
	v_cndmask_b32_e64 v1, 0, 1, vcc
	v_cmp_ne_u32_e32 vcc, s45, v0
	v_lshlrev_b32_e32 v1, 1, v1
	s_nop 0
	v_cndmask_b32_e64 v0, 0, 1, vcc
	v_or_b32_e32 v0, v0, v1
	v_and_b32_e32 v0, 3, v0
	v_or_b32_e32 v0, v0, v2
	v_and_b32_e32 v0, 15, v0
	v_cmp_eq_u32_e32 vcc, 0, v0
	s_cbranch_vccnz .LBB0_1177
	buffer_wbl2 sc1
	s_waitcnt vmcnt(0)

.LBB0_1188:
	s_or_b64 exec, exec, s[46:47]
	s_mul_hi_i32 s59, s54, 0x9000
	s_mul_i32 s58, s54, 0x9000
	s_mul_hi_i32 s57, s55, 0x9000
	s_add_i32 s56, s58, 0x48000
	v_lshl_add_u64 v[4:5], v[138:139], 0, s[58:59]
	s_mul_hi_i32 s55, s53, 0x9000
	s_add_i32 s54, s58, 0x90000
	s_barrier
	global_load_dwordx4 v[0:3], v[136:137], off
	v_lshl_add_u64 v[8:9], v[138:139], 0, s[56:57]
	global_load_dwordx4 v[4:7], v[4:5], off
	s_mul_hi_i32 s53, s52, 0x9000
	s_add_i32 s52, s58, 0xd8000
	global_load_dwordx4 v[8:11], v[8:9], off
	v_lshl_add_u64 v[12:13], v[138:139], 0, s[54:55]
	s_mul_hi_i32 s51, s81, 0x9000
	s_add_i32 s50, s58, 0x120000
	global_load_dwordx4 v[12:15], v[12:13], off
	v_lshl_add_u64 v[16:17], v[138:139], 0, s[52:53]
	s_mul_hi_i32 s49, s80, 0x9000
	s_add_i32 s48, s58, 0x168000
	global_load_dwordx4 v[16:19], v[16:17], off
	v_lshl_add_u64 v[20:21], v[138:139], 0, s[50:51]
	s_mul_hi_i32 s47, s43, 0x9000
	s_add_i32 s46, s58, 0x1b0000
	global_load_dwordx4 v[20:23], v[20:21], off
	v_lshl_add_u64 v[24:25], v[138:139], 0, s[48:49]
	s_mul_hi_i32 s45, s37, 0x9000
	s_add_i32 s44, s58, 0x1f8000
	global_load_dwordx4 v[24:27], v[24:25], off
	v_lshl_add_u64 v[28:29], v[138:139], 0, s[46:47]
	global_load_dwordx4 v[28:31], v[28:29], off
	v_lshl_add_u64 v[32:33], v[138:139], 0, s[44:45]
	global_load_dwordx4 v[32:35], v[32:33], off
	s_lshl_b32 s37, s42, 6
	s_ashr_i32 s42, s82, 3
	s_add_i32 s35, s35, s37
	s_and_b32 s37, s42, -8
	s_add_i32 s42, s35, s37
	s_ashr_i32 s43, s42, 31
	s_lshl_b64 s[44:45], s[42:43], 12
	v_lshl_add_u64 v[36:37], v[140:141], 0, s[44:45]
	s_or_b32 s48, s42, 1
	s_ashr_i32 s49, s48, 31
	s_lshl_b64 s[44:45], s[48:49], 12
	v_mov_b64_e32 v[84:85], s[30:31]
	s_or_b32 s46, s42, 2
	s_ashr_i32 s47, s46, 31
	s_lshl_b64 s[52:53], s[46:47], 12
	s_lshl_b64 s[50:51], s[42:43], 11
	s_waitcnt vmcnt(7)
	v_pk_add_f32 v[2:3], v[2:3], v[6:7]
	v_pk_add_f32 v[0:1], v[0:1], v[4:5]
	s_waitcnt vmcnt(6)
	v_pk_add_f32 v[2:3], v[2:3], v[10:11]
	v_pk_add_f32 v[0:1], v[0:1], v[8:9]
	v_lshl_add_u64 v[8:9], v[140:141], 0, s[44:45]
	s_or_b32 s44, s42, 3
	s_waitcnt vmcnt(5)
	v_pk_add_f32 v[2:3], v[2:3], v[14:15]
	v_pk_add_f32 v[0:1], v[0:1], v[12:13]
	s_ashr_i32 s45, s44, 31
	s_lshl_b64 s[54:55], s[44:45], 12
	s_waitcnt vmcnt(4)
	v_pk_add_f32 v[2:3], v[2:3], v[18:19]
	v_pk_add_f32 v[0:1], v[0:1], v[16:17]
	s_waitcnt vmcnt(3)
	v_pk_add_f32 v[2:3], v[2:3], v[22:23]
	v_pk_add_f32 v[0:1], v[0:1], v[20:21]
	s_waitcnt vmcnt(2)
	v_pk_add_f32 v[2:3], v[2:3], v[26:27]
	v_pk_add_f32 v[0:1], v[0:1], v[24:25]
	s_waitcnt vmcnt(1)
	v_pk_add_f32 v[2:3], v[2:3], v[30:31]
	v_pk_add_f32 v[0:1], v[0:1], v[28:29]
	s_waitcnt vmcnt(0)
	v_pk_add_f32 v[2:3], v[2:3], v[34:35]
	v_pk_add_f32 v[0:1], v[0:1], v[32:33]
	v_pk_add_f32 v[4:5], v[2:3], 1.0 op_sel_hi:[1,0]
	v_pk_add_f32 v[6:7], v[0:1], 1.0 op_sel_hi:[1,0]
	v_cndmask_b32_e64 v3, v5, v3, s[6:7]
	v_cndmask_b32_e64 v2, v4, v2, s[6:7]
	v_cndmask_b32_e64 v1, v7, v1, s[6:7]
	v_cndmask_b32_e64 v0, v6, v0, s[6:7]
	ds_write_b128 v183, v[0:3]
	s_waitcnt lgkmcnt(0)
	s_barrier
	global_load_dwordx4 v[108:111], v[142:143], off
	global_load_dwordx4 v[112:115], v[146:147], off
	global_load_dwordx4 v[116:119], v[148:149], off
	global_load_dwordx4 v[120:123], v[150:151], off
	global_load_dwordx4 v[16:19], v[36:37], off
	global_load_dwordx4 v[4:7], v[36:37], off offset:1024
	global_load_dwordx4 v[80:83], v[36:37], off offset:3072
	global_load_dwordx4 v[0:3], v[36:37], off offset:2048
	global_load_dwordx4 v[76:79], v[8:9], off
	global_load_dwordx4 v[68:71], v[8:9], off offset:1024
	s_nop 0
	global_load_dwordx4 v[36:39], v[8:9], off offset:3072
	global_load_dwordx4 v[64:67], v[8:9], off offset:2048
	s_waitcnt vmcnt(3)
	v_pk_mul_f32 v[28:29], v[78:79], v[78:79]
	v_pk_mul_f32 v[8:9], v[18:19], v[18:19]
	v_pk_mul_f32 v[10:11], v[16:17], v[16:17]
	v_pk_mul_f32 v[12:13], v[6:7], v[6:7]
	v_pk_mul_f32 v[14:15], v[4:5], v[4:5]
	v_mul_f32_e32 v24, v1, v1
	v_mul_f32_e32 v26, v3, v3
	v_pk_mul_f32 v[30:31], v[76:77], v[76:77]
	s_waitcnt vmcnt(2)
	v_pk_mul_f32 v[32:33], v[70:71], v[70:71]
	v_pk_mul_f32 v[34:35], v[68:69], v[68:69]
	v_mul_f32_e32 v47, v82, v82
	v_mul_f32_e32 v48, v83, v83
	v_pk_mov_b32 v[44:45], v[10:11], v[8:9] op_sel:[1, 0]
	v_mov_b32_e32 v11, v9
	v_pk_mov_b32 v[8:9], v[14:15], v[12:13] op_sel:[1, 0]
	v_mov_b32_e32 v15, v13
	v_pk_fma_f32 v[12:13], v[0:1], v[0:1], v[24:25] op_sel_hi:[1, 1, 0]
	v_pk_fma_f32 v[24:25], v[2:3], v[2:3], v[26:27] op_sel_hi:[1, 1, 0]
	v_pk_mov_b32 v[26:27], v[30:31], v[28:29] op_sel:[1, 0]
	v_mov_b32_e32 v31, v29
	v_pk_mov_b32 v[28:29], v[34:35], v[32:33] op_sel:[1, 0]
	v_mov_b32_e32 v35, v33
	v_mul_f32_e32 v43, v80, v80
	s_waitcnt vmcnt(0)
	v_mul_f32_e32 v40, v65, v65
	v_mul_f32_e32 v42, v67, v67
	v_pk_add_f32 v[10:11], v[44:45], v[10:11]
	v_pk_add_f32 v[8:9], v[8:9], v[14:15]
	v_mov_b32_e32 v13, v47
	v_mov_b32_e32 v25, v48
	v_pk_add_f32 v[14:15], v[26:27], v[30:31]
	v_pk_add_f32 v[26:27], v[28:29], v[34:35]
	v_mul_f32_e32 v46, v81, v81
	v_mul_f32_e32 v49, v36, v36
	v_mul_f32_e32 v50, v37, v37
	v_mul_f32_e32 v51, v38, v38
	v_mul_f32_e32 v52, v39, v39
	v_pk_fma_f32 v[32:33], v[64:65], v[64:65], v[40:41] op_sel_hi:[1, 1, 0]
	v_pk_fma_f32 v[40:41], v[66:67], v[66:67], v[42:43] op_sel_hi:[1, 1, 0]
	v_pk_add_f32 v[10:11], v[10:11], v[10:11] op_sel:[0, 1] op_sel_hi:[1, 0]
	v_pk_add_f32 v[8:9], v[8:9], v[8:9] op_sel:[0, 1] op_sel_hi:[1, 0]
	v_pk_add_f32 v[12:13], v[12:13], v[24:25]
	v_pk_add_f32 v[14:15], v[14:15], v[14:15] op_sel:[0, 1] op_sel_hi:[1, 0]
	v_pk_add_f32 v[24:25], v[26:27], v[26:27] op_sel:[0, 1] op_sel_hi:[1, 0]
	v_mov_b32_e32 v33, v51
	v_mov_b32_e32 v41, v52
	v_mov_b32_e32 v11, v43
	v_mov_b32_e32 v9, v46
	v_mov_b32_e32 v15, v49
	v_mov_b32_e32 v25, v50
	v_pk_add_f32 v[26:27], v[32:33], v[40:41]
	v_pk_add_f32 v[8:9], v[10:11], v[8:9]
	v_pk_add_f32 v[10:11], v[14:15], v[24:25]
	v_pk_add_f32 v[8:9], v[8:9], v[12:13]
	v_pk_add_f32 v[10:11], v[10:11], v[26:27]
	v_mov_b32_e32 v13, v8
	v_mov_b32_e32 v12, v10
	v_mov_b32_e32 v8, v11
	v_pk_add_f32 v[8:9], v[12:13], v[8:9]
	v_lshl_add_u64 v[12:13], v[140:141], 0, s[52:53]
	v_lshl_add_u64 v[14:15], v[140:141], 0, s[54:55]
	global_load_dwordx4 v[72:75], v[12:13], off
	global_load_dwordx4 v[60:63], v[12:13], off offset:1024
	global_load_dwordx4 v[56:59], v[12:13], off offset:2048
	global_load_dwordx4 v[52:55], v[12:13], off offset:3072
	global_load_dwordx4 v[48:51], v[14:15], off
	global_load_dwordx4 v[44:47], v[14:15], off offset:1024
	s_waitcnt lgkmcnt(0)
	s_nop 1
	v_add_f32_dpp v8, v8, v8 quad_perm:[1,0,3,2] row_mask:0xf bank_mask:0xf
	v_add_f32_dpp v9, v9, v9 quad_perm:[1,0,3,2] row_mask:0xf bank_mask:0xf
	global_load_dwordx4 v[40:43], v[14:15], off offset:2048
	global_load_dwordx4 v[32:35], v[14:15], off offset:3072
	v_lshl_add_u64 v[24:25], v[144:145], 0, s[50:51]
	s_add_u32 s50, s16, s50
	s_addc_u32 s51, s17, s51
	s_waitcnt lgkmcnt(0)
	s_nop 1
	v_add_f32_dpp v8, v8, v8 quad_perm:[2,3,0,1] row_mask:0xf bank_mask:0xf
	v_add_f32_dpp v9, v9, v9 quad_perm:[2,3,0,1] row_mask:0xf bank_mask:0xf
	s_lshl_b64 s[48:49], s[48:49], 11
	s_waitcnt lgkmcnt(0)
	s_nop 1
	v_add_f32_dpp v8, v8, v8 row_half_mirror row_mask:0xf bank_mask:0xf
	v_add_f32_dpp v9, v9, v9 row_half_mirror row_mask:0xf bank_mask:0xf
	s_waitcnt lgkmcnt(0)
	s_nop 1
	v_add_f32_dpp v8, v8, v8 row_mirror row_mask:0xf bank_mask:0xf
	v_add_f32_dpp v9, v9, v9 row_mirror row_mask:0xf bank_mask:0xf
	ds_bpermute_b32 v11, v188, v9
	ds_bpermute_b32 v10, v188, v8
	s_waitcnt lgkmcnt(0)
	v_pk_add_f32 v[8:9], v[8:9], v[10:11]
	s_waitcnt lgkmcnt(0)
	v_mov_b32_e32 v10, v8
	v_mov_b32_e32 v11, v9
	s_nop 1
	v_permlane32_swap_b32_e32 v10, v8
	v_permlane32_swap_b32_e32 v11, v9
	v_pk_add_f32 v[8:9], v[8:9], v[10:11]
	s_nop 0
	v_pk_fma_f32 v[90:91], v[8:9], s[28:29], v[84:85] op_sel_hi:[1, 0, 0]
	s_waitcnt vmcnt(4)
	v_mul_f32_e32 v99, v53, v53
	v_mul_f32_e32 v8, 0x4b800000, v91
	v_cmp_gt_f32_e32 vcc, s79, v91
	s_waitcnt vmcnt(2)
	v_pk_mul_f32 v[94:95], v[44:45], v[44:45]
	v_mul_f32_e32 v102, v54, v54
	v_cndmask_b32_e32 v8, v91, v8, vcc
	v_rsq_f32_e32 v26, v8
	ds_read_b128 v[8:11], v190
	ds_read_b128 v[12:15], v191
	s_waitcnt vmcnt(1)
	v_mul_f32_e32 v96, v41, v41
	v_mul_f32_e32 v98, v43, v43
	v_mul_f32_e32 v27, 0x45800000, v26
	v_cndmask_b32_e32 v92, v26, v27, vcc
	v_pk_mul_f32 v[18:19], v[18:19], v[92:93] op_sel_hi:[1, 0]
	v_pk_mul_f32 v[16:17], v[16:17], v[92:93] op_sel_hi:[1, 0]
	v_pk_mul_f32 v[18:19], v[110:111], v[18:19]
	v_pk_mul_f32 v[16:17], v[108:109], v[16:17]
	s_waitcnt lgkmcnt(0)
	v_pk_fma_f32 v[18:19], v[14:15], v[18:19], v[10:11]
	v_pk_fma_f32 v[16:17], v[12:13], v[16:17], v[8:9]
	v_pk_mul_f32 v[6:7], v[6:7], v[92:93] op_sel_hi:[1, 0]
	v_cvt_pk_bf16_f32 v16, v16, v17
	v_cvt_pk_bf16_f32 v17, v18, v19
	global_store_dwordx2 v[24:25], v[16:17], off sc1
	ds_read_b128 v[16:19], v192
	ds_read_b128 v[20:23], v193
	v_pk_mul_f32 v[4:5], v[4:5], v[92:93] op_sel_hi:[1, 0]
	v_pk_mul_f32 v[2:3], v[2:3], v[92:93] op_sel_hi:[1, 0]
	v_pk_mul_f32 v[0:1], v[0:1], v[92:93] op_sel_hi:[1, 0]
	v_pk_mul_f32 v[82:83], v[82:83], v[92:93] op_sel_hi:[1, 0]
	v_pk_mul_f32 v[80:81], v[80:81], v[92:93] op_sel_hi:[1, 0]
	v_cmp_gt_f32_e32 vcc, s79, v90
	v_pk_mul_f32 v[92:93], v[46:47], v[46:47]
	v_mul_f32_e32 v103, v55, v55
	s_waitcnt vmcnt(1)
	v_mul_f32_e32 v104, v32, v32
	v_mul_f32_e32 v105, v33, v33
	v_mul_f32_e32 v106, v34, v34
	v_mul_f32_e32 v107, v35, v35
	v_pk_mul_f32 v[4:5], v[112:113], v[4:5]
	v_pk_mul_f32 v[6:7], v[114:115], v[6:7]
	s_waitcnt lgkmcnt(0)
	v_pk_fma_f32 v[4:5], v[20:21], v[4:5], v[16:17]
	v_pk_fma_f32 v[6:7], v[22:23], v[6:7], v[18:19]
	v_cvt_pk_bf16_f32 v4, v4, v5
	v_cvt_pk_bf16_f32 v5, v6, v7
	global_store_dwordx2 v200, v[4:5], s[50:51] sc1
	ds_read_b128 v[24:27], v194
	ds_read_b128 v[28:31], v195
	v_pk_mul_f32 v[0:1], v[116:117], v[0:1]
	v_pk_mul_f32 v[2:3], v[118:119], v[2:3]
	s_waitcnt lgkmcnt(0)
	v_pk_fma_f32 v[0:1], v[28:29], v[0:1], v[24:25]
	v_pk_fma_f32 v[2:3], v[30:31], v[2:3], v[26:27]
	v_cvt_pk_bf16_f32 v0, v0, v1
	v_cvt_pk_bf16_f32 v1, v2, v3
	global_store_dwordx2 v201, v[0:1], s[50:51] sc1
	ds_read_b128 v[0:3], v196
	ds_read_b128 v[4:7], v197
	v_pk_mul_f32 v[80:81], v[80:81], v[120:121]
	v_pk_mul_f32 v[82:83], v[82:83], v[122:123]
	s_waitcnt lgkmcnt(0)
	v_pk_fma_f32 v[80:81], v[80:81], v[4:5], v[0:1]
	v_pk_fma_f32 v[82:83], v[82:83], v[6:7], v[2:3]
	v_cvt_pk_bf16_f32 v80, v80, v81
	v_cvt_pk_bf16_f32 v81, v82, v83
	global_store_dwordx2 v210, v[80:81], s[50:51] sc1
	v_mul_f32_e32 v86, 0x4b800000, v90
	v_cndmask_b32_e32 v86, v90, v86, vcc
	v_rsq_f32_e32 v88, v86
	v_lshl_add_u64 v[86:87], v[144:145], 0, s[48:49]
	s_add_u32 s48, s16, s48
	s_addc_u32 s49, s17, s49
	v_mul_f32_e32 v89, 0x45800000, v88
	v_cndmask_b32_e32 v88, v88, v89, vcc
	v_pk_mul_f32 v[78:79], v[78:79], v[88:89] op_sel_hi:[1, 0]
	v_pk_mul_f32 v[76:77], v[76:77], v[88:89] op_sel_hi:[1, 0]
	v_pk_mul_f32 v[70:71], v[70:71], v[88:89] op_sel_hi:[1, 0]
	v_pk_mul_f32 v[68:69], v[68:69], v[88:89] op_sel_hi:[1, 0]
	v_pk_mul_f32 v[66:67], v[66:67], v[88:89] op_sel_hi:[1, 0]
	v_pk_mul_f32 v[64:65], v[64:65], v[88:89] op_sel_hi:[1, 0]
	v_mul_f32_e32 v89, v52, v52
	v_pk_mul_f32 v[38:39], v[38:39], v[88:89] op_sel_hi:[1, 0]
	v_pk_mul_f32 v[36:37], v[36:37], v[88:89] op_sel_hi:[1, 0]
	v_pk_mul_f32 v[90:91], v[48:49], v[48:49]
	s_lshl_b64 s[46:47], s[46:47], 11
	v_pk_mul_f32 v[76:77], v[108:109], v[76:77]
	v_pk_mul_f32 v[78:79], v[110:111], v[78:79]
	v_pk_fma_f32 v[76:77], v[12:13], v[76:77], v[8:9]
	v_pk_fma_f32 v[78:79], v[14:15], v[78:79], v[10:11]
	v_cvt_pk_bf16_f32 v76, v76, v77
	v_cvt_pk_bf16_f32 v77, v78, v79
	global_store_dwordx2 v[86:87], v[76:77], off sc1
	v_mul_f32_e32 v80, v57, v57
	v_mul_f32_e32 v82, v59, v59
	v_pk_mul_f32 v[86:87], v[50:51], v[50:51]
	v_pk_mul_f32 v[68:69], v[112:113], v[68:69]
	v_pk_mul_f32 v[70:71], v[114:115], v[70:71]
	v_pk_fma_f32 v[68:69], v[20:21], v[68:69], v[16:17]
	v_pk_fma_f32 v[70:71], v[22:23], v[70:71], v[18:19]
	v_cvt_pk_bf16_f32 v68, v68, v69
	v_cvt_pk_bf16_f32 v69, v70, v71
	global_store_dwordx2 v200, v[68:69], s[48:49] sc1
	v_pk_mul_f32 v[76:77], v[62:63], v[62:63]
	v_pk_mul_f32 v[78:79], v[60:61], v[60:61]
	v_pk_mul_f32 v[64:65], v[116:117], v[64:65]
	v_pk_mul_f32 v[66:67], v[118:119], v[66:67]
	v_pk_fma_f32 v[64:65], v[28:29], v[64:65], v[24:25]
	v_pk_fma_f32 v[66:67], v[30:31], v[66:67], v[26:27]
	v_cvt_pk_bf16_f32 v64, v64, v65
	v_cvt_pk_bf16_f32 v65, v66, v67
	global_store_dwordx2 v201, v[64:65], s[48:49] sc1
	v_pk_mul_f32 v[68:69], v[74:75], v[74:75]
	v_pk_mul_f32 v[70:71], v[72:73], v[72:73]
	v_pk_mul_f32 v[36:37], v[120:121], v[36:37]
	v_pk_mul_f32 v[38:39], v[122:123], v[38:39]
	v_pk_fma_f32 v[36:37], v[4:5], v[36:37], v[0:1]
	v_pk_fma_f32 v[38:39], v[6:7], v[38:39], v[2:3]
	v_cvt_pk_bf16_f32 v36, v36, v37
	v_cvt_pk_bf16_f32 v37, v38, v39
	global_store_dwordx2 v210, v[36:37], s[48:49] sc1
	v_pk_mov_b32 v[100:101], v[70:71], v[68:69] op_sel:[1, 0]
	v_mov_b32_e32 v71, v69
	v_pk_mov_b32 v[68:69], v[78:79], v[76:77] op_sel:[1, 0]
	v_mov_b32_e32 v79, v77
	v_pk_fma_f32 v[76:77], v[56:57], v[56:57], v[80:81] op_sel_hi:[1, 1, 0]
	v_pk_fma_f32 v[80:81], v[58:59], v[58:59], v[82:83] op_sel_hi:[1, 1, 0]
	v_pk_mov_b32 v[82:83], v[90:91], v[86:87] op_sel:[1, 0]
	v_mov_b32_e32 v91, v87
	v_pk_mov_b32 v[86:87], v[94:95], v[92:93] op_sel:[1, 0]
	v_mov_b32_e32 v95, v93
	v_pk_add_f32 v[70:71], v[100:101], v[70:71]
	v_pk_add_f32 v[64:65], v[68:69], v[78:79]
	v_pk_add_f32 v[66:67], v[82:83], v[90:91]
	v_pk_add_f32 v[68:69], v[86:87], v[94:95]
	v_pk_fma_f32 v[92:93], v[40:41], v[40:41], v[96:97] op_sel_hi:[1, 1, 0]
	v_pk_fma_f32 v[96:97], v[42:43], v[42:43], v[98:99] op_sel_hi:[1, 1, 0]
	v_pk_add_f32 v[70:71], v[70:71], v[70:71] op_sel:[0, 1] op_sel_hi:[1, 0]
	v_pk_add_f32 v[64:65], v[64:65], v[64:65] op_sel:[0, 1] op_sel_hi:[1, 0]
	v_pk_add_f32 v[66:67], v[66:67], v[66:67] op_sel:[0, 1] op_sel_hi:[1, 0]
	v_pk_add_f32 v[68:69], v[68:69], v[68:69] op_sel:[0, 1] op_sel_hi:[1, 0]
	v_mov_b32_e32 v77, v102
	v_mov_b32_e32 v81, v103
	v_mov_b32_e32 v93, v106
	v_mov_b32_e32 v97, v107
	v_mov_b32_e32 v71, v89
	v_mov_b32_e32 v65, v99
	v_mov_b32_e32 v67, v104
	v_mov_b32_e32 v69, v105
	v_pk_add_f32 v[76:77], v[76:77], v[80:81]
	v_pk_add_f32 v[78:79], v[92:93], v[96:97]
	v_pk_add_f32 v[64:65], v[70:71], v[64:65]
	v_pk_add_f32 v[66:67], v[66:67], v[68:69]
	v_pk_add_f32 v[64:65], v[64:65], v[76:77]
	v_pk_add_f32 v[66:67], v[66:67], v[78:79]
	v_mov_b32_e32 v69, v64
	v_mov_b32_e32 v68, v66
	v_mov_b32_e32 v64, v67
	v_pk_add_f32 v[64:65], v[68:69], v[64:65]
	s_waitcnt lgkmcnt(0)
	s_nop 1
	v_add_f32_dpp v64, v64, v64 quad_perm:[1,0,3,2] row_mask:0xf bank_mask:0xf
	v_add_f32_dpp v65, v65, v65 quad_perm:[1,0,3,2] row_mask:0xf bank_mask:0xf
	s_waitcnt lgkmcnt(0)
	s_nop 1
	v_add_f32_dpp v64, v64, v64 quad_perm:[2,3,0,1] row_mask:0xf bank_mask:0xf
	v_add_f32_dpp v65, v65, v65 quad_perm:[2,3,0,1] row_mask:0xf bank_mask:0xf
	s_waitcnt lgkmcnt(0)
	s_nop 1
	v_add_f32_dpp v64, v64, v64 row_half_mirror row_mask:0xf bank_mask:0xf
	v_add_f32_dpp v65, v65, v65 row_half_mirror row_mask:0xf bank_mask:0xf
	s_waitcnt lgkmcnt(0)
	s_nop 1
	v_add_f32_dpp v64, v64, v64 row_mirror row_mask:0xf bank_mask:0xf
	v_add_f32_dpp v65, v65, v65 row_mirror row_mask:0xf bank_mask:0xf
	ds_bpermute_b32 v67, v188, v65
	ds_bpermute_b32 v66, v188, v64
	s_waitcnt lgkmcnt(0)
	v_pk_add_f32 v[64:65], v[64:65], v[66:67]
	s_waitcnt lgkmcnt(0)
	v_mov_b32_e32 v66, v64
	v_mov_b32_e32 v67, v65
	s_nop 1
	v_permlane32_swap_b32_e32 v66, v64
	v_permlane32_swap_b32_e32 v67, v65
	v_pk_add_f32 v[64:65], v[64:65], v[66:67]
	s_nop 0
	v_pk_fma_f32 v[64:65], v[64:65], s[28:29], v[84:85] op_sel_hi:[1, 0, 0]
	s_nop 0
	v_mul_f32_e32 v66, 0x4b800000, v65
	v_cmp_gt_f32_e32 vcc, s79, v65
	s_nop 1
	v_cndmask_b32_e32 v65, v65, v66, vcc
	v_rsq_f32_e32 v65, v65
	v_lshl_add_u64 v[66:67], v[144:145], 0, s[46:47]
	s_add_u32 s46, s16, s46
	s_addc_u32 s47, s17, s47
	v_mul_f32_e32 v68, 0x45800000, v65
	v_cndmask_b32_e32 v68, v65, v68, vcc
	v_pk_mul_f32 v[70:71], v[74:75], v[68:69] op_sel_hi:[1, 0]
	v_pk_mul_f32 v[72:73], v[72:73], v[68:69] op_sel_hi:[1, 0]
	v_pk_mul_f32 v[38:39], v[110:111], v[70:71]
	v_pk_mul_f32 v[36:37], v[108:109], v[72:73]
	v_pk_fma_f32 v[38:39], v[14:15], v[38:39], v[10:11]
	v_pk_fma_f32 v[36:37], v[12:13], v[36:37], v[8:9]
	v_pk_mul_f32 v[62:63], v[62:63], v[68:69] op_sel_hi:[1, 0]
	v_cvt_pk_bf16_f32 v36, v36, v37
	v_cvt_pk_bf16_f32 v37, v38, v39
	global_store_dwordx2 v[66:67], v[36:37], off sc1
	v_pk_mul_f32 v[60:61], v[60:61], v[68:69] op_sel_hi:[1, 0]
	v_pk_mul_f32 v[58:59], v[58:59], v[68:69] op_sel_hi:[1, 0]
	v_pk_mul_f32 v[56:57], v[56:57], v[68:69] op_sel_hi:[1, 0]
	v_pk_mul_f32 v[54:55], v[54:55], v[68:69] op_sel_hi:[1, 0]
	v_pk_mul_f32 v[52:53], v[52:53], v[68:69] op_sel_hi:[1, 0]
	v_cmp_gt_f32_e32 vcc, s79, v64
	s_lshl_b64 s[44:45], s[44:45], 11
	v_pk_mul_f32 v[36:37], v[112:113], v[60:61]
	v_pk_mul_f32 v[38:39], v[114:115], v[62:63]
	v_pk_fma_f32 v[36:37], v[20:21], v[36:37], v[16:17]
	v_pk_fma_f32 v[38:39], v[22:23], v[38:39], v[18:19]
	v_cvt_pk_bf16_f32 v36, v36, v37
	v_cvt_pk_bf16_f32 v37, v38, v39
	global_store_dwordx2 v200, v[36:37], s[46:47] sc1
	v_pk_mul_f32 v[36:37], v[116:117], v[56:57]
	v_pk_mul_f32 v[38:39], v[118:119], v[58:59]
	v_pk_fma_f32 v[36:37], v[28:29], v[36:37], v[24:25]
	v_pk_fma_f32 v[38:39], v[30:31], v[38:39], v[26:27]
	v_cvt_pk_bf16_f32 v36, v36, v37
	v_cvt_pk_bf16_f32 v37, v38, v39
	global_store_dwordx2 v201, v[36:37], s[46:47] sc1
	v_pk_mul_f32 v[36:37], v[120:121], v[52:53]
	v_pk_mul_f32 v[38:39], v[122:123], v[54:55]
	v_pk_fma_f32 v[36:37], v[4:5], v[36:37], v[0:1]
	v_pk_fma_f32 v[38:39], v[6:7], v[38:39], v[2:3]
	v_cvt_pk_bf16_f32 v36, v36, v37
	v_cvt_pk_bf16_f32 v37, v38, v39
	global_store_dwordx2 v210, v[36:37], s[46:47] sc1
	v_mul_f32_e32 v52, 0x4b800000, v64
	v_cndmask_b32_e32 v52, v64, v52, vcc
	v_rsq_f32_e32 v54, v52
	v_lshl_add_u64 v[52:53], v[144:145], 0, s[44:45]
	s_add_u32 s44, s16, s44
	s_addc_u32 s45, s17, s45
	v_mul_f32_e32 v55, 0x45800000, v54
	v_cndmask_b32_e32 v54, v54, v55, vcc
	v_pk_mul_f32 v[50:51], v[50:51], v[54:55] op_sel_hi:[1, 0]
	v_pk_mul_f32 v[48:49], v[48:49], v[54:55] op_sel_hi:[1, 0]
	v_pk_mul_f32 v[46:47], v[46:47], v[54:55] op_sel_hi:[1, 0]
	v_pk_mul_f32 v[44:45], v[44:45], v[54:55] op_sel_hi:[1, 0]
	v_pk_mul_f32 v[42:43], v[42:43], v[54:55] op_sel_hi:[1, 0]
	v_pk_mul_f32 v[40:41], v[40:41], v[54:55] op_sel_hi:[1, 0]
	v_pk_mul_f32 v[34:35], v[34:35], v[54:55] op_sel_hi:[1, 0]
	v_pk_mul_f32 v[32:33], v[32:33], v[54:55] op_sel_hi:[1, 0]
	s_or_b32 s48, s42, 4
	s_ashr_i32 s49, s48, 31
	s_lshl_b64 s[46:47], s[48:49], 12
	s_lshl_b64 s[48:49], s[48:49], 11
	v_lshl_add_u64 v[104:105], v[144:145], 0, s[48:49]
	v_pk_mul_f32 v[36:37], v[108:109], v[48:49]
	v_pk_mul_f32 v[38:39], v[110:111], v[50:51]
	v_pk_fma_f32 v[36:37], v[12:13], v[36:37], v[8:9]
	v_pk_fma_f32 v[38:39], v[14:15], v[38:39], v[10:11]
	v_cvt_pk_bf16_f32 v36, v36, v37
	v_cvt_pk_bf16_f32 v37, v38, v39
	global_store_dwordx2 v[52:53], v[36:37], off sc1
	v_pk_mul_f32 v[36:37], v[112:113], v[44:45]
	v_pk_mul_f32 v[38:39], v[114:115], v[46:47]
	v_pk_fma_f32 v[36:37], v[20:21], v[36:37], v[16:17]
	v_pk_fma_f32 v[38:39], v[22:23], v[38:39], v[18:19]
	v_cvt_pk_bf16_f32 v36, v36, v37
	v_cvt_pk_bf16_f32 v37, v38, v39
	global_store_dwordx2 v200, v[36:37], s[44:45] sc1
	v_pk_mul_f32 v[36:37], v[116:117], v[40:41]
	v_pk_mul_f32 v[38:39], v[118:119], v[42:43]
	v_pk_fma_f32 v[36:37], v[28:29], v[36:37], v[24:25]
	v_pk_fma_f32 v[38:39], v[30:31], v[38:39], v[26:27]
	v_cvt_pk_bf16_f32 v36, v36, v37
	v_cvt_pk_bf16_f32 v37, v38, v39
	global_store_dwordx2 v201, v[36:37], s[44:45] sc1
	v_lshl_add_u64 v[40:41], v[140:141], 0, s[46:47]
	s_or_b32 s46, s42, 5
	s_ashr_i32 s47, s46, 31
	v_pk_mul_f32 v[32:33], v[120:121], v[32:33]
	v_pk_mul_f32 v[34:35], v[122:123], v[34:35]
	v_pk_fma_f32 v[32:33], v[4:5], v[32:33], v[0:1]
	v_pk_fma_f32 v[34:35], v[6:7], v[34:35], v[2:3]
	v_cvt_pk_bf16_f32 v32, v32, v33
	v_cvt_pk_bf16_f32 v33, v34, v35
	global_store_dwordx2 v210, v[32:33], s[44:45] sc1
	global_load_dwordx4 v[86:89], v[40:41], off
	global_load_dwordx4 v[90:93], v[40:41], off offset:1024
	global_load_dwordx4 v[80:83], v[40:41], off offset:3072
	global_load_dwordx4 v[94:97], v[40:41], off offset:2048
	s_lshl_b64 s[44:45], s[46:47], 12
	v_lshl_add_u64 v[32:33], v[140:141], 0, s[44:45]
	global_load_dwordx4 v[76:79], v[32:33], off
	global_load_dwordx4 v[72:75], v[32:33], off offset:1024
	global_load_dwordx4 v[36:39], v[32:33], off offset:3072
	global_load_dwordx4 v[68:71], v[32:33], off offset:2048
	s_or_b32 s44, s42, 6
	s_or_b32 s42, s42, 7
	s_ashr_i32 s45, s44, 31
	s_ashr_i32 s43, s42, 31
	s_lshl_b64 s[50:51], s[44:45], 12
	s_lshl_b64 s[52:53], s[42:43], 12
	s_add_u32 s48, s16, s48
	s_addc_u32 s49, s17, s49
	s_lshl_b64 s[46:47], s[46:47], 11
	s_waitcnt vmcnt(7)
	v_pk_mul_f32 v[32:33], v[88:89], v[88:89]
	v_pk_mul_f32 v[34:35], v[86:87], v[86:87]
	s_waitcnt vmcnt(6)
	v_pk_mul_f32 v[40:41], v[92:93], v[92:93]
	v_pk_mul_f32 v[42:43], v[90:91], v[90:91]
	s_waitcnt vmcnt(4)
	v_mul_f32_e32 v44, v95, v95
	v_mul_f32_e32 v46, v97, v97
	s_waitcnt vmcnt(3)
	v_pk_mul_f32 v[48:49], v[78:79], v[78:79]
	v_pk_mul_f32 v[50:51], v[76:77], v[76:77]
	s_waitcnt vmcnt(2)
	v_pk_mul_f32 v[52:53], v[74:75], v[74:75]
	v_pk_mul_f32 v[54:55], v[72:73], v[72:73]
	v_mul_f32_e32 v63, v82, v82
	v_mul_f32_e32 v64, v83, v83
	v_pk_mov_b32 v[60:61], v[34:35], v[32:33] op_sel:[1, 0]
	v_mov_b32_e32 v35, v33
	v_pk_mov_b32 v[32:33], v[42:43], v[40:41] op_sel:[1, 0]
	v_mov_b32_e32 v43, v41
	v_pk_fma_f32 v[40:41], v[94:95], v[94:95], v[44:45] op_sel_hi:[1, 1, 0]
	v_pk_fma_f32 v[44:45], v[96:97], v[96:97], v[46:47] op_sel_hi:[1, 1, 0]
	v_pk_mov_b32 v[46:47], v[50:51], v[48:49] op_sel:[1, 0]
	v_mov_b32_e32 v51, v49
	v_pk_mov_b32 v[48:49], v[54:55], v[52:53] op_sel:[1, 0]
	v_mov_b32_e32 v55, v53
	v_mul_f32_e32 v59, v80, v80
	s_waitcnt vmcnt(0)
	v_mul_f32_e32 v56, v69, v69
	v_mul_f32_e32 v58, v71, v71
	v_pk_add_f32 v[34:35], v[60:61], v[34:35]
	v_pk_add_f32 v[32:33], v[32:33], v[42:43]
	v_mov_b32_e32 v41, v63
	v_mov_b32_e32 v45, v64
	v_pk_add_f32 v[42:43], v[46:47], v[50:51]
	v_pk_add_f32 v[46:47], v[48:49], v[54:55]
	v_mul_f32_e32 v62, v81, v81
	v_mul_f32_e32 v65, v36, v36
	v_mul_f32_e32 v66, v37, v37
	v_mul_f32_e32 v67, v38, v38
	v_mul_f32_e32 v102, v39, v39
	v_pk_fma_f32 v[52:53], v[68:69], v[68:69], v[56:57] op_sel_hi:[1, 1, 0]
	v_pk_fma_f32 v[56:57], v[70:71], v[70:71], v[58:59] op_sel_hi:[1, 1, 0]
	v_pk_add_f32 v[34:35], v[34:35], v[34:35] op_sel:[0, 1] op_sel_hi:[1, 0]
	v_pk_add_f32 v[32:33], v[32:33], v[32:33] op_sel:[0, 1] op_sel_hi:[1, 0]
	v_pk_add_f32 v[40:41], v[40:41], v[44:45]
	v_pk_add_f32 v[42:43], v[42:43], v[42:43] op_sel:[0, 1] op_sel_hi:[1, 0]
	v_pk_add_f32 v[44:45], v[46:47], v[46:47] op_sel:[0, 1] op_sel_hi:[1, 0]
	v_mov_b32_e32 v53, v67
	v_mov_b32_e32 v57, v102
	v_mov_b32_e32 v35, v59
	v_mov_b32_e32 v33, v62
	v_mov_b32_e32 v43, v65
	v_mov_b32_e32 v45, v66
	v_pk_add_f32 v[46:47], v[52:53], v[56:57]
	v_pk_add_f32 v[32:33], v[34:35], v[32:33]
	v_pk_add_f32 v[34:35], v[42:43], v[44:45]
	v_pk_add_f32 v[32:33], v[32:33], v[40:41]
	v_pk_add_f32 v[34:35], v[34:35], v[46:47]
	v_mov_b32_e32 v41, v32
	v_mov_b32_e32 v40, v34
	v_mov_b32_e32 v32, v35
	v_pk_add_f32 v[32:33], v[40:41], v[32:33]
	v_lshl_add_u64 v[40:41], v[140:141], 0, s[50:51]
	v_lshl_add_u64 v[102:103], v[140:141], 0, s[52:53]
	global_load_dwordx4 v[64:67], v[40:41], off
	global_load_dwordx4 v[60:63], v[40:41], off offset:1024
	global_load_dwordx4 v[56:59], v[40:41], off offset:2048
	global_load_dwordx4 v[52:55], v[40:41], off offset:3072
	s_waitcnt lgkmcnt(0)
	s_nop 1
	v_add_f32_dpp v32, v32, v32 quad_perm:[1,0,3,2] row_mask:0xf bank_mask:0xf
	v_add_f32_dpp v33, v33, v33 quad_perm:[1,0,3,2] row_mask:0xf bank_mask:0xf
	s_waitcnt lgkmcnt(0)
	s_nop 1
	v_add_f32_dpp v32, v32, v32 quad_perm:[2,3,0,1] row_mask:0xf bank_mask:0xf
	v_add_f32_dpp v33, v33, v33 quad_perm:[2,3,0,1] row_mask:0xf bank_mask:0xf
	s_waitcnt lgkmcnt(0)
	s_nop 1
	v_add_f32_dpp v32, v32, v32 row_half_mirror row_mask:0xf bank_mask:0xf
	v_add_f32_dpp v33, v33, v33 row_half_mirror row_mask:0xf bank_mask:0xf
	s_waitcnt lgkmcnt(0)
	s_nop 1
	v_add_f32_dpp v32, v32, v32 row_mirror row_mask:0xf bank_mask:0xf
	v_add_f32_dpp v33, v33, v33 row_mirror row_mask:0xf bank_mask:0xf
	ds_bpermute_b32 v35, v188, v33
	ds_bpermute_b32 v34, v188, v32
	s_waitcnt lgkmcnt(0)
	v_pk_add_f32 v[32:33], v[32:33], v[34:35]
	s_waitcnt lgkmcnt(0)
	v_mov_b32_e32 v34, v32
	v_mov_b32_e32 v35, v33
	s_nop 1
	v_permlane32_swap_b32_e32 v34, v32
	v_permlane32_swap_b32_e32 v35, v33
	v_pk_add_f32 v[32:33], v[32:33], v[34:35]
	s_nop 0
	v_pk_fma_f32 v[106:107], v[32:33], s[28:29], v[84:85] op_sel_hi:[1, 0, 0]
	s_nop 0
	v_mul_f32_e32 v32, 0x4b800000, v107
	v_cmp_gt_f32_e32 vcc, s79, v107
	s_nop 1
	v_cndmask_b32_e32 v32, v107, v32, vcc
	v_rsq_f32_e32 v107, v32
	global_load_dwordx4 v[48:51], v[102:103], off
	global_load_dwordx4 v[44:47], v[102:103], off offset:1024
	global_load_dwordx4 v[40:43], v[102:103], off offset:2048
	global_load_dwordx4 v[32:35], v[102:103], off offset:3072
	v_mul_f32_e32 v102, 0x45800000, v107
	v_cndmask_b32_e32 v102, v107, v102, vcc
	v_pk_mul_f32 v[88:89], v[88:89], v[102:103] op_sel_hi:[1, 0]
	v_pk_mul_f32 v[86:87], v[86:87], v[102:103] op_sel_hi:[1, 0]
	v_pk_mul_f32 v[88:89], v[110:111], v[88:89]
	v_pk_mul_f32 v[86:87], v[108:109], v[86:87]
	v_pk_fma_f32 v[88:89], v[14:15], v[88:89], v[10:11]
	v_pk_fma_f32 v[86:87], v[12:13], v[86:87], v[8:9]
	v_pk_mul_f32 v[92:93], v[92:93], v[102:103] op_sel_hi:[1, 0]
	v_cvt_pk_bf16_f32 v86, v86, v87
	v_cvt_pk_bf16_f32 v87, v88, v89
	global_store_dwordx2 v[104:105], v[86:87], off sc1
	v_pk_mul_f32 v[90:91], v[90:91], v[102:103] op_sel_hi:[1, 0]
	v_pk_mul_f32 v[82:83], v[82:83], v[102:103] op_sel_hi:[1, 0]
	v_pk_mul_f32 v[80:81], v[80:81], v[102:103] op_sel_hi:[1, 0]
	v_cmp_gt_f32_e32 vcc, s79, v106
	s_waitcnt vmcnt(5)
	v_mul_f32_e32 v99, v53, v53
	s_waitcnt vmcnt(2)
	v_mul_f32_e32 v98, v43, v43
	s_waitcnt vmcnt(1)
	v_mul_f32_e32 v104, v32, v32
	v_mul_f32_e32 v105, v33, v33
	v_mul_f32_e32 v107, v35, v35
	v_pk_mul_f32 v[86:87], v[112:113], v[90:91]
	v_pk_mul_f32 v[88:89], v[114:115], v[92:93]
	v_pk_fma_f32 v[86:87], v[20:21], v[86:87], v[16:17]
	v_pk_fma_f32 v[88:89], v[22:23], v[88:89], v[18:19]
	v_cvt_pk_bf16_f32 v86, v86, v87
	v_cvt_pk_bf16_f32 v87, v88, v89
	global_store_dwordx2 v200, v[86:87], s[48:49] sc1
	v_pk_mul_f32 v[90:91], v[96:97], v[102:103] op_sel_hi:[1, 0]
	v_pk_mul_f32 v[92:93], v[94:95], v[102:103] op_sel_hi:[1, 0]
	v_pk_mul_f32 v[94:95], v[44:45], v[44:45]
	v_mul_f32_e32 v96, v41, v41
	v_mul_f32_e32 v102, v54, v54
	v_mul_f32_e32 v103, v55, v55
	v_pk_mul_f32 v[86:87], v[116:117], v[92:93]
	v_pk_mul_f32 v[88:89], v[118:119], v[90:91]
	v_pk_fma_f32 v[86:87], v[28:29], v[86:87], v[24:25]
	v_pk_fma_f32 v[88:89], v[30:31], v[88:89], v[26:27]
	v_cvt_pk_bf16_f32 v86, v86, v87
	v_cvt_pk_bf16_f32 v87, v88, v89
	global_store_dwordx2 v201, v[86:87], s[48:49] sc1
	v_pk_mul_f32 v[90:91], v[48:49], v[48:49]
	v_pk_mul_f32 v[92:93], v[46:47], v[46:47]
	v_pk_mul_f32 v[80:81], v[120:121], v[80:81]
	v_pk_mul_f32 v[82:83], v[122:123], v[82:83]
	v_pk_fma_f32 v[80:81], v[4:5], v[80:81], v[0:1]
	v_pk_fma_f32 v[82:83], v[6:7], v[82:83], v[2:3]
	v_cvt_pk_bf16_f32 v80, v80, v81
	v_cvt_pk_bf16_f32 v81, v82, v83
	global_store_dwordx2 v210, v[80:81], s[48:49] sc1
	v_mul_f32_e32 v86, 0x4b800000, v106
	v_cndmask_b32_e32 v86, v106, v86, vcc
	v_rsq_f32_e32 v88, v86
	v_lshl_add_u64 v[86:87], v[144:145], 0, s[46:47]
	s_add_u32 s46, s16, s46
	s_addc_u32 s47, s17, s47
	v_mul_f32_e32 v89, 0x45800000, v88
	v_cndmask_b32_e32 v88, v88, v89, vcc
	v_pk_mul_f32 v[78:79], v[78:79], v[88:89] op_sel_hi:[1, 0]
	v_pk_mul_f32 v[76:77], v[76:77], v[88:89] op_sel_hi:[1, 0]
	v_pk_mul_f32 v[74:75], v[74:75], v[88:89] op_sel_hi:[1, 0]
	v_pk_mul_f32 v[72:73], v[72:73], v[88:89] op_sel_hi:[1, 0]
	v_pk_mul_f32 v[70:71], v[70:71], v[88:89] op_sel_hi:[1, 0]
	v_pk_mul_f32 v[68:69], v[68:69], v[88:89] op_sel_hi:[1, 0]
	v_mul_f32_e32 v89, v52, v52
	v_pk_mul_f32 v[38:39], v[38:39], v[88:89] op_sel_hi:[1, 0]
	v_pk_mul_f32 v[36:37], v[36:37], v[88:89] op_sel_hi:[1, 0]
	v_mul_f32_e32 v106, v34, v34
	s_lshl_b64 s[44:45], s[44:45], 11
	v_pk_mul_f32 v[76:77], v[108:109], v[76:77]
	v_pk_mul_f32 v[78:79], v[110:111], v[78:79]
	v_pk_fma_f32 v[76:77], v[12:13], v[76:77], v[8:9]
	v_pk_fma_f32 v[78:79], v[14:15], v[78:79], v[10:11]
	v_cvt_pk_bf16_f32 v76, v76, v77
	v_cvt_pk_bf16_f32 v77, v78, v79
	global_store_dwordx2 v[86:87], v[76:77], off sc1
	v_mul_f32_e32 v80, v57, v57
	v_mul_f32_e32 v82, v59, v59
	v_pk_mul_f32 v[86:87], v[50:51], v[50:51]
	v_pk_mul_f32 v[72:73], v[112:113], v[72:73]
	v_pk_mul_f32 v[74:75], v[114:115], v[74:75]
	v_pk_fma_f32 v[72:73], v[20:21], v[72:73], v[16:17]
	v_pk_fma_f32 v[74:75], v[22:23], v[74:75], v[18:19]
	v_cvt_pk_bf16_f32 v72, v72, v73
	v_cvt_pk_bf16_f32 v73, v74, v75
	global_store_dwordx2 v200, v[72:73], s[46:47] sc1
	v_pk_mul_f32 v[76:77], v[62:63], v[62:63]
	v_pk_mul_f32 v[78:79], v[60:61], v[60:61]
	v_pk_mul_f32 v[68:69], v[116:117], v[68:69]
	v_pk_mul_f32 v[70:71], v[118:119], v[70:71]
	v_pk_fma_f32 v[68:69], v[28:29], v[68:69], v[24:25]
	v_pk_fma_f32 v[70:71], v[30:31], v[70:71], v[26:27]
	v_cvt_pk_bf16_f32 v68, v68, v69
	v_cvt_pk_bf16_f32 v69, v70, v71
	global_store_dwordx2 v201, v[68:69], s[46:47] sc1
	v_pk_mul_f32 v[72:73], v[66:67], v[66:67]
	v_pk_mul_f32 v[74:75], v[64:65], v[64:65]
	v_pk_mul_f32 v[36:37], v[120:121], v[36:37]
	v_pk_mul_f32 v[38:39], v[122:123], v[38:39]
	v_pk_fma_f32 v[36:37], v[4:5], v[36:37], v[0:1]
	v_pk_fma_f32 v[38:39], v[6:7], v[38:39], v[2:3]
	v_cvt_pk_bf16_f32 v36, v36, v37
	v_cvt_pk_bf16_f32 v37, v38, v39
	global_store_dwordx2 v210, v[36:37], s[46:47] sc1
	v_pk_mov_b32 v[100:101], v[74:75], v[72:73] op_sel:[1, 0]
	v_mov_b32_e32 v75, v73
	v_pk_mov_b32 v[72:73], v[78:79], v[76:77] op_sel:[1, 0]
	v_mov_b32_e32 v79, v77
	v_pk_fma_f32 v[76:77], v[56:57], v[56:57], v[80:81] op_sel_hi:[1, 1, 0]
	v_pk_fma_f32 v[80:81], v[58:59], v[58:59], v[82:83] op_sel_hi:[1, 1, 0]
	v_pk_mov_b32 v[82:83], v[90:91], v[86:87] op_sel:[1, 0]
	v_mov_b32_e32 v91, v87
	v_pk_mov_b32 v[86:87], v[94:95], v[92:93] op_sel:[1, 0]
	v_mov_b32_e32 v95, v93
	v_pk_add_f32 v[74:75], v[100:101], v[74:75]
	v_pk_add_f32 v[68:69], v[72:73], v[78:79]
	v_pk_add_f32 v[70:71], v[82:83], v[90:91]
	v_pk_add_f32 v[72:73], v[86:87], v[94:95]
	v_pk_fma_f32 v[92:93], v[40:41], v[40:41], v[96:97] op_sel_hi:[1, 1, 0]
	v_pk_fma_f32 v[96:97], v[42:43], v[42:43], v[98:99] op_sel_hi:[1, 1, 0]
	v_pk_add_f32 v[74:75], v[74:75], v[74:75] op_sel:[0, 1] op_sel_hi:[1, 0]
	v_pk_add_f32 v[68:69], v[68:69], v[68:69] op_sel:[0, 1] op_sel_hi:[1, 0]
	v_pk_add_f32 v[70:71], v[70:71], v[70:71] op_sel:[0, 1] op_sel_hi:[1, 0]
	v_pk_add_f32 v[72:73], v[72:73], v[72:73] op_sel:[0, 1] op_sel_hi:[1, 0]
	v_mov_b32_e32 v77, v102
	v_mov_b32_e32 v81, v103
	v_mov_b32_e32 v93, v106
	v_mov_b32_e32 v97, v107
	v_mov_b32_e32 v75, v89
	v_mov_b32_e32 v69, v99
	v_mov_b32_e32 v71, v104
	v_mov_b32_e32 v73, v105
	v_pk_add_f32 v[76:77], v[76:77], v[80:81]
	v_pk_add_f32 v[78:79], v[92:93], v[96:97]
	v_pk_add_f32 v[68:69], v[74:75], v[68:69]
	v_pk_add_f32 v[70:71], v[70:71], v[72:73]
	v_pk_add_f32 v[68:69], v[68:69], v[76:77]
	v_pk_add_f32 v[70:71], v[70:71], v[78:79]
	v_mov_b32_e32 v73, v68
	v_mov_b32_e32 v72, v70
	v_mov_b32_e32 v68, v71
	v_pk_add_f32 v[68:69], v[72:73], v[68:69]
	s_waitcnt lgkmcnt(0)
	s_nop 1
	v_add_f32_dpp v68, v68, v68 quad_perm:[1,0,3,2] row_mask:0xf bank_mask:0xf
	v_add_f32_dpp v69, v69, v69 quad_perm:[1,0,3,2] row_mask:0xf bank_mask:0xf
	s_waitcnt lgkmcnt(0)
	s_nop 1
	v_add_f32_dpp v68, v68, v68 quad_perm:[2,3,0,1] row_mask:0xf bank_mask:0xf
	v_add_f32_dpp v69, v69, v69 quad_perm:[2,3,0,1] row_mask:0xf bank_mask:0xf
	s_waitcnt lgkmcnt(0)
	s_nop 1
	v_add_f32_dpp v68, v68, v68 row_half_mirror row_mask:0xf bank_mask:0xf
	v_add_f32_dpp v69, v69, v69 row_half_mirror row_mask:0xf bank_mask:0xf
	s_waitcnt lgkmcnt(0)
	s_nop 1
	v_add_f32_dpp v68, v68, v68 row_mirror row_mask:0xf bank_mask:0xf
	v_add_f32_dpp v69, v69, v69 row_mirror row_mask:0xf bank_mask:0xf
	ds_bpermute_b32 v71, v188, v69
	ds_bpermute_b32 v70, v188, v68
	s_waitcnt lgkmcnt(0)
	v_pk_add_f32 v[68:69], v[68:69], v[70:71]
	s_waitcnt lgkmcnt(0)
	v_mov_b32_e32 v70, v68
	v_mov_b32_e32 v71, v69
	s_nop 1
	v_permlane32_swap_b32_e32 v70, v68
	v_permlane32_swap_b32_e32 v71, v69
	v_pk_add_f32 v[68:69], v[68:69], v[70:71]
	s_nop 0
	v_pk_fma_f32 v[68:69], v[68:69], s[28:29], v[84:85] op_sel_hi:[1, 0, 0]
	s_nop 0
	v_mul_f32_e32 v70, 0x4b800000, v69
	v_cmp_gt_f32_e32 vcc, s79, v69
	s_nop 1
	v_cndmask_b32_e32 v69, v69, v70, vcc
	v_rsq_f32_e32 v69, v69
	v_lshl_add_u64 v[70:71], v[144:145], 0, s[44:45]
	s_add_u32 s44, s16, s44
	s_addc_u32 s45, s17, s45
	v_mul_f32_e32 v72, 0x45800000, v69
	v_cndmask_b32_e32 v72, v69, v72, vcc
	v_pk_mul_f32 v[66:67], v[66:67], v[72:73] op_sel_hi:[1, 0]
	v_pk_mul_f32 v[64:65], v[64:65], v[72:73] op_sel_hi:[1, 0]
	v_pk_mul_f32 v[38:39], v[110:111], v[66:67]
	v_pk_mul_f32 v[36:37], v[108:109], v[64:65]
	v_pk_fma_f32 v[38:39], v[14:15], v[38:39], v[10:11]
	v_pk_fma_f32 v[36:37], v[12:13], v[36:37], v[8:9]
	v_pk_mul_f32 v[62:63], v[62:63], v[72:73] op_sel_hi:[1, 0]
	v_cvt_pk_bf16_f32 v36, v36, v37
	v_cvt_pk_bf16_f32 v37, v38, v39
	global_store_dwordx2 v[70:71], v[36:37], off sc1
	v_pk_mul_f32 v[60:61], v[60:61], v[72:73] op_sel_hi:[1, 0]
	v_pk_mul_f32 v[58:59], v[58:59], v[72:73] op_sel_hi:[1, 0]
	v_pk_mul_f32 v[56:57], v[56:57], v[72:73] op_sel_hi:[1, 0]
	v_pk_mul_f32 v[54:55], v[54:55], v[72:73] op_sel_hi:[1, 0]
	v_pk_mul_f32 v[52:53], v[52:53], v[72:73] op_sel_hi:[1, 0]
	v_cmp_gt_f32_e32 vcc, s79, v68
	s_lshl_b64 s[42:43], s[42:43], 11
	v_pk_mul_f32 v[36:37], v[112:113], v[60:61]
	v_pk_mul_f32 v[38:39], v[114:115], v[62:63]
	v_pk_fma_f32 v[36:37], v[20:21], v[36:37], v[16:17]
	v_pk_fma_f32 v[38:39], v[22:23], v[38:39], v[18:19]
	v_cvt_pk_bf16_f32 v36, v36, v37
	v_cvt_pk_bf16_f32 v37, v38, v39
	global_store_dwordx2 v200, v[36:37], s[44:45] sc1
	v_pk_mul_f32 v[36:37], v[116:117], v[56:57]
	v_pk_mul_f32 v[38:39], v[118:119], v[58:59]
	v_pk_fma_f32 v[36:37], v[28:29], v[36:37], v[24:25]
	v_pk_fma_f32 v[38:39], v[30:31], v[38:39], v[26:27]
	v_cvt_pk_bf16_f32 v36, v36, v37
	v_cvt_pk_bf16_f32 v37, v38, v39
	global_store_dwordx2 v201, v[36:37], s[44:45] sc1
	v_pk_mul_f32 v[36:37], v[120:121], v[52:53]
	v_pk_mul_f32 v[38:39], v[122:123], v[54:55]
	v_pk_fma_f32 v[36:37], v[4:5], v[36:37], v[0:1]
	v_pk_fma_f32 v[38:39], v[6:7], v[38:39], v[2:3]
	v_cvt_pk_bf16_f32 v36, v36, v37
	v_cvt_pk_bf16_f32 v37, v38, v39
	global_store_dwordx2 v210, v[36:37], s[44:45] sc1
	v_mul_f32_e32 v52, 0x4b800000, v68
	v_cndmask_b32_e32 v52, v68, v52, vcc
	v_rsq_f32_e32 v54, v52
	v_lshl_add_u64 v[52:53], v[144:145], 0, s[42:43]
	s_add_u32 s42, s16, s42
	s_addc_u32 s43, s17, s43
	v_mul_f32_e32 v55, 0x45800000, v54
	v_cndmask_b32_e32 v54, v54, v55, vcc
	v_pk_mul_f32 v[50:51], v[50:51], v[54:55] op_sel_hi:[1, 0]
	v_pk_mul_f32 v[48:49], v[48:49], v[54:55] op_sel_hi:[1, 0]
	s_andn2_b64 vcc, exec, s[8:9]
	s_mov_b64 s[8:9], -1
	v_pk_mul_f32 v[36:37], v[108:109], v[48:49]
	v_pk_mul_f32 v[38:39], v[110:111], v[50:51]
	v_pk_fma_f32 v[8:9], v[12:13], v[36:37], v[8:9]
	v_pk_fma_f32 v[10:11], v[14:15], v[38:39], v[10:11]
	v_cvt_pk_bf16_f32 v8, v8, v9
	v_cvt_pk_bf16_f32 v9, v10, v11
	global_store_dwordx2 v[52:53], v[8:9], off sc1
	v_pk_mul_f32 v[12:13], v[46:47], v[54:55] op_sel_hi:[1, 0]
	v_pk_mul_f32 v[14:15], v[44:45], v[54:55] op_sel_hi:[1, 0]
	v_pk_mul_f32 v[10:11], v[114:115], v[12:13]
	v_pk_mul_f32 v[8:9], v[112:113], v[14:15]
	v_pk_fma_f32 v[10:11], v[22:23], v[10:11], v[18:19]
	v_pk_fma_f32 v[8:9], v[20:21], v[8:9], v[16:17]
	v_pk_mul_f32 v[12:13], v[42:43], v[54:55] op_sel_hi:[1, 0]
	v_cvt_pk_bf16_f32 v8, v8, v9
	v_cvt_pk_bf16_f32 v9, v10, v11
	global_store_dwordx2 v200, v[8:9], s[42:43] sc1
	v_pk_mul_f32 v[14:15], v[40:41], v[54:55] op_sel_hi:[1, 0]
	v_pk_mul_f32 v[10:11], v[118:119], v[12:13]
	v_pk_mul_f32 v[8:9], v[116:117], v[14:15]
	v_pk_fma_f32 v[10:11], v[30:31], v[10:11], v[26:27]
	v_pk_fma_f32 v[8:9], v[28:29], v[8:9], v[24:25]
	v_pk_mul_f32 v[12:13], v[34:35], v[54:55] op_sel_hi:[1, 0]
	v_cvt_pk_bf16_f32 v8, v8, v9
	v_cvt_pk_bf16_f32 v9, v10, v11
	global_store_dwordx2 v201, v[8:9], s[42:43] sc1
	v_pk_mul_f32 v[14:15], v[32:33], v[54:55] op_sel_hi:[1, 0]
	v_pk_mul_f32 v[10:11], v[122:123], v[12:13]
	v_pk_mul_f32 v[8:9], v[120:121], v[14:15]
	v_pk_fma_f32 v[2:3], v[6:7], v[10:11], v[2:3]
	v_pk_fma_f32 v[0:1], v[4:5], v[8:9], v[0:1]
	s_nop 0
	v_cvt_pk_bf16_f32 v0, v0, v1
	v_cvt_pk_bf16_f32 v1, v2, v3
	global_store_dwordx2 v210, v[0:1], s[42:43] sc1
	s_cbranch_vccnz .LBB0_1163
	s_andn2_b64 vcc, exec, s[10:11]
	s_cbranch_vccnz .LBB0_1162
	s_barrier
	s_branch .LBB0_1162

.LBB0_1484:
	v_lshl_or_b32 v172, s66, 8, v198
	v_add_u32_e32 v156, 0x2000, v172
	v_ashrrev_i32_e32 v157, 31, v156
	v_lshlrev_b64 v[160:161], 2, v[156:157]
	s_ashr_i32 s69, s67, 3
	v_lshl_add_u64 v[164:165], s[14:15], 0, v[160:161]
	v_lshl_add_u64 v[156:157], s[16:17], 0, v[160:161]
	v_mad_i64_i32 v[160:161], s[70:71], s69, v211, v[164:165]
	global_load_dwordx4 v[156:159], v[156:157], off
	s_add_i32 s42, s69, 8
	s_add_i32 s41, s69, 16
	s_add_i32 s40, s69, 24
	s_add_i32 s39, s69, 32
	s_add_i32 s38, s69, 40
	s_add_i32 s37, s69, 48
	s_add_i32 s36, s69, 56
	s_lshl_b32 s68, s67, 8
	global_load_dwordx4 v[160:163], v[160:161], off
	v_mad_i64_i32 v[212:213], s[70:71], s42, v211, v[164:165]
	global_load_dwordx4 v[212:215], v[212:213], off
	v_mad_i64_i32 v[216:217], s[70:71], s41, v211, v[164:165]
	global_load_dwordx4 v[216:219], v[216:217], off
	v_mad_i64_i32 v[220:221], s[70:71], s40, v211, v[164:165]
	global_load_dwordx4 v[220:223], v[220:221], off
	v_mad_i64_i32 v[224:225], s[70:71], s39, v211, v[164:165]
	global_load_dwordx4 v[224:227], v[224:225], off
	v_mad_i64_i32 v[228:229], s[70:71], s38, v211, v[164:165]
	global_load_dwordx4 v[228:231], v[228:229], off
	v_mad_i64_i32 v[232:233], s[70:71], s37, v211, v[164:165]
	global_load_dwordx4 v[232:235], v[232:233], off
	v_mad_i64_i32 v[236:237], s[70:71], s36, v211, v[164:165]
	global_load_dwordx4 v[236:239], v[236:237], off
	v_ashrrev_i32_e32 v173, 31, v172
	s_waitcnt vmcnt(7)
	v_pk_add_f32 v[160:161], v[156:157], v[160:161]
	v_pk_add_f32 v[162:163], v[158:159], v[162:163]
	s_waitcnt vmcnt(6)
	v_pk_add_f32 v[160:161], v[160:161], v[212:213]
	v_pk_add_f32 v[162:163], v[162:163], v[214:215]
	s_waitcnt vmcnt(5)
	v_pk_add_f32 v[160:161], v[160:161], v[216:217]
	v_pk_add_f32 v[162:163], v[162:163], v[218:219]
	s_waitcnt vmcnt(4)
	v_pk_add_f32 v[160:161], v[160:161], v[220:221]
	v_pk_add_f32 v[162:163], v[162:163], v[222:223]
	s_waitcnt vmcnt(3)
	v_pk_add_f32 v[160:161], v[160:161], v[224:225]
	v_pk_add_f32 v[162:163], v[162:163], v[226:227]
	s_waitcnt vmcnt(2)
	v_pk_add_f32 v[160:161], v[160:161], v[228:229]
	v_pk_add_f32 v[162:163], v[162:163], v[230:231]
	s_waitcnt vmcnt(1)
	v_pk_add_f32 v[160:161], v[160:161], v[232:233]
	v_pk_add_f32 v[162:163], v[162:163], v[234:235]
	s_waitcnt vmcnt(0)
	v_pk_add_f32 v[158:159], v[162:163], v[238:239]
	v_pk_add_f32 v[160:161], v[160:161], v[236:237]
	v_pk_mul_f32 v[156:157], v[158:159], 0.5 op_sel_hi:[1, 0]
	v_pk_mul_f32 v[158:159], v[160:161], 0.5 op_sel_hi:[1, 0]
	v_add_u32_e32 v160, 0x2010, v172
	v_ashrrev_i32_e32 v161, 31, v160
	v_lshlrev_b64 v[164:165], 2, v[160:161]
	v_lshl_add_u64 v[168:169], s[14:15], 0, v[164:165]
	v_lshl_add_u64 v[160:161], s[16:17], 0, v[164:165]
	v_mad_i64_i32 v[164:165], s[70:71], s69, v211, v[168:169]
	global_load_dwordx4 v[160:163], v[160:161], off
	global_load_dwordx4 v[164:167], v[164:165], off
	v_mad_i64_i32 v[212:213], s[70:71], s42, v211, v[168:169]
	global_load_dwordx4 v[212:215], v[212:213], off
	v_mad_i64_i32 v[216:217], s[70:71], s41, v211, v[168:169]
	global_load_dwordx4 v[216:219], v[216:217], off
	v_mad_i64_i32 v[220:221], s[70:71], s40, v211, v[168:169]
	global_load_dwordx4 v[220:223], v[220:221], off
	v_mad_i64_i32 v[224:225], s[70:71], s39, v211, v[168:169]
	global_load_dwordx4 v[224:227], v[224:225], off
	v_mad_i64_i32 v[228:229], s[70:71], s38, v211, v[168:169]
	global_load_dwordx4 v[228:231], v[228:229], off
	v_mad_i64_i32 v[232:233], s[70:71], s37, v211, v[168:169]
	global_load_dwordx4 v[232:235], v[232:233], off
	v_mad_i64_i32 v[236:237], s[70:71], s36, v211, v[168:169]
	global_load_dwordx4 v[236:239], v[236:237], off
	s_waitcnt vmcnt(7)
	v_pk_add_f32 v[164:165], v[160:161], v[164:165]
	v_pk_add_f32 v[166:167], v[162:163], v[166:167]
	s_waitcnt vmcnt(6)
	v_pk_add_f32 v[164:165], v[164:165], v[212:213]
	v_pk_add_f32 v[166:167], v[166:167], v[214:215]
	s_waitcnt vmcnt(5)
	v_pk_add_f32 v[164:165], v[164:165], v[216:217]
	v_pk_add_f32 v[166:167], v[166:167], v[218:219]
	s_waitcnt vmcnt(4)
	v_pk_add_f32 v[164:165], v[164:165], v[220:221]
	v_pk_add_f32 v[166:167], v[166:167], v[222:223]
	s_waitcnt vmcnt(3)
	v_pk_add_f32 v[164:165], v[164:165], v[224:225]
	v_pk_add_f32 v[166:167], v[166:167], v[226:227]
	s_waitcnt vmcnt(2)
	v_pk_add_f32 v[164:165], v[164:165], v[228:229]
	v_pk_add_f32 v[166:167], v[166:167], v[230:231]
	s_waitcnt vmcnt(1)
	v_pk_add_f32 v[164:165], v[164:165], v[232:233]
	v_pk_add_f32 v[166:167], v[166:167], v[234:235]
	s_waitcnt vmcnt(0)
	v_pk_add_f32 v[162:163], v[166:167], v[238:239]
	v_pk_add_f32 v[164:165], v[164:165], v[236:237]
	v_pk_mul_f32 v[160:161], v[162:163], 0.5 op_sel_hi:[1, 0]
	v_pk_mul_f32 v[162:163], v[164:165], 0.5 op_sel_hi:[1, 0]
	v_add_u32_e32 v164, 0x2080, v172
	v_ashrrev_i32_e32 v165, 31, v164
	v_lshlrev_b64 v[168:169], 2, v[164:165]
	v_lshl_add_u64 v[174:175], s[14:15], 0, v[168:169]
	v_lshl_add_u64 v[164:165], s[16:17], 0, v[168:169]
	v_mad_i64_i32 v[168:169], s[70:71], s69, v211, v[174:175]
	global_load_dwordx4 v[164:167], v[164:165], off
	global_load_dwordx4 v[168:171], v[168:169], off
	v_mad_i64_i32 v[212:213], s[70:71], s42, v211, v[174:175]
	global_load_dwordx4 v[212:215], v[212:213], off
	v_mad_i64_i32 v[216:217], s[70:71], s41, v211, v[174:175]
	global_load_dwordx4 v[216:219], v[216:217], off
	v_mad_i64_i32 v[220:221], s[70:71], s40, v211, v[174:175]
	global_load_dwordx4 v[220:223], v[220:221], off
	v_mad_i64_i32 v[224:225], s[70:71], s39, v211, v[174:175]
	global_load_dwordx4 v[224:227], v[224:225], off
	v_mad_i64_i32 v[228:229], s[70:71], s38, v211, v[174:175]
	global_load_dwordx4 v[228:231], v[228:229], off
	v_mad_i64_i32 v[232:233], s[70:71], s37, v211, v[174:175]
	global_load_dwordx4 v[232:235], v[232:233], off
	v_mad_i64_i32 v[236:237], s[70:71], s36, v211, v[174:175]
	global_load_dwordx4 v[236:239], v[236:237], off
	s_waitcnt vmcnt(7)
	v_pk_add_f32 v[168:169], v[164:165], v[168:169]
	v_pk_add_f32 v[170:171], v[166:167], v[170:171]
	s_waitcnt vmcnt(6)
	v_pk_add_f32 v[168:169], v[168:169], v[212:213]
	v_pk_add_f32 v[170:171], v[170:171], v[214:215]
	s_waitcnt vmcnt(5)
	v_pk_add_f32 v[168:169], v[168:169], v[216:217]
	v_pk_add_f32 v[170:171], v[170:171], v[218:219]
	s_waitcnt vmcnt(4)
	v_pk_add_f32 v[168:169], v[168:169], v[220:221]
	v_pk_add_f32 v[170:171], v[170:171], v[222:223]
	s_waitcnt vmcnt(3)
	v_pk_add_f32 v[168:169], v[168:169], v[224:225]
	v_pk_add_f32 v[170:171], v[170:171], v[226:227]
	s_waitcnt vmcnt(2)
	v_pk_add_f32 v[168:169], v[168:169], v[228:229]
	v_pk_add_f32 v[170:171], v[170:171], v[230:231]
	s_waitcnt vmcnt(1)
	v_pk_add_f32 v[168:169], v[168:169], v[232:233]
	v_pk_add_f32 v[170:171], v[170:171], v[234:235]
	s_waitcnt vmcnt(0)
	v_pk_add_f32 v[166:167], v[170:171], v[238:239]
	v_pk_add_f32 v[168:169], v[168:169], v[236:237]
	v_pk_mul_f32 v[164:165], v[166:167], 0.5 op_sel_hi:[1, 0]
	v_pk_mul_f32 v[166:167], v[168:169], 0.5 op_sel_hi:[1, 0]
	v_add_u32_e32 v168, 0x2090, v172
	v_ashrrev_i32_e32 v169, 31, v168
	v_lshlrev_b64 v[174:175], 2, v[168:169]
	v_lshl_add_u64 v[178:179], s[14:15], 0, v[174:175]
	v_lshl_add_u64 v[168:169], s[16:17], 0, v[174:175]
	v_mad_i64_i32 v[174:175], s[70:71], s69, v211, v[178:179]
	global_load_dwordx4 v[168:171], v[168:169], off
	global_load_dwordx4 v[174:177], v[174:175], off
	v_mad_i64_i32 v[212:213], s[42:43], s42, v211, v[178:179]
	global_load_dwordx4 v[212:215], v[212:213], off
	v_mad_i64_i32 v[216:217], s[42:43], s41, v211, v[178:179]
	global_load_dwordx4 v[216:219], v[216:217], off
	v_mad_i64_i32 v[220:221], s[40:41], s40, v211, v[178:179]
	global_load_dwordx4 v[220:223], v[220:221], off
	v_mad_i64_i32 v[224:225], s[40:41], s39, v211, v[178:179]
	global_load_dwordx4 v[224:227], v[224:225], off
	v_mad_i64_i32 v[228:229], s[38:39], s38, v211, v[178:179]
	global_load_dwordx4 v[228:231], v[228:229], off
	v_mad_i64_i32 v[232:233], s[38:39], s37, v211, v[178:179]
	global_load_dwordx4 v[232:235], v[232:233], off
	v_mad_i64_i32 v[236:237], s[36:37], s36, v211, v[178:179]
	global_load_dwordx4 v[236:239], v[236:237], off
	v_lshlrev_b64 v[172:173], 2, v[172:173]
	v_readfirstlane_b32 s70, v180
	s_waitcnt vmcnt(7)
	v_pk_add_f32 v[174:175], v[168:169], v[174:175]
	v_pk_add_f32 v[176:177], v[170:171], v[176:177]
	s_waitcnt vmcnt(6)
	v_pk_add_f32 v[174:175], v[174:175], v[212:213]
	v_pk_add_f32 v[176:177], v[176:177], v[214:215]
	s_waitcnt vmcnt(5)
	v_pk_add_f32 v[174:175], v[174:175], v[216:217]
	v_pk_add_f32 v[176:177], v[176:177], v[218:219]
	s_waitcnt vmcnt(4)
	v_pk_add_f32 v[174:175], v[174:175], v[220:221]
	v_pk_add_f32 v[176:177], v[176:177], v[222:223]
	s_waitcnt vmcnt(3)
	v_pk_add_f32 v[174:175], v[174:175], v[224:225]
	v_pk_add_f32 v[176:177], v[176:177], v[226:227]
	s_waitcnt vmcnt(2)
	v_pk_add_f32 v[174:175], v[174:175], v[228:229]
	v_pk_add_f32 v[176:177], v[176:177], v[230:231]
	s_waitcnt vmcnt(1)
	v_pk_add_f32 v[174:175], v[174:175], v[232:233]
	v_pk_add_f32 v[176:177], v[176:177], v[234:235]
	v_add_u32_e32 v178, s68, v181
	v_ashrrev_i32_e32 v179, 31, v178
	s_waitcnt vmcnt(0)
	v_pk_add_f32 v[170:171], v[176:177], v[238:239]
	v_pk_add_f32 v[174:175], v[174:175], v[236:237]
	v_pk_mul_f32 v[168:169], v[170:171], 0.5 op_sel_hi:[1, 0]
	v_pk_mul_f32 v[170:171], v[174:175], 0.5 op_sel_hi:[1, 0]
	v_lshl_add_u64 v[174:175], s[12:13], 0, v[172:173]
	v_lshlrev_b64 v[176:177], 12, v[178:179]
	v_lshl_add_u64 v[204:205], v[174:175], 0, v[176:177]
	global_load_dwordx4 v[212:215], v[204:205], off
	global_load_dwordx4 v[216:219], v[204:205], off offset:64
	global_load_dwordx4 v[220:223], v[204:205], off offset:512
	global_load_dwordx4 v[224:227], v[204:205], off offset:576
	v_or_b32_e32 v204, 16, v178
	v_ashrrev_i32_e32 v205, 31, v204
	v_lshlrev_b64 v[204:205], 12, v[204:205]
	v_lshl_add_u64 v[206:207], v[174:175], 0, v[204:205]
	global_load_dwordx4 v[228:231], v[206:207], off
	global_load_dwordx4 v[232:235], v[206:207], off offset:64
	global_load_dwordx4 v[236:239], v[206:207], off offset:512
	global_load_dwordx4 v[240:243], v[206:207], off offset:576
	v_lshl_add_u64 v[206:207], s[12:13], 0, v[176:177]
	v_lshl_add_u64 v[206:207], v[206:207], 0, v[172:173]
	s_waitcnt vmcnt(7)
	v_pk_fma_f32 v[126:127], v[126:127], v[156:157], v[214:215]
	v_pk_fma_f32 v[124:125], v[124:125], v[158:159], v[212:213]
	s_waitcnt vmcnt(5)
	v_pk_fma_f32 v[110:111], v[110:111], v[164:165], v[222:223]
	v_pk_fma_f32 v[108:109], v[108:109], v[166:167], v[220:221]
	global_store_dwordx4 v[206:207], v[108:111], off offset:512 sc1
	s_waitcnt vmcnt(5)
	v_pk_fma_f32 v[106:107], v[106:107], v[168:169], v[226:227]
	v_pk_fma_f32 v[104:105], v[104:105], v[170:171], v[224:225]
	v_lshl_add_u64 v[108:109], s[12:13], 0, v[204:205]
	v_lshl_add_u64 v[108:109], v[108:109], 0, v[172:173]
	s_waitcnt vmcnt(1)
	v_pk_fma_f32 v[98:99], v[98:99], v[168:169], v[242:243]
	v_pk_fma_f32 v[96:97], v[96:97], v[170:171], v[240:241]
	global_store_dwordx4 v[108:109], v[96:99], off offset:576 sc1
	global_store_dwordx4 v[206:207], v[104:107], off offset:576 sc1
	v_pk_fma_f32 v[122:123], v[122:123], v[160:161], v[218:219]
	v_or_b32_e32 v96, 32, v178
	v_pk_fma_f32 v[106:107], v[118:119], v[156:157], v[230:231]
	v_pk_fma_f32 v[104:105], v[116:117], v[158:159], v[228:229]
	v_ashrrev_i32_e32 v97, 31, v96
	v_pk_fma_f32 v[120:121], v[120:121], v[162:163], v[216:217]
	global_store_dwordx4 v[108:109], v[104:107], off sc1
	v_pk_fma_f32 v[102:103], v[102:103], v[164:165], v[238:239]
	v_pk_fma_f32 v[100:101], v[100:101], v[166:167], v[236:237]
	v_pk_fma_f32 v[106:107], v[114:115], v[160:161], v[234:235]
	v_pk_fma_f32 v[104:105], v[112:113], v[162:163], v[232:233]
	v_lshlrev_b64 v[204:205], 12, v[96:97]
	v_or_b32_e32 v112, 48, v178
	global_store_dwordx4 v[206:207], v[124:127], off sc1
	global_store_dwordx4 v[206:207], v[120:123], off offset:64 sc1
	global_store_dwordx4 v[108:109], v[104:107], off offset:64 sc1
	global_store_dwordx4 v[108:109], v[100:103], off offset:512 sc1
	v_lshl_add_u64 v[108:109], v[174:175], 0, v[204:205]
	v_ashrrev_i32_e32 v113, 31, v112
	global_load_dwordx4 v[96:99], v[108:109], off
	global_load_dwordx4 v[100:103], v[108:109], off offset:64
	global_load_dwordx4 v[104:107], v[108:109], off offset:512
	s_nop 0
	global_load_dwordx4 v[108:111], v[108:109], off offset:576
	v_lshlrev_b64 v[178:179], 12, v[112:113]
	v_lshl_add_u64 v[124:125], v[174:175], 0, v[178:179]
	global_load_dwordx4 v[112:115], v[124:125], off
	global_load_dwordx4 v[116:119], v[124:125], off offset:64
	global_load_dwordx4 v[120:123], v[124:125], off offset:512
	s_nop 0
	global_load_dwordx4 v[124:127], v[124:125], off offset:576
	s_waitcnt vmcnt(7)
	v_pk_fma_f32 v[92:93], v[92:93], v[158:159], v[96:97]
	v_lshl_add_u64 v[96:97], s[12:13], 0, v[204:205]
	v_lshl_add_u64 v[96:97], v[96:97], 0, v[172:173]
	s_waitcnt vmcnt(5)
	v_pk_fma_f32 v[78:79], v[78:79], v[164:165], v[106:107]
	v_pk_fma_f32 v[76:77], v[76:77], v[166:167], v[104:105]
	global_store_dwordx4 v[96:97], v[76:79], off offset:512 sc1
	s_waitcnt vmcnt(5)
	v_pk_fma_f32 v[74:75], v[74:75], v[168:169], v[110:111]
	v_pk_fma_f32 v[72:73], v[72:73], v[170:171], v[108:109]
	v_lshl_add_u64 v[76:77], s[12:13], 0, v[178:179]
	v_pk_fma_f32 v[94:95], v[94:95], v[156:157], v[98:99]
	v_pk_fma_f32 v[90:91], v[90:91], v[160:161], v[102:103]
	v_pk_fma_f32 v[88:89], v[88:89], v[162:163], v[100:101]
	global_store_dwordx4 v[96:97], v[72:75], off offset:576 sc1
	v_lshl_add_u64 v[76:77], v[76:77], 0, v[172:173]
	global_store_dwordx4 v[96:97], v[92:95], off sc1
	s_waitcnt vmcnt(6)
	v_pk_fma_f32 v[74:75], v[86:87], v[156:157], v[114:115]
	v_pk_fma_f32 v[72:73], v[84:85], v[158:159], v[112:113]
	global_store_dwordx4 v[96:97], v[88:91], off offset:64 sc1
	global_store_dwordx4 v[76:77], v[72:75], off sc1
	s_waitcnt vmcnt(6)
	v_pk_fma_f32 v[70:71], v[70:71], v[164:165], v[122:123]
	v_pk_fma_f32 v[68:69], v[68:69], v[166:167], v[120:121]
	v_pk_fma_f32 v[74:75], v[82:83], v[160:161], v[118:119]
	v_pk_fma_f32 v[72:73], v[80:81], v[162:163], v[116:117]
	s_waitcnt vmcnt(5)
	v_pk_fma_f32 v[66:67], v[66:67], v[168:169], v[126:127]
	v_pk_fma_f32 v[64:65], v[64:65], v[170:171], v[124:125]
	v_lshl_add_u64 v[96:97], v[176:177], 0, s[20:21]
	global_store_dwordx4 v[76:77], v[72:75], off offset:64 sc1
	global_store_dwordx4 v[76:77], v[68:71], off offset:512 sc1
	global_store_dwordx4 v[76:77], v[64:67], off offset:576 sc1
	v_lshl_add_u64 v[76:77], v[174:175], 0, v[96:97]
	global_load_dwordx4 v[64:67], v[76:77], off
	global_load_dwordx4 v[68:71], v[76:77], off offset:64
	global_load_dwordx4 v[72:75], v[76:77], off offset:512
	s_nop 0
	global_load_dwordx4 v[76:79], v[76:77], off offset:576
	v_lshl_add_u64 v[98:99], v[176:177], 0, s[22:23]
	v_lshl_add_u64 v[92:93], v[174:175], 0, v[98:99]
	global_load_dwordx4 v[80:83], v[92:93], off
	global_load_dwordx4 v[84:87], v[92:93], off offset:64
	global_load_dwordx4 v[88:91], v[92:93], off offset:512
	s_nop 0
	global_load_dwordx4 v[92:95], v[92:93], off offset:576
	s_waitcnt vmcnt(7)
	v_pk_fma_f32 v[60:61], v[60:61], v[158:159], v[64:65]
	v_lshl_add_u64 v[64:65], s[12:13], 0, v[96:97]
	v_lshl_add_u64 v[64:65], v[64:65], 0, v[172:173]
	s_waitcnt vmcnt(5)
	v_pk_fma_f32 v[46:47], v[46:47], v[164:165], v[74:75]
	v_pk_fma_f32 v[44:45], v[44:45], v[166:167], v[72:73]
	global_store_dwordx4 v[64:65], v[44:47], off offset:512 sc1
	s_waitcnt vmcnt(5)
	v_pk_fma_f32 v[42:43], v[42:43], v[168:169], v[78:79]
	v_pk_fma_f32 v[40:41], v[40:41], v[170:171], v[76:77]
	v_lshl_add_u64 v[44:45], s[12:13], 0, v[98:99]
	v_pk_fma_f32 v[62:63], v[62:63], v[156:157], v[66:67]
	v_pk_fma_f32 v[58:59], v[58:59], v[160:161], v[70:71]
	v_pk_fma_f32 v[56:57], v[56:57], v[162:163], v[68:69]
	global_store_dwordx4 v[64:65], v[40:43], off offset:576 sc1
	v_lshl_add_u64 v[44:45], v[44:45], 0, v[172:173]
	global_store_dwordx4 v[64:65], v[60:63], off sc1
	s_waitcnt vmcnt(6)
	v_pk_fma_f32 v[42:43], v[54:55], v[156:157], v[82:83]
	v_pk_fma_f32 v[40:41], v[52:53], v[158:159], v[80:81]
	global_store_dwordx4 v[64:65], v[56:59], off offset:64 sc1
	global_store_dwordx4 v[44:45], v[40:43], off sc1
	s_waitcnt vmcnt(6)
	v_pk_fma_f32 v[38:39], v[38:39], v[164:165], v[90:91]
	v_pk_fma_f32 v[36:37], v[36:37], v[166:167], v[88:89]
	v_pk_fma_f32 v[42:43], v[50:51], v[160:161], v[86:87]
	v_pk_fma_f32 v[40:41], v[48:49], v[162:163], v[84:85]
	s_waitcnt vmcnt(5)
	v_pk_fma_f32 v[34:35], v[34:35], v[168:169], v[94:95]
	v_pk_fma_f32 v[32:33], v[32:33], v[170:171], v[92:93]
	v_lshl_add_u64 v[64:65], v[176:177], 0, s[24:25]
	global_store_dwordx4 v[44:45], v[40:43], off offset:64 sc1
	global_store_dwordx4 v[44:45], v[36:39], off offset:512 sc1
	global_store_dwordx4 v[44:45], v[32:35], off offset:576 sc1
	v_lshl_add_u64 v[44:45], v[174:175], 0, v[64:65]
	global_load_dwordx4 v[32:35], v[44:45], off
	global_load_dwordx4 v[36:39], v[44:45], off offset:64
	global_load_dwordx4 v[40:43], v[44:45], off offset:512
	s_nop 0
	global_load_dwordx4 v[44:47], v[44:45], off offset:576
	v_lshl_add_u64 v[66:67], v[176:177], 0, s[26:27]
	v_lshl_add_u64 v[60:61], v[174:175], 0, v[66:67]
	global_load_dwordx4 v[48:51], v[60:61], off
	global_load_dwordx4 v[52:55], v[60:61], off offset:64
	global_load_dwordx4 v[56:59], v[60:61], off offset:512
	s_nop 0
	global_load_dwordx4 v[60:63], v[60:61], off offset:576
	s_waitcnt vmcnt(7)
	v_pk_fma_f32 v[28:29], v[28:29], v[158:159], v[32:33]
	v_lshl_add_u64 v[32:33], s[12:13], 0, v[64:65]
	v_lshl_add_u64 v[32:33], v[32:33], 0, v[172:173]
	s_waitcnt vmcnt(5)
	v_pk_fma_f32 v[18:19], v[18:19], v[164:165], v[42:43]
	v_pk_fma_f32 v[16:17], v[16:17], v[166:167], v[40:41]
	global_store_dwordx4 v[32:33], v[16:19], off offset:512 sc1
	s_waitcnt vmcnt(5)
	v_pk_fma_f32 v[10:11], v[10:11], v[168:169], v[46:47]
	v_pk_fma_f32 v[8:9], v[8:9], v[170:171], v[44:45]
	v_lshl_add_u64 v[16:17], s[12:13], 0, v[66:67]
	global_store_dwordx4 v[32:33], v[8:11], off offset:576 sc1
	v_lshl_add_u64 v[16:17], v[16:17], 0, v[172:173]
	v_pk_fma_f32 v[30:31], v[30:31], v[156:157], v[34:35]
	s_waitcnt vmcnt(5)
	v_pk_fma_f32 v[10:11], v[22:23], v[156:157], v[50:51]
	v_pk_fma_f32 v[8:9], v[20:21], v[158:159], v[48:49]
	v_pk_fma_f32 v[26:27], v[26:27], v[160:161], v[38:39]
	v_pk_fma_f32 v[24:25], v[24:25], v[162:163], v[36:37]
	global_store_dwordx4 v[16:17], v[8:11], off sc1
	s_waitcnt vmcnt(4)
	v_pk_fma_f32 v[6:7], v[6:7], v[164:165], v[58:59]
	v_pk_fma_f32 v[4:5], v[4:5], v[166:167], v[56:57]
	v_pk_fma_f32 v[10:11], v[14:15], v[160:161], v[54:55]
	v_pk_fma_f32 v[8:9], v[12:13], v[162:163], v[52:53]
	s_waitcnt vmcnt(3)
	v_pk_fma_f32 v[2:3], v[2:3], v[168:169], v[62:63]
	v_pk_fma_f32 v[0:1], v[0:1], v[170:171], v[60:61]
	global_store_dwordx4 v[32:33], v[28:31], off sc1
	global_store_dwordx4 v[32:33], v[24:27], off offset:64 sc1
	global_store_dwordx4 v[16:17], v[8:11], off offset:64 sc1
	global_store_dwordx4 v[16:17], v[4:7], off offset:512 sc1
	global_store_dwordx4 v[16:17], v[0:3], off offset:576 sc1
	s_waitcnt vmcnt(0)
	s_barrier
	s_and_saveexec_b64 s[36:37], s[4:5]
	s_cbranch_execz .LBB0_1498
	s_lshl_b32 s38, s67, 2
	s_ashr_i32 s39, s38, 31
	s_lshl_b64 s[38:39], s[38:39], 2
	s_add_u32 s38, s55, s38
	s_addc_u32 s39, s56, s39
	s_getreg_b32 s40, hwreg(HW_REG_XCC_ID, 0, 4)
	global_load_dwordx4 v[0:3], v129, s[38:39]
	s_and_b32 s38, s40, 15
	s_add_i32 s38, s38, 1
	s_waitcnt vmcnt(0)
	v_cmp_ne_u32_e32 vcc, s38, v2
	s_nop 1
	v_cndmask_b32_e64 v2, 0, 1, vcc
	v_cmp_ne_u32_e32 vcc, s38, v3
	v_lshlrev_b32_e32 v2, 2, v2
	s_nop 0
	v_cndmask_b32_e64 v3, 0, 1, vcc
	v_cmp_ne_u32_e32 vcc, s38, v1
	v_lshlrev_b32_e32 v3, 3, v3
	v_or_b32_e32 v2, v3, v2
	v_cndmask_b32_e64 v1, 0, 1, vcc
	v_cmp_ne_u32_e32 vcc, s38, v0
	v_lshlrev_b32_e32 v1, 1, v1
	s_nop 0
	v_cndmask_b32_e64 v0, 0, 1, vcc
	v_or_b32_e32 v0, v0, v1
	v_and_b32_e32 v0, 3, v0
	v_or_b32_e32 v0, v0, v2
	v_and_b32_e32 v0, 15, v0
	v_cmp_eq_u32_e32 vcc, 0, v0
	s_cbranch_vccnz .LBB0_1487
	buffer_wbl2 sc1
	s_waitcnt vmcnt(0)

.LBB0_1498:
	s_or_b64 exec, exec, s[36:37]
	s_add_i32 s36, s69, 64
	v_mad_i64_i32 v[4:5], s[36:37], s36, v211, v[134:135]
	s_add_i32 s36, s69, 0x48
	s_nop 0
	v_mad_i64_i32 v[8:9], s[36:37], s36, v211, v[134:135]
	s_add_i32 s36, s69, 0x50
	s_nop 0
	v_mad_i64_i32 v[12:13], s[36:37], s36, v211, v[134:135]
	s_add_i32 s36, s69, 0x58
	s_nop 0
	v_mad_i64_i32 v[16:17], s[36:37], s36, v211, v[134:135]
	s_barrier
	global_load_dwordx4 v[0:3], v[132:133], off
	s_add_i32 s36, s69, 0x60
	global_load_dwordx4 v[4:7], v[4:5], off
	s_nop 0
	global_load_dwordx4 v[8:11], v[8:9], off
	v_mad_i64_i32 v[20:21], s[36:37], s36, v211, v[134:135]
	s_add_i32 s36, s69, 0x68
	global_load_dwordx4 v[12:15], v[12:13], off
	s_nop 0
	global_load_dwordx4 v[16:19], v[16:17], off
	v_mad_i64_i32 v[24:25], s[36:37], s36, v211, v[134:135]
	s_add_i32 s36, s69, 0x70
	global_load_dwordx4 v[20:23], v[20:21], off
	s_nop 0
	global_load_dwordx4 v[24:27], v[24:25], off
	v_mad_i64_i32 v[28:29], s[36:37], s36, v211, v[134:135]
	s_addk_i32 s69, 0x78
	global_load_dwordx4 v[28:31], v[28:29], off
	v_mad_i64_i32 v[32:33], s[36:37], s69, v211, v[134:135]
	global_load_dwordx4 v[32:35], v[32:33], off
	s_lshl_b32 s36, s66, 6
	s_ashr_i32 s37, s70, 3
	s_add_i32 s36, s68, s36
	s_and_b32 s37, s37, -8
	s_add_i32 s36, s36, s37
	s_ashr_i32 s37, s36, 31
	s_lshl_b64 s[38:39], s[36:37], 12
	v_lshl_add_u64 v[36:37], v[136:137], 0, s[38:39]
	s_or_b32 s42, s36, 1
	s_ashr_i32 s43, s42, 31
	s_lshl_b64 s[38:39], s[42:43], 12
	v_mov_b64_e32 v[88:89], s[30:31]
	s_or_b32 s40, s36, 2
	s_ashr_i32 s41, s40, 31
	s_lshl_b64 s[68:69], s[40:41], 12
	s_lshl_b64 s[66:67], s[36:37], 11
	s_waitcnt vmcnt(7)
	v_pk_add_f32 v[2:3], v[2:3], v[6:7]
	v_pk_add_f32 v[0:1], v[0:1], v[4:5]
	s_waitcnt vmcnt(6)
	v_pk_add_f32 v[2:3], v[2:3], v[10:11]
	v_pk_add_f32 v[0:1], v[0:1], v[8:9]
	s_waitcnt vmcnt(5)
	v_pk_add_f32 v[2:3], v[2:3], v[14:15]
	v_pk_add_f32 v[0:1], v[0:1], v[12:13]
	s_waitcnt vmcnt(4)
	v_pk_add_f32 v[2:3], v[2:3], v[18:19]
	v_pk_add_f32 v[0:1], v[0:1], v[16:17]
	s_waitcnt vmcnt(3)
	v_pk_add_f32 v[2:3], v[2:3], v[22:23]
	v_pk_add_f32 v[0:1], v[0:1], v[20:21]
	s_waitcnt vmcnt(2)
	v_pk_add_f32 v[2:3], v[2:3], v[26:27]
	v_pk_add_f32 v[0:1], v[0:1], v[24:25]
	v_lshl_add_u64 v[8:9], v[136:137], 0, s[38:39]
	s_waitcnt vmcnt(1)
	v_pk_add_f32 v[2:3], v[2:3], v[30:31]
	v_pk_add_f32 v[0:1], v[0:1], v[28:29]
	s_or_b32 s38, s36, 3
	s_waitcnt vmcnt(0)
	v_pk_add_f32 v[2:3], v[2:3], v[34:35]
	v_pk_add_f32 v[0:1], v[0:1], v[32:33]
	v_pk_add_f32 v[4:5], v[2:3], 1.0 op_sel_hi:[1,0]
	v_pk_add_f32 v[6:7], v[0:1], 1.0 op_sel_hi:[1,0]
	v_cndmask_b32_e64 v3, v5, v3, s[6:7]
	v_cndmask_b32_e64 v2, v4, v2, s[6:7]
	v_cndmask_b32_e64 v1, v7, v1, s[6:7]
	v_cndmask_b32_e64 v0, v6, v0, s[6:7]
	ds_write_b128 v183, v[0:3]
	s_waitcnt lgkmcnt(0)
	s_barrier
	global_load_dwordx4 v[108:111], v[138:139], off
	global_load_dwordx4 v[112:115], v[142:143], off
	global_load_dwordx4 v[116:119], v[144:145], off
	global_load_dwordx4 v[120:123], v[146:147], off
	global_load_dwordx4 v[16:19], v[36:37], off
	global_load_dwordx4 v[4:7], v[36:37], off offset:1024
	global_load_dwordx4 v[80:83], v[36:37], off offset:3072
	global_load_dwordx4 v[0:3], v[36:37], off offset:2048
	global_load_dwordx4 v[76:79], v[8:9], off
	global_load_dwordx4 v[68:71], v[8:9], off offset:1024
	s_nop 0
	global_load_dwordx4 v[36:39], v[8:9], off offset:3072
	global_load_dwordx4 v[64:67], v[8:9], off offset:2048
	s_ashr_i32 s39, s38, 31
	s_lshl_b64 s[70:71], s[38:39], 12
	s_waitcnt vmcnt(3)
	v_pk_mul_f32 v[28:29], v[78:79], v[78:79]
	v_pk_mul_f32 v[8:9], v[18:19], v[18:19]
	v_pk_mul_f32 v[10:11], v[16:17], v[16:17]
	v_pk_mul_f32 v[12:13], v[6:7], v[6:7]
	v_pk_mul_f32 v[14:15], v[4:5], v[4:5]
	v_mul_f32_e32 v24, v1, v1
	v_mul_f32_e32 v26, v3, v3
	v_pk_mul_f32 v[30:31], v[76:77], v[76:77]
	s_waitcnt vmcnt(2)
	v_pk_mul_f32 v[32:33], v[70:71], v[70:71]
	v_pk_mul_f32 v[34:35], v[68:69], v[68:69]
	v_mul_f32_e32 v47, v82, v82
	v_mul_f32_e32 v48, v83, v83
	v_pk_mov_b32 v[44:45], v[10:11], v[8:9] op_sel:[1, 0]
	v_mov_b32_e32 v11, v9
	v_pk_mov_b32 v[8:9], v[14:15], v[12:13] op_sel:[1, 0]
	v_mov_b32_e32 v15, v13
	v_pk_fma_f32 v[12:13], v[0:1], v[0:1], v[24:25] op_sel_hi:[1, 1, 0]
	v_pk_fma_f32 v[24:25], v[2:3], v[2:3], v[26:27] op_sel_hi:[1, 1, 0]
	v_pk_mov_b32 v[26:27], v[30:31], v[28:29] op_sel:[1, 0]
	v_mov_b32_e32 v31, v29
	v_pk_mov_b32 v[28:29], v[34:35], v[32:33] op_sel:[1, 0]
	v_mov_b32_e32 v35, v33
	v_mul_f32_e32 v43, v80, v80
	s_waitcnt vmcnt(0)
	v_mul_f32_e32 v40, v65, v65
	v_mul_f32_e32 v42, v67, v67
	v_pk_add_f32 v[10:11], v[44:45], v[10:11]
	v_pk_add_f32 v[8:9], v[8:9], v[14:15]
	v_mov_b32_e32 v13, v47
	v_mov_b32_e32 v25, v48
	v_pk_add_f32 v[14:15], v[26:27], v[30:31]
	v_pk_add_f32 v[26:27], v[28:29], v[34:35]
	v_mul_f32_e32 v46, v81, v81
	v_mul_f32_e32 v49, v36, v36
	v_mul_f32_e32 v50, v37, v37
	v_mul_f32_e32 v51, v38, v38
	v_mul_f32_e32 v52, v39, v39
	v_pk_fma_f32 v[32:33], v[64:65], v[64:65], v[40:41] op_sel_hi:[1, 1, 0]
	v_pk_fma_f32 v[40:41], v[66:67], v[66:67], v[42:43] op_sel_hi:[1, 1, 0]
	v_pk_add_f32 v[10:11], v[10:11], v[10:11] op_sel:[0, 1] op_sel_hi:[1, 0]
	v_pk_add_f32 v[8:9], v[8:9], v[8:9] op_sel:[0, 1] op_sel_hi:[1, 0]
	v_pk_add_f32 v[12:13], v[12:13], v[24:25]
	v_pk_add_f32 v[14:15], v[14:15], v[14:15] op_sel:[0, 1] op_sel_hi:[1, 0]
	v_pk_add_f32 v[24:25], v[26:27], v[26:27] op_sel:[0, 1] op_sel_hi:[1, 0]
	v_mov_b32_e32 v33, v51
	v_mov_b32_e32 v41, v52
	v_mov_b32_e32 v11, v43
	v_mov_b32_e32 v9, v46
	v_mov_b32_e32 v15, v49
	v_mov_b32_e32 v25, v50
	v_pk_add_f32 v[26:27], v[32:33], v[40:41]
	v_pk_add_f32 v[8:9], v[10:11], v[8:9]
	v_pk_add_f32 v[10:11], v[14:15], v[24:25]
	v_pk_add_f32 v[8:9], v[8:9], v[12:13]
	v_pk_add_f32 v[10:11], v[10:11], v[26:27]
	v_mov_b32_e32 v13, v8
	v_mov_b32_e32 v12, v10
	v_mov_b32_e32 v8, v11
	v_pk_add_f32 v[8:9], v[12:13], v[8:9]
	v_lshl_add_u64 v[12:13], v[136:137], 0, s[68:69]
	v_lshl_add_u64 v[14:15], v[136:137], 0, s[70:71]
	global_load_dwordx4 v[72:75], v[12:13], off
	global_load_dwordx4 v[60:63], v[12:13], off offset:1024
	global_load_dwordx4 v[56:59], v[12:13], off offset:2048
	global_load_dwordx4 v[52:55], v[12:13], off offset:3072
	global_load_dwordx4 v[48:51], v[14:15], off
	global_load_dwordx4 v[44:47], v[14:15], off offset:1024
	s_waitcnt lgkmcnt(0)
	s_nop 1
	v_add_f32_dpp v8, v8, v8 quad_perm:[1,0,3,2] row_mask:0xf bank_mask:0xf
	v_add_f32_dpp v9, v9, v9 quad_perm:[1,0,3,2] row_mask:0xf bank_mask:0xf
	global_load_dwordx4 v[40:43], v[14:15], off offset:2048
	global_load_dwordx4 v[32:35], v[14:15], off offset:3072
	v_lshl_add_u64 v[24:25], v[140:141], 0, s[66:67]
	s_add_u32 s66, s10, s66
	s_addc_u32 s67, s11, s67
	s_waitcnt lgkmcnt(0)
	s_nop 1
	v_add_f32_dpp v8, v8, v8 quad_perm:[2,3,0,1] row_mask:0xf bank_mask:0xf
	v_add_f32_dpp v9, v9, v9 quad_perm:[2,3,0,1] row_mask:0xf bank_mask:0xf
	s_lshl_b64 s[42:43], s[42:43], 11
	s_waitcnt lgkmcnt(0)
	s_nop 1
	v_add_f32_dpp v8, v8, v8 row_half_mirror row_mask:0xf bank_mask:0xf
	v_add_f32_dpp v9, v9, v9 row_half_mirror row_mask:0xf bank_mask:0xf
	s_waitcnt lgkmcnt(0)
	s_nop 1
	v_add_f32_dpp v8, v8, v8 row_mirror row_mask:0xf bank_mask:0xf
	v_add_f32_dpp v9, v9, v9 row_mirror row_mask:0xf bank_mask:0xf
	ds_bpermute_b32 v11, v188, v9
	ds_bpermute_b32 v10, v188, v8
	s_waitcnt lgkmcnt(0)
	v_pk_add_f32 v[8:9], v[8:9], v[10:11]
	s_waitcnt lgkmcnt(0)
	v_mov_b32_e32 v10, v8
	v_mov_b32_e32 v11, v9
	s_nop 1
	v_permlane32_swap_b32_e32 v10, v8
	v_permlane32_swap_b32_e32 v11, v9
	v_pk_add_f32 v[8:9], v[8:9], v[10:11]
	s_nop 0
	v_pk_fma_f32 v[90:91], v[8:9], s[28:29], v[88:89] op_sel_hi:[1, 0, 0]
	s_waitcnt vmcnt(4)
	v_mul_f32_e32 v99, v53, v53
	v_mul_f32_e32 v8, 0x4b800000, v91
	v_cmp_gt_f32_e32 vcc, s63, v91
	s_waitcnt vmcnt(2)
	v_pk_mul_f32 v[94:95], v[44:45], v[44:45]
	v_mul_f32_e32 v102, v54, v54
	v_cndmask_b32_e32 v8, v91, v8, vcc
	v_rsq_f32_e32 v26, v8
	ds_read_b128 v[8:11], v190
	ds_read_b128 v[12:15], v191
	s_waitcnt vmcnt(1)
	v_mul_f32_e32 v96, v41, v41
	v_mul_f32_e32 v98, v43, v43
	v_mul_f32_e32 v27, 0x45800000, v26
	v_cndmask_b32_e32 v92, v26, v27, vcc
	v_pk_mul_f32 v[18:19], v[18:19], v[92:93] op_sel_hi:[1, 0]
	v_pk_mul_f32 v[16:17], v[16:17], v[92:93] op_sel_hi:[1, 0]
	v_pk_mul_f32 v[18:19], v[110:111], v[18:19]
	v_pk_mul_f32 v[16:17], v[108:109], v[16:17]
	s_waitcnt lgkmcnt(0)
	v_pk_fma_f32 v[18:19], v[14:15], v[18:19], v[10:11]
	v_pk_fma_f32 v[16:17], v[12:13], v[16:17], v[8:9]
	v_pk_mul_f32 v[6:7], v[6:7], v[92:93] op_sel_hi:[1, 0]
	v_cvt_pk_bf16_f32 v16, v16, v17
	v_cvt_pk_bf16_f32 v17, v18, v19
	global_store_dwordx2 v[24:25], v[16:17], off sc1
	ds_read_b128 v[16:19], v192
	ds_read_b128 v[20:23], v193
	v_pk_mul_f32 v[4:5], v[4:5], v[92:93] op_sel_hi:[1, 0]
	v_pk_mul_f32 v[2:3], v[2:3], v[92:93] op_sel_hi:[1, 0]
	v_pk_mul_f32 v[0:1], v[0:1], v[92:93] op_sel_hi:[1, 0]
	v_pk_mul_f32 v[82:83], v[82:83], v[92:93] op_sel_hi:[1, 0]
	v_pk_mul_f32 v[80:81], v[80:81], v[92:93] op_sel_hi:[1, 0]
	v_cmp_gt_f32_e32 vcc, s63, v90
	v_pk_mul_f32 v[92:93], v[46:47], v[46:47]
	v_mul_f32_e32 v103, v55, v55
	s_waitcnt vmcnt(1)
	v_mul_f32_e32 v104, v32, v32
	v_mul_f32_e32 v105, v33, v33
	v_mul_f32_e32 v106, v34, v34
	v_mul_f32_e32 v107, v35, v35
	v_pk_mul_f32 v[4:5], v[112:113], v[4:5]
	v_pk_mul_f32 v[6:7], v[114:115], v[6:7]
	s_waitcnt lgkmcnt(0)
	v_pk_fma_f32 v[4:5], v[20:21], v[4:5], v[16:17]
	v_pk_fma_f32 v[6:7], v[22:23], v[6:7], v[18:19]
	v_cvt_pk_bf16_f32 v4, v4, v5
	v_cvt_pk_bf16_f32 v5, v6, v7
	global_store_dwordx2 v200, v[4:5], s[66:67] sc1
	ds_read_b128 v[24:27], v194
	ds_read_b128 v[28:31], v195
	v_pk_mul_f32 v[0:1], v[116:117], v[0:1]
	v_pk_mul_f32 v[2:3], v[118:119], v[2:3]
	s_waitcnt lgkmcnt(0)
	v_pk_fma_f32 v[0:1], v[28:29], v[0:1], v[24:25]
	v_pk_fma_f32 v[2:3], v[30:31], v[2:3], v[26:27]
	v_cvt_pk_bf16_f32 v0, v0, v1
	v_cvt_pk_bf16_f32 v1, v2, v3
	global_store_dwordx2 v201, v[0:1], s[66:67] sc1
	ds_read_b128 v[0:3], v196
	ds_read_b128 v[4:7], v197
	v_pk_mul_f32 v[80:81], v[80:81], v[120:121]
	v_pk_mul_f32 v[82:83], v[82:83], v[122:123]
	s_waitcnt lgkmcnt(0)
	v_pk_fma_f32 v[80:81], v[80:81], v[4:5], v[0:1]
	v_pk_fma_f32 v[82:83], v[82:83], v[6:7], v[2:3]
	v_cvt_pk_bf16_f32 v80, v80, v81
	v_cvt_pk_bf16_f32 v81, v82, v83
	global_store_dwordx2 v210, v[80:81], s[66:67] sc1
	v_mul_f32_e32 v84, 0x4b800000, v90
	v_cndmask_b32_e32 v84, v90, v84, vcc
	v_rsq_f32_e32 v86, v84
	v_lshl_add_u64 v[84:85], v[140:141], 0, s[42:43]
	s_add_u32 s42, s10, s42
	s_addc_u32 s43, s11, s43
	v_mul_f32_e32 v87, 0x45800000, v86
	v_cndmask_b32_e32 v86, v86, v87, vcc
	v_pk_mul_f32 v[78:79], v[78:79], v[86:87] op_sel_hi:[1, 0]
	v_pk_mul_f32 v[76:77], v[76:77], v[86:87] op_sel_hi:[1, 0]
	v_pk_mul_f32 v[70:71], v[70:71], v[86:87] op_sel_hi:[1, 0]
	v_pk_mul_f32 v[68:69], v[68:69], v[86:87] op_sel_hi:[1, 0]
	v_pk_mul_f32 v[66:67], v[66:67], v[86:87] op_sel_hi:[1, 0]
	v_pk_mul_f32 v[64:65], v[64:65], v[86:87] op_sel_hi:[1, 0]
	v_mul_f32_e32 v87, v52, v52
	v_pk_mul_f32 v[38:39], v[38:39], v[86:87] op_sel_hi:[1, 0]
	v_pk_mul_f32 v[36:37], v[36:37], v[86:87] op_sel_hi:[1, 0]
	v_pk_mul_f32 v[90:91], v[48:49], v[48:49]
	s_lshl_b64 s[40:41], s[40:41], 11
	v_pk_mul_f32 v[76:77], v[108:109], v[76:77]
	v_pk_mul_f32 v[78:79], v[110:111], v[78:79]
	v_pk_fma_f32 v[76:77], v[12:13], v[76:77], v[8:9]
	v_pk_fma_f32 v[78:79], v[14:15], v[78:79], v[10:11]
	v_cvt_pk_bf16_f32 v76, v76, v77
	v_cvt_pk_bf16_f32 v77, v78, v79
	global_store_dwordx2 v[84:85], v[76:77], off sc1
	v_mul_f32_e32 v80, v57, v57
	v_mul_f32_e32 v82, v59, v59
	v_pk_mul_f32 v[84:85], v[50:51], v[50:51]
	v_pk_mul_f32 v[68:69], v[112:113], v[68:69]
	v_pk_mul_f32 v[70:71], v[114:115], v[70:71]
	v_pk_fma_f32 v[68:69], v[20:21], v[68:69], v[16:17]
	v_pk_fma_f32 v[70:71], v[22:23], v[70:71], v[18:19]
	v_cvt_pk_bf16_f32 v68, v68, v69
	v_cvt_pk_bf16_f32 v69, v70, v71
	global_store_dwordx2 v200, v[68:69], s[42:43] sc1
	v_pk_mul_f32 v[76:77], v[62:63], v[62:63]
	v_pk_mul_f32 v[78:79], v[60:61], v[60:61]
	v_pk_mul_f32 v[64:65], v[116:117], v[64:65]
	v_pk_mul_f32 v[66:67], v[118:119], v[66:67]
	v_pk_fma_f32 v[64:65], v[28:29], v[64:65], v[24:25]
	v_pk_fma_f32 v[66:67], v[30:31], v[66:67], v[26:27]
	v_cvt_pk_bf16_f32 v64, v64, v65
	v_cvt_pk_bf16_f32 v65, v66, v67
	global_store_dwordx2 v201, v[64:65], s[42:43] sc1
	v_pk_mul_f32 v[68:69], v[74:75], v[74:75]
	v_pk_mul_f32 v[70:71], v[72:73], v[72:73]
	v_pk_mul_f32 v[36:37], v[120:121], v[36:37]
	v_pk_mul_f32 v[38:39], v[122:123], v[38:39]
	v_pk_fma_f32 v[36:37], v[4:5], v[36:37], v[0:1]
	v_pk_fma_f32 v[38:39], v[6:7], v[38:39], v[2:3]
	v_cvt_pk_bf16_f32 v36, v36, v37
	v_cvt_pk_bf16_f32 v37, v38, v39
	global_store_dwordx2 v210, v[36:37], s[42:43] sc1
	v_pk_mov_b32 v[100:101], v[70:71], v[68:69] op_sel:[1, 0]
	v_mov_b32_e32 v71, v69
	v_pk_mov_b32 v[68:69], v[78:79], v[76:77] op_sel:[1, 0]
	v_mov_b32_e32 v79, v77
	v_pk_fma_f32 v[76:77], v[56:57], v[56:57], v[80:81] op_sel_hi:[1, 1, 0]
	v_pk_fma_f32 v[80:81], v[58:59], v[58:59], v[82:83] op_sel_hi:[1, 1, 0]
	v_pk_mov_b32 v[82:83], v[90:91], v[84:85] op_sel:[1, 0]
	v_mov_b32_e32 v91, v85
	v_pk_mov_b32 v[84:85], v[94:95], v[92:93] op_sel:[1, 0]
	v_mov_b32_e32 v95, v93
	v_pk_add_f32 v[70:71], v[100:101], v[70:71]
	v_pk_add_f32 v[64:65], v[68:69], v[78:79]
	v_pk_add_f32 v[66:67], v[82:83], v[90:91]
	v_pk_add_f32 v[68:69], v[84:85], v[94:95]
	v_pk_fma_f32 v[92:93], v[40:41], v[40:41], v[96:97] op_sel_hi:[1, 1, 0]
	v_pk_fma_f32 v[96:97], v[42:43], v[42:43], v[98:99] op_sel_hi:[1, 1, 0]
	v_pk_add_f32 v[70:71], v[70:71], v[70:71] op_sel:[0, 1] op_sel_hi:[1, 0]
	v_pk_add_f32 v[64:65], v[64:65], v[64:65] op_sel:[0, 1] op_sel_hi:[1, 0]
	v_pk_add_f32 v[66:67], v[66:67], v[66:67] op_sel:[0, 1] op_sel_hi:[1, 0]
	v_pk_add_f32 v[68:69], v[68:69], v[68:69] op_sel:[0, 1] op_sel_hi:[1, 0]
	v_mov_b32_e32 v77, v102
	v_mov_b32_e32 v81, v103
	v_mov_b32_e32 v93, v106
	v_mov_b32_e32 v97, v107
	v_mov_b32_e32 v71, v87
	v_mov_b32_e32 v65, v99
	v_mov_b32_e32 v67, v104
	v_mov_b32_e32 v69, v105
	v_pk_add_f32 v[76:77], v[76:77], v[80:81]
	v_pk_add_f32 v[78:79], v[92:93], v[96:97]
	v_pk_add_f32 v[64:65], v[70:71], v[64:65]
	v_pk_add_f32 v[66:67], v[66:67], v[68:69]
	v_pk_add_f32 v[64:65], v[64:65], v[76:77]
	v_pk_add_f32 v[66:67], v[66:67], v[78:79]
	v_mov_b32_e32 v69, v64
	v_mov_b32_e32 v68, v66
	v_mov_b32_e32 v64, v67
	v_pk_add_f32 v[64:65], v[68:69], v[64:65]
	s_waitcnt lgkmcnt(0)
	s_nop 1
	v_add_f32_dpp v64, v64, v64 quad_perm:[1,0,3,2] row_mask:0xf bank_mask:0xf
	v_add_f32_dpp v65, v65, v65 quad_perm:[1,0,3,2] row_mask:0xf bank_mask:0xf
	s_waitcnt lgkmcnt(0)
	s_nop 1
	v_add_f32_dpp v64, v64, v64 quad_perm:[2,3,0,1] row_mask:0xf bank_mask:0xf
	v_add_f32_dpp v65, v65, v65 quad_perm:[2,3,0,1] row_mask:0xf bank_mask:0xf
	s_waitcnt lgkmcnt(0)
	s_nop 1
	v_add_f32_dpp v64, v64, v64 row_half_mirror row_mask:0xf bank_mask:0xf
	v_add_f32_dpp v65, v65, v65 row_half_mirror row_mask:0xf bank_mask:0xf
	s_waitcnt lgkmcnt(0)
	s_nop 1
	v_add_f32_dpp v64, v64, v64 row_mirror row_mask:0xf bank_mask:0xf
	v_add_f32_dpp v65, v65, v65 row_mirror row_mask:0xf bank_mask:0xf
	ds_bpermute_b32 v67, v188, v65
	ds_bpermute_b32 v66, v188, v64
	s_waitcnt lgkmcnt(0)
	v_pk_add_f32 v[64:65], v[64:65], v[66:67]
	s_waitcnt lgkmcnt(0)
	v_mov_b32_e32 v66, v64
	v_mov_b32_e32 v67, v65
	s_nop 1
	v_permlane32_swap_b32_e32 v66, v64
	v_permlane32_swap_b32_e32 v67, v65
	v_pk_add_f32 v[64:65], v[64:65], v[66:67]
	s_nop 0
	v_pk_fma_f32 v[64:65], v[64:65], s[28:29], v[88:89] op_sel_hi:[1, 0, 0]
	s_nop 0
	v_mul_f32_e32 v66, 0x4b800000, v65
	v_cmp_gt_f32_e32 vcc, s63, v65
	s_nop 1
	v_cndmask_b32_e32 v65, v65, v66, vcc
	v_rsq_f32_e32 v65, v65
	v_lshl_add_u64 v[66:67], v[140:141], 0, s[40:41]
	s_add_u32 s40, s10, s40
	s_addc_u32 s41, s11, s41
	v_mul_f32_e32 v68, 0x45800000, v65
	v_cndmask_b32_e32 v68, v65, v68, vcc
	v_pk_mul_f32 v[70:71], v[74:75], v[68:69] op_sel_hi:[1, 0]
	v_pk_mul_f32 v[72:73], v[72:73], v[68:69] op_sel_hi:[1, 0]
	v_pk_mul_f32 v[38:39], v[110:111], v[70:71]
	v_pk_mul_f32 v[36:37], v[108:109], v[72:73]
	v_pk_fma_f32 v[38:39], v[14:15], v[38:39], v[10:11]
	v_pk_fma_f32 v[36:37], v[12:13], v[36:37], v[8:9]
	v_pk_mul_f32 v[62:63], v[62:63], v[68:69] op_sel_hi:[1, 0]
	v_cvt_pk_bf16_f32 v36, v36, v37
	v_cvt_pk_bf16_f32 v37, v38, v39
	global_store_dwordx2 v[66:67], v[36:37], off sc1
	v_pk_mul_f32 v[60:61], v[60:61], v[68:69] op_sel_hi:[1, 0]
	v_pk_mul_f32 v[58:59], v[58:59], v[68:69] op_sel_hi:[1, 0]
	v_pk_mul_f32 v[56:57], v[56:57], v[68:69] op_sel_hi:[1, 0]
	v_pk_mul_f32 v[54:55], v[54:55], v[68:69] op_sel_hi:[1, 0]
	v_pk_mul_f32 v[52:53], v[52:53], v[68:69] op_sel_hi:[1, 0]
	v_cmp_gt_f32_e32 vcc, s63, v64
	s_lshl_b64 s[38:39], s[38:39], 11
	v_pk_mul_f32 v[36:37], v[112:113], v[60:61]
	v_pk_mul_f32 v[38:39], v[114:115], v[62:63]
	v_pk_fma_f32 v[36:37], v[20:21], v[36:37], v[16:17]
	v_pk_fma_f32 v[38:39], v[22:23], v[38:39], v[18:19]
	v_cvt_pk_bf16_f32 v36, v36, v37
	v_cvt_pk_bf16_f32 v37, v38, v39
	global_store_dwordx2 v200, v[36:37], s[40:41] sc1
	v_pk_mul_f32 v[36:37], v[116:117], v[56:57]
	v_pk_mul_f32 v[38:39], v[118:119], v[58:59]
	v_pk_fma_f32 v[36:37], v[28:29], v[36:37], v[24:25]
	v_pk_fma_f32 v[38:39], v[30:31], v[38:39], v[26:27]
	v_cvt_pk_bf16_f32 v36, v36, v37
	v_cvt_pk_bf16_f32 v37, v38, v39
	global_store_dwordx2 v201, v[36:37], s[40:41] sc1
	v_pk_mul_f32 v[36:37], v[120:121], v[52:53]
	v_pk_mul_f32 v[38:39], v[122:123], v[54:55]
	v_pk_fma_f32 v[36:37], v[4:5], v[36:37], v[0:1]
	v_pk_fma_f32 v[38:39], v[6:7], v[38:39], v[2:3]
	v_cvt_pk_bf16_f32 v36, v36, v37
	v_cvt_pk_bf16_f32 v37, v38, v39
	global_store_dwordx2 v210, v[36:37], s[40:41] sc1
	v_mul_f32_e32 v52, 0x4b800000, v64
	v_cndmask_b32_e32 v52, v64, v52, vcc
	v_rsq_f32_e32 v54, v52
	v_lshl_add_u64 v[52:53], v[140:141], 0, s[38:39]
	s_add_u32 s38, s10, s38
	s_addc_u32 s39, s11, s39
	v_mul_f32_e32 v55, 0x45800000, v54
	v_cndmask_b32_e32 v54, v54, v55, vcc
	v_pk_mul_f32 v[50:51], v[50:51], v[54:55] op_sel_hi:[1, 0]
	v_pk_mul_f32 v[48:49], v[48:49], v[54:55] op_sel_hi:[1, 0]
	v_pk_mul_f32 v[46:47], v[46:47], v[54:55] op_sel_hi:[1, 0]
	v_pk_mul_f32 v[44:45], v[44:45], v[54:55] op_sel_hi:[1, 0]
	v_pk_mul_f32 v[42:43], v[42:43], v[54:55] op_sel_hi:[1, 0]
	v_pk_mul_f32 v[40:41], v[40:41], v[54:55] op_sel_hi:[1, 0]
	v_pk_mul_f32 v[34:35], v[34:35], v[54:55] op_sel_hi:[1, 0]
	v_pk_mul_f32 v[32:33], v[32:33], v[54:55] op_sel_hi:[1, 0]
	s_or_b32 s42, s36, 4
	s_ashr_i32 s43, s42, 31
	s_lshl_b64 s[40:41], s[42:43], 12
	s_lshl_b64 s[42:43], s[42:43], 11
	v_lshl_add_u64 v[104:105], v[140:141], 0, s[42:43]
	v_pk_mul_f32 v[36:37], v[108:109], v[48:49]
	v_pk_mul_f32 v[38:39], v[110:111], v[50:51]
	v_pk_fma_f32 v[36:37], v[12:13], v[36:37], v[8:9]
	v_pk_fma_f32 v[38:39], v[14:15], v[38:39], v[10:11]
	v_cvt_pk_bf16_f32 v36, v36, v37
	v_cvt_pk_bf16_f32 v37, v38, v39
	global_store_dwordx2 v[52:53], v[36:37], off sc1
	v_pk_mul_f32 v[36:37], v[112:113], v[44:45]
	v_pk_mul_f32 v[38:39], v[114:115], v[46:47]
	v_pk_fma_f32 v[36:37], v[20:21], v[36:37], v[16:17]
	v_pk_fma_f32 v[38:39], v[22:23], v[38:39], v[18:19]
	v_cvt_pk_bf16_f32 v36, v36, v37
	v_cvt_pk_bf16_f32 v37, v38, v39
	global_store_dwordx2 v200, v[36:37], s[38:39] sc1
	v_pk_mul_f32 v[36:37], v[116:117], v[40:41]
	v_pk_mul_f32 v[38:39], v[118:119], v[42:43]
	v_pk_fma_f32 v[36:37], v[28:29], v[36:37], v[24:25]
	v_pk_fma_f32 v[38:39], v[30:31], v[38:39], v[26:27]
	v_cvt_pk_bf16_f32 v36, v36, v37
	v_cvt_pk_bf16_f32 v37, v38, v39
	global_store_dwordx2 v201, v[36:37], s[38:39] sc1
	v_lshl_add_u64 v[40:41], v[136:137], 0, s[40:41]
	s_or_b32 s40, s36, 5
	s_ashr_i32 s41, s40, 31
	v_pk_mul_f32 v[32:33], v[120:121], v[32:33]
	v_pk_mul_f32 v[34:35], v[122:123], v[34:35]
	v_pk_fma_f32 v[32:33], v[4:5], v[32:33], v[0:1]
	v_pk_fma_f32 v[34:35], v[6:7], v[34:35], v[2:3]
	v_cvt_pk_bf16_f32 v32, v32, v33
	v_cvt_pk_bf16_f32 v33, v34, v35
	global_store_dwordx2 v210, v[32:33], s[38:39] sc1
	global_load_dwordx4 v[90:93], v[40:41], off
	global_load_dwordx4 v[94:97], v[40:41], off offset:1024
	global_load_dwordx4 v[80:83], v[40:41], off offset:3072
	global_load_dwordx4 v[84:87], v[40:41], off offset:2048
	s_lshl_b64 s[38:39], s[40:41], 12
	v_lshl_add_u64 v[32:33], v[136:137], 0, s[38:39]
	global_load_dwordx4 v[76:79], v[32:33], off
	global_load_dwordx4 v[72:75], v[32:33], off offset:1024
	global_load_dwordx4 v[36:39], v[32:33], off offset:3072
	global_load_dwordx4 v[68:71], v[32:33], off offset:2048
	s_or_b32 s38, s36, 6
	s_or_b32 s36, s36, 7
	s_ashr_i32 s39, s38, 31
	s_ashr_i32 s37, s36, 31
	s_lshl_b64 s[66:67], s[38:39], 12
	s_lshl_b64 s[68:69], s[36:37], 12
	s_add_u32 s42, s10, s42
	s_addc_u32 s43, s11, s43
	s_lshl_b64 s[40:41], s[40:41], 11
	s_waitcnt vmcnt(7)
	v_pk_mul_f32 v[32:33], v[92:93], v[92:93]
	v_pk_mul_f32 v[34:35], v[90:91], v[90:91]
	s_waitcnt vmcnt(6)
	v_pk_mul_f32 v[40:41], v[96:97], v[96:97]
	v_pk_mul_f32 v[42:43], v[94:95], v[94:95]
	s_waitcnt vmcnt(4)
	v_mul_f32_e32 v44, v85, v85
	v_mul_f32_e32 v46, v87, v87
	s_waitcnt vmcnt(3)
	v_pk_mul_f32 v[48:49], v[78:79], v[78:79]
	v_pk_mul_f32 v[50:51], v[76:77], v[76:77]
	s_waitcnt vmcnt(2)
	v_pk_mul_f32 v[52:53], v[74:75], v[74:75]
	v_pk_mul_f32 v[54:55], v[72:73], v[72:73]
	v_mul_f32_e32 v63, v82, v82
	v_mul_f32_e32 v64, v83, v83
	v_pk_mov_b32 v[60:61], v[34:35], v[32:33] op_sel:[1, 0]
	v_mov_b32_e32 v35, v33
	v_pk_mov_b32 v[32:33], v[42:43], v[40:41] op_sel:[1, 0]
	v_mov_b32_e32 v43, v41
	v_pk_fma_f32 v[40:41], v[84:85], v[84:85], v[44:45] op_sel_hi:[1, 1, 0]
	v_pk_fma_f32 v[44:45], v[86:87], v[86:87], v[46:47] op_sel_hi:[1, 1, 0]
	v_pk_mov_b32 v[46:47], v[50:51], v[48:49] op_sel:[1, 0]
	v_mov_b32_e32 v51, v49
	v_pk_mov_b32 v[48:49], v[54:55], v[52:53] op_sel:[1, 0]
	v_mov_b32_e32 v55, v53
	v_mul_f32_e32 v59, v80, v80
	s_waitcnt vmcnt(0)
	v_mul_f32_e32 v56, v69, v69
	v_mul_f32_e32 v58, v71, v71
	v_pk_add_f32 v[34:35], v[60:61], v[34:35]
	v_pk_add_f32 v[32:33], v[32:33], v[42:43]
	v_mov_b32_e32 v41, v63
	v_mov_b32_e32 v45, v64
	v_pk_add_f32 v[42:43], v[46:47], v[50:51]
	v_pk_add_f32 v[46:47], v[48:49], v[54:55]
	v_mul_f32_e32 v62, v81, v81
	v_mul_f32_e32 v65, v36, v36
	v_mul_f32_e32 v66, v37, v37
	v_mul_f32_e32 v67, v38, v38
	v_mul_f32_e32 v102, v39, v39
	v_pk_fma_f32 v[52:53], v[68:69], v[68:69], v[56:57] op_sel_hi:[1, 1, 0]
	v_pk_fma_f32 v[56:57], v[70:71], v[70:71], v[58:59] op_sel_hi:[1, 1, 0]
	v_pk_add_f32 v[34:35], v[34:35], v[34:35] op_sel:[0, 1] op_sel_hi:[1, 0]
	v_pk_add_f32 v[32:33], v[32:33], v[32:33] op_sel:[0, 1] op_sel_hi:[1, 0]
	v_pk_add_f32 v[40:41], v[40:41], v[44:45]
	v_pk_add_f32 v[42:43], v[42:43], v[42:43] op_sel:[0, 1] op_sel_hi:[1, 0]
	v_pk_add_f32 v[44:45], v[46:47], v[46:47] op_sel:[0, 1] op_sel_hi:[1, 0]
	v_mov_b32_e32 v53, v67
	v_mov_b32_e32 v57, v102
	v_mov_b32_e32 v35, v59
	v_mov_b32_e32 v33, v62
	v_mov_b32_e32 v43, v65
	v_mov_b32_e32 v45, v66
	v_pk_add_f32 v[46:47], v[52:53], v[56:57]
	v_pk_add_f32 v[32:33], v[34:35], v[32:33]
	v_pk_add_f32 v[34:35], v[42:43], v[44:45]
	v_pk_add_f32 v[32:33], v[32:33], v[40:41]
	v_pk_add_f32 v[34:35], v[34:35], v[46:47]
	v_mov_b32_e32 v41, v32
	v_mov_b32_e32 v40, v34
	v_mov_b32_e32 v32, v35
	v_pk_add_f32 v[32:33], v[40:41], v[32:33]
	v_lshl_add_u64 v[40:41], v[136:137], 0, s[66:67]
	v_lshl_add_u64 v[102:103], v[136:137], 0, s[68:69]
	global_load_dwordx4 v[64:67], v[40:41], off
	global_load_dwordx4 v[60:63], v[40:41], off offset:1024
	global_load_dwordx4 v[56:59], v[40:41], off offset:2048
	global_load_dwordx4 v[52:55], v[40:41], off offset:3072
	s_waitcnt lgkmcnt(0)
	s_nop 1
	v_add_f32_dpp v32, v32, v32 quad_perm:[1,0,3,2] row_mask:0xf bank_mask:0xf
	v_add_f32_dpp v33, v33, v33 quad_perm:[1,0,3,2] row_mask:0xf bank_mask:0xf
	s_waitcnt lgkmcnt(0)
	s_nop 1
	v_add_f32_dpp v32, v32, v32 quad_perm:[2,3,0,1] row_mask:0xf bank_mask:0xf
	v_add_f32_dpp v33, v33, v33 quad_perm:[2,3,0,1] row_mask:0xf bank_mask:0xf
	s_waitcnt lgkmcnt(0)
	s_nop 1
	v_add_f32_dpp v32, v32, v32 row_half_mirror row_mask:0xf bank_mask:0xf
	v_add_f32_dpp v33, v33, v33 row_half_mirror row_mask:0xf bank_mask:0xf
	s_waitcnt lgkmcnt(0)
	s_nop 1
	v_add_f32_dpp v32, v32, v32 row_mirror row_mask:0xf bank_mask:0xf
	v_add_f32_dpp v33, v33, v33 row_mirror row_mask:0xf bank_mask:0xf
	ds_bpermute_b32 v35, v188, v33
	ds_bpermute_b32 v34, v188, v32
	s_waitcnt lgkmcnt(0)
	v_pk_add_f32 v[32:33], v[32:33], v[34:35]
	s_waitcnt lgkmcnt(0)
	v_mov_b32_e32 v34, v32
	v_mov_b32_e32 v35, v33
	s_nop 1
	v_permlane32_swap_b32_e32 v34, v32
	v_permlane32_swap_b32_e32 v35, v33
	v_pk_add_f32 v[32:33], v[32:33], v[34:35]
	s_nop 0
	v_pk_fma_f32 v[106:107], v[32:33], s[28:29], v[88:89] op_sel_hi:[1, 0, 0]
	s_nop 0
	v_mul_f32_e32 v32, 0x4b800000, v107
	v_cmp_gt_f32_e32 vcc, s63, v107
	s_nop 1
	v_cndmask_b32_e32 v32, v107, v32, vcc
	v_rsq_f32_e32 v107, v32
	global_load_dwordx4 v[48:51], v[102:103], off
	global_load_dwordx4 v[44:47], v[102:103], off offset:1024
	global_load_dwordx4 v[40:43], v[102:103], off offset:2048
	global_load_dwordx4 v[32:35], v[102:103], off offset:3072
	v_mul_f32_e32 v102, 0x45800000, v107
	v_cndmask_b32_e32 v102, v107, v102, vcc
	v_pk_mul_f32 v[92:93], v[92:93], v[102:103] op_sel_hi:[1, 0]
	v_pk_mul_f32 v[90:91], v[90:91], v[102:103] op_sel_hi:[1, 0]
	v_pk_mul_f32 v[92:93], v[110:111], v[92:93]
	v_pk_mul_f32 v[90:91], v[108:109], v[90:91]
	v_pk_fma_f32 v[92:93], v[14:15], v[92:93], v[10:11]
	v_pk_fma_f32 v[90:91], v[12:13], v[90:91], v[8:9]
	v_pk_mul_f32 v[96:97], v[96:97], v[102:103] op_sel_hi:[1, 0]
	v_cvt_pk_bf16_f32 v90, v90, v91
	v_cvt_pk_bf16_f32 v91, v92, v93
	global_store_dwordx2 v[104:105], v[90:91], off sc1
	v_pk_mul_f32 v[94:95], v[94:95], v[102:103] op_sel_hi:[1, 0]
	v_pk_mul_f32 v[86:87], v[86:87], v[102:103] op_sel_hi:[1, 0]
	v_pk_mul_f32 v[84:85], v[84:85], v[102:103] op_sel_hi:[1, 0]
	v_pk_mul_f32 v[82:83], v[82:83], v[102:103] op_sel_hi:[1, 0]
	v_pk_mul_f32 v[80:81], v[80:81], v[102:103] op_sel_hi:[1, 0]
	v_cmp_gt_f32_e32 vcc, s63, v106
	s_waitcnt vmcnt(5)
	v_mul_f32_e32 v99, v53, v53
	v_mul_f32_e32 v102, v54, v54
	v_mul_f32_e32 v103, v55, v55
	s_waitcnt vmcnt(2)
	v_mul_f32_e32 v98, v43, v43
	s_waitcnt vmcnt(1)
	v_mul_f32_e32 v104, v32, v32
	v_mul_f32_e32 v105, v33, v33
	v_mul_f32_e32 v107, v35, v35
	v_pk_mul_f32 v[90:91], v[112:113], v[94:95]
	v_pk_mul_f32 v[92:93], v[114:115], v[96:97]
	v_pk_fma_f32 v[90:91], v[20:21], v[90:91], v[16:17]
	v_pk_fma_f32 v[92:93], v[22:23], v[92:93], v[18:19]
	v_cvt_pk_bf16_f32 v90, v90, v91
	v_cvt_pk_bf16_f32 v91, v92, v93
	global_store_dwordx2 v200, v[90:91], s[42:43] sc1
	v_pk_mul_f32 v[94:95], v[44:45], v[44:45]
	v_mul_f32_e32 v96, v41, v41
	v_pk_mul_f32 v[84:85], v[116:117], v[84:85]
	v_pk_mul_f32 v[86:87], v[118:119], v[86:87]
	v_pk_fma_f32 v[84:85], v[28:29], v[84:85], v[24:25]
	v_pk_fma_f32 v[86:87], v[30:31], v[86:87], v[26:27]
	v_cvt_pk_bf16_f32 v84, v84, v85
	v_cvt_pk_bf16_f32 v85, v86, v87
	global_store_dwordx2 v201, v[84:85], s[42:43] sc1
	v_pk_mul_f32 v[90:91], v[48:49], v[48:49]
	v_pk_mul_f32 v[92:93], v[46:47], v[46:47]
	v_pk_mul_f32 v[80:81], v[120:121], v[80:81]
	v_pk_mul_f32 v[82:83], v[122:123], v[82:83]
	v_pk_fma_f32 v[80:81], v[4:5], v[80:81], v[0:1]
	v_pk_fma_f32 v[82:83], v[6:7], v[82:83], v[2:3]
	v_cvt_pk_bf16_f32 v80, v80, v81
	v_cvt_pk_bf16_f32 v81, v82, v83
	global_store_dwordx2 v210, v[80:81], s[42:43] sc1
	v_mul_f32_e32 v84, 0x4b800000, v106
	v_cndmask_b32_e32 v84, v106, v84, vcc
	v_rsq_f32_e32 v86, v84
	v_lshl_add_u64 v[84:85], v[140:141], 0, s[40:41]
	s_add_u32 s40, s10, s40
	s_addc_u32 s41, s11, s41
	v_mul_f32_e32 v87, 0x45800000, v86
	v_cndmask_b32_e32 v86, v86, v87, vcc
	v_pk_mul_f32 v[78:79], v[78:79], v[86:87] op_sel_hi:[1, 0]
	v_pk_mul_f32 v[76:77], v[76:77], v[86:87] op_sel_hi:[1, 0]
	v_pk_mul_f32 v[74:75], v[74:75], v[86:87] op_sel_hi:[1, 0]
	v_pk_mul_f32 v[72:73], v[72:73], v[86:87] op_sel_hi:[1, 0]
	v_pk_mul_f32 v[70:71], v[70:71], v[86:87] op_sel_hi:[1, 0]
	v_pk_mul_f32 v[68:69], v[68:69], v[86:87] op_sel_hi:[1, 0]
	v_mul_f32_e32 v87, v52, v52
	v_pk_mul_f32 v[38:39], v[38:39], v[86:87] op_sel_hi:[1, 0]
	v_pk_mul_f32 v[36:37], v[36:37], v[86:87] op_sel_hi:[1, 0]
	v_mul_f32_e32 v106, v34, v34
	s_lshl_b64 s[38:39], s[38:39], 11
	v_pk_mul_f32 v[76:77], v[108:109], v[76:77]
	v_pk_mul_f32 v[78:79], v[110:111], v[78:79]
	v_pk_fma_f32 v[76:77], v[12:13], v[76:77], v[8:9]
	v_pk_fma_f32 v[78:79], v[14:15], v[78:79], v[10:11]
	v_cvt_pk_bf16_f32 v76, v76, v77
	v_cvt_pk_bf16_f32 v77, v78, v79
	global_store_dwordx2 v[84:85], v[76:77], off sc1
	v_mul_f32_e32 v80, v57, v57
	v_mul_f32_e32 v82, v59, v59
	v_pk_mul_f32 v[84:85], v[50:51], v[50:51]
	v_pk_mul_f32 v[72:73], v[112:113], v[72:73]
	v_pk_mul_f32 v[74:75], v[114:115], v[74:75]
	v_pk_fma_f32 v[72:73], v[20:21], v[72:73], v[16:17]
	v_pk_fma_f32 v[74:75], v[22:23], v[74:75], v[18:19]
	v_cvt_pk_bf16_f32 v72, v72, v73
	v_cvt_pk_bf16_f32 v73, v74, v75
	global_store_dwordx2 v200, v[72:73], s[40:41] sc1
	v_pk_mul_f32 v[76:77], v[62:63], v[62:63]
	v_pk_mul_f32 v[78:79], v[60:61], v[60:61]
	v_pk_mul_f32 v[68:69], v[116:117], v[68:69]
	v_pk_mul_f32 v[70:71], v[118:119], v[70:71]
	v_pk_fma_f32 v[68:69], v[28:29], v[68:69], v[24:25]
	v_pk_fma_f32 v[70:71], v[30:31], v[70:71], v[26:27]
	v_cvt_pk_bf16_f32 v68, v68, v69
	v_cvt_pk_bf16_f32 v69, v70, v71
	global_store_dwordx2 v201, v[68:69], s[40:41] sc1
	v_pk_mul_f32 v[72:73], v[66:67], v[66:67]
	v_pk_mul_f32 v[74:75], v[64:65], v[64:65]
	v_pk_mul_f32 v[36:37], v[120:121], v[36:37]
	v_pk_mul_f32 v[38:39], v[122:123], v[38:39]
	v_pk_fma_f32 v[36:37], v[4:5], v[36:37], v[0:1]
	v_pk_fma_f32 v[38:39], v[6:7], v[38:39], v[2:3]
	v_cvt_pk_bf16_f32 v36, v36, v37
	v_cvt_pk_bf16_f32 v37, v38, v39
	global_store_dwordx2 v210, v[36:37], s[40:41] sc1
	v_pk_mov_b32 v[100:101], v[74:75], v[72:73] op_sel:[1, 0]
	v_mov_b32_e32 v75, v73
	v_pk_mov_b32 v[72:73], v[78:79], v[76:77] op_sel:[1, 0]
	v_mov_b32_e32 v79, v77
	v_pk_fma_f32 v[76:77], v[56:57], v[56:57], v[80:81] op_sel_hi:[1, 1, 0]
	v_pk_fma_f32 v[80:81], v[58:59], v[58:59], v[82:83] op_sel_hi:[1, 1, 0]
	v_pk_mov_b32 v[82:83], v[90:91], v[84:85] op_sel:[1, 0]
	v_mov_b32_e32 v91, v85
	v_pk_mov_b32 v[84:85], v[94:95], v[92:93] op_sel:[1, 0]
	v_mov_b32_e32 v95, v93
	v_pk_add_f32 v[74:75], v[100:101], v[74:75]
	v_pk_add_f32 v[68:69], v[72:73], v[78:79]
	v_pk_add_f32 v[70:71], v[82:83], v[90:91]
	v_pk_add_f32 v[72:73], v[84:85], v[94:95]
	v_pk_fma_f32 v[92:93], v[40:41], v[40:41], v[96:97] op_sel_hi:[1, 1, 0]
	v_pk_fma_f32 v[96:97], v[42:43], v[42:43], v[98:99] op_sel_hi:[1, 1, 0]
	v_pk_add_f32 v[74:75], v[74:75], v[74:75] op_sel:[0, 1] op_sel_hi:[1, 0]
	v_pk_add_f32 v[68:69], v[68:69], v[68:69] op_sel:[0, 1] op_sel_hi:[1, 0]
	v_pk_add_f32 v[70:71], v[70:71], v[70:71] op_sel:[0, 1] op_sel_hi:[1, 0]
	v_pk_add_f32 v[72:73], v[72:73], v[72:73] op_sel:[0, 1] op_sel_hi:[1, 0]
	v_mov_b32_e32 v77, v102
	v_mov_b32_e32 v81, v103
	v_mov_b32_e32 v93, v106
	v_mov_b32_e32 v97, v107
	v_mov_b32_e32 v75, v87
	v_mov_b32_e32 v69, v99
	v_mov_b32_e32 v71, v104
	v_mov_b32_e32 v73, v105
	v_pk_add_f32 v[76:77], v[76:77], v[80:81]
	v_pk_add_f32 v[78:79], v[92:93], v[96:97]
	v_pk_add_f32 v[68:69], v[74:75], v[68:69]
	v_pk_add_f32 v[70:71], v[70:71], v[72:73]
	v_pk_add_f32 v[68:69], v[68:69], v[76:77]
	v_pk_add_f32 v[70:71], v[70:71], v[78:79]
	v_mov_b32_e32 v73, v68
	v_mov_b32_e32 v72, v70
	v_mov_b32_e32 v68, v71
	v_pk_add_f32 v[68:69], v[72:73], v[68:69]
	s_waitcnt lgkmcnt(0)
	s_nop 1
	v_add_f32_dpp v68, v68, v68 quad_perm:[1,0,3,2] row_mask:0xf bank_mask:0xf
	v_add_f32_dpp v69, v69, v69 quad_perm:[1,0,3,2] row_mask:0xf bank_mask:0xf
	s_waitcnt lgkmcnt(0)
	s_nop 1
	v_add_f32_dpp v68, v68, v68 quad_perm:[2,3,0,1] row_mask:0xf bank_mask:0xf
	v_add_f32_dpp v69, v69, v69 quad_perm:[2,3,0,1] row_mask:0xf bank_mask:0xf
	s_waitcnt lgkmcnt(0)
	s_nop 1
	v_add_f32_dpp v68, v68, v68 row_half_mirror row_mask:0xf bank_mask:0xf
	v_add_f32_dpp v69, v69, v69 row_half_mirror row_mask:0xf bank_mask:0xf
	s_waitcnt lgkmcnt(0)
	s_nop 1
	v_add_f32_dpp v68, v68, v68 row_mirror row_mask:0xf bank_mask:0xf
	v_add_f32_dpp v69, v69, v69 row_mirror row_mask:0xf bank_mask:0xf
	ds_bpermute_b32 v71, v188, v69
	ds_bpermute_b32 v70, v188, v68
	s_waitcnt lgkmcnt(0)
	v_pk_add_f32 v[68:69], v[68:69], v[70:71]
	s_waitcnt lgkmcnt(0)
	v_mov_b32_e32 v70, v68
	v_mov_b32_e32 v71, v69
	s_nop 1
	v_permlane32_swap_b32_e32 v70, v68
	v_permlane32_swap_b32_e32 v71, v69
	v_pk_add_f32 v[68:69], v[68:69], v[70:71]
	s_nop 0
	v_pk_fma_f32 v[68:69], v[68:69], s[28:29], v[88:89] op_sel_hi:[1, 0, 0]
	s_nop 0
	v_mul_f32_e32 v70, 0x4b800000, v69
	v_cmp_gt_f32_e32 vcc, s63, v69
	s_nop 1
	v_cndmask_b32_e32 v69, v69, v70, vcc
	v_rsq_f32_e32 v69, v69
	v_lshl_add_u64 v[70:71], v[140:141], 0, s[38:39]
	s_add_u32 s38, s10, s38
	s_addc_u32 s39, s11, s39
	v_mul_f32_e32 v72, 0x45800000, v69
	v_cndmask_b32_e32 v72, v69, v72, vcc
	v_pk_mul_f32 v[66:67], v[66:67], v[72:73] op_sel_hi:[1, 0]
	v_pk_mul_f32 v[64:65], v[64:65], v[72:73] op_sel_hi:[1, 0]
	v_pk_mul_f32 v[38:39], v[110:111], v[66:67]
	v_pk_mul_f32 v[36:37], v[108:109], v[64:65]
	v_pk_fma_f32 v[38:39], v[14:15], v[38:39], v[10:11]
	v_pk_fma_f32 v[36:37], v[12:13], v[36:37], v[8:9]
	v_pk_mul_f32 v[62:63], v[62:63], v[72:73] op_sel_hi:[1, 0]
	v_cvt_pk_bf16_f32 v36, v36, v37
	v_cvt_pk_bf16_f32 v37, v38, v39
	global_store_dwordx2 v[70:71], v[36:37], off sc1
	v_pk_mul_f32 v[60:61], v[60:61], v[72:73] op_sel_hi:[1, 0]
	v_pk_mul_f32 v[58:59], v[58:59], v[72:73] op_sel_hi:[1, 0]
	v_pk_mul_f32 v[56:57], v[56:57], v[72:73] op_sel_hi:[1, 0]
	v_pk_mul_f32 v[54:55], v[54:55], v[72:73] op_sel_hi:[1, 0]
	v_pk_mul_f32 v[52:53], v[52:53], v[72:73] op_sel_hi:[1, 0]
	v_cmp_gt_f32_e32 vcc, s63, v68
	s_lshl_b64 s[36:37], s[36:37], 11
	v_pk_mul_f32 v[36:37], v[112:113], v[60:61]
	v_pk_mul_f32 v[38:39], v[114:115], v[62:63]
	v_pk_fma_f32 v[36:37], v[20:21], v[36:37], v[16:17]
	v_pk_fma_f32 v[38:39], v[22:23], v[38:39], v[18:19]
	v_cvt_pk_bf16_f32 v36, v36, v37
	v_cvt_pk_bf16_f32 v37, v38, v39
	global_store_dwordx2 v200, v[36:37], s[38:39] sc1
	v_pk_mul_f32 v[36:37], v[116:117], v[56:57]
	v_pk_mul_f32 v[38:39], v[118:119], v[58:59]
	v_pk_fma_f32 v[36:37], v[28:29], v[36:37], v[24:25]
	v_pk_fma_f32 v[38:39], v[30:31], v[38:39], v[26:27]
	v_cvt_pk_bf16_f32 v36, v36, v37
	v_cvt_pk_bf16_f32 v37, v38, v39
	global_store_dwordx2 v201, v[36:37], s[38:39] sc1
	v_pk_mul_f32 v[36:37], v[120:121], v[52:53]
	v_pk_mul_f32 v[38:39], v[122:123], v[54:55]
	v_pk_fma_f32 v[36:37], v[4:5], v[36:37], v[0:1]
	v_pk_fma_f32 v[38:39], v[6:7], v[38:39], v[2:3]
	v_cvt_pk_bf16_f32 v36, v36, v37
	v_cvt_pk_bf16_f32 v37, v38, v39
	global_store_dwordx2 v210, v[36:37], s[38:39] sc1
	v_mul_f32_e32 v52, 0x4b800000, v68
	v_cndmask_b32_e32 v52, v68, v52, vcc
	v_rsq_f32_e32 v54, v52
	v_lshl_add_u64 v[52:53], v[140:141], 0, s[36:37]
	s_add_u32 s36, s10, s36
	s_addc_u32 s37, s11, s37
	v_mul_f32_e32 v55, 0x45800000, v54
	v_cndmask_b32_e32 v54, v54, v55, vcc
	v_pk_mul_f32 v[50:51], v[50:51], v[54:55] op_sel_hi:[1, 0]
	v_pk_mul_f32 v[48:49], v[48:49], v[54:55] op_sel_hi:[1, 0]
	s_and_b64 vcc, exec, s[8:9]
	s_mov_b64 s[8:9], -1
	v_pk_mul_f32 v[36:37], v[108:109], v[48:49]
	v_pk_mul_f32 v[38:39], v[110:111], v[50:51]
	v_pk_fma_f32 v[8:9], v[12:13], v[36:37], v[8:9]
	v_pk_fma_f32 v[10:11], v[14:15], v[38:39], v[10:11]
	v_cvt_pk_bf16_f32 v8, v8, v9
	v_cvt_pk_bf16_f32 v9, v10, v11
	global_store_dwordx2 v[52:53], v[8:9], off sc1
	v_pk_mul_f32 v[12:13], v[46:47], v[54:55] op_sel_hi:[1, 0]
	v_pk_mul_f32 v[14:15], v[44:45], v[54:55] op_sel_hi:[1, 0]
	v_pk_mul_f32 v[10:11], v[114:115], v[12:13]
	v_pk_mul_f32 v[8:9], v[112:113], v[14:15]
	v_pk_fma_f32 v[10:11], v[22:23], v[10:11], v[18:19]
	v_pk_fma_f32 v[8:9], v[20:21], v[8:9], v[16:17]
	v_pk_mul_f32 v[12:13], v[42:43], v[54:55] op_sel_hi:[1, 0]
	v_cvt_pk_bf16_f32 v8, v8, v9
	v_cvt_pk_bf16_f32 v9, v10, v11
	global_store_dwordx2 v200, v[8:9], s[36:37] sc1
	v_pk_mul_f32 v[14:15], v[40:41], v[54:55] op_sel_hi:[1, 0]
	v_pk_mul_f32 v[10:11], v[118:119], v[12:13]
	v_pk_mul_f32 v[8:9], v[116:117], v[14:15]
	v_pk_fma_f32 v[10:11], v[30:31], v[10:11], v[26:27]
	v_pk_fma_f32 v[8:9], v[28:29], v[8:9], v[24:25]
	v_pk_mul_f32 v[12:13], v[34:35], v[54:55] op_sel_hi:[1, 0]
	v_cvt_pk_bf16_f32 v8, v8, v9
	v_cvt_pk_bf16_f32 v9, v10, v11
	global_store_dwordx2 v201, v[8:9], s[36:37] sc1
	v_pk_mul_f32 v[14:15], v[32:33], v[54:55] op_sel_hi:[1, 0]
	v_pk_mul_f32 v[10:11], v[122:123], v[12:13]
	v_pk_mul_f32 v[8:9], v[120:121], v[14:15]
	v_pk_fma_f32 v[2:3], v[6:7], v[10:11], v[2:3]
	v_pk_fma_f32 v[0:1], v[4:5], v[8:9], v[0:1]
	s_nop 0
	v_cvt_pk_bf16_f32 v0, v0, v1
	v_cvt_pk_bf16_f32 v1, v2, v3
	global_store_dwordx2 v210, v[0:1], s[36:37] sc1
	s_cbranch_vccnz .LBB0_1469
	s_andn2_b64 vcc, exec, s[2:3]
	s_cbranch_vccnz .LBB0_1468
	s_barrier
	s_branch .LBB0_1468

.LBB0_1648:
	v_lshl_or_b32 v172, s74, 8, v198
	v_add_u32_e32 v156, 0x800, v172
	v_ashrrev_i32_e32 v157, 31, v156
	s_ashr_i32 s48, s44, 3
	v_lshlrev_b64 v[160:161], 2, v[156:157]
	s_add_i32 s49, s48, 64
	v_lshl_add_u64 v[164:165], s[14:15], 0, v[160:161]
	v_lshl_add_u64 v[156:157], s[18:19], 0, v[160:161]
	v_mad_i64_i32 v[160:161], s[36:37], s49, v211, v[164:165]
	global_load_dwordx4 v[156:159], v[156:157], off
	s_add_i32 s47, s48, 0x48
	s_add_i32 s46, s48, 0x50
	s_add_i32 s45, s48, 0x58
	s_add_i32 s79, s48, 0x60
	s_add_i32 s78, s48, 0x68
	s_add_i32 s77, s48, 0x70
	s_add_i32 s76, s48, 0x78
	s_lshl_b32 s75, s44, 8
	global_load_dwordx4 v[160:163], v[160:161], off
	v_mad_i64_i32 v[212:213], s[36:37], s47, v211, v[164:165]
	global_load_dwordx4 v[212:215], v[212:213], off
	v_mad_i64_i32 v[216:217], s[36:37], s46, v211, v[164:165]
	global_load_dwordx4 v[216:219], v[216:217], off
	v_mad_i64_i32 v[220:221], s[36:37], s45, v211, v[164:165]
	global_load_dwordx4 v[220:223], v[220:221], off
	v_mad_i64_i32 v[224:225], s[36:37], s79, v211, v[164:165]
	global_load_dwordx4 v[224:227], v[224:225], off
	v_mad_i64_i32 v[228:229], s[36:37], s78, v211, v[164:165]
	global_load_dwordx4 v[228:231], v[228:229], off
	v_mad_i64_i32 v[232:233], s[36:37], s77, v211, v[164:165]
	global_load_dwordx4 v[232:235], v[232:233], off
	v_mad_i64_i32 v[236:237], s[36:37], s76, v211, v[164:165]
	global_load_dwordx4 v[236:239], v[236:237], off
	v_ashrrev_i32_e32 v173, 31, v172
	v_readfirstlane_b32 s80, v180
	s_waitcnt vmcnt(7)
	v_pk_add_f32 v[160:161], v[156:157], v[160:161]
	v_pk_add_f32 v[162:163], v[158:159], v[162:163]
	s_waitcnt vmcnt(6)
	v_pk_add_f32 v[160:161], v[160:161], v[212:213]
	v_pk_add_f32 v[162:163], v[162:163], v[214:215]
	s_waitcnt vmcnt(5)
	v_pk_add_f32 v[160:161], v[160:161], v[216:217]
	v_pk_add_f32 v[162:163], v[162:163], v[218:219]
	s_waitcnt vmcnt(4)
	v_pk_add_f32 v[160:161], v[160:161], v[220:221]
	v_pk_add_f32 v[162:163], v[162:163], v[222:223]
	s_waitcnt vmcnt(3)
	v_pk_add_f32 v[160:161], v[160:161], v[224:225]
	v_pk_add_f32 v[162:163], v[162:163], v[226:227]
	s_waitcnt vmcnt(2)
	v_pk_add_f32 v[160:161], v[160:161], v[228:229]
	v_pk_add_f32 v[162:163], v[162:163], v[230:231]
	s_waitcnt vmcnt(1)
	v_pk_add_f32 v[160:161], v[160:161], v[232:233]
	v_pk_add_f32 v[162:163], v[162:163], v[234:235]
	s_waitcnt vmcnt(0)
	v_pk_add_f32 v[158:159], v[162:163], v[238:239]
	v_pk_add_f32 v[160:161], v[160:161], v[236:237]
	v_pk_mul_f32 v[156:157], v[158:159], 0.5 op_sel_hi:[1, 0]
	v_pk_mul_f32 v[158:159], v[160:161], 0.5 op_sel_hi:[1, 0]
	v_add_u32_e32 v160, 0x810, v172
	v_ashrrev_i32_e32 v161, 31, v160
	v_lshlrev_b64 v[164:165], 2, v[160:161]
	v_lshl_add_u64 v[168:169], s[14:15], 0, v[164:165]
	v_lshl_add_u64 v[160:161], s[18:19], 0, v[164:165]
	v_mad_i64_i32 v[164:165], s[36:37], s49, v211, v[168:169]
	global_load_dwordx4 v[160:163], v[160:161], off
	global_load_dwordx4 v[164:167], v[164:165], off
	v_mad_i64_i32 v[212:213], s[36:37], s47, v211, v[168:169]
	global_load_dwordx4 v[212:215], v[212:213], off
	v_mad_i64_i32 v[216:217], s[36:37], s46, v211, v[168:169]
	global_load_dwordx4 v[216:219], v[216:217], off
	v_mad_i64_i32 v[220:221], s[36:37], s45, v211, v[168:169]
	global_load_dwordx4 v[220:223], v[220:221], off
	v_mad_i64_i32 v[224:225], s[36:37], s79, v211, v[168:169]
	global_load_dwordx4 v[224:227], v[224:225], off
	v_mad_i64_i32 v[228:229], s[36:37], s78, v211, v[168:169]
	global_load_dwordx4 v[228:231], v[228:229], off
	v_mad_i64_i32 v[232:233], s[36:37], s77, v211, v[168:169]
	global_load_dwordx4 v[232:235], v[232:233], off
	v_mad_i64_i32 v[236:237], s[36:37], s76, v211, v[168:169]
	global_load_dwordx4 v[236:239], v[236:237], off
	s_waitcnt vmcnt(7)
	v_pk_add_f32 v[164:165], v[160:161], v[164:165]
	v_pk_add_f32 v[166:167], v[162:163], v[166:167]
	s_waitcnt vmcnt(6)
	v_pk_add_f32 v[164:165], v[164:165], v[212:213]
	v_pk_add_f32 v[166:167], v[166:167], v[214:215]
	s_waitcnt vmcnt(5)
	v_pk_add_f32 v[164:165], v[164:165], v[216:217]
	v_pk_add_f32 v[166:167], v[166:167], v[218:219]
	s_waitcnt vmcnt(4)
	v_pk_add_f32 v[164:165], v[164:165], v[220:221]
	v_pk_add_f32 v[166:167], v[166:167], v[222:223]
	s_waitcnt vmcnt(3)
	v_pk_add_f32 v[164:165], v[164:165], v[224:225]
	v_pk_add_f32 v[166:167], v[166:167], v[226:227]
	s_waitcnt vmcnt(2)
	v_pk_add_f32 v[164:165], v[164:165], v[228:229]
	v_pk_add_f32 v[166:167], v[166:167], v[230:231]
	s_waitcnt vmcnt(1)
	v_pk_add_f32 v[164:165], v[164:165], v[232:233]
	v_pk_add_f32 v[166:167], v[166:167], v[234:235]
	s_waitcnt vmcnt(0)
	v_pk_add_f32 v[162:163], v[166:167], v[238:239]
	v_pk_add_f32 v[164:165], v[164:165], v[236:237]
	v_pk_mul_f32 v[160:161], v[162:163], 0.5 op_sel_hi:[1, 0]
	v_pk_mul_f32 v[162:163], v[164:165], 0.5 op_sel_hi:[1, 0]
	v_add_u32_e32 v164, 0x880, v172
	v_ashrrev_i32_e32 v165, 31, v164
	v_lshlrev_b64 v[168:169], 2, v[164:165]
	v_lshl_add_u64 v[174:175], s[14:15], 0, v[168:169]
	v_lshl_add_u64 v[164:165], s[18:19], 0, v[168:169]
	v_mad_i64_i32 v[168:169], s[36:37], s49, v211, v[174:175]
	global_load_dwordx4 v[164:167], v[164:165], off
	global_load_dwordx4 v[168:171], v[168:169], off
	v_mad_i64_i32 v[212:213], s[36:37], s47, v211, v[174:175]
	global_load_dwordx4 v[212:215], v[212:213], off
	v_mad_i64_i32 v[216:217], s[36:37], s46, v211, v[174:175]
	global_load_dwordx4 v[216:219], v[216:217], off
	v_mad_i64_i32 v[220:221], s[36:37], s45, v211, v[174:175]
	global_load_dwordx4 v[220:223], v[220:221], off
	v_mad_i64_i32 v[224:225], s[36:37], s79, v211, v[174:175]
	global_load_dwordx4 v[224:227], v[224:225], off
	v_mad_i64_i32 v[228:229], s[36:37], s78, v211, v[174:175]
	global_load_dwordx4 v[228:231], v[228:229], off
	v_mad_i64_i32 v[232:233], s[36:37], s77, v211, v[174:175]
	global_load_dwordx4 v[232:235], v[232:233], off
	v_mad_i64_i32 v[236:237], s[36:37], s76, v211, v[174:175]
	global_load_dwordx4 v[236:239], v[236:237], off
	s_waitcnt vmcnt(7)
	v_pk_add_f32 v[168:169], v[164:165], v[168:169]
	v_pk_add_f32 v[170:171], v[166:167], v[170:171]
	s_waitcnt vmcnt(6)
	v_pk_add_f32 v[168:169], v[168:169], v[212:213]
	v_pk_add_f32 v[170:171], v[170:171], v[214:215]
	s_waitcnt vmcnt(5)
	v_pk_add_f32 v[168:169], v[168:169], v[216:217]
	v_pk_add_f32 v[170:171], v[170:171], v[218:219]
	s_waitcnt vmcnt(4)
	v_pk_add_f32 v[168:169], v[168:169], v[220:221]
	v_pk_add_f32 v[170:171], v[170:171], v[222:223]
	s_waitcnt vmcnt(3)
	v_pk_add_f32 v[168:169], v[168:169], v[224:225]
	v_pk_add_f32 v[170:171], v[170:171], v[226:227]
	s_waitcnt vmcnt(2)
	v_pk_add_f32 v[168:169], v[168:169], v[228:229]
	v_pk_add_f32 v[170:171], v[170:171], v[230:231]
	s_waitcnt vmcnt(1)
	v_pk_add_f32 v[168:169], v[168:169], v[232:233]
	v_pk_add_f32 v[170:171], v[170:171], v[234:235]
	s_waitcnt vmcnt(0)
	v_pk_add_f32 v[166:167], v[170:171], v[238:239]
	v_pk_add_f32 v[168:169], v[168:169], v[236:237]
	v_pk_mul_f32 v[164:165], v[166:167], 0.5 op_sel_hi:[1, 0]
	v_pk_mul_f32 v[166:167], v[168:169], 0.5 op_sel_hi:[1, 0]
	v_add_u32_e32 v168, 0x890, v172
	v_ashrrev_i32_e32 v169, 31, v168
	v_lshlrev_b64 v[174:175], 2, v[168:169]
	v_lshl_add_u64 v[178:179], s[14:15], 0, v[174:175]
	v_lshl_add_u64 v[168:169], s[18:19], 0, v[174:175]
	v_mad_i64_i32 v[174:175], s[36:37], s49, v211, v[178:179]
	global_load_dwordx4 v[168:171], v[168:169], off
	global_load_dwordx4 v[174:177], v[174:175], off
	v_mad_i64_i32 v[212:213], s[36:37], s47, v211, v[178:179]
	global_load_dwordx4 v[212:215], v[212:213], off
	v_mad_i64_i32 v[216:217], s[36:37], s46, v211, v[178:179]
	global_load_dwordx4 v[216:219], v[216:217], off
	v_mad_i64_i32 v[220:221], s[36:37], s45, v211, v[178:179]
	global_load_dwordx4 v[220:223], v[220:221], off
	v_mad_i64_i32 v[224:225], s[36:37], s79, v211, v[178:179]
	global_load_dwordx4 v[224:227], v[224:225], off
	v_mad_i64_i32 v[228:229], s[36:37], s78, v211, v[178:179]
	global_load_dwordx4 v[228:231], v[228:229], off
	v_mad_i64_i32 v[232:233], s[36:37], s77, v211, v[178:179]
	global_load_dwordx4 v[232:235], v[232:233], off
	v_mad_i64_i32 v[236:237], s[36:37], s76, v211, v[178:179]
	global_load_dwordx4 v[236:239], v[236:237], off
	v_lshlrev_b64 v[172:173], 2, v[172:173]
	s_waitcnt vmcnt(7)
	v_pk_add_f32 v[174:175], v[168:169], v[174:175]
	v_pk_add_f32 v[176:177], v[170:171], v[176:177]
	s_waitcnt vmcnt(6)
	v_pk_add_f32 v[174:175], v[174:175], v[212:213]
	v_pk_add_f32 v[176:177], v[176:177], v[214:215]
	s_waitcnt vmcnt(5)
	v_pk_add_f32 v[174:175], v[174:175], v[216:217]
	v_pk_add_f32 v[176:177], v[176:177], v[218:219]
	s_waitcnt vmcnt(4)
	v_pk_add_f32 v[174:175], v[174:175], v[220:221]
	v_pk_add_f32 v[176:177], v[176:177], v[222:223]
	s_waitcnt vmcnt(3)
	v_pk_add_f32 v[174:175], v[174:175], v[224:225]
	v_pk_add_f32 v[176:177], v[176:177], v[226:227]
	s_waitcnt vmcnt(2)
	v_pk_add_f32 v[174:175], v[174:175], v[228:229]
	v_pk_add_f32 v[176:177], v[176:177], v[230:231]
	s_waitcnt vmcnt(1)
	v_pk_add_f32 v[174:175], v[174:175], v[232:233]
	v_pk_add_f32 v[176:177], v[176:177], v[234:235]
	v_add_u32_e32 v178, s75, v181
	v_ashrrev_i32_e32 v179, 31, v178
	s_waitcnt vmcnt(0)
	v_pk_add_f32 v[170:171], v[176:177], v[238:239]
	v_pk_add_f32 v[174:175], v[174:175], v[236:237]
	v_pk_mul_f32 v[168:169], v[170:171], 0.5 op_sel_hi:[1, 0]
	v_pk_mul_f32 v[170:171], v[174:175], 0.5 op_sel_hi:[1, 0]
	v_lshl_add_u64 v[174:175], s[12:13], 0, v[172:173]
	v_lshlrev_b64 v[176:177], 12, v[178:179]
	v_lshl_add_u64 v[204:205], v[174:175], 0, v[176:177]
	global_load_dwordx4 v[212:215], v[204:205], off
	global_load_dwordx4 v[216:219], v[204:205], off offset:64
	global_load_dwordx4 v[220:223], v[204:205], off offset:512
	global_load_dwordx4 v[224:227], v[204:205], off offset:576
	v_or_b32_e32 v204, 16, v178
	v_ashrrev_i32_e32 v205, 31, v204
	v_lshlrev_b64 v[204:205], 12, v[204:205]
	v_lshl_add_u64 v[206:207], v[174:175], 0, v[204:205]
	global_load_dwordx4 v[228:231], v[206:207], off
	global_load_dwordx4 v[232:235], v[206:207], off offset:64
	global_load_dwordx4 v[236:239], v[206:207], off offset:512
	global_load_dwordx4 v[240:243], v[206:207], off offset:576
	v_lshl_add_u64 v[206:207], s[12:13], 0, v[176:177]
	v_lshl_add_u64 v[206:207], v[206:207], 0, v[172:173]
	s_waitcnt vmcnt(7)
	v_pk_fma_f32 v[126:127], v[126:127], v[156:157], v[214:215]
	v_pk_fma_f32 v[124:125], v[124:125], v[158:159], v[212:213]
	s_waitcnt vmcnt(5)
	v_pk_fma_f32 v[110:111], v[110:111], v[164:165], v[222:223]
	v_pk_fma_f32 v[108:109], v[108:109], v[166:167], v[220:221]
	global_store_dwordx4 v[206:207], v[108:111], off offset:512 sc1
	s_waitcnt vmcnt(5)
	v_pk_fma_f32 v[106:107], v[106:107], v[168:169], v[226:227]
	v_pk_fma_f32 v[104:105], v[104:105], v[170:171], v[224:225]
	v_lshl_add_u64 v[108:109], s[12:13], 0, v[204:205]
	v_lshl_add_u64 v[108:109], v[108:109], 0, v[172:173]
	s_waitcnt vmcnt(1)
	v_pk_fma_f32 v[98:99], v[98:99], v[168:169], v[242:243]
	v_pk_fma_f32 v[96:97], v[96:97], v[170:171], v[240:241]
	global_store_dwordx4 v[108:109], v[96:99], off offset:576 sc1
	global_store_dwordx4 v[206:207], v[104:107], off offset:576 sc1
	v_pk_fma_f32 v[122:123], v[122:123], v[160:161], v[218:219]
	v_or_b32_e32 v96, 32, v178
	v_pk_fma_f32 v[106:107], v[118:119], v[156:157], v[230:231]
	v_pk_fma_f32 v[104:105], v[116:117], v[158:159], v[228:229]
	v_ashrrev_i32_e32 v97, 31, v96
	v_pk_fma_f32 v[120:121], v[120:121], v[162:163], v[216:217]
	global_store_dwordx4 v[108:109], v[104:107], off sc1
	v_pk_fma_f32 v[102:103], v[102:103], v[164:165], v[238:239]
	v_pk_fma_f32 v[100:101], v[100:101], v[166:167], v[236:237]
	v_pk_fma_f32 v[106:107], v[114:115], v[160:161], v[234:235]
	v_pk_fma_f32 v[104:105], v[112:113], v[162:163], v[232:233]
	v_lshlrev_b64 v[204:205], 12, v[96:97]
	v_or_b32_e32 v112, 48, v178
	global_store_dwordx4 v[206:207], v[124:127], off sc1
	global_store_dwordx4 v[206:207], v[120:123], off offset:64 sc1
	global_store_dwordx4 v[108:109], v[104:107], off offset:64 sc1
	global_store_dwordx4 v[108:109], v[100:103], off offset:512 sc1
	v_lshl_add_u64 v[108:109], v[174:175], 0, v[204:205]
	v_ashrrev_i32_e32 v113, 31, v112
	global_load_dwordx4 v[96:99], v[108:109], off
	global_load_dwordx4 v[100:103], v[108:109], off offset:64
	global_load_dwordx4 v[104:107], v[108:109], off offset:512
	s_nop 0
	global_load_dwordx4 v[108:111], v[108:109], off offset:576
	v_lshlrev_b64 v[178:179], 12, v[112:113]
	v_lshl_add_u64 v[124:125], v[174:175], 0, v[178:179]
	global_load_dwordx4 v[112:115], v[124:125], off
	global_load_dwordx4 v[116:119], v[124:125], off offset:64
	global_load_dwordx4 v[120:123], v[124:125], off offset:512
	s_nop 0
	global_load_dwordx4 v[124:127], v[124:125], off offset:576
	s_waitcnt vmcnt(7)
	v_pk_fma_f32 v[92:93], v[92:93], v[158:159], v[96:97]
	v_lshl_add_u64 v[96:97], s[12:13], 0, v[204:205]
	v_lshl_add_u64 v[96:97], v[96:97], 0, v[172:173]
	s_waitcnt vmcnt(5)
	v_pk_fma_f32 v[78:79], v[78:79], v[164:165], v[106:107]
	v_pk_fma_f32 v[76:77], v[76:77], v[166:167], v[104:105]
	global_store_dwordx4 v[96:97], v[76:79], off offset:512 sc1
	s_waitcnt vmcnt(5)
	v_pk_fma_f32 v[74:75], v[74:75], v[168:169], v[110:111]
	v_pk_fma_f32 v[72:73], v[72:73], v[170:171], v[108:109]
	v_lshl_add_u64 v[76:77], s[12:13], 0, v[178:179]
	v_pk_fma_f32 v[94:95], v[94:95], v[156:157], v[98:99]
	v_pk_fma_f32 v[90:91], v[90:91], v[160:161], v[102:103]
	v_pk_fma_f32 v[88:89], v[88:89], v[162:163], v[100:101]
	global_store_dwordx4 v[96:97], v[72:75], off offset:576 sc1
	v_lshl_add_u64 v[76:77], v[76:77], 0, v[172:173]
	global_store_dwordx4 v[96:97], v[92:95], off sc1
	s_waitcnt vmcnt(6)
	v_pk_fma_f32 v[74:75], v[86:87], v[156:157], v[114:115]
	v_pk_fma_f32 v[72:73], v[84:85], v[158:159], v[112:113]
	global_store_dwordx4 v[96:97], v[88:91], off offset:64 sc1
	global_store_dwordx4 v[76:77], v[72:75], off sc1
	s_waitcnt vmcnt(6)
	v_pk_fma_f32 v[70:71], v[70:71], v[164:165], v[122:123]
	v_pk_fma_f32 v[68:69], v[68:69], v[166:167], v[120:121]
	v_pk_fma_f32 v[74:75], v[82:83], v[160:161], v[118:119]
	v_pk_fma_f32 v[72:73], v[80:81], v[162:163], v[116:117]
	s_waitcnt vmcnt(5)
	v_pk_fma_f32 v[66:67], v[66:67], v[168:169], v[126:127]
	v_pk_fma_f32 v[64:65], v[64:65], v[170:171], v[124:125]
	v_lshl_add_u64 v[96:97], v[176:177], 0, s[20:21]
	global_store_dwordx4 v[76:77], v[72:75], off offset:64 sc1
	global_store_dwordx4 v[76:77], v[68:71], off offset:512 sc1
	global_store_dwordx4 v[76:77], v[64:67], off offset:576 sc1
	v_lshl_add_u64 v[76:77], v[174:175], 0, v[96:97]
	global_load_dwordx4 v[64:67], v[76:77], off
	global_load_dwordx4 v[68:71], v[76:77], off offset:64
	global_load_dwordx4 v[72:75], v[76:77], off offset:512
	s_nop 0
	global_load_dwordx4 v[76:79], v[76:77], off offset:576
	v_lshl_add_u64 v[98:99], v[176:177], 0, s[22:23]
	v_lshl_add_u64 v[92:93], v[174:175], 0, v[98:99]
	global_load_dwordx4 v[80:83], v[92:93], off
	global_load_dwordx4 v[84:87], v[92:93], off offset:64
	global_load_dwordx4 v[88:91], v[92:93], off offset:512
	s_nop 0
	global_load_dwordx4 v[92:95], v[92:93], off offset:576
	s_waitcnt vmcnt(7)
	v_pk_fma_f32 v[60:61], v[60:61], v[158:159], v[64:65]
	v_lshl_add_u64 v[64:65], s[12:13], 0, v[96:97]
	v_lshl_add_u64 v[64:65], v[64:65], 0, v[172:173]
	s_waitcnt vmcnt(5)
	v_pk_fma_f32 v[46:47], v[46:47], v[164:165], v[74:75]
	v_pk_fma_f32 v[44:45], v[44:45], v[166:167], v[72:73]
	global_store_dwordx4 v[64:65], v[44:47], off offset:512 sc1
	s_waitcnt vmcnt(5)
	v_pk_fma_f32 v[42:43], v[42:43], v[168:169], v[78:79]
	v_pk_fma_f32 v[40:41], v[40:41], v[170:171], v[76:77]
	v_lshl_add_u64 v[44:45], s[12:13], 0, v[98:99]
	v_pk_fma_f32 v[62:63], v[62:63], v[156:157], v[66:67]
	v_pk_fma_f32 v[58:59], v[58:59], v[160:161], v[70:71]
	v_pk_fma_f32 v[56:57], v[56:57], v[162:163], v[68:69]
	global_store_dwordx4 v[64:65], v[40:43], off offset:576 sc1
	v_lshl_add_u64 v[44:45], v[44:45], 0, v[172:173]
	global_store_dwordx4 v[64:65], v[60:63], off sc1
	s_waitcnt vmcnt(6)
	v_pk_fma_f32 v[42:43], v[54:55], v[156:157], v[82:83]
	v_pk_fma_f32 v[40:41], v[52:53], v[158:159], v[80:81]
	global_store_dwordx4 v[64:65], v[56:59], off offset:64 sc1
	global_store_dwordx4 v[44:45], v[40:43], off sc1
	s_waitcnt vmcnt(6)
	v_pk_fma_f32 v[38:39], v[38:39], v[164:165], v[90:91]
	v_pk_fma_f32 v[36:37], v[36:37], v[166:167], v[88:89]
	v_pk_fma_f32 v[42:43], v[50:51], v[160:161], v[86:87]
	v_pk_fma_f32 v[40:41], v[48:49], v[162:163], v[84:85]
	s_waitcnt vmcnt(5)
	v_pk_fma_f32 v[34:35], v[34:35], v[168:169], v[94:95]
	v_pk_fma_f32 v[32:33], v[32:33], v[170:171], v[92:93]
	v_lshl_add_u64 v[64:65], v[176:177], 0, s[24:25]
	global_store_dwordx4 v[44:45], v[40:43], off offset:64 sc1
	global_store_dwordx4 v[44:45], v[36:39], off offset:512 sc1
	global_store_dwordx4 v[44:45], v[32:35], off offset:576 sc1
	v_lshl_add_u64 v[44:45], v[174:175], 0, v[64:65]
	global_load_dwordx4 v[32:35], v[44:45], off
	global_load_dwordx4 v[36:39], v[44:45], off offset:64
	global_load_dwordx4 v[40:43], v[44:45], off offset:512
	s_nop 0
	global_load_dwordx4 v[44:47], v[44:45], off offset:576
	v_lshl_add_u64 v[66:67], v[176:177], 0, s[26:27]
	v_lshl_add_u64 v[60:61], v[174:175], 0, v[66:67]
	global_load_dwordx4 v[48:51], v[60:61], off
	global_load_dwordx4 v[52:55], v[60:61], off offset:64
	global_load_dwordx4 v[56:59], v[60:61], off offset:512
	s_nop 0
	global_load_dwordx4 v[60:63], v[60:61], off offset:576
	s_waitcnt vmcnt(7)
	v_pk_fma_f32 v[28:29], v[28:29], v[158:159], v[32:33]
	v_lshl_add_u64 v[32:33], s[12:13], 0, v[64:65]
	v_lshl_add_u64 v[32:33], v[32:33], 0, v[172:173]
	s_waitcnt vmcnt(5)
	v_pk_fma_f32 v[18:19], v[18:19], v[164:165], v[42:43]
	v_pk_fma_f32 v[16:17], v[16:17], v[166:167], v[40:41]
	global_store_dwordx4 v[32:33], v[16:19], off offset:512 sc1
	s_waitcnt vmcnt(5)
	v_pk_fma_f32 v[10:11], v[10:11], v[168:169], v[46:47]
	v_pk_fma_f32 v[8:9], v[8:9], v[170:171], v[44:45]
	v_lshl_add_u64 v[16:17], s[12:13], 0, v[66:67]
	global_store_dwordx4 v[32:33], v[8:11], off offset:576 sc1
	v_lshl_add_u64 v[16:17], v[16:17], 0, v[172:173]
	v_pk_fma_f32 v[30:31], v[30:31], v[156:157], v[34:35]
	s_waitcnt vmcnt(5)
	v_pk_fma_f32 v[10:11], v[22:23], v[156:157], v[50:51]
	v_pk_fma_f32 v[8:9], v[20:21], v[158:159], v[48:49]
	v_pk_fma_f32 v[26:27], v[26:27], v[160:161], v[38:39]
	v_pk_fma_f32 v[24:25], v[24:25], v[162:163], v[36:37]
	global_store_dwordx4 v[16:17], v[8:11], off sc1
	s_waitcnt vmcnt(4)
	v_pk_fma_f32 v[6:7], v[6:7], v[164:165], v[58:59]
	v_pk_fma_f32 v[4:5], v[4:5], v[166:167], v[56:57]
	v_pk_fma_f32 v[10:11], v[14:15], v[160:161], v[54:55]
	v_pk_fma_f32 v[8:9], v[12:13], v[162:163], v[52:53]
	s_waitcnt vmcnt(3)
	v_pk_fma_f32 v[2:3], v[2:3], v[168:169], v[62:63]
	v_pk_fma_f32 v[0:1], v[0:1], v[170:171], v[60:61]
	global_store_dwordx4 v[32:33], v[28:31], off sc1
	global_store_dwordx4 v[32:33], v[24:27], off offset:64 sc1
	global_store_dwordx4 v[16:17], v[8:11], off offset:64 sc1
	global_store_dwordx4 v[16:17], v[4:7], off offset:512 sc1
	global_store_dwordx4 v[16:17], v[0:3], off offset:576 sc1
	s_waitcnt vmcnt(0)
	s_barrier
	s_and_saveexec_b64 s[36:37], s[4:5]
	s_cbranch_execz .LBB0_1662
	s_lshl_b32 s38, s44, 2
	s_ashr_i32 s39, s38, 31
	s_lshl_b64 s[38:39], s[38:39], 2
	s_add_u32 s38, s63, s38
	s_addc_u32 s39, s64, s39
	s_getreg_b32 s40, hwreg(HW_REG_XCC_ID, 0, 4)
	global_load_dwordx4 v[0:3], v129, s[38:39]
	s_and_b32 s38, s40, 15
	s_add_i32 s38, s38, 1
	s_waitcnt vmcnt(0)
	v_cmp_ne_u32_e32 vcc, s38, v2
	s_nop 1
	v_cndmask_b32_e64 v2, 0, 1, vcc
	v_cmp_ne_u32_e32 vcc, s38, v3
	v_lshlrev_b32_e32 v2, 2, v2
	s_nop 0
	v_cndmask_b32_e64 v3, 0, 1, vcc
	v_cmp_ne_u32_e32 vcc, s38, v1
	v_lshlrev_b32_e32 v3, 3, v3
	v_or_b32_e32 v2, v3, v2
	v_cndmask_b32_e64 v1, 0, 1, vcc
	v_cmp_ne_u32_e32 vcc, s38, v0
	v_lshlrev_b32_e32 v1, 1, v1
	s_nop 0
	v_cndmask_b32_e64 v0, 0, 1, vcc
	v_or_b32_e32 v0, v0, v1
	v_and_b32_e32 v0, 3, v0
	v_or_b32_e32 v0, v0, v2
	v_and_b32_e32 v0, 15, v0
	v_cmp_eq_u32_e32 vcc, 0, v0
	s_cbranch_vccnz .LBB0_1651
	buffer_wbl2 sc1
	s_waitcnt vmcnt(0)

.LBB0_1662:
	s_or_b64 exec, exec, s[36:37]
	s_mul_i32 s36, s48, 0x9000
	s_mul_hi_i32 s51, s49, 0x9000
	s_add_i32 s50, s36, 0x240000
	s_mul_hi_i32 s49, s47, 0x9000
	s_add_i32 s48, s36, 0x288000
	v_lshl_add_u64 v[4:5], v[134:135], 0, s[50:51]
	s_mul_hi_i32 s47, s46, 0x9000
	s_add_i32 s46, s36, 0x2d0000
	s_barrier
	global_load_dwordx4 v[0:3], v[132:133], off
	v_lshl_add_u64 v[8:9], v[134:135], 0, s[48:49]
	global_load_dwordx4 v[4:7], v[4:5], off
	s_mul_hi_i32 s45, s45, 0x9000
	s_add_i32 s44, s36, 0x318000
	global_load_dwordx4 v[8:11], v[8:9], off
	v_lshl_add_u64 v[12:13], v[134:135], 0, s[46:47]
	s_mul_hi_i32 s43, s79, 0x9000
	s_add_i32 s42, s36, 0x360000
	global_load_dwordx4 v[12:15], v[12:13], off
	v_lshl_add_u64 v[16:17], v[134:135], 0, s[44:45]
	s_mul_hi_i32 s41, s78, 0x9000
	s_add_i32 s40, s36, 0x3a8000
	global_load_dwordx4 v[16:19], v[16:17], off
	v_lshl_add_u64 v[20:21], v[134:135], 0, s[42:43]
	s_mul_hi_i32 s39, s77, 0x9000
	s_add_i32 s38, s36, 0x3f0000
	global_load_dwordx4 v[20:23], v[20:21], off
	v_lshl_add_u64 v[24:25], v[134:135], 0, s[40:41]
	s_mul_hi_i32 s37, s76, 0x9000
	s_add_i32 s36, s36, 0x438000
	global_load_dwordx4 v[24:27], v[24:25], off
	v_lshl_add_u64 v[28:29], v[134:135], 0, s[38:39]
	global_load_dwordx4 v[28:31], v[28:29], off
	v_lshl_add_u64 v[32:33], v[134:135], 0, s[36:37]
	global_load_dwordx4 v[32:35], v[32:33], off
	s_lshl_b32 s36, s74, 6
	s_ashr_i32 s37, s80, 3
	s_add_i32 s36, s75, s36
	s_and_b32 s37, s37, -8
	s_add_i32 s36, s36, s37
	s_ashr_i32 s37, s36, 31
	s_lshl_b64 s[38:39], s[36:37], 12
	v_lshl_add_u64 v[36:37], v[136:137], 0, s[38:39]
	s_or_b32 s42, s36, 1
	s_ashr_i32 s43, s42, 31
	s_lshl_b64 s[38:39], s[42:43], 12
	v_mov_b64_e32 v[88:89], s[30:31]
	s_or_b32 s40, s36, 2
	s_ashr_i32 s41, s40, 31
	s_lshl_b64 s[46:47], s[40:41], 12
	s_lshl_b64 s[44:45], s[36:37], 11
	s_waitcnt vmcnt(7)
	v_pk_add_f32 v[2:3], v[2:3], v[6:7]
	v_pk_add_f32 v[0:1], v[0:1], v[4:5]
	s_waitcnt vmcnt(6)
	v_pk_add_f32 v[2:3], v[2:3], v[10:11]
	v_pk_add_f32 v[0:1], v[0:1], v[8:9]
	v_lshl_add_u64 v[8:9], v[136:137], 0, s[38:39]
	s_or_b32 s38, s36, 3
	s_waitcnt vmcnt(5)
	v_pk_add_f32 v[2:3], v[2:3], v[14:15]
	v_pk_add_f32 v[0:1], v[0:1], v[12:13]
	s_ashr_i32 s39, s38, 31
	s_lshl_b64 s[48:49], s[38:39], 12
	s_waitcnt vmcnt(4)
	v_pk_add_f32 v[2:3], v[2:3], v[18:19]
	v_pk_add_f32 v[0:1], v[0:1], v[16:17]
	s_waitcnt vmcnt(3)
	v_pk_add_f32 v[2:3], v[2:3], v[22:23]
	v_pk_add_f32 v[0:1], v[0:1], v[20:21]
	s_waitcnt vmcnt(2)
	v_pk_add_f32 v[2:3], v[2:3], v[26:27]
	v_pk_add_f32 v[0:1], v[0:1], v[24:25]
	s_waitcnt vmcnt(1)
	v_pk_add_f32 v[2:3], v[2:3], v[30:31]
	v_pk_add_f32 v[0:1], v[0:1], v[28:29]
	s_waitcnt vmcnt(0)
	v_pk_add_f32 v[2:3], v[2:3], v[34:35]
	v_pk_add_f32 v[0:1], v[0:1], v[32:33]
	v_pk_add_f32 v[4:5], v[2:3], 1.0 op_sel_hi:[1,0]
	v_pk_add_f32 v[6:7], v[0:1], 1.0 op_sel_hi:[1,0]
	v_cndmask_b32_e64 v3, v5, v3, s[6:7]
	v_cndmask_b32_e64 v2, v4, v2, s[6:7]
	v_cndmask_b32_e64 v1, v7, v1, s[6:7]
	v_cndmask_b32_e64 v0, v6, v0, s[6:7]
	ds_write_b128 v183, v[0:3]
	s_waitcnt lgkmcnt(0)
	s_barrier
	global_load_dwordx4 v[108:111], v[138:139], off
	global_load_dwordx4 v[112:115], v[142:143], off
	global_load_dwordx4 v[116:119], v[144:145], off
	global_load_dwordx4 v[120:123], v[146:147], off
	global_load_dwordx4 v[16:19], v[36:37], off
	global_load_dwordx4 v[4:7], v[36:37], off offset:1024
	global_load_dwordx4 v[80:83], v[36:37], off offset:3072
	global_load_dwordx4 v[0:3], v[36:37], off offset:2048
	global_load_dwordx4 v[76:79], v[8:9], off
	global_load_dwordx4 v[68:71], v[8:9], off offset:1024
	s_nop 0
	global_load_dwordx4 v[36:39], v[8:9], off offset:3072
	global_load_dwordx4 v[64:67], v[8:9], off offset:2048
	s_waitcnt vmcnt(3)
	v_pk_mul_f32 v[28:29], v[78:79], v[78:79]
	v_pk_mul_f32 v[8:9], v[18:19], v[18:19]
	v_pk_mul_f32 v[10:11], v[16:17], v[16:17]
	v_pk_mul_f32 v[12:13], v[6:7], v[6:7]
	v_pk_mul_f32 v[14:15], v[4:5], v[4:5]
	v_mul_f32_e32 v24, v1, v1
	v_mul_f32_e32 v26, v3, v3
	v_pk_mul_f32 v[30:31], v[76:77], v[76:77]
	s_waitcnt vmcnt(2)
	v_pk_mul_f32 v[32:33], v[70:71], v[70:71]
	v_pk_mul_f32 v[34:35], v[68:69], v[68:69]
	v_mul_f32_e32 v47, v82, v82
	v_mul_f32_e32 v48, v83, v83
	v_pk_mov_b32 v[44:45], v[10:11], v[8:9] op_sel:[1, 0]
	v_mov_b32_e32 v11, v9
	v_pk_mov_b32 v[8:9], v[14:15], v[12:13] op_sel:[1, 0]
	v_mov_b32_e32 v15, v13
	v_pk_fma_f32 v[12:13], v[0:1], v[0:1], v[24:25] op_sel_hi:[1, 1, 0]
	v_pk_fma_f32 v[24:25], v[2:3], v[2:3], v[26:27] op_sel_hi:[1, 1, 0]
	v_pk_mov_b32 v[26:27], v[30:31], v[28:29] op_sel:[1, 0]
	v_mov_b32_e32 v31, v29
	v_pk_mov_b32 v[28:29], v[34:35], v[32:33] op_sel:[1, 0]
	v_mov_b32_e32 v35, v33
	v_mul_f32_e32 v43, v80, v80
	s_waitcnt vmcnt(0)
	v_mul_f32_e32 v40, v65, v65
	v_mul_f32_e32 v42, v67, v67
	v_pk_add_f32 v[10:11], v[44:45], v[10:11]
	v_pk_add_f32 v[8:9], v[8:9], v[14:15]
	v_mov_b32_e32 v13, v47
	v_mov_b32_e32 v25, v48
	v_pk_add_f32 v[14:15], v[26:27], v[30:31]
	v_pk_add_f32 v[26:27], v[28:29], v[34:35]
	v_mul_f32_e32 v46, v81, v81
	v_mul_f32_e32 v49, v36, v36
	v_mul_f32_e32 v50, v37, v37
	v_mul_f32_e32 v51, v38, v38
	v_mul_f32_e32 v52, v39, v39
	v_pk_fma_f32 v[32:33], v[64:65], v[64:65], v[40:41] op_sel_hi:[1, 1, 0]
	v_pk_fma_f32 v[40:41], v[66:67], v[66:67], v[42:43] op_sel_hi:[1, 1, 0]
	v_pk_add_f32 v[10:11], v[10:11], v[10:11] op_sel:[0, 1] op_sel_hi:[1, 0]
	v_pk_add_f32 v[8:9], v[8:9], v[8:9] op_sel:[0, 1] op_sel_hi:[1, 0]
	v_pk_add_f32 v[12:13], v[12:13], v[24:25]
	v_pk_add_f32 v[14:15], v[14:15], v[14:15] op_sel:[0, 1] op_sel_hi:[1, 0]
	v_pk_add_f32 v[24:25], v[26:27], v[26:27] op_sel:[0, 1] op_sel_hi:[1, 0]
	v_mov_b32_e32 v33, v51
	v_mov_b32_e32 v41, v52
	v_mov_b32_e32 v11, v43
	v_mov_b32_e32 v9, v46
	v_mov_b32_e32 v15, v49
	v_mov_b32_e32 v25, v50
	v_pk_add_f32 v[26:27], v[32:33], v[40:41]
	v_pk_add_f32 v[8:9], v[10:11], v[8:9]
	v_pk_add_f32 v[10:11], v[14:15], v[24:25]
	v_pk_add_f32 v[8:9], v[8:9], v[12:13]
	v_pk_add_f32 v[10:11], v[10:11], v[26:27]
	v_mov_b32_e32 v13, v8
	v_mov_b32_e32 v12, v10
	v_mov_b32_e32 v8, v11
	v_pk_add_f32 v[8:9], v[12:13], v[8:9]
	v_lshl_add_u64 v[12:13], v[136:137], 0, s[46:47]
	v_lshl_add_u64 v[14:15], v[136:137], 0, s[48:49]
	global_load_dwordx4 v[72:75], v[12:13], off
	global_load_dwordx4 v[60:63], v[12:13], off offset:1024
	global_load_dwordx4 v[56:59], v[12:13], off offset:2048
	global_load_dwordx4 v[52:55], v[12:13], off offset:3072
	global_load_dwordx4 v[48:51], v[14:15], off
	global_load_dwordx4 v[44:47], v[14:15], off offset:1024
	s_waitcnt lgkmcnt(0)
	s_nop 1
	v_add_f32_dpp v8, v8, v8 quad_perm:[1,0,3,2] row_mask:0xf bank_mask:0xf
	v_add_f32_dpp v9, v9, v9 quad_perm:[1,0,3,2] row_mask:0xf bank_mask:0xf
	global_load_dwordx4 v[40:43], v[14:15], off offset:2048
	global_load_dwordx4 v[32:35], v[14:15], off offset:3072
	v_lshl_add_u64 v[24:25], v[140:141], 0, s[44:45]
	s_add_u32 s44, s16, s44
	s_addc_u32 s45, s17, s45
	s_waitcnt lgkmcnt(0)
	s_nop 1
	v_add_f32_dpp v8, v8, v8 quad_perm:[2,3,0,1] row_mask:0xf bank_mask:0xf
	v_add_f32_dpp v9, v9, v9 quad_perm:[2,3,0,1] row_mask:0xf bank_mask:0xf
	s_lshl_b64 s[42:43], s[42:43], 11
	s_waitcnt lgkmcnt(0)
	s_nop 1
	v_add_f32_dpp v8, v8, v8 row_half_mirror row_mask:0xf bank_mask:0xf
	v_add_f32_dpp v9, v9, v9 row_half_mirror row_mask:0xf bank_mask:0xf
	s_waitcnt lgkmcnt(0)
	s_nop 1
	v_add_f32_dpp v8, v8, v8 row_mirror row_mask:0xf bank_mask:0xf
	v_add_f32_dpp v9, v9, v9 row_mirror row_mask:0xf bank_mask:0xf
	ds_bpermute_b32 v11, v188, v9
	ds_bpermute_b32 v10, v188, v8
	s_waitcnt lgkmcnt(0)
	v_pk_add_f32 v[8:9], v[8:9], v[10:11]
	s_waitcnt lgkmcnt(0)
	v_mov_b32_e32 v10, v8
	v_mov_b32_e32 v11, v9
	s_nop 1
	v_permlane32_swap_b32_e32 v10, v8
	v_permlane32_swap_b32_e32 v11, v9
	v_pk_add_f32 v[8:9], v[8:9], v[10:11]
	s_nop 0
	v_pk_fma_f32 v[90:91], v[8:9], s[28:29], v[88:89] op_sel_hi:[1, 0, 0]
	s_waitcnt vmcnt(4)
	v_mul_f32_e32 v99, v53, v53
	v_mul_f32_e32 v8, 0x4b800000, v91
	v_cmp_gt_f32_e32 vcc, s71, v91
	s_waitcnt vmcnt(2)
	v_pk_mul_f32 v[94:95], v[44:45], v[44:45]
	v_mul_f32_e32 v102, v54, v54
	v_cndmask_b32_e32 v8, v91, v8, vcc
	v_rsq_f32_e32 v26, v8
	ds_read_b128 v[8:11], v190
	ds_read_b128 v[12:15], v191
	s_waitcnt vmcnt(1)
	v_mul_f32_e32 v96, v41, v41
	v_mul_f32_e32 v98, v43, v43
	v_mul_f32_e32 v27, 0x45800000, v26
	v_cndmask_b32_e32 v92, v26, v27, vcc
	v_pk_mul_f32 v[18:19], v[18:19], v[92:93] op_sel_hi:[1, 0]
	v_pk_mul_f32 v[16:17], v[16:17], v[92:93] op_sel_hi:[1, 0]
	v_pk_mul_f32 v[18:19], v[110:111], v[18:19]
	v_pk_mul_f32 v[16:17], v[108:109], v[16:17]
	s_waitcnt lgkmcnt(0)
	v_pk_fma_f32 v[18:19], v[14:15], v[18:19], v[10:11]
	v_pk_fma_f32 v[16:17], v[12:13], v[16:17], v[8:9]
	v_pk_mul_f32 v[6:7], v[6:7], v[92:93] op_sel_hi:[1, 0]
	v_cvt_pk_bf16_f32 v16, v16, v17
	v_cvt_pk_bf16_f32 v17, v18, v19
	global_store_dwordx2 v[24:25], v[16:17], off sc1
	ds_read_b128 v[16:19], v192
	ds_read_b128 v[20:23], v193
	v_pk_mul_f32 v[4:5], v[4:5], v[92:93] op_sel_hi:[1, 0]
	v_pk_mul_f32 v[2:3], v[2:3], v[92:93] op_sel_hi:[1, 0]
	v_pk_mul_f32 v[0:1], v[0:1], v[92:93] op_sel_hi:[1, 0]
	v_pk_mul_f32 v[82:83], v[82:83], v[92:93] op_sel_hi:[1, 0]
	v_pk_mul_f32 v[80:81], v[80:81], v[92:93] op_sel_hi:[1, 0]
	v_cmp_gt_f32_e32 vcc, s71, v90
	v_pk_mul_f32 v[92:93], v[46:47], v[46:47]
	v_mul_f32_e32 v103, v55, v55
	s_waitcnt vmcnt(1)
	v_mul_f32_e32 v104, v32, v32
	v_mul_f32_e32 v105, v33, v33
	v_mul_f32_e32 v106, v34, v34
	v_mul_f32_e32 v107, v35, v35
	v_pk_mul_f32 v[4:5], v[112:113], v[4:5]
	v_pk_mul_f32 v[6:7], v[114:115], v[6:7]
	s_waitcnt lgkmcnt(0)
	v_pk_fma_f32 v[4:5], v[20:21], v[4:5], v[16:17]
	v_pk_fma_f32 v[6:7], v[22:23], v[6:7], v[18:19]
	v_cvt_pk_bf16_f32 v4, v4, v5
	v_cvt_pk_bf16_f32 v5, v6, v7
	global_store_dwordx2 v200, v[4:5], s[44:45] sc1
	ds_read_b128 v[24:27], v194
	ds_read_b128 v[28:31], v195
	v_pk_mul_f32 v[0:1], v[116:117], v[0:1]
	v_pk_mul_f32 v[2:3], v[118:119], v[2:3]
	s_waitcnt lgkmcnt(0)
	v_pk_fma_f32 v[0:1], v[28:29], v[0:1], v[24:25]
	v_pk_fma_f32 v[2:3], v[30:31], v[2:3], v[26:27]
	v_cvt_pk_bf16_f32 v0, v0, v1
	v_cvt_pk_bf16_f32 v1, v2, v3
	global_store_dwordx2 v201, v[0:1], s[44:45] sc1
	ds_read_b128 v[0:3], v196
	ds_read_b128 v[4:7], v197
	v_pk_mul_f32 v[80:81], v[80:81], v[120:121]
	v_pk_mul_f32 v[82:83], v[82:83], v[122:123]
	s_waitcnt lgkmcnt(0)
	v_pk_fma_f32 v[80:81], v[80:81], v[4:5], v[0:1]
	v_pk_fma_f32 v[82:83], v[82:83], v[6:7], v[2:3]
	v_cvt_pk_bf16_f32 v80, v80, v81
	v_cvt_pk_bf16_f32 v81, v82, v83
	global_store_dwordx2 v210, v[80:81], s[44:45] sc1
	v_mul_f32_e32 v84, 0x4b800000, v90
	v_cndmask_b32_e32 v84, v90, v84, vcc
	v_rsq_f32_e32 v86, v84
	v_lshl_add_u64 v[84:85], v[140:141], 0, s[42:43]
	s_add_u32 s42, s16, s42
	s_addc_u32 s43, s17, s43
	v_mul_f32_e32 v87, 0x45800000, v86
	v_cndmask_b32_e32 v86, v86, v87, vcc
	v_pk_mul_f32 v[78:79], v[78:79], v[86:87] op_sel_hi:[1, 0]
	v_pk_mul_f32 v[76:77], v[76:77], v[86:87] op_sel_hi:[1, 0]
	v_pk_mul_f32 v[70:71], v[70:71], v[86:87] op_sel_hi:[1, 0]
	v_pk_mul_f32 v[68:69], v[68:69], v[86:87] op_sel_hi:[1, 0]
	v_pk_mul_f32 v[66:67], v[66:67], v[86:87] op_sel_hi:[1, 0]
	v_pk_mul_f32 v[64:65], v[64:65], v[86:87] op_sel_hi:[1, 0]
	v_mul_f32_e32 v87, v52, v52
	v_pk_mul_f32 v[38:39], v[38:39], v[86:87] op_sel_hi:[1, 0]
	v_pk_mul_f32 v[36:37], v[36:37], v[86:87] op_sel_hi:[1, 0]
	v_pk_mul_f32 v[90:91], v[48:49], v[48:49]
	s_lshl_b64 s[40:41], s[40:41], 11
	v_pk_mul_f32 v[76:77], v[108:109], v[76:77]
	v_pk_mul_f32 v[78:79], v[110:111], v[78:79]
	v_pk_fma_f32 v[76:77], v[12:13], v[76:77], v[8:9]
	v_pk_fma_f32 v[78:79], v[14:15], v[78:79], v[10:11]
	v_cvt_pk_bf16_f32 v76, v76, v77
	v_cvt_pk_bf16_f32 v77, v78, v79
	global_store_dwordx2 v[84:85], v[76:77], off sc1
	v_mul_f32_e32 v80, v57, v57
	v_mul_f32_e32 v82, v59, v59
	v_pk_mul_f32 v[84:85], v[50:51], v[50:51]
	v_pk_mul_f32 v[68:69], v[112:113], v[68:69]
	v_pk_mul_f32 v[70:71], v[114:115], v[70:71]
	v_pk_fma_f32 v[68:69], v[20:21], v[68:69], v[16:17]
	v_pk_fma_f32 v[70:71], v[22:23], v[70:71], v[18:19]
	v_cvt_pk_bf16_f32 v68, v68, v69
	v_cvt_pk_bf16_f32 v69, v70, v71
	global_store_dwordx2 v200, v[68:69], s[42:43] sc1
	v_pk_mul_f32 v[76:77], v[62:63], v[62:63]
	v_pk_mul_f32 v[78:79], v[60:61], v[60:61]
	v_pk_mul_f32 v[64:65], v[116:117], v[64:65]
	v_pk_mul_f32 v[66:67], v[118:119], v[66:67]
	v_pk_fma_f32 v[64:65], v[28:29], v[64:65], v[24:25]
	v_pk_fma_f32 v[66:67], v[30:31], v[66:67], v[26:27]
	v_cvt_pk_bf16_f32 v64, v64, v65
	v_cvt_pk_bf16_f32 v65, v66, v67
	global_store_dwordx2 v201, v[64:65], s[42:43] sc1
	v_pk_mul_f32 v[68:69], v[74:75], v[74:75]
	v_pk_mul_f32 v[70:71], v[72:73], v[72:73]
	v_pk_mul_f32 v[36:37], v[120:121], v[36:37]
	v_pk_mul_f32 v[38:39], v[122:123], v[38:39]
	v_pk_fma_f32 v[36:37], v[4:5], v[36:37], v[0:1]
	v_pk_fma_f32 v[38:39], v[6:7], v[38:39], v[2:3]
	v_cvt_pk_bf16_f32 v36, v36, v37
	v_cvt_pk_bf16_f32 v37, v38, v39
	global_store_dwordx2 v210, v[36:37], s[42:43] sc1
	v_pk_mov_b32 v[100:101], v[70:71], v[68:69] op_sel:[1, 0]
	v_mov_b32_e32 v71, v69
	v_pk_mov_b32 v[68:69], v[78:79], v[76:77] op_sel:[1, 0]
	v_mov_b32_e32 v79, v77
	v_pk_fma_f32 v[76:77], v[56:57], v[56:57], v[80:81] op_sel_hi:[1, 1, 0]
	v_pk_fma_f32 v[80:81], v[58:59], v[58:59], v[82:83] op_sel_hi:[1, 1, 0]
	v_pk_mov_b32 v[82:83], v[90:91], v[84:85] op_sel:[1, 0]
	v_mov_b32_e32 v91, v85
	v_pk_mov_b32 v[84:85], v[94:95], v[92:93] op_sel:[1, 0]
	v_mov_b32_e32 v95, v93
	v_pk_add_f32 v[70:71], v[100:101], v[70:71]
	v_pk_add_f32 v[64:65], v[68:69], v[78:79]
	v_pk_add_f32 v[66:67], v[82:83], v[90:91]
	v_pk_add_f32 v[68:69], v[84:85], v[94:95]
	v_pk_fma_f32 v[92:93], v[40:41], v[40:41], v[96:97] op_sel_hi:[1, 1, 0]
	v_pk_fma_f32 v[96:97], v[42:43], v[42:43], v[98:99] op_sel_hi:[1, 1, 0]
	v_pk_add_f32 v[70:71], v[70:71], v[70:71] op_sel:[0, 1] op_sel_hi:[1, 0]
	v_pk_add_f32 v[64:65], v[64:65], v[64:65] op_sel:[0, 1] op_sel_hi:[1, 0]
	v_pk_add_f32 v[66:67], v[66:67], v[66:67] op_sel:[0, 1] op_sel_hi:[1, 0]
	v_pk_add_f32 v[68:69], v[68:69], v[68:69] op_sel:[0, 1] op_sel_hi:[1, 0]
	v_mov_b32_e32 v77, v102
	v_mov_b32_e32 v81, v103
	v_mov_b32_e32 v93, v106
	v_mov_b32_e32 v97, v107
	v_mov_b32_e32 v71, v87
	v_mov_b32_e32 v65, v99
	v_mov_b32_e32 v67, v104
	v_mov_b32_e32 v69, v105
	v_pk_add_f32 v[76:77], v[76:77], v[80:81]
	v_pk_add_f32 v[78:79], v[92:93], v[96:97]
	v_pk_add_f32 v[64:65], v[70:71], v[64:65]
	v_pk_add_f32 v[66:67], v[66:67], v[68:69]
	v_pk_add_f32 v[64:65], v[64:65], v[76:77]
	v_pk_add_f32 v[66:67], v[66:67], v[78:79]
	v_mov_b32_e32 v69, v64
	v_mov_b32_e32 v68, v66
	v_mov_b32_e32 v64, v67
	v_pk_add_f32 v[64:65], v[68:69], v[64:65]
	s_waitcnt lgkmcnt(0)
	s_nop 1
	v_add_f32_dpp v64, v64, v64 quad_perm:[1,0,3,2] row_mask:0xf bank_mask:0xf
	v_add_f32_dpp v65, v65, v65 quad_perm:[1,0,3,2] row_mask:0xf bank_mask:0xf
	s_waitcnt lgkmcnt(0)
	s_nop 1
	v_add_f32_dpp v64, v64, v64 quad_perm:[2,3,0,1] row_mask:0xf bank_mask:0xf
	v_add_f32_dpp v65, v65, v65 quad_perm:[2,3,0,1] row_mask:0xf bank_mask:0xf
	s_waitcnt lgkmcnt(0)
	s_nop 1
	v_add_f32_dpp v64, v64, v64 row_half_mirror row_mask:0xf bank_mask:0xf
	v_add_f32_dpp v65, v65, v65 row_half_mirror row_mask:0xf bank_mask:0xf
	s_waitcnt lgkmcnt(0)
	s_nop 1
	v_add_f32_dpp v64, v64, v64 row_mirror row_mask:0xf bank_mask:0xf
	v_add_f32_dpp v65, v65, v65 row_mirror row_mask:0xf bank_mask:0xf
	ds_bpermute_b32 v67, v188, v65
	ds_bpermute_b32 v66, v188, v64
	s_waitcnt lgkmcnt(0)
	v_pk_add_f32 v[64:65], v[64:65], v[66:67]
	s_waitcnt lgkmcnt(0)
	v_mov_b32_e32 v66, v64
	v_mov_b32_e32 v67, v65
	s_nop 1
	v_permlane32_swap_b32_e32 v66, v64
	v_permlane32_swap_b32_e32 v67, v65
	v_pk_add_f32 v[64:65], v[64:65], v[66:67]
	s_nop 0
	v_pk_fma_f32 v[64:65], v[64:65], s[28:29], v[88:89] op_sel_hi:[1, 0, 0]
	s_nop 0
	v_mul_f32_e32 v66, 0x4b800000, v65
	v_cmp_gt_f32_e32 vcc, s71, v65
	s_nop 1
	v_cndmask_b32_e32 v65, v65, v66, vcc
	v_rsq_f32_e32 v65, v65
	v_lshl_add_u64 v[66:67], v[140:141], 0, s[40:41]
	s_add_u32 s40, s16, s40
	s_addc_u32 s41, s17, s41
	v_mul_f32_e32 v68, 0x45800000, v65
	v_cndmask_b32_e32 v68, v65, v68, vcc
	v_pk_mul_f32 v[70:71], v[74:75], v[68:69] op_sel_hi:[1, 0]
	v_pk_mul_f32 v[72:73], v[72:73], v[68:69] op_sel_hi:[1, 0]
	v_pk_mul_f32 v[38:39], v[110:111], v[70:71]
	v_pk_mul_f32 v[36:37], v[108:109], v[72:73]
	v_pk_fma_f32 v[38:39], v[14:15], v[38:39], v[10:11]
	v_pk_fma_f32 v[36:37], v[12:13], v[36:37], v[8:9]
	v_pk_mul_f32 v[62:63], v[62:63], v[68:69] op_sel_hi:[1, 0]
	v_cvt_pk_bf16_f32 v36, v36, v37
	v_cvt_pk_bf16_f32 v37, v38, v39
	global_store_dwordx2 v[66:67], v[36:37], off sc1
	v_pk_mul_f32 v[60:61], v[60:61], v[68:69] op_sel_hi:[1, 0]
	v_pk_mul_f32 v[58:59], v[58:59], v[68:69] op_sel_hi:[1, 0]
	v_pk_mul_f32 v[56:57], v[56:57], v[68:69] op_sel_hi:[1, 0]
	v_pk_mul_f32 v[54:55], v[54:55], v[68:69] op_sel_hi:[1, 0]
	v_pk_mul_f32 v[52:53], v[52:53], v[68:69] op_sel_hi:[1, 0]
	v_cmp_gt_f32_e32 vcc, s71, v64
	s_lshl_b64 s[38:39], s[38:39], 11
	v_pk_mul_f32 v[36:37], v[112:113], v[60:61]
	v_pk_mul_f32 v[38:39], v[114:115], v[62:63]
	v_pk_fma_f32 v[36:37], v[20:21], v[36:37], v[16:17]
	v_pk_fma_f32 v[38:39], v[22:23], v[38:39], v[18:19]
	v_cvt_pk_bf16_f32 v36, v36, v37
	v_cvt_pk_bf16_f32 v37, v38, v39
	global_store_dwordx2 v200, v[36:37], s[40:41] sc1
	v_pk_mul_f32 v[36:37], v[116:117], v[56:57]
	v_pk_mul_f32 v[38:39], v[118:119], v[58:59]
	v_pk_fma_f32 v[36:37], v[28:29], v[36:37], v[24:25]
	v_pk_fma_f32 v[38:39], v[30:31], v[38:39], v[26:27]
	v_cvt_pk_bf16_f32 v36, v36, v37
	v_cvt_pk_bf16_f32 v37, v38, v39
	global_store_dwordx2 v201, v[36:37], s[40:41] sc1
	v_pk_mul_f32 v[36:37], v[120:121], v[52:53]
	v_pk_mul_f32 v[38:39], v[122:123], v[54:55]
	v_pk_fma_f32 v[36:37], v[4:5], v[36:37], v[0:1]
	v_pk_fma_f32 v[38:39], v[6:7], v[38:39], v[2:3]
	v_cvt_pk_bf16_f32 v36, v36, v37
	v_cvt_pk_bf16_f32 v37, v38, v39
	global_store_dwordx2 v210, v[36:37], s[40:41] sc1
	v_mul_f32_e32 v52, 0x4b800000, v64
	v_cndmask_b32_e32 v52, v64, v52, vcc
	v_rsq_f32_e32 v54, v52
	v_lshl_add_u64 v[52:53], v[140:141], 0, s[38:39]
	s_add_u32 s38, s16, s38
	s_addc_u32 s39, s17, s39
	v_mul_f32_e32 v55, 0x45800000, v54
	v_cndmask_b32_e32 v54, v54, v55, vcc
	v_pk_mul_f32 v[50:51], v[50:51], v[54:55] op_sel_hi:[1, 0]
	v_pk_mul_f32 v[48:49], v[48:49], v[54:55] op_sel_hi:[1, 0]
	v_pk_mul_f32 v[46:47], v[46:47], v[54:55] op_sel_hi:[1, 0]
	v_pk_mul_f32 v[44:45], v[44:45], v[54:55] op_sel_hi:[1, 0]
	v_pk_mul_f32 v[42:43], v[42:43], v[54:55] op_sel_hi:[1, 0]
	v_pk_mul_f32 v[40:41], v[40:41], v[54:55] op_sel_hi:[1, 0]
	v_pk_mul_f32 v[34:35], v[34:35], v[54:55] op_sel_hi:[1, 0]
	v_pk_mul_f32 v[32:33], v[32:33], v[54:55] op_sel_hi:[1, 0]
	s_or_b32 s42, s36, 4
	s_ashr_i32 s43, s42, 31
	s_lshl_b64 s[40:41], s[42:43], 12
	s_lshl_b64 s[42:43], s[42:43], 11
	v_lshl_add_u64 v[104:105], v[140:141], 0, s[42:43]
	v_pk_mul_f32 v[36:37], v[108:109], v[48:49]
	v_pk_mul_f32 v[38:39], v[110:111], v[50:51]
	v_pk_fma_f32 v[36:37], v[12:13], v[36:37], v[8:9]
	v_pk_fma_f32 v[38:39], v[14:15], v[38:39], v[10:11]
	v_cvt_pk_bf16_f32 v36, v36, v37
	v_cvt_pk_bf16_f32 v37, v38, v39
	global_store_dwordx2 v[52:53], v[36:37], off sc1
	v_pk_mul_f32 v[36:37], v[112:113], v[44:45]
	v_pk_mul_f32 v[38:39], v[114:115], v[46:47]
	v_pk_fma_f32 v[36:37], v[20:21], v[36:37], v[16:17]
	v_pk_fma_f32 v[38:39], v[22:23], v[38:39], v[18:19]
	v_cvt_pk_bf16_f32 v36, v36, v37
	v_cvt_pk_bf16_f32 v37, v38, v39
	global_store_dwordx2 v200, v[36:37], s[38:39] sc1
	v_pk_mul_f32 v[36:37], v[116:117], v[40:41]
	v_pk_mul_f32 v[38:39], v[118:119], v[42:43]
	v_pk_fma_f32 v[36:37], v[28:29], v[36:37], v[24:25]
	v_pk_fma_f32 v[38:39], v[30:31], v[38:39], v[26:27]
	v_cvt_pk_bf16_f32 v36, v36, v37
	v_cvt_pk_bf16_f32 v37, v38, v39
	global_store_dwordx2 v201, v[36:37], s[38:39] sc1
	v_lshl_add_u64 v[40:41], v[136:137], 0, s[40:41]
	s_or_b32 s40, s36, 5
	s_ashr_i32 s41, s40, 31
	v_pk_mul_f32 v[32:33], v[120:121], v[32:33]
	v_pk_mul_f32 v[34:35], v[122:123], v[34:35]
	v_pk_fma_f32 v[32:33], v[4:5], v[32:33], v[0:1]
	v_pk_fma_f32 v[34:35], v[6:7], v[34:35], v[2:3]
	v_cvt_pk_bf16_f32 v32, v32, v33
	v_cvt_pk_bf16_f32 v33, v34, v35
	global_store_dwordx2 v210, v[32:33], s[38:39] sc1
	global_load_dwordx4 v[90:93], v[40:41], off
	global_load_dwordx4 v[94:97], v[40:41], off offset:1024
	global_load_dwordx4 v[80:83], v[40:41], off offset:3072
	global_load_dwordx4 v[84:87], v[40:41], off offset:2048
	s_lshl_b64 s[38:39], s[40:41], 12
	v_lshl_add_u64 v[32:33], v[136:137], 0, s[38:39]
	global_load_dwordx4 v[76:79], v[32:33], off
	global_load_dwordx4 v[72:75], v[32:33], off offset:1024
	global_load_dwordx4 v[36:39], v[32:33], off offset:3072
	global_load_dwordx4 v[68:71], v[32:33], off offset:2048
	s_or_b32 s38, s36, 6
	s_or_b32 s36, s36, 7
	s_ashr_i32 s39, s38, 31
	s_ashr_i32 s37, s36, 31
	s_lshl_b64 s[44:45], s[38:39], 12
	s_lshl_b64 s[46:47], s[36:37], 12
	s_add_u32 s42, s16, s42
	s_addc_u32 s43, s17, s43
	s_lshl_b64 s[40:41], s[40:41], 11
	s_waitcnt vmcnt(7)
	v_pk_mul_f32 v[32:33], v[92:93], v[92:93]
	v_pk_mul_f32 v[34:35], v[90:91], v[90:91]
	s_waitcnt vmcnt(6)
	v_pk_mul_f32 v[40:41], v[96:97], v[96:97]
	v_pk_mul_f32 v[42:43], v[94:95], v[94:95]
	s_waitcnt vmcnt(4)
	v_mul_f32_e32 v44, v85, v85
	v_mul_f32_e32 v46, v87, v87
	s_waitcnt vmcnt(3)
	v_pk_mul_f32 v[48:49], v[78:79], v[78:79]
	v_pk_mul_f32 v[50:51], v[76:77], v[76:77]
	s_waitcnt vmcnt(2)
	v_pk_mul_f32 v[52:53], v[74:75], v[74:75]
	v_pk_mul_f32 v[54:55], v[72:73], v[72:73]
	v_mul_f32_e32 v63, v82, v82
	v_mul_f32_e32 v64, v83, v83
	v_pk_mov_b32 v[60:61], v[34:35], v[32:33] op_sel:[1, 0]
	v_mov_b32_e32 v35, v33
	v_pk_mov_b32 v[32:33], v[42:43], v[40:41] op_sel:[1, 0]
	v_mov_b32_e32 v43, v41
	v_pk_fma_f32 v[40:41], v[84:85], v[84:85], v[44:45] op_sel_hi:[1, 1, 0]
	v_pk_fma_f32 v[44:45], v[86:87], v[86:87], v[46:47] op_sel_hi:[1, 1, 0]
	v_pk_mov_b32 v[46:47], v[50:51], v[48:49] op_sel:[1, 0]
	v_mov_b32_e32 v51, v49
	v_pk_mov_b32 v[48:49], v[54:55], v[52:53] op_sel:[1, 0]
	v_mov_b32_e32 v55, v53
	v_mul_f32_e32 v59, v80, v80
	s_waitcnt vmcnt(0)
	v_mul_f32_e32 v56, v69, v69
	v_mul_f32_e32 v58, v71, v71
	v_pk_add_f32 v[34:35], v[60:61], v[34:35]
	v_pk_add_f32 v[32:33], v[32:33], v[42:43]
	v_mov_b32_e32 v41, v63
	v_mov_b32_e32 v45, v64
	v_pk_add_f32 v[42:43], v[46:47], v[50:51]
	v_pk_add_f32 v[46:47], v[48:49], v[54:55]
	v_mul_f32_e32 v62, v81, v81
	v_mul_f32_e32 v65, v36, v36
	v_mul_f32_e32 v66, v37, v37
	v_mul_f32_e32 v67, v38, v38
	v_mul_f32_e32 v102, v39, v39
	v_pk_fma_f32 v[52:53], v[68:69], v[68:69], v[56:57] op_sel_hi:[1, 1, 0]
	v_pk_fma_f32 v[56:57], v[70:71], v[70:71], v[58:59] op_sel_hi:[1, 1, 0]
	v_pk_add_f32 v[34:35], v[34:35], v[34:35] op_sel:[0, 1] op_sel_hi:[1, 0]
	v_pk_add_f32 v[32:33], v[32:33], v[32:33] op_sel:[0, 1] op_sel_hi:[1, 0]
	v_pk_add_f32 v[40:41], v[40:41], v[44:45]
	v_pk_add_f32 v[42:43], v[42:43], v[42:43] op_sel:[0, 1] op_sel_hi:[1, 0]
	v_pk_add_f32 v[44:45], v[46:47], v[46:47] op_sel:[0, 1] op_sel_hi:[1, 0]
	v_mov_b32_e32 v53, v67
	v_mov_b32_e32 v57, v102
	v_mov_b32_e32 v35, v59
	v_mov_b32_e32 v33, v62
	v_mov_b32_e32 v43, v65
	v_mov_b32_e32 v45, v66
	v_pk_add_f32 v[46:47], v[52:53], v[56:57]
	v_pk_add_f32 v[32:33], v[34:35], v[32:33]
	v_pk_add_f32 v[34:35], v[42:43], v[44:45]
	v_pk_add_f32 v[32:33], v[32:33], v[40:41]
	v_pk_add_f32 v[34:35], v[34:35], v[46:47]
	v_mov_b32_e32 v41, v32
	v_mov_b32_e32 v40, v34
	v_mov_b32_e32 v32, v35
	v_pk_add_f32 v[32:33], v[40:41], v[32:33]
	v_lshl_add_u64 v[40:41], v[136:137], 0, s[44:45]
	v_lshl_add_u64 v[102:103], v[136:137], 0, s[46:47]
	global_load_dwordx4 v[64:67], v[40:41], off
	global_load_dwordx4 v[60:63], v[40:41], off offset:1024
	global_load_dwordx4 v[56:59], v[40:41], off offset:2048
	global_load_dwordx4 v[52:55], v[40:41], off offset:3072
	s_waitcnt lgkmcnt(0)
	s_nop 1
	v_add_f32_dpp v32, v32, v32 quad_perm:[1,0,3,2] row_mask:0xf bank_mask:0xf
	v_add_f32_dpp v33, v33, v33 quad_perm:[1,0,3,2] row_mask:0xf bank_mask:0xf
	s_waitcnt lgkmcnt(0)
	s_nop 1
	v_add_f32_dpp v32, v32, v32 quad_perm:[2,3,0,1] row_mask:0xf bank_mask:0xf
	v_add_f32_dpp v33, v33, v33 quad_perm:[2,3,0,1] row_mask:0xf bank_mask:0xf
	s_waitcnt lgkmcnt(0)
	s_nop 1
	v_add_f32_dpp v32, v32, v32 row_half_mirror row_mask:0xf bank_mask:0xf
	v_add_f32_dpp v33, v33, v33 row_half_mirror row_mask:0xf bank_mask:0xf
	s_waitcnt lgkmcnt(0)
	s_nop 1
	v_add_f32_dpp v32, v32, v32 row_mirror row_mask:0xf bank_mask:0xf
	v_add_f32_dpp v33, v33, v33 row_mirror row_mask:0xf bank_mask:0xf
	ds_bpermute_b32 v35, v188, v33
	ds_bpermute_b32 v34, v188, v32
	s_waitcnt lgkmcnt(0)
	v_pk_add_f32 v[32:33], v[32:33], v[34:35]
	s_waitcnt lgkmcnt(0)
	v_mov_b32_e32 v34, v32
	v_mov_b32_e32 v35, v33
	s_nop 1
	v_permlane32_swap_b32_e32 v34, v32
	v_permlane32_swap_b32_e32 v35, v33
	v_pk_add_f32 v[32:33], v[32:33], v[34:35]
	s_nop 0
	v_pk_fma_f32 v[106:107], v[32:33], s[28:29], v[88:89] op_sel_hi:[1, 0, 0]
	s_nop 0
	v_mul_f32_e32 v32, 0x4b800000, v107
	v_cmp_gt_f32_e32 vcc, s71, v107
	s_nop 1
	v_cndmask_b32_e32 v32, v107, v32, vcc
	v_rsq_f32_e32 v107, v32
	global_load_dwordx4 v[48:51], v[102:103], off
	global_load_dwordx4 v[44:47], v[102:103], off offset:1024
	global_load_dwordx4 v[40:43], v[102:103], off offset:2048
	global_load_dwordx4 v[32:35], v[102:103], off offset:3072
	v_mul_f32_e32 v102, 0x45800000, v107
	v_cndmask_b32_e32 v102, v107, v102, vcc
	v_pk_mul_f32 v[92:93], v[92:93], v[102:103] op_sel_hi:[1, 0]
	v_pk_mul_f32 v[90:91], v[90:91], v[102:103] op_sel_hi:[1, 0]
	v_pk_mul_f32 v[92:93], v[110:111], v[92:93]
	v_pk_mul_f32 v[90:91], v[108:109], v[90:91]
	v_pk_fma_f32 v[92:93], v[14:15], v[92:93], v[10:11]
	v_pk_fma_f32 v[90:91], v[12:13], v[90:91], v[8:9]
	v_pk_mul_f32 v[96:97], v[96:97], v[102:103] op_sel_hi:[1, 0]
	v_cvt_pk_bf16_f32 v90, v90, v91
	v_cvt_pk_bf16_f32 v91, v92, v93
	global_store_dwordx2 v[104:105], v[90:91], off sc1
	v_pk_mul_f32 v[94:95], v[94:95], v[102:103] op_sel_hi:[1, 0]
	v_pk_mul_f32 v[86:87], v[86:87], v[102:103] op_sel_hi:[1, 0]
	v_pk_mul_f32 v[84:85], v[84:85], v[102:103] op_sel_hi:[1, 0]
	v_pk_mul_f32 v[82:83], v[82:83], v[102:103] op_sel_hi:[1, 0]
	v_pk_mul_f32 v[80:81], v[80:81], v[102:103] op_sel_hi:[1, 0]
	v_cmp_gt_f32_e32 vcc, s71, v106
	s_waitcnt vmcnt(5)
	v_mul_f32_e32 v99, v53, v53
	v_mul_f32_e32 v102, v54, v54
	v_mul_f32_e32 v103, v55, v55
	s_waitcnt vmcnt(2)
	v_mul_f32_e32 v98, v43, v43
	s_waitcnt vmcnt(1)
	v_mul_f32_e32 v104, v32, v32
	v_mul_f32_e32 v105, v33, v33
	v_mul_f32_e32 v107, v35, v35
	v_pk_mul_f32 v[90:91], v[112:113], v[94:95]
	v_pk_mul_f32 v[92:93], v[114:115], v[96:97]
	v_pk_fma_f32 v[90:91], v[20:21], v[90:91], v[16:17]
	v_pk_fma_f32 v[92:93], v[22:23], v[92:93], v[18:19]
	v_cvt_pk_bf16_f32 v90, v90, v91
	v_cvt_pk_bf16_f32 v91, v92, v93
	global_store_dwordx2 v200, v[90:91], s[42:43] sc1
	v_pk_mul_f32 v[94:95], v[44:45], v[44:45]
	v_mul_f32_e32 v96, v41, v41
	v_pk_mul_f32 v[84:85], v[116:117], v[84:85]
	v_pk_mul_f32 v[86:87], v[118:119], v[86:87]
	v_pk_fma_f32 v[84:85], v[28:29], v[84:85], v[24:25]
	v_pk_fma_f32 v[86:87], v[30:31], v[86:87], v[26:27]
	v_cvt_pk_bf16_f32 v84, v84, v85
	v_cvt_pk_bf16_f32 v85, v86, v87
	global_store_dwordx2 v201, v[84:85], s[42:43] sc1
	v_pk_mul_f32 v[90:91], v[48:49], v[48:49]
	v_pk_mul_f32 v[92:93], v[46:47], v[46:47]
	v_pk_mul_f32 v[80:81], v[120:121], v[80:81]
	v_pk_mul_f32 v[82:83], v[122:123], v[82:83]
	v_pk_fma_f32 v[80:81], v[4:5], v[80:81], v[0:1]
	v_pk_fma_f32 v[82:83], v[6:7], v[82:83], v[2:3]
	v_cvt_pk_bf16_f32 v80, v80, v81
	v_cvt_pk_bf16_f32 v81, v82, v83
	global_store_dwordx2 v210, v[80:81], s[42:43] sc1
	v_mul_f32_e32 v84, 0x4b800000, v106
	v_cndmask_b32_e32 v84, v106, v84, vcc
	v_rsq_f32_e32 v86, v84
	v_lshl_add_u64 v[84:85], v[140:141], 0, s[40:41]
	s_add_u32 s40, s16, s40
	s_addc_u32 s41, s17, s41
	v_mul_f32_e32 v87, 0x45800000, v86
	v_cndmask_b32_e32 v86, v86, v87, vcc
	v_pk_mul_f32 v[78:79], v[78:79], v[86:87] op_sel_hi:[1, 0]
	v_pk_mul_f32 v[76:77], v[76:77], v[86:87] op_sel_hi:[1, 0]
	v_pk_mul_f32 v[74:75], v[74:75], v[86:87] op_sel_hi:[1, 0]
	v_pk_mul_f32 v[72:73], v[72:73], v[86:87] op_sel_hi:[1, 0]
	v_pk_mul_f32 v[70:71], v[70:71], v[86:87] op_sel_hi:[1, 0]
	v_pk_mul_f32 v[68:69], v[68:69], v[86:87] op_sel_hi:[1, 0]
	v_mul_f32_e32 v87, v52, v52
	v_pk_mul_f32 v[38:39], v[38:39], v[86:87] op_sel_hi:[1, 0]
	v_pk_mul_f32 v[36:37], v[36:37], v[86:87] op_sel_hi:[1, 0]
	v_mul_f32_e32 v106, v34, v34
	s_lshl_b64 s[38:39], s[38:39], 11
	v_pk_mul_f32 v[76:77], v[108:109], v[76:77]
	v_pk_mul_f32 v[78:79], v[110:111], v[78:79]
	v_pk_fma_f32 v[76:77], v[12:13], v[76:77], v[8:9]
	v_pk_fma_f32 v[78:79], v[14:15], v[78:79], v[10:11]
	v_cvt_pk_bf16_f32 v76, v76, v77
	v_cvt_pk_bf16_f32 v77, v78, v79
	global_store_dwordx2 v[84:85], v[76:77], off sc1
	v_mul_f32_e32 v80, v57, v57
	v_mul_f32_e32 v82, v59, v59
	v_pk_mul_f32 v[84:85], v[50:51], v[50:51]
	v_pk_mul_f32 v[72:73], v[112:113], v[72:73]
	v_pk_mul_f32 v[74:75], v[114:115], v[74:75]
	v_pk_fma_f32 v[72:73], v[20:21], v[72:73], v[16:17]
	v_pk_fma_f32 v[74:75], v[22:23], v[74:75], v[18:19]
	v_cvt_pk_bf16_f32 v72, v72, v73
	v_cvt_pk_bf16_f32 v73, v74, v75
	global_store_dwordx2 v200, v[72:73], s[40:41] sc1
	v_pk_mul_f32 v[76:77], v[62:63], v[62:63]
	v_pk_mul_f32 v[78:79], v[60:61], v[60:61]
	v_pk_mul_f32 v[68:69], v[116:117], v[68:69]
	v_pk_mul_f32 v[70:71], v[118:119], v[70:71]
	v_pk_fma_f32 v[68:69], v[28:29], v[68:69], v[24:25]
	v_pk_fma_f32 v[70:71], v[30:31], v[70:71], v[26:27]
	v_cvt_pk_bf16_f32 v68, v68, v69
	v_cvt_pk_bf16_f32 v69, v70, v71
	global_store_dwordx2 v201, v[68:69], s[40:41] sc1
	v_pk_mul_f32 v[72:73], v[66:67], v[66:67]
	v_pk_mul_f32 v[74:75], v[64:65], v[64:65]
	v_pk_mul_f32 v[36:37], v[120:121], v[36:37]
	v_pk_mul_f32 v[38:39], v[122:123], v[38:39]
	v_pk_fma_f32 v[36:37], v[4:5], v[36:37], v[0:1]
	v_pk_fma_f32 v[38:39], v[6:7], v[38:39], v[2:3]
	v_cvt_pk_bf16_f32 v36, v36, v37
	v_cvt_pk_bf16_f32 v37, v38, v39
	global_store_dwordx2 v210, v[36:37], s[40:41] sc1
	v_pk_mov_b32 v[100:101], v[74:75], v[72:73] op_sel:[1, 0]
	v_mov_b32_e32 v75, v73
	v_pk_mov_b32 v[72:73], v[78:79], v[76:77] op_sel:[1, 0]
	v_mov_b32_e32 v79, v77
	v_pk_fma_f32 v[76:77], v[56:57], v[56:57], v[80:81] op_sel_hi:[1, 1, 0]
	v_pk_fma_f32 v[80:81], v[58:59], v[58:59], v[82:83] op_sel_hi:[1, 1, 0]
	v_pk_mov_b32 v[82:83], v[90:91], v[84:85] op_sel:[1, 0]
	v_mov_b32_e32 v91, v85
	v_pk_mov_b32 v[84:85], v[94:95], v[92:93] op_sel:[1, 0]
	v_mov_b32_e32 v95, v93
	v_pk_add_f32 v[74:75], v[100:101], v[74:75]
	v_pk_add_f32 v[68:69], v[72:73], v[78:79]
	v_pk_add_f32 v[70:71], v[82:83], v[90:91]
	v_pk_add_f32 v[72:73], v[84:85], v[94:95]
	v_pk_fma_f32 v[92:93], v[40:41], v[40:41], v[96:97] op_sel_hi:[1, 1, 0]
	v_pk_fma_f32 v[96:97], v[42:43], v[42:43], v[98:99] op_sel_hi:[1, 1, 0]
	v_pk_add_f32 v[74:75], v[74:75], v[74:75] op_sel:[0, 1] op_sel_hi:[1, 0]
	v_pk_add_f32 v[68:69], v[68:69], v[68:69] op_sel:[0, 1] op_sel_hi:[1, 0]
	v_pk_add_f32 v[70:71], v[70:71], v[70:71] op_sel:[0, 1] op_sel_hi:[1, 0]
	v_pk_add_f32 v[72:73], v[72:73], v[72:73] op_sel:[0, 1] op_sel_hi:[1, 0]
	v_mov_b32_e32 v77, v102
	v_mov_b32_e32 v81, v103
	v_mov_b32_e32 v93, v106
	v_mov_b32_e32 v97, v107
	v_mov_b32_e32 v75, v87
	v_mov_b32_e32 v69, v99
	v_mov_b32_e32 v71, v104
	v_mov_b32_e32 v73, v105
	v_pk_add_f32 v[76:77], v[76:77], v[80:81]
	v_pk_add_f32 v[78:79], v[92:93], v[96:97]
	v_pk_add_f32 v[68:69], v[74:75], v[68:69]
	v_pk_add_f32 v[70:71], v[70:71], v[72:73]
	v_pk_add_f32 v[68:69], v[68:69], v[76:77]
	v_pk_add_f32 v[70:71], v[70:71], v[78:79]
	v_mov_b32_e32 v73, v68
	v_mov_b32_e32 v72, v70
	v_mov_b32_e32 v68, v71
	v_pk_add_f32 v[68:69], v[72:73], v[68:69]
	s_waitcnt lgkmcnt(0)
	s_nop 1
	v_add_f32_dpp v68, v68, v68 quad_perm:[1,0,3,2] row_mask:0xf bank_mask:0xf
	v_add_f32_dpp v69, v69, v69 quad_perm:[1,0,3,2] row_mask:0xf bank_mask:0xf
	s_waitcnt lgkmcnt(0)
	s_nop 1
	v_add_f32_dpp v68, v68, v68 quad_perm:[2,3,0,1] row_mask:0xf bank_mask:0xf
	v_add_f32_dpp v69, v69, v69 quad_perm:[2,3,0,1] row_mask:0xf bank_mask:0xf
	s_waitcnt lgkmcnt(0)
	s_nop 1
	v_add_f32_dpp v68, v68, v68 row_half_mirror row_mask:0xf bank_mask:0xf
	v_add_f32_dpp v69, v69, v69 row_half_mirror row_mask:0xf bank_mask:0xf
	s_waitcnt lgkmcnt(0)
	s_nop 1
	v_add_f32_dpp v68, v68, v68 row_mirror row_mask:0xf bank_mask:0xf
	v_add_f32_dpp v69, v69, v69 row_mirror row_mask:0xf bank_mask:0xf
	ds_bpermute_b32 v71, v188, v69
	ds_bpermute_b32 v70, v188, v68
	s_waitcnt lgkmcnt(0)
	v_pk_add_f32 v[68:69], v[68:69], v[70:71]
	s_waitcnt lgkmcnt(0)
	v_mov_b32_e32 v70, v68
	v_mov_b32_e32 v71, v69
	s_nop 1
	v_permlane32_swap_b32_e32 v70, v68
	v_permlane32_swap_b32_e32 v71, v69
	v_pk_add_f32 v[68:69], v[68:69], v[70:71]
	s_nop 0
	v_pk_fma_f32 v[68:69], v[68:69], s[28:29], v[88:89] op_sel_hi:[1, 0, 0]
	s_nop 0
	v_mul_f32_e32 v70, 0x4b800000, v69
	v_cmp_gt_f32_e32 vcc, s71, v69
	s_nop 1
	v_cndmask_b32_e32 v69, v69, v70, vcc
	v_rsq_f32_e32 v69, v69
	v_lshl_add_u64 v[70:71], v[140:141], 0, s[38:39]
	s_add_u32 s38, s16, s38
	s_addc_u32 s39, s17, s39
	v_mul_f32_e32 v72, 0x45800000, v69
	v_cndmask_b32_e32 v72, v69, v72, vcc
	v_pk_mul_f32 v[66:67], v[66:67], v[72:73] op_sel_hi:[1, 0]
	v_pk_mul_f32 v[64:65], v[64:65], v[72:73] op_sel_hi:[1, 0]
	v_pk_mul_f32 v[38:39], v[110:111], v[66:67]
	v_pk_mul_f32 v[36:37], v[108:109], v[64:65]
	v_pk_fma_f32 v[38:39], v[14:15], v[38:39], v[10:11]
	v_pk_fma_f32 v[36:37], v[12:13], v[36:37], v[8:9]
	v_pk_mul_f32 v[62:63], v[62:63], v[72:73] op_sel_hi:[1, 0]
	v_cvt_pk_bf16_f32 v36, v36, v37
	v_cvt_pk_bf16_f32 v37, v38, v39
	global_store_dwordx2 v[70:71], v[36:37], off sc1
	v_pk_mul_f32 v[60:61], v[60:61], v[72:73] op_sel_hi:[1, 0]
	v_pk_mul_f32 v[58:59], v[58:59], v[72:73] op_sel_hi:[1, 0]
	v_pk_mul_f32 v[56:57], v[56:57], v[72:73] op_sel_hi:[1, 0]
	v_pk_mul_f32 v[54:55], v[54:55], v[72:73] op_sel_hi:[1, 0]
	v_pk_mul_f32 v[52:53], v[52:53], v[72:73] op_sel_hi:[1, 0]
	v_cmp_gt_f32_e32 vcc, s71, v68
	s_lshl_b64 s[36:37], s[36:37], 11
	v_pk_mul_f32 v[36:37], v[112:113], v[60:61]
	v_pk_mul_f32 v[38:39], v[114:115], v[62:63]
	v_pk_fma_f32 v[36:37], v[20:21], v[36:37], v[16:17]
	v_pk_fma_f32 v[38:39], v[22:23], v[38:39], v[18:19]
	v_cvt_pk_bf16_f32 v36, v36, v37
	v_cvt_pk_bf16_f32 v37, v38, v39
	global_store_dwordx2 v200, v[36:37], s[38:39] sc1
	v_pk_mul_f32 v[36:37], v[116:117], v[56:57]
	v_pk_mul_f32 v[38:39], v[118:119], v[58:59]
	v_pk_fma_f32 v[36:37], v[28:29], v[36:37], v[24:25]
	v_pk_fma_f32 v[38:39], v[30:31], v[38:39], v[26:27]
	v_cvt_pk_bf16_f32 v36, v36, v37
	v_cvt_pk_bf16_f32 v37, v38, v39
	global_store_dwordx2 v201, v[36:37], s[38:39] sc1
	v_pk_mul_f32 v[36:37], v[120:121], v[52:53]
	v_pk_mul_f32 v[38:39], v[122:123], v[54:55]
	v_pk_fma_f32 v[36:37], v[4:5], v[36:37], v[0:1]
	v_pk_fma_f32 v[38:39], v[6:7], v[38:39], v[2:3]
	v_cvt_pk_bf16_f32 v36, v36, v37
	v_cvt_pk_bf16_f32 v37, v38, v39
	global_store_dwordx2 v210, v[36:37], s[38:39] sc1
	v_mul_f32_e32 v52, 0x4b800000, v68
	v_cndmask_b32_e32 v52, v68, v52, vcc
	v_rsq_f32_e32 v54, v52
	v_lshl_add_u64 v[52:53], v[140:141], 0, s[36:37]
	s_add_u32 s36, s16, s36
	s_addc_u32 s37, s17, s37
	v_mul_f32_e32 v55, 0x45800000, v54
	v_cndmask_b32_e32 v54, v54, v55, vcc
	v_pk_mul_f32 v[50:51], v[50:51], v[54:55] op_sel_hi:[1, 0]
	v_pk_mul_f32 v[48:49], v[48:49], v[54:55] op_sel_hi:[1, 0]
	s_and_b64 vcc, exec, s[8:9]
	s_mov_b64 s[8:9], -1
	v_pk_mul_f32 v[36:37], v[108:109], v[48:49]
	v_pk_mul_f32 v[38:39], v[110:111], v[50:51]
	v_pk_fma_f32 v[8:9], v[12:13], v[36:37], v[8:9]
	v_pk_fma_f32 v[10:11], v[14:15], v[38:39], v[10:11]
	v_cvt_pk_bf16_f32 v8, v8, v9
	v_cvt_pk_bf16_f32 v9, v10, v11
	global_store_dwordx2 v[52:53], v[8:9], off sc1
	v_pk_mul_f32 v[12:13], v[46:47], v[54:55] op_sel_hi:[1, 0]
	v_pk_mul_f32 v[14:15], v[44:45], v[54:55] op_sel_hi:[1, 0]
	v_pk_mul_f32 v[10:11], v[114:115], v[12:13]
	v_pk_mul_f32 v[8:9], v[112:113], v[14:15]
	v_pk_fma_f32 v[10:11], v[22:23], v[10:11], v[18:19]
	v_pk_fma_f32 v[8:9], v[20:21], v[8:9], v[16:17]
	v_pk_mul_f32 v[12:13], v[42:43], v[54:55] op_sel_hi:[1, 0]
	v_cvt_pk_bf16_f32 v8, v8, v9
	v_cvt_pk_bf16_f32 v9, v10, v11
	global_store_dwordx2 v200, v[8:9], s[36:37] sc1
	v_pk_mul_f32 v[14:15], v[40:41], v[54:55] op_sel_hi:[1, 0]
	v_pk_mul_f32 v[10:11], v[118:119], v[12:13]
	v_pk_mul_f32 v[8:9], v[116:117], v[14:15]
	v_pk_fma_f32 v[10:11], v[30:31], v[10:11], v[26:27]
	v_pk_fma_f32 v[8:9], v[28:29], v[8:9], v[24:25]
	v_pk_mul_f32 v[12:13], v[34:35], v[54:55] op_sel_hi:[1, 0]
	v_cvt_pk_bf16_f32 v8, v8, v9
	v_cvt_pk_bf16_f32 v9, v10, v11
	global_store_dwordx2 v201, v[8:9], s[36:37] sc1
	v_pk_mul_f32 v[14:15], v[32:33], v[54:55] op_sel_hi:[1, 0]
	v_pk_mul_f32 v[10:11], v[122:123], v[12:13]
	v_pk_mul_f32 v[8:9], v[120:121], v[14:15]
	v_pk_fma_f32 v[2:3], v[6:7], v[10:11], v[2:3]
	v_pk_fma_f32 v[0:1], v[4:5], v[8:9], v[0:1]
	s_nop 0
	v_cvt_pk_bf16_f32 v0, v0, v1
	v_cvt_pk_bf16_f32 v1, v2, v3
	global_store_dwordx2 v210, v[0:1], s[36:37] sc1
	s_cbranch_vccnz .LBB0_1633
	s_andn2_b64 vcc, exec, s[10:11]
	s_cbranch_vccnz .LBB0_1632
	s_barrier
	s_branch .LBB0_1632

.LBB0_2361:
	v_lshl_or_b32 v172, s42, 8, v198
	v_add_u32_e32 v156, 0x1400, v172
	v_ashrrev_i32_e32 v157, 31, v156
	s_ashr_i32 s55, s44, 3
	v_lshlrev_b64 v[160:161], 2, v[156:157]
	s_add_i32 s56, s55, 64
	v_lshl_add_u64 v[164:165], s[2:3], 0, v[160:161]
	v_lshl_add_u64 v[156:157], s[18:19], 0, v[160:161]
	v_mad_i64_i32 v[160:161], s[46:47], s56, v211, v[164:165]
	global_load_dwordx4 v[156:159], v[156:157], off
	s_add_i32 s54, s55, 0x48
	s_add_i32 s53, s55, 0x50
	s_add_i32 s52, s55, 0x58
	s_add_i32 s81, s55, 0x60
	s_add_i32 s80, s55, 0x68
	s_add_i32 s43, s55, 0x70
	s_add_i32 s37, s55, 0x78
	s_lshl_b32 s35, s44, 8
	global_load_dwordx4 v[160:163], v[160:161], off
	v_mad_i64_i32 v[212:213], s[46:47], s54, v211, v[164:165]
	global_load_dwordx4 v[212:215], v[212:213], off
	v_mad_i64_i32 v[216:217], s[46:47], s53, v211, v[164:165]
	global_load_dwordx4 v[216:219], v[216:217], off
	v_mad_i64_i32 v[220:221], s[46:47], s52, v211, v[164:165]
	global_load_dwordx4 v[220:223], v[220:221], off
	v_mad_i64_i32 v[224:225], s[46:47], s81, v211, v[164:165]
	global_load_dwordx4 v[224:227], v[224:225], off
	v_mad_i64_i32 v[228:229], s[46:47], s80, v211, v[164:165]
	global_load_dwordx4 v[228:231], v[228:229], off
	v_mad_i64_i32 v[232:233], s[46:47], s43, v211, v[164:165]
	global_load_dwordx4 v[232:235], v[232:233], off
	v_mad_i64_i32 v[236:237], s[46:47], s37, v211, v[164:165]
	global_load_dwordx4 v[236:239], v[236:237], off
	v_ashrrev_i32_e32 v173, 31, v172
	v_readfirstlane_b32 s82, v180
	s_waitcnt vmcnt(7)
	v_pk_add_f32 v[160:161], v[156:157], v[160:161]
	v_pk_add_f32 v[162:163], v[158:159], v[162:163]
	s_waitcnt vmcnt(6)
	v_pk_add_f32 v[160:161], v[160:161], v[212:213]
	v_pk_add_f32 v[162:163], v[162:163], v[214:215]
	s_waitcnt vmcnt(5)
	v_pk_add_f32 v[160:161], v[160:161], v[216:217]
	v_pk_add_f32 v[162:163], v[162:163], v[218:219]
	s_waitcnt vmcnt(4)
	v_pk_add_f32 v[160:161], v[160:161], v[220:221]
	v_pk_add_f32 v[162:163], v[162:163], v[222:223]
	s_waitcnt vmcnt(3)
	v_pk_add_f32 v[160:161], v[160:161], v[224:225]
	v_pk_add_f32 v[162:163], v[162:163], v[226:227]
	s_waitcnt vmcnt(2)
	v_pk_add_f32 v[160:161], v[160:161], v[228:229]
	v_pk_add_f32 v[162:163], v[162:163], v[230:231]
	s_waitcnt vmcnt(1)
	v_pk_add_f32 v[166:167], v[160:161], v[232:233]
	v_pk_add_f32 v[162:163], v[162:163], v[234:235]
	s_waitcnt vmcnt(0)
	v_pk_add_f32 v[156:157], v[162:163], v[238:239]
	v_add_u32_e32 v160, 0x1410, v172
	v_ashrrev_i32_e32 v161, 31, v160
	v_lshlrev_b64 v[164:165], 2, v[160:161]
	v_lshl_add_u64 v[168:169], s[2:3], 0, v[164:165]
	v_lshl_add_u64 v[160:161], s[18:19], 0, v[164:165]
	v_mad_i64_i32 v[164:165], s[46:47], s56, v211, v[168:169]
	v_pk_add_f32 v[158:159], v[166:167], v[236:237]
	global_load_dwordx4 v[160:163], v[160:161], off
	global_load_dwordx4 v[164:167], v[164:165], off
	v_mad_i64_i32 v[212:213], s[46:47], s54, v211, v[168:169]
	global_load_dwordx4 v[212:215], v[212:213], off
	v_mad_i64_i32 v[216:217], s[46:47], s53, v211, v[168:169]
	global_load_dwordx4 v[216:219], v[216:217], off
	v_mad_i64_i32 v[220:221], s[46:47], s52, v211, v[168:169]
	global_load_dwordx4 v[220:223], v[220:221], off
	v_mad_i64_i32 v[224:225], s[46:47], s81, v211, v[168:169]
	global_load_dwordx4 v[224:227], v[224:225], off
	v_mad_i64_i32 v[228:229], s[46:47], s80, v211, v[168:169]
	global_load_dwordx4 v[228:231], v[228:229], off
	v_mad_i64_i32 v[232:233], s[46:47], s43, v211, v[168:169]
	global_load_dwordx4 v[232:235], v[232:233], off
	v_mad_i64_i32 v[236:237], s[46:47], s37, v211, v[168:169]
	global_load_dwordx4 v[236:239], v[236:237], off
	s_waitcnt vmcnt(7)
	v_pk_add_f32 v[164:165], v[160:161], v[164:165]
	v_pk_add_f32 v[166:167], v[162:163], v[166:167]
	s_waitcnt vmcnt(6)
	v_pk_add_f32 v[164:165], v[164:165], v[212:213]
	v_pk_add_f32 v[166:167], v[166:167], v[214:215]
	s_waitcnt vmcnt(5)
	v_pk_add_f32 v[164:165], v[164:165], v[216:217]
	v_pk_add_f32 v[166:167], v[166:167], v[218:219]
	s_waitcnt vmcnt(4)
	v_pk_add_f32 v[164:165], v[164:165], v[220:221]
	v_pk_add_f32 v[166:167], v[166:167], v[222:223]
	s_waitcnt vmcnt(3)
	v_pk_add_f32 v[164:165], v[164:165], v[224:225]
	v_pk_add_f32 v[166:167], v[166:167], v[226:227]
	s_waitcnt vmcnt(2)
	v_pk_add_f32 v[164:165], v[164:165], v[228:229]
	v_pk_add_f32 v[166:167], v[166:167], v[230:231]
	s_waitcnt vmcnt(1)
	v_pk_add_f32 v[170:171], v[164:165], v[232:233]
	v_pk_add_f32 v[166:167], v[166:167], v[234:235]
	s_waitcnt vmcnt(0)
	v_pk_add_f32 v[160:161], v[166:167], v[238:239]
	v_add_u32_e32 v164, 0x1480, v172
	v_ashrrev_i32_e32 v165, 31, v164
	v_lshlrev_b64 v[168:169], 2, v[164:165]
	v_lshl_add_u64 v[174:175], s[2:3], 0, v[168:169]
	v_lshl_add_u64 v[164:165], s[18:19], 0, v[168:169]
	v_mad_i64_i32 v[168:169], s[46:47], s56, v211, v[174:175]
	v_pk_add_f32 v[162:163], v[170:171], v[236:237]
	global_load_dwordx4 v[164:167], v[164:165], off
	global_load_dwordx4 v[168:171], v[168:169], off
	v_mad_i64_i32 v[212:213], s[46:47], s54, v211, v[174:175]
	global_load_dwordx4 v[212:215], v[212:213], off
	v_mad_i64_i32 v[216:217], s[46:47], s53, v211, v[174:175]
	global_load_dwordx4 v[216:219], v[216:217], off
	v_mad_i64_i32 v[220:221], s[46:47], s52, v211, v[174:175]
	global_load_dwordx4 v[220:223], v[220:221], off
	v_mad_i64_i32 v[224:225], s[46:47], s81, v211, v[174:175]
	global_load_dwordx4 v[224:227], v[224:225], off
	v_mad_i64_i32 v[228:229], s[46:47], s80, v211, v[174:175]
	global_load_dwordx4 v[228:231], v[228:229], off
	v_mad_i64_i32 v[232:233], s[46:47], s43, v211, v[174:175]
	global_load_dwordx4 v[232:235], v[232:233], off
	v_mad_i64_i32 v[236:237], s[46:47], s37, v211, v[174:175]
	global_load_dwordx4 v[236:239], v[236:237], off
	s_waitcnt vmcnt(7)
	v_pk_add_f32 v[168:169], v[164:165], v[168:169]
	v_pk_add_f32 v[170:171], v[166:167], v[170:171]
	s_waitcnt vmcnt(6)
	v_pk_add_f32 v[168:169], v[168:169], v[212:213]
	v_pk_add_f32 v[170:171], v[170:171], v[214:215]
	s_waitcnt vmcnt(5)
	v_pk_add_f32 v[168:169], v[168:169], v[216:217]
	v_pk_add_f32 v[170:171], v[170:171], v[218:219]
	s_waitcnt vmcnt(4)
	v_pk_add_f32 v[168:169], v[168:169], v[220:221]
	v_pk_add_f32 v[170:171], v[170:171], v[222:223]
	s_waitcnt vmcnt(3)
	v_pk_add_f32 v[168:169], v[168:169], v[224:225]
	v_pk_add_f32 v[170:171], v[170:171], v[226:227]
	s_waitcnt vmcnt(2)
	v_pk_add_f32 v[168:169], v[168:169], v[228:229]
	v_pk_add_f32 v[170:171], v[170:171], v[230:231]
	s_waitcnt vmcnt(1)
	v_pk_add_f32 v[176:177], v[168:169], v[232:233]
	v_pk_add_f32 v[170:171], v[170:171], v[234:235]
	s_waitcnt vmcnt(0)
	v_pk_add_f32 v[164:165], v[170:171], v[238:239]
	v_add_u32_e32 v168, 0x1490, v172
	v_ashrrev_i32_e32 v169, 31, v168
	v_lshlrev_b64 v[174:175], 2, v[168:169]
	v_lshl_add_u64 v[178:179], s[2:3], 0, v[174:175]
	v_lshl_add_u64 v[168:169], s[18:19], 0, v[174:175]
	v_mad_i64_i32 v[174:175], s[46:47], s56, v211, v[178:179]
	v_pk_add_f32 v[166:167], v[176:177], v[236:237]
	global_load_dwordx4 v[168:171], v[168:169], off
	global_load_dwordx4 v[174:177], v[174:175], off
	v_mad_i64_i32 v[212:213], s[46:47], s54, v211, v[178:179]
	global_load_dwordx4 v[212:215], v[212:213], off
	v_mad_i64_i32 v[216:217], s[46:47], s53, v211, v[178:179]
	global_load_dwordx4 v[216:219], v[216:217], off
	v_mad_i64_i32 v[220:221], s[46:47], s52, v211, v[178:179]
	global_load_dwordx4 v[220:223], v[220:221], off
	v_mad_i64_i32 v[224:225], s[46:47], s81, v211, v[178:179]
	global_load_dwordx4 v[224:227], v[224:225], off
	v_mad_i64_i32 v[228:229], s[46:47], s80, v211, v[178:179]
	global_load_dwordx4 v[228:231], v[228:229], off
	v_mad_i64_i32 v[232:233], s[46:47], s43, v211, v[178:179]
	global_load_dwordx4 v[232:235], v[232:233], off
	v_mad_i64_i32 v[236:237], s[46:47], s37, v211, v[178:179]
	global_load_dwordx4 v[236:239], v[236:237], off
	v_lshlrev_b64 v[172:173], 2, v[172:173]
	s_waitcnt vmcnt(7)
	v_pk_add_f32 v[174:175], v[168:169], v[174:175]
	v_pk_add_f32 v[176:177], v[170:171], v[176:177]
	s_waitcnt vmcnt(6)
	v_pk_add_f32 v[174:175], v[174:175], v[212:213]
	v_pk_add_f32 v[176:177], v[176:177], v[214:215]
	s_waitcnt vmcnt(5)
	v_pk_add_f32 v[174:175], v[174:175], v[216:217]
	v_pk_add_f32 v[176:177], v[176:177], v[218:219]
	s_waitcnt vmcnt(4)
	v_pk_add_f32 v[174:175], v[174:175], v[220:221]
	v_pk_add_f32 v[176:177], v[176:177], v[222:223]
	s_waitcnt vmcnt(3)
	v_pk_add_f32 v[174:175], v[174:175], v[224:225]
	v_pk_add_f32 v[176:177], v[176:177], v[226:227]
	s_waitcnt vmcnt(2)
	v_pk_add_f32 v[174:175], v[174:175], v[228:229]
	v_pk_add_f32 v[176:177], v[176:177], v[230:231]
	s_waitcnt vmcnt(1)
	v_pk_add_f32 v[204:205], v[174:175], v[232:233]
	v_pk_add_f32 v[170:171], v[176:177], v[234:235]
	v_add_u32_e32 v178, s35, v181
	v_ashrrev_i32_e32 v179, 31, v178
	s_waitcnt vmcnt(0)
	v_pk_add_f32 v[168:169], v[170:171], v[238:239]
	v_pk_add_f32 v[170:171], v[204:205], v[236:237]
	v_lshl_add_u64 v[174:175], s[0:1], 0, v[172:173]
	v_lshlrev_b64 v[176:177], 12, v[178:179]
	v_lshl_add_u64 v[204:205], v[174:175], 0, v[176:177]
	global_load_dwordx4 v[212:215], v[204:205], off
	global_load_dwordx4 v[216:219], v[204:205], off offset:64
	global_load_dwordx4 v[220:223], v[204:205], off offset:512
	global_load_dwordx4 v[224:227], v[204:205], off offset:576
	v_or_b32_e32 v204, 16, v178
	v_ashrrev_i32_e32 v205, 31, v204
	v_lshlrev_b64 v[204:205], 12, v[204:205]
	v_lshl_add_u64 v[206:207], v[174:175], 0, v[204:205]
	global_load_dwordx4 v[228:231], v[206:207], off
	global_load_dwordx4 v[232:235], v[206:207], off offset:64
	global_load_dwordx4 v[236:239], v[206:207], off offset:512
	global_load_dwordx4 v[240:243], v[206:207], off offset:576
	v_lshl_add_u64 v[206:207], s[0:1], 0, v[176:177]
	v_lshl_add_u64 v[206:207], v[206:207], 0, v[172:173]
	s_waitcnt vmcnt(7)
	v_pk_fma_f32 v[126:127], v[126:127], v[156:157], v[214:215]
	v_pk_fma_f32 v[124:125], v[124:125], v[158:159], v[212:213]
	s_waitcnt vmcnt(5)
	v_pk_fma_f32 v[110:111], v[110:111], v[164:165], v[222:223]
	v_pk_fma_f32 v[108:109], v[108:109], v[166:167], v[220:221]
	global_store_dwordx4 v[206:207], v[108:111], off offset:512 sc1
	s_waitcnt vmcnt(5)
	v_pk_fma_f32 v[106:107], v[106:107], v[168:169], v[226:227]
	v_pk_fma_f32 v[104:105], v[104:105], v[170:171], v[224:225]
	v_lshl_add_u64 v[108:109], s[0:1], 0, v[204:205]
	v_lshl_add_u64 v[108:109], v[108:109], 0, v[172:173]
	s_waitcnt vmcnt(1)
	v_pk_fma_f32 v[98:99], v[98:99], v[168:169], v[242:243]
	v_pk_fma_f32 v[96:97], v[96:97], v[170:171], v[240:241]
	global_store_dwordx4 v[108:109], v[96:99], off offset:576 sc1
	global_store_dwordx4 v[206:207], v[104:107], off offset:576 sc1
	v_pk_fma_f32 v[122:123], v[122:123], v[160:161], v[218:219]
	v_or_b32_e32 v96, 32, v178
	v_pk_fma_f32 v[106:107], v[118:119], v[156:157], v[230:231]
	v_pk_fma_f32 v[104:105], v[116:117], v[158:159], v[228:229]
	v_ashrrev_i32_e32 v97, 31, v96
	v_pk_fma_f32 v[120:121], v[120:121], v[162:163], v[216:217]
	global_store_dwordx4 v[108:109], v[104:107], off sc1
	v_pk_fma_f32 v[102:103], v[102:103], v[164:165], v[238:239]
	v_pk_fma_f32 v[100:101], v[100:101], v[166:167], v[236:237]
	v_pk_fma_f32 v[106:107], v[114:115], v[160:161], v[234:235]
	v_pk_fma_f32 v[104:105], v[112:113], v[162:163], v[232:233]
	v_lshlrev_b64 v[204:205], 12, v[96:97]
	v_or_b32_e32 v112, 48, v178
	global_store_dwordx4 v[206:207], v[124:127], off sc1
	global_store_dwordx4 v[206:207], v[120:123], off offset:64 sc1
	global_store_dwordx4 v[108:109], v[104:107], off offset:64 sc1
	global_store_dwordx4 v[108:109], v[100:103], off offset:512 sc1
	v_lshl_add_u64 v[108:109], v[174:175], 0, v[204:205]
	v_ashrrev_i32_e32 v113, 31, v112
	global_load_dwordx4 v[96:99], v[108:109], off
	global_load_dwordx4 v[100:103], v[108:109], off offset:64
	global_load_dwordx4 v[104:107], v[108:109], off offset:512
	s_nop 0
	global_load_dwordx4 v[108:111], v[108:109], off offset:576
	v_lshlrev_b64 v[178:179], 12, v[112:113]
	v_lshl_add_u64 v[124:125], v[174:175], 0, v[178:179]
	global_load_dwordx4 v[112:115], v[124:125], off
	global_load_dwordx4 v[116:119], v[124:125], off offset:64
	global_load_dwordx4 v[120:123], v[124:125], off offset:512
	s_nop 0
	global_load_dwordx4 v[124:127], v[124:125], off offset:576
	s_waitcnt vmcnt(7)
	v_pk_fma_f32 v[92:93], v[92:93], v[158:159], v[96:97]
	v_lshl_add_u64 v[96:97], s[0:1], 0, v[204:205]
	v_lshl_add_u64 v[96:97], v[96:97], 0, v[172:173]
	s_waitcnt vmcnt(5)
	v_pk_fma_f32 v[78:79], v[78:79], v[164:165], v[106:107]
	v_pk_fma_f32 v[76:77], v[76:77], v[166:167], v[104:105]
	global_store_dwordx4 v[96:97], v[76:79], off offset:512 sc1
	s_waitcnt vmcnt(5)
	v_pk_fma_f32 v[74:75], v[74:75], v[168:169], v[110:111]
	v_pk_fma_f32 v[72:73], v[72:73], v[170:171], v[108:109]
	v_lshl_add_u64 v[76:77], s[0:1], 0, v[178:179]
	v_pk_fma_f32 v[94:95], v[94:95], v[156:157], v[98:99]
	v_pk_fma_f32 v[90:91], v[90:91], v[160:161], v[102:103]
	v_pk_fma_f32 v[88:89], v[88:89], v[162:163], v[100:101]
	global_store_dwordx4 v[96:97], v[72:75], off offset:576 sc1
	v_lshl_add_u64 v[76:77], v[76:77], 0, v[172:173]
	global_store_dwordx4 v[96:97], v[92:95], off sc1
	s_waitcnt vmcnt(6)
	v_pk_fma_f32 v[74:75], v[86:87], v[156:157], v[114:115]
	v_pk_fma_f32 v[72:73], v[84:85], v[158:159], v[112:113]
	global_store_dwordx4 v[96:97], v[88:91], off offset:64 sc1
	global_store_dwordx4 v[76:77], v[72:75], off sc1
	s_waitcnt vmcnt(6)
	v_pk_fma_f32 v[70:71], v[70:71], v[164:165], v[122:123]
	v_pk_fma_f32 v[68:69], v[68:69], v[166:167], v[120:121]
	v_pk_fma_f32 v[74:75], v[82:83], v[160:161], v[118:119]
	v_pk_fma_f32 v[72:73], v[80:81], v[162:163], v[116:117]
	s_waitcnt vmcnt(5)
	v_pk_fma_f32 v[66:67], v[66:67], v[168:169], v[126:127]
	v_pk_fma_f32 v[64:65], v[64:65], v[170:171], v[124:125]
	v_lshl_add_u64 v[96:97], v[176:177], 0, s[20:21]
	global_store_dwordx4 v[76:77], v[72:75], off offset:64 sc1
	global_store_dwordx4 v[76:77], v[68:71], off offset:512 sc1
	global_store_dwordx4 v[76:77], v[64:67], off offset:576 sc1
	v_lshl_add_u64 v[76:77], v[174:175], 0, v[96:97]
	global_load_dwordx4 v[64:67], v[76:77], off
	global_load_dwordx4 v[68:71], v[76:77], off offset:64
	global_load_dwordx4 v[72:75], v[76:77], off offset:512
	s_nop 0
	global_load_dwordx4 v[76:79], v[76:77], off offset:576
	v_lshl_add_u64 v[98:99], v[176:177], 0, s[22:23]
	v_lshl_add_u64 v[92:93], v[174:175], 0, v[98:99]
	global_load_dwordx4 v[80:83], v[92:93], off
	global_load_dwordx4 v[84:87], v[92:93], off offset:64
	global_load_dwordx4 v[88:91], v[92:93], off offset:512
	s_nop 0
	global_load_dwordx4 v[92:95], v[92:93], off offset:576
	s_waitcnt vmcnt(7)
	v_pk_fma_f32 v[60:61], v[60:61], v[158:159], v[64:65]
	v_lshl_add_u64 v[64:65], s[0:1], 0, v[96:97]
	v_lshl_add_u64 v[64:65], v[64:65], 0, v[172:173]
	s_waitcnt vmcnt(5)
	v_pk_fma_f32 v[46:47], v[46:47], v[164:165], v[74:75]
	v_pk_fma_f32 v[44:45], v[44:45], v[166:167], v[72:73]
	global_store_dwordx4 v[64:65], v[44:47], off offset:512 sc1
	s_waitcnt vmcnt(5)
	v_pk_fma_f32 v[42:43], v[42:43], v[168:169], v[78:79]
	v_pk_fma_f32 v[40:41], v[40:41], v[170:171], v[76:77]
	v_lshl_add_u64 v[44:45], s[0:1], 0, v[98:99]
	global_store_dwordx4 v[64:65], v[40:43], off offset:576 sc1
	v_lshl_add_u64 v[44:45], v[44:45], 0, v[172:173]
	v_pk_fma_f32 v[62:63], v[62:63], v[156:157], v[66:67]
	s_waitcnt vmcnt(5)
	v_pk_fma_f32 v[42:43], v[54:55], v[156:157], v[82:83]
	v_pk_fma_f32 v[40:41], v[52:53], v[158:159], v[80:81]
	v_pk_fma_f32 v[58:59], v[58:59], v[160:161], v[70:71]
	v_pk_fma_f32 v[56:57], v[56:57], v[162:163], v[68:69]
	global_store_dwordx4 v[44:45], v[40:43], off sc1
	s_waitcnt vmcnt(4)
	v_pk_fma_f32 v[38:39], v[38:39], v[164:165], v[90:91]
	v_pk_fma_f32 v[36:37], v[36:37], v[166:167], v[88:89]
	v_pk_fma_f32 v[42:43], v[50:51], v[160:161], v[86:87]
	v_pk_fma_f32 v[40:41], v[48:49], v[162:163], v[84:85]
	s_waitcnt vmcnt(3)
	v_pk_fma_f32 v[34:35], v[34:35], v[168:169], v[94:95]
	v_pk_fma_f32 v[32:33], v[32:33], v[170:171], v[92:93]
	v_lshl_add_u64 v[66:67], v[176:177], 0, s[24:25]
	global_store_dwordx4 v[64:65], v[60:63], off sc1
	global_store_dwordx4 v[64:65], v[56:59], off offset:64 sc1
	global_store_dwordx4 v[44:45], v[40:43], off offset:64 sc1
	global_store_dwordx4 v[44:45], v[36:39], off offset:512 sc1
	global_store_dwordx4 v[44:45], v[32:35], off offset:576 sc1
	v_lshl_add_u64 v[64:65], v[176:177], 0, s[26:27]
	v_lshl_add_u64 v[36:37], v[174:175], 0, v[64:65]
	v_lshl_add_u64 v[32:33], v[174:175], 0, v[66:67]
	global_load_dwordx4 v[48:51], v[32:33], off
	global_load_dwordx4 v[60:63], v[32:33], off offset:64
	global_load_dwordx4 v[56:59], v[32:33], off offset:512
	global_load_dwordx4 v[52:55], v[32:33], off offset:576
	s_nop 0
	global_load_dwordx4 v[32:35], v[36:37], off
	global_load_dwordx4 v[44:47], v[36:37], off offset:64
	global_load_dwordx4 v[40:43], v[36:37], off offset:512
	s_nop 0
	global_load_dwordx4 v[36:39], v[36:37], off offset:576
	s_waitcnt vmcnt(7)
	v_pk_fma_f32 v[28:29], v[28:29], v[158:159], v[48:49]
	v_lshl_add_u64 v[48:49], s[0:1], 0, v[66:67]
	v_lshl_add_u64 v[48:49], v[48:49], 0, v[172:173]
	s_waitcnt vmcnt(5)
	v_pk_fma_f32 v[18:19], v[18:19], v[164:165], v[58:59]
	v_pk_fma_f32 v[16:17], v[16:17], v[166:167], v[56:57]
	global_store_dwordx4 v[48:49], v[16:19], off offset:512 sc1
	s_waitcnt vmcnt(5)
	v_pk_fma_f32 v[10:11], v[10:11], v[168:169], v[54:55]
	v_pk_fma_f32 v[8:9], v[8:9], v[170:171], v[52:53]
	v_lshl_add_u64 v[16:17], s[0:1], 0, v[64:65]
	global_store_dwordx4 v[48:49], v[8:11], off offset:576 sc1
	v_lshl_add_u64 v[16:17], v[16:17], 0, v[172:173]
	v_pk_fma_f32 v[30:31], v[30:31], v[156:157], v[50:51]
	s_waitcnt vmcnt(5)
	v_pk_fma_f32 v[10:11], v[22:23], v[156:157], v[34:35]
	v_pk_fma_f32 v[8:9], v[20:21], v[158:159], v[32:33]
	v_pk_fma_f32 v[26:27], v[26:27], v[160:161], v[62:63]
	v_pk_fma_f32 v[24:25], v[24:25], v[162:163], v[60:61]
	global_store_dwordx4 v[16:17], v[8:11], off sc1
	s_waitcnt vmcnt(4)
	v_pk_fma_f32 v[6:7], v[6:7], v[164:165], v[42:43]
	v_pk_fma_f32 v[4:5], v[4:5], v[166:167], v[40:41]
	v_pk_fma_f32 v[10:11], v[14:15], v[160:161], v[46:47]
	v_pk_fma_f32 v[8:9], v[12:13], v[162:163], v[44:45]
	s_waitcnt vmcnt(3)
	v_pk_fma_f32 v[2:3], v[2:3], v[168:169], v[38:39]
	v_pk_fma_f32 v[0:1], v[0:1], v[170:171], v[36:37]
	global_store_dwordx4 v[48:49], v[28:31], off sc1
	global_store_dwordx4 v[48:49], v[24:27], off offset:64 sc1
	global_store_dwordx4 v[16:17], v[8:11], off offset:64 sc1
	global_store_dwordx4 v[16:17], v[4:7], off offset:512 sc1
	global_store_dwordx4 v[16:17], v[0:3], off offset:576 sc1
	s_waitcnt vmcnt(0)
	s_barrier
	s_and_saveexec_b64 s[46:47], s[4:5]
	s_cbranch_execz .LBB0_2375
	s_lshl_b32 s48, s44, 2
	s_ashr_i32 s49, s48, 31
	s_lshl_b64 s[48:49], s[48:49], 2
	s_add_u32 s48, s72, s48
	s_addc_u32 s49, s73, s49
	s_getreg_b32 s45, hwreg(HW_REG_XCC_ID, 0, 4)
	global_load_dwordx4 v[0:3], v131, s[48:49]
	s_and_b32 s45, s45, 15
	s_add_i32 s45, s45, 1
	s_waitcnt vmcnt(0)
	v_cmp_ne_u32_e32 vcc, s45, v2
	s_nop 1
	v_cndmask_b32_e64 v2, 0, 1, vcc
	v_cmp_ne_u32_e32 vcc, s45, v3
	v_lshlrev_b32_e32 v2, 2, v2
	s_nop 0
	v_cndmask_b32_e64 v3, 0, 1, vcc
	v_cmp_ne_u32_e32 vcc, s45, v1
	v_lshlrev_b32_e32 v3, 3, v3
	v_or_b32_e32 v2, v3, v2
	v_cndmask_b32_e64 v1, 0, 1, vcc
	v_cmp_ne_u32_e32 vcc, s45, v0
	v_lshlrev_b32_e32 v1, 1, v1
	s_nop 0
	v_cndmask_b32_e64 v0, 0, 1, vcc
	v_or_b32_e32 v0, v0, v1
	v_and_b32_e32 v0, 3, v0
	v_or_b32_e32 v0, v0, v2
	v_and_b32_e32 v0, 15, v0
	v_cmp_eq_u32_e32 vcc, 0, v0
	s_cbranch_vccnz .LBB0_2364
	buffer_wbl2 sc1
	s_waitcnt vmcnt(0)

.LBB0_2375:
	s_or_b64 exec, exec, s[46:47]
	s_mul_i32 s44, s55, 0x9000
	s_mul_hi_i32 s59, s56, 0x9000
	s_add_i32 s58, s44, 0x240000
	s_mul_hi_i32 s57, s54, 0x9000
	s_add_i32 s56, s44, 0x288000
	v_lshl_add_u64 v[4:5], v[138:139], 0, s[58:59]
	s_mul_hi_i32 s55, s53, 0x9000
	s_add_i32 s54, s44, 0x2d0000
	s_barrier
	global_load_dwordx4 v[0:3], v[136:137], off
	v_lshl_add_u64 v[8:9], v[138:139], 0, s[56:57]
	global_load_dwordx4 v[4:7], v[4:5], off
	s_mul_hi_i32 s53, s52, 0x9000
	s_add_i32 s52, s44, 0x318000
	global_load_dwordx4 v[8:11], v[8:9], off
	v_lshl_add_u64 v[12:13], v[138:139], 0, s[54:55]
	s_mul_hi_i32 s51, s81, 0x9000
	s_add_i32 s50, s44, 0x360000
	global_load_dwordx4 v[12:15], v[12:13], off
	v_lshl_add_u64 v[16:17], v[138:139], 0, s[52:53]
	s_mul_hi_i32 s49, s80, 0x9000
	s_add_i32 s48, s44, 0x3a8000
	global_load_dwordx4 v[16:19], v[16:17], off
	v_lshl_add_u64 v[20:21], v[138:139], 0, s[50:51]
	s_mul_hi_i32 s47, s43, 0x9000
	s_add_i32 s46, s44, 0x3f0000
	global_load_dwordx4 v[20:23], v[20:21], off
	v_lshl_add_u64 v[24:25], v[138:139], 0, s[48:49]
	s_mul_hi_i32 s45, s37, 0x9000
	s_add_i32 s44, s44, 0x438000
	global_load_dwordx4 v[24:27], v[24:25], off
	v_lshl_add_u64 v[28:29], v[138:139], 0, s[46:47]
	global_load_dwordx4 v[28:31], v[28:29], off
	v_lshl_add_u64 v[32:33], v[138:139], 0, s[44:45]
	global_load_dwordx4 v[32:35], v[32:33], off
	s_lshl_b32 s37, s42, 6
	s_ashr_i32 s42, s82, 3
	s_add_i32 s35, s35, s37
	s_and_b32 s37, s42, -8
	s_add_i32 s42, s35, s37
	s_ashr_i32 s43, s42, 31
	s_lshl_b64 s[44:45], s[42:43], 12
	v_lshl_add_u64 v[36:37], v[140:141], 0, s[44:45]
	s_or_b32 s48, s42, 1
	s_ashr_i32 s49, s48, 31
	s_lshl_b64 s[44:45], s[48:49], 12
	v_mov_b64_e32 v[84:85], s[30:31]
	s_or_b32 s46, s42, 2
	s_ashr_i32 s47, s46, 31
	s_lshl_b64 s[52:53], s[46:47], 12
	s_lshl_b64 s[50:51], s[42:43], 11
	s_waitcnt vmcnt(7)
	v_pk_add_f32 v[2:3], v[2:3], v[6:7]
	v_pk_add_f32 v[0:1], v[0:1], v[4:5]
	s_waitcnt vmcnt(6)
	v_pk_add_f32 v[2:3], v[2:3], v[10:11]
	v_pk_add_f32 v[0:1], v[0:1], v[8:9]
	v_lshl_add_u64 v[8:9], v[140:141], 0, s[44:45]
	s_or_b32 s44, s42, 3
	s_waitcnt vmcnt(5)
	v_pk_add_f32 v[2:3], v[2:3], v[14:15]
	v_pk_add_f32 v[0:1], v[0:1], v[12:13]
	s_ashr_i32 s45, s44, 31
	s_lshl_b64 s[54:55], s[44:45], 12
	s_waitcnt vmcnt(4)
	v_pk_add_f32 v[2:3], v[2:3], v[18:19]
	v_pk_add_f32 v[0:1], v[0:1], v[16:17]
	s_waitcnt vmcnt(3)
	v_pk_add_f32 v[2:3], v[2:3], v[22:23]
	v_pk_add_f32 v[0:1], v[0:1], v[20:21]
	s_waitcnt vmcnt(2)
	v_pk_add_f32 v[2:3], v[2:3], v[26:27]
	v_pk_add_f32 v[0:1], v[0:1], v[24:25]
	s_waitcnt vmcnt(1)
	v_pk_add_f32 v[2:3], v[2:3], v[30:31]
	v_pk_add_f32 v[0:1], v[0:1], v[28:29]
	s_waitcnt vmcnt(0)
	v_pk_add_f32 v[2:3], v[2:3], v[34:35]
	v_pk_add_f32 v[0:1], v[0:1], v[32:33]
	v_pk_add_f32 v[4:5], v[2:3], 1.0 op_sel_hi:[1,0]
	v_pk_add_f32 v[6:7], v[0:1], 1.0 op_sel_hi:[1,0]
	v_cndmask_b32_e64 v3, v5, v3, s[6:7]
	v_cndmask_b32_e64 v2, v4, v2, s[6:7]
	v_cndmask_b32_e64 v1, v7, v1, s[6:7]
	v_cndmask_b32_e64 v0, v6, v0, s[6:7]
	ds_write_b128 v183, v[0:3]
	s_waitcnt lgkmcnt(0)
	s_barrier
	global_load_dwordx4 v[108:111], v[142:143], off
	global_load_dwordx4 v[112:115], v[146:147], off
	global_load_dwordx4 v[116:119], v[148:149], off
	global_load_dwordx4 v[120:123], v[150:151], off
	global_load_dwordx4 v[16:19], v[36:37], off
	global_load_dwordx4 v[4:7], v[36:37], off offset:1024
	global_load_dwordx4 v[80:83], v[36:37], off offset:3072
	global_load_dwordx4 v[0:3], v[36:37], off offset:2048
	global_load_dwordx4 v[76:79], v[8:9], off
	global_load_dwordx4 v[68:71], v[8:9], off offset:1024
	s_nop 0
	global_load_dwordx4 v[36:39], v[8:9], off offset:3072
	global_load_dwordx4 v[64:67], v[8:9], off offset:2048
	s_waitcnt vmcnt(3)
	v_pk_mul_f32 v[28:29], v[78:79], v[78:79]
	v_pk_mul_f32 v[8:9], v[18:19], v[18:19]
	v_pk_mul_f32 v[10:11], v[16:17], v[16:17]
	v_pk_mul_f32 v[12:13], v[6:7], v[6:7]
	v_pk_mul_f32 v[14:15], v[4:5], v[4:5]
	v_mul_f32_e32 v24, v1, v1
	v_mul_f32_e32 v26, v3, v3
	v_pk_mul_f32 v[30:31], v[76:77], v[76:77]
	s_waitcnt vmcnt(2)
	v_pk_mul_f32 v[32:33], v[70:71], v[70:71]
	v_pk_mul_f32 v[34:35], v[68:69], v[68:69]
	v_mul_f32_e32 v47, v82, v82
	v_mul_f32_e32 v48, v83, v83
	v_pk_mov_b32 v[44:45], v[10:11], v[8:9] op_sel:[1, 0]
	v_mov_b32_e32 v11, v9
	v_pk_mov_b32 v[8:9], v[14:15], v[12:13] op_sel:[1, 0]
	v_mov_b32_e32 v15, v13
	v_pk_fma_f32 v[12:13], v[0:1], v[0:1], v[24:25] op_sel_hi:[1, 1, 0]
	v_pk_fma_f32 v[24:25], v[2:3], v[2:3], v[26:27] op_sel_hi:[1, 1, 0]
	v_pk_mov_b32 v[26:27], v[30:31], v[28:29] op_sel:[1, 0]
	v_mov_b32_e32 v31, v29
	v_pk_mov_b32 v[28:29], v[34:35], v[32:33] op_sel:[1, 0]
	v_mov_b32_e32 v35, v33
	v_mul_f32_e32 v43, v80, v80
	s_waitcnt vmcnt(0)
	v_mul_f32_e32 v40, v65, v65
	v_mul_f32_e32 v42, v67, v67
	v_pk_add_f32 v[10:11], v[44:45], v[10:11]
	v_pk_add_f32 v[8:9], v[8:9], v[14:15]
	v_mov_b32_e32 v13, v47
	v_mov_b32_e32 v25, v48
	v_pk_add_f32 v[14:15], v[26:27], v[30:31]
	v_pk_add_f32 v[26:27], v[28:29], v[34:35]
	v_mul_f32_e32 v46, v81, v81
	v_mul_f32_e32 v49, v36, v36
	v_mul_f32_e32 v50, v37, v37
	v_mul_f32_e32 v51, v38, v38
	v_mul_f32_e32 v52, v39, v39
	v_pk_fma_f32 v[32:33], v[64:65], v[64:65], v[40:41] op_sel_hi:[1, 1, 0]
	v_pk_fma_f32 v[40:41], v[66:67], v[66:67], v[42:43] op_sel_hi:[1, 1, 0]
	v_pk_add_f32 v[10:11], v[10:11], v[10:11] op_sel:[0, 1] op_sel_hi:[1, 0]
	v_pk_add_f32 v[8:9], v[8:9], v[8:9] op_sel:[0, 1] op_sel_hi:[1, 0]
	v_pk_add_f32 v[12:13], v[12:13], v[24:25]
	v_pk_add_f32 v[14:15], v[14:15], v[14:15] op_sel:[0, 1] op_sel_hi:[1, 0]
	v_pk_add_f32 v[24:25], v[26:27], v[26:27] op_sel:[0, 1] op_sel_hi:[1, 0]
	v_mov_b32_e32 v33, v51
	v_mov_b32_e32 v41, v52
	v_mov_b32_e32 v11, v43
	v_mov_b32_e32 v9, v46
	v_mov_b32_e32 v15, v49
	v_mov_b32_e32 v25, v50
	v_pk_add_f32 v[26:27], v[32:33], v[40:41]
	v_pk_add_f32 v[8:9], v[10:11], v[8:9]
	v_pk_add_f32 v[10:11], v[14:15], v[24:25]
	v_pk_add_f32 v[8:9], v[8:9], v[12:13]
	v_pk_add_f32 v[10:11], v[10:11], v[26:27]
	v_mov_b32_e32 v13, v8
	v_mov_b32_e32 v12, v10
	v_mov_b32_e32 v8, v11
	v_pk_add_f32 v[8:9], v[12:13], v[8:9]
	v_lshl_add_u64 v[12:13], v[140:141], 0, s[52:53]
	v_lshl_add_u64 v[14:15], v[140:141], 0, s[54:55]
	global_load_dwordx4 v[72:75], v[12:13], off
	global_load_dwordx4 v[60:63], v[12:13], off offset:1024
	global_load_dwordx4 v[56:59], v[12:13], off offset:2048
	global_load_dwordx4 v[52:55], v[12:13], off offset:3072
	global_load_dwordx4 v[48:51], v[14:15], off
	global_load_dwordx4 v[44:47], v[14:15], off offset:1024
	s_waitcnt lgkmcnt(0)
	s_nop 1
	v_add_f32_dpp v8, v8, v8 quad_perm:[1,0,3,2] row_mask:0xf bank_mask:0xf
	v_add_f32_dpp v9, v9, v9 quad_perm:[1,0,3,2] row_mask:0xf bank_mask:0xf
	global_load_dwordx4 v[40:43], v[14:15], off offset:2048
	global_load_dwordx4 v[32:35], v[14:15], off offset:3072
	v_lshl_add_u64 v[24:25], v[144:145], 0, s[50:51]
	s_add_u32 s50, s12, s50
	s_addc_u32 s51, s13, s51
	s_waitcnt lgkmcnt(0)
	s_nop 1
	v_add_f32_dpp v8, v8, v8 quad_perm:[2,3,0,1] row_mask:0xf bank_mask:0xf
	v_add_f32_dpp v9, v9, v9 quad_perm:[2,3,0,1] row_mask:0xf bank_mask:0xf
	s_lshl_b64 s[48:49], s[48:49], 11
	s_waitcnt lgkmcnt(0)
	s_nop 1
	v_add_f32_dpp v8, v8, v8 row_half_mirror row_mask:0xf bank_mask:0xf
	v_add_f32_dpp v9, v9, v9 row_half_mirror row_mask:0xf bank_mask:0xf
	s_waitcnt lgkmcnt(0)
	s_nop 1
	v_add_f32_dpp v8, v8, v8 row_mirror row_mask:0xf bank_mask:0xf
	v_add_f32_dpp v9, v9, v9 row_mirror row_mask:0xf bank_mask:0xf
	ds_bpermute_b32 v11, v188, v9
	ds_bpermute_b32 v10, v188, v8
	s_waitcnt lgkmcnt(0)
	v_pk_add_f32 v[8:9], v[8:9], v[10:11]
	s_waitcnt lgkmcnt(0)
	v_mov_b32_e32 v10, v8
	v_mov_b32_e32 v11, v9
	s_nop 1
	v_permlane32_swap_b32_e32 v10, v8
	v_permlane32_swap_b32_e32 v11, v9
	v_pk_add_f32 v[8:9], v[8:9], v[10:11]
	s_nop 0
	v_pk_fma_f32 v[90:91], v[8:9], s[28:29], v[84:85] op_sel_hi:[1, 0, 0]
	s_waitcnt vmcnt(4)
	v_mul_f32_e32 v99, v53, v53
	v_mul_f32_e32 v8, 0x4b800000, v91
	v_cmp_gt_f32_e32 vcc, s79, v91
	s_waitcnt vmcnt(2)
	v_pk_mul_f32 v[94:95], v[44:45], v[44:45]
	v_mul_f32_e32 v102, v54, v54
	v_cndmask_b32_e32 v8, v91, v8, vcc
	v_rsq_f32_e32 v26, v8
	ds_read_b128 v[8:11], v190
	ds_read_b128 v[12:15], v191
	s_waitcnt vmcnt(1)
	v_mul_f32_e32 v96, v41, v41
	v_mul_f32_e32 v98, v43, v43
	v_mul_f32_e32 v27, 0x45800000, v26
	v_cndmask_b32_e32 v92, v26, v27, vcc
	v_pk_mul_f32 v[18:19], v[18:19], v[92:93] op_sel_hi:[1, 0]
	v_pk_mul_f32 v[16:17], v[16:17], v[92:93] op_sel_hi:[1, 0]
	v_pk_mul_f32 v[18:19], v[110:111], v[18:19]
	v_pk_mul_f32 v[16:17], v[108:109], v[16:17]
	s_waitcnt lgkmcnt(0)
	v_pk_fma_f32 v[18:19], v[14:15], v[18:19], v[10:11]
	v_pk_fma_f32 v[16:17], v[12:13], v[16:17], v[8:9]
	v_pk_mul_f32 v[6:7], v[6:7], v[92:93] op_sel_hi:[1, 0]
	v_cvt_pk_bf16_f32 v16, v16, v17
	v_cvt_pk_bf16_f32 v17, v18, v19
	global_store_dwordx2 v[24:25], v[16:17], off sc1
	ds_read_b128 v[16:19], v192
	ds_read_b128 v[20:23], v193
	v_pk_mul_f32 v[4:5], v[4:5], v[92:93] op_sel_hi:[1, 0]
	v_pk_mul_f32 v[2:3], v[2:3], v[92:93] op_sel_hi:[1, 0]
	v_pk_mul_f32 v[0:1], v[0:1], v[92:93] op_sel_hi:[1, 0]
	v_pk_mul_f32 v[82:83], v[82:83], v[92:93] op_sel_hi:[1, 0]
	v_pk_mul_f32 v[80:81], v[80:81], v[92:93] op_sel_hi:[1, 0]
	v_cmp_gt_f32_e32 vcc, s79, v90
	v_pk_mul_f32 v[92:93], v[46:47], v[46:47]
	v_mul_f32_e32 v103, v55, v55
	s_waitcnt vmcnt(1)
	v_mul_f32_e32 v104, v32, v32
	v_mul_f32_e32 v105, v33, v33
	v_mul_f32_e32 v106, v34, v34
	v_mul_f32_e32 v107, v35, v35
	v_pk_mul_f32 v[4:5], v[112:113], v[4:5]
	v_pk_mul_f32 v[6:7], v[114:115], v[6:7]
	s_waitcnt lgkmcnt(0)
	v_pk_fma_f32 v[4:5], v[20:21], v[4:5], v[16:17]
	v_pk_fma_f32 v[6:7], v[22:23], v[6:7], v[18:19]
	v_cvt_pk_bf16_f32 v4, v4, v5
	v_cvt_pk_bf16_f32 v5, v6, v7
	global_store_dwordx2 v200, v[4:5], s[50:51] sc1
	ds_read_b128 v[24:27], v194
	ds_read_b128 v[28:31], v195
	v_pk_mul_f32 v[0:1], v[116:117], v[0:1]
	v_pk_mul_f32 v[2:3], v[118:119], v[2:3]
	s_waitcnt lgkmcnt(0)
	v_pk_fma_f32 v[0:1], v[28:29], v[0:1], v[24:25]
	v_pk_fma_f32 v[2:3], v[30:31], v[2:3], v[26:27]
	v_cvt_pk_bf16_f32 v0, v0, v1
	v_cvt_pk_bf16_f32 v1, v2, v3
	global_store_dwordx2 v201, v[0:1], s[50:51] sc1
	ds_read_b128 v[0:3], v196
	ds_read_b128 v[4:7], v197
	v_pk_mul_f32 v[80:81], v[80:81], v[120:121]
	v_pk_mul_f32 v[82:83], v[82:83], v[122:123]
	s_waitcnt lgkmcnt(0)
	v_pk_fma_f32 v[80:81], v[80:81], v[4:5], v[0:1]
	v_pk_fma_f32 v[82:83], v[82:83], v[6:7], v[2:3]
	v_cvt_pk_bf16_f32 v80, v80, v81
	v_cvt_pk_bf16_f32 v81, v82, v83
	global_store_dwordx2 v210, v[80:81], s[50:51] sc1
	v_mul_f32_e32 v86, 0x4b800000, v90
	v_cndmask_b32_e32 v86, v90, v86, vcc
	v_rsq_f32_e32 v88, v86
	v_lshl_add_u64 v[86:87], v[144:145], 0, s[48:49]
	s_add_u32 s48, s12, s48
	s_addc_u32 s49, s13, s49
	v_mul_f32_e32 v89, 0x45800000, v88
	v_cndmask_b32_e32 v88, v88, v89, vcc
	v_pk_mul_f32 v[78:79], v[78:79], v[88:89] op_sel_hi:[1, 0]
	v_pk_mul_f32 v[76:77], v[76:77], v[88:89] op_sel_hi:[1, 0]
	v_pk_mul_f32 v[70:71], v[70:71], v[88:89] op_sel_hi:[1, 0]
	v_pk_mul_f32 v[68:69], v[68:69], v[88:89] op_sel_hi:[1, 0]
	v_pk_mul_f32 v[66:67], v[66:67], v[88:89] op_sel_hi:[1, 0]
	v_pk_mul_f32 v[64:65], v[64:65], v[88:89] op_sel_hi:[1, 0]
	v_mul_f32_e32 v89, v52, v52
	v_pk_mul_f32 v[38:39], v[38:39], v[88:89] op_sel_hi:[1, 0]
	v_pk_mul_f32 v[36:37], v[36:37], v[88:89] op_sel_hi:[1, 0]
	v_pk_mul_f32 v[90:91], v[48:49], v[48:49]
	s_lshl_b64 s[46:47], s[46:47], 11
	v_pk_mul_f32 v[76:77], v[108:109], v[76:77]
	v_pk_mul_f32 v[78:79], v[110:111], v[78:79]
	v_pk_fma_f32 v[76:77], v[12:13], v[76:77], v[8:9]
	v_pk_fma_f32 v[78:79], v[14:15], v[78:79], v[10:11]
	v_cvt_pk_bf16_f32 v76, v76, v77
	v_cvt_pk_bf16_f32 v77, v78, v79
	global_store_dwordx2 v[86:87], v[76:77], off sc1
	v_mul_f32_e32 v80, v57, v57
	v_mul_f32_e32 v82, v59, v59
	v_pk_mul_f32 v[86:87], v[50:51], v[50:51]
	v_pk_mul_f32 v[68:69], v[112:113], v[68:69]
	v_pk_mul_f32 v[70:71], v[114:115], v[70:71]
	v_pk_fma_f32 v[68:69], v[20:21], v[68:69], v[16:17]
	v_pk_fma_f32 v[70:71], v[22:23], v[70:71], v[18:19]
	v_cvt_pk_bf16_f32 v68, v68, v69
	v_cvt_pk_bf16_f32 v69, v70, v71
	global_store_dwordx2 v200, v[68:69], s[48:49] sc1
	v_pk_mul_f32 v[76:77], v[62:63], v[62:63]
	v_pk_mul_f32 v[78:79], v[60:61], v[60:61]
	v_pk_mul_f32 v[64:65], v[116:117], v[64:65]
	v_pk_mul_f32 v[66:67], v[118:119], v[66:67]
	v_pk_fma_f32 v[64:65], v[28:29], v[64:65], v[24:25]
	v_pk_fma_f32 v[66:67], v[30:31], v[66:67], v[26:27]
	v_cvt_pk_bf16_f32 v64, v64, v65
	v_cvt_pk_bf16_f32 v65, v66, v67
	global_store_dwordx2 v201, v[64:65], s[48:49] sc1
	v_pk_mul_f32 v[68:69], v[74:75], v[74:75]
	v_pk_mul_f32 v[70:71], v[72:73], v[72:73]
	v_pk_mul_f32 v[36:37], v[120:121], v[36:37]
	v_pk_mul_f32 v[38:39], v[122:123], v[38:39]
	v_pk_fma_f32 v[36:37], v[4:5], v[36:37], v[0:1]
	v_pk_fma_f32 v[38:39], v[6:7], v[38:39], v[2:3]
	v_cvt_pk_bf16_f32 v36, v36, v37
	v_cvt_pk_bf16_f32 v37, v38, v39
	global_store_dwordx2 v210, v[36:37], s[48:49] sc1
	v_pk_mov_b32 v[100:101], v[70:71], v[68:69] op_sel:[1, 0]
	v_mov_b32_e32 v71, v69
	v_pk_mov_b32 v[68:69], v[78:79], v[76:77] op_sel:[1, 0]
	v_mov_b32_e32 v79, v77
	v_pk_fma_f32 v[76:77], v[56:57], v[56:57], v[80:81] op_sel_hi:[1, 1, 0]
	v_pk_fma_f32 v[80:81], v[58:59], v[58:59], v[82:83] op_sel_hi:[1, 1, 0]
	v_pk_mov_b32 v[82:83], v[90:91], v[86:87] op_sel:[1, 0]
	v_mov_b32_e32 v91, v87
	v_pk_mov_b32 v[86:87], v[94:95], v[92:93] op_sel:[1, 0]
	v_mov_b32_e32 v95, v93
	v_pk_add_f32 v[70:71], v[100:101], v[70:71]
	v_pk_add_f32 v[64:65], v[68:69], v[78:79]
	v_pk_add_f32 v[66:67], v[82:83], v[90:91]
	v_pk_add_f32 v[68:69], v[86:87], v[94:95]
	v_pk_fma_f32 v[92:93], v[40:41], v[40:41], v[96:97] op_sel_hi:[1, 1, 0]
	v_pk_fma_f32 v[96:97], v[42:43], v[42:43], v[98:99] op_sel_hi:[1, 1, 0]
	v_pk_add_f32 v[70:71], v[70:71], v[70:71] op_sel:[0, 1] op_sel_hi:[1, 0]
	v_pk_add_f32 v[64:65], v[64:65], v[64:65] op_sel:[0, 1] op_sel_hi:[1, 0]
	v_pk_add_f32 v[66:67], v[66:67], v[66:67] op_sel:[0, 1] op_sel_hi:[1, 0]
	v_pk_add_f32 v[68:69], v[68:69], v[68:69] op_sel:[0, 1] op_sel_hi:[1, 0]
	v_mov_b32_e32 v77, v102
	v_mov_b32_e32 v81, v103
	v_mov_b32_e32 v93, v106
	v_mov_b32_e32 v97, v107
	v_mov_b32_e32 v71, v89
	v_mov_b32_e32 v65, v99
	v_mov_b32_e32 v67, v104
	v_mov_b32_e32 v69, v105
	v_pk_add_f32 v[76:77], v[76:77], v[80:81]
	v_pk_add_f32 v[78:79], v[92:93], v[96:97]
	v_pk_add_f32 v[64:65], v[70:71], v[64:65]
	v_pk_add_f32 v[66:67], v[66:67], v[68:69]
	v_pk_add_f32 v[64:65], v[64:65], v[76:77]
	v_pk_add_f32 v[66:67], v[66:67], v[78:79]
	v_mov_b32_e32 v69, v64
	v_mov_b32_e32 v68, v66
	v_mov_b32_e32 v64, v67
	v_pk_add_f32 v[64:65], v[68:69], v[64:65]
	s_waitcnt lgkmcnt(0)
	s_nop 1
	v_add_f32_dpp v64, v64, v64 quad_perm:[1,0,3,2] row_mask:0xf bank_mask:0xf
	v_add_f32_dpp v65, v65, v65 quad_perm:[1,0,3,2] row_mask:0xf bank_mask:0xf
	s_waitcnt lgkmcnt(0)
	s_nop 1
	v_add_f32_dpp v64, v64, v64 quad_perm:[2,3,0,1] row_mask:0xf bank_mask:0xf
	v_add_f32_dpp v65, v65, v65 quad_perm:[2,3,0,1] row_mask:0xf bank_mask:0xf
	s_waitcnt lgkmcnt(0)
	s_nop 1
	v_add_f32_dpp v64, v64, v64 row_half_mirror row_mask:0xf bank_mask:0xf
	v_add_f32_dpp v65, v65, v65 row_half_mirror row_mask:0xf bank_mask:0xf
	s_waitcnt lgkmcnt(0)
	s_nop 1
	v_add_f32_dpp v64, v64, v64 row_mirror row_mask:0xf bank_mask:0xf
	v_add_f32_dpp v65, v65, v65 row_mirror row_mask:0xf bank_mask:0xf
	ds_bpermute_b32 v67, v188, v65
	ds_bpermute_b32 v66, v188, v64
	s_waitcnt lgkmcnt(0)
	v_pk_add_f32 v[64:65], v[64:65], v[66:67]
	s_waitcnt lgkmcnt(0)
	v_mov_b32_e32 v66, v64
	v_mov_b32_e32 v67, v65
	s_nop 1
	v_permlane32_swap_b32_e32 v66, v64
	v_permlane32_swap_b32_e32 v67, v65
	v_pk_add_f32 v[64:65], v[64:65], v[66:67]
	s_nop 0
	v_pk_fma_f32 v[64:65], v[64:65], s[28:29], v[84:85] op_sel_hi:[1, 0, 0]
	s_nop 0
	v_mul_f32_e32 v66, 0x4b800000, v65
	v_cmp_gt_f32_e32 vcc, s79, v65
	s_nop 1
	v_cndmask_b32_e32 v65, v65, v66, vcc
	v_rsq_f32_e32 v65, v65
	v_lshl_add_u64 v[66:67], v[144:145], 0, s[46:47]
	s_add_u32 s46, s12, s46
	s_addc_u32 s47, s13, s47
	v_mul_f32_e32 v68, 0x45800000, v65
	v_cndmask_b32_e32 v68, v65, v68, vcc
	v_pk_mul_f32 v[70:71], v[74:75], v[68:69] op_sel_hi:[1, 0]
	v_pk_mul_f32 v[72:73], v[72:73], v[68:69] op_sel_hi:[1, 0]
	v_pk_mul_f32 v[38:39], v[110:111], v[70:71]
	v_pk_mul_f32 v[36:37], v[108:109], v[72:73]
	v_pk_fma_f32 v[38:39], v[14:15], v[38:39], v[10:11]
	v_pk_fma_f32 v[36:37], v[12:13], v[36:37], v[8:9]
	v_pk_mul_f32 v[62:63], v[62:63], v[68:69] op_sel_hi:[1, 0]
	v_cvt_pk_bf16_f32 v36, v36, v37
	v_cvt_pk_bf16_f32 v37, v38, v39
	global_store_dwordx2 v[66:67], v[36:37], off sc1
	v_pk_mul_f32 v[60:61], v[60:61], v[68:69] op_sel_hi:[1, 0]
	v_pk_mul_f32 v[58:59], v[58:59], v[68:69] op_sel_hi:[1, 0]
	v_pk_mul_f32 v[56:57], v[56:57], v[68:69] op_sel_hi:[1, 0]
	v_pk_mul_f32 v[54:55], v[54:55], v[68:69] op_sel_hi:[1, 0]
	v_pk_mul_f32 v[52:53], v[52:53], v[68:69] op_sel_hi:[1, 0]
	v_cmp_gt_f32_e32 vcc, s79, v64
	s_lshl_b64 s[44:45], s[44:45], 11
	v_pk_mul_f32 v[36:37], v[112:113], v[60:61]
	v_pk_mul_f32 v[38:39], v[114:115], v[62:63]
	v_pk_fma_f32 v[36:37], v[20:21], v[36:37], v[16:17]
	v_pk_fma_f32 v[38:39], v[22:23], v[38:39], v[18:19]
	v_cvt_pk_bf16_f32 v36, v36, v37
	v_cvt_pk_bf16_f32 v37, v38, v39
	global_store_dwordx2 v200, v[36:37], s[46:47] sc1
	v_pk_mul_f32 v[36:37], v[116:117], v[56:57]
	v_pk_mul_f32 v[38:39], v[118:119], v[58:59]
	v_pk_fma_f32 v[36:37], v[28:29], v[36:37], v[24:25]
	v_pk_fma_f32 v[38:39], v[30:31], v[38:39], v[26:27]
	v_cvt_pk_bf16_f32 v36, v36, v37
	v_cvt_pk_bf16_f32 v37, v38, v39
	global_store_dwordx2 v201, v[36:37], s[46:47] sc1
	v_pk_mul_f32 v[36:37], v[120:121], v[52:53]
	v_pk_mul_f32 v[38:39], v[122:123], v[54:55]
	v_pk_fma_f32 v[36:37], v[4:5], v[36:37], v[0:1]
	v_pk_fma_f32 v[38:39], v[6:7], v[38:39], v[2:3]
	v_cvt_pk_bf16_f32 v36, v36, v37
	v_cvt_pk_bf16_f32 v37, v38, v39
	global_store_dwordx2 v210, v[36:37], s[46:47] sc1
	v_mul_f32_e32 v52, 0x4b800000, v64
	v_cndmask_b32_e32 v52, v64, v52, vcc
	v_rsq_f32_e32 v54, v52
	v_lshl_add_u64 v[52:53], v[144:145], 0, s[44:45]
	s_add_u32 s44, s12, s44
	s_addc_u32 s45, s13, s45
	v_mul_f32_e32 v55, 0x45800000, v54
	v_cndmask_b32_e32 v54, v54, v55, vcc
	v_pk_mul_f32 v[50:51], v[50:51], v[54:55] op_sel_hi:[1, 0]
	v_pk_mul_f32 v[48:49], v[48:49], v[54:55] op_sel_hi:[1, 0]
	v_pk_mul_f32 v[46:47], v[46:47], v[54:55] op_sel_hi:[1, 0]
	v_pk_mul_f32 v[44:45], v[44:45], v[54:55] op_sel_hi:[1, 0]
	v_pk_mul_f32 v[42:43], v[42:43], v[54:55] op_sel_hi:[1, 0]
	v_pk_mul_f32 v[40:41], v[40:41], v[54:55] op_sel_hi:[1, 0]
	v_pk_mul_f32 v[34:35], v[34:35], v[54:55] op_sel_hi:[1, 0]
	v_pk_mul_f32 v[32:33], v[32:33], v[54:55] op_sel_hi:[1, 0]
	s_or_b32 s48, s42, 4
	s_ashr_i32 s49, s48, 31
	s_lshl_b64 s[46:47], s[48:49], 12
	s_lshl_b64 s[48:49], s[48:49], 11
	v_lshl_add_u64 v[104:105], v[144:145], 0, s[48:49]
	v_pk_mul_f32 v[36:37], v[108:109], v[48:49]
	v_pk_mul_f32 v[38:39], v[110:111], v[50:51]
	v_pk_fma_f32 v[36:37], v[12:13], v[36:37], v[8:9]
	v_pk_fma_f32 v[38:39], v[14:15], v[38:39], v[10:11]
	v_cvt_pk_bf16_f32 v36, v36, v37
	v_cvt_pk_bf16_f32 v37, v38, v39
	global_store_dwordx2 v[52:53], v[36:37], off sc1
	v_pk_mul_f32 v[36:37], v[112:113], v[44:45]
	v_pk_mul_f32 v[38:39], v[114:115], v[46:47]
	v_pk_fma_f32 v[36:37], v[20:21], v[36:37], v[16:17]
	v_pk_fma_f32 v[38:39], v[22:23], v[38:39], v[18:19]
	v_cvt_pk_bf16_f32 v36, v36, v37
	v_cvt_pk_bf16_f32 v37, v38, v39
	global_store_dwordx2 v200, v[36:37], s[44:45] sc1
	v_pk_mul_f32 v[36:37], v[116:117], v[40:41]
	v_pk_mul_f32 v[38:39], v[118:119], v[42:43]
	v_pk_fma_f32 v[36:37], v[28:29], v[36:37], v[24:25]
	v_pk_fma_f32 v[38:39], v[30:31], v[38:39], v[26:27]
	v_cvt_pk_bf16_f32 v36, v36, v37
	v_cvt_pk_bf16_f32 v37, v38, v39
	global_store_dwordx2 v201, v[36:37], s[44:45] sc1
	v_lshl_add_u64 v[40:41], v[140:141], 0, s[46:47]
	s_or_b32 s46, s42, 5
	s_ashr_i32 s47, s46, 31
	v_pk_mul_f32 v[32:33], v[120:121], v[32:33]
	v_pk_mul_f32 v[34:35], v[122:123], v[34:35]
	v_pk_fma_f32 v[32:33], v[4:5], v[32:33], v[0:1]
	v_pk_fma_f32 v[34:35], v[6:7], v[34:35], v[2:3]
	v_cvt_pk_bf16_f32 v32, v32, v33
	v_cvt_pk_bf16_f32 v33, v34, v35
	global_store_dwordx2 v210, v[32:33], s[44:45] sc1
	global_load_dwordx4 v[86:89], v[40:41], off
	global_load_dwordx4 v[90:93], v[40:41], off offset:1024
	global_load_dwordx4 v[80:83], v[40:41], off offset:3072
	global_load_dwordx4 v[94:97], v[40:41], off offset:2048
	s_lshl_b64 s[44:45], s[46:47], 12
	v_lshl_add_u64 v[32:33], v[140:141], 0, s[44:45]
	global_load_dwordx4 v[76:79], v[32:33], off
	global_load_dwordx4 v[72:75], v[32:33], off offset:1024
	global_load_dwordx4 v[36:39], v[32:33], off offset:3072
	global_load_dwordx4 v[68:71], v[32:33], off offset:2048
	s_or_b32 s44, s42, 6
	s_or_b32 s42, s42, 7
	s_ashr_i32 s45, s44, 31
	s_ashr_i32 s43, s42, 31
	s_lshl_b64 s[50:51], s[44:45], 12
	s_lshl_b64 s[52:53], s[42:43], 12
	s_add_u32 s48, s12, s48
	s_addc_u32 s49, s13, s49
	s_lshl_b64 s[46:47], s[46:47], 11
	s_waitcnt vmcnt(7)
	v_pk_mul_f32 v[32:33], v[88:89], v[88:89]
	v_pk_mul_f32 v[34:35], v[86:87], v[86:87]
	s_waitcnt vmcnt(6)
	v_pk_mul_f32 v[40:41], v[92:93], v[92:93]
	v_pk_mul_f32 v[42:43], v[90:91], v[90:91]
	s_waitcnt vmcnt(4)
	v_mul_f32_e32 v44, v95, v95
	v_mul_f32_e32 v46, v97, v97
	s_waitcnt vmcnt(3)
	v_pk_mul_f32 v[48:49], v[78:79], v[78:79]
	v_pk_mul_f32 v[50:51], v[76:77], v[76:77]
	s_waitcnt vmcnt(2)
	v_pk_mul_f32 v[52:53], v[74:75], v[74:75]
	v_pk_mul_f32 v[54:55], v[72:73], v[72:73]
	v_mul_f32_e32 v63, v82, v82
	v_mul_f32_e32 v64, v83, v83
	v_pk_mov_b32 v[60:61], v[34:35], v[32:33] op_sel:[1, 0]
	v_mov_b32_e32 v35, v33
	v_pk_mov_b32 v[32:33], v[42:43], v[40:41] op_sel:[1, 0]
	v_mov_b32_e32 v43, v41
	v_pk_fma_f32 v[40:41], v[94:95], v[94:95], v[44:45] op_sel_hi:[1, 1, 0]
	v_pk_fma_f32 v[44:45], v[96:97], v[96:97], v[46:47] op_sel_hi:[1, 1, 0]
	v_pk_mov_b32 v[46:47], v[50:51], v[48:49] op_sel:[1, 0]
	v_mov_b32_e32 v51, v49
	v_pk_mov_b32 v[48:49], v[54:55], v[52:53] op_sel:[1, 0]
	v_mov_b32_e32 v55, v53
	v_mul_f32_e32 v59, v80, v80
	s_waitcnt vmcnt(0)
	v_mul_f32_e32 v56, v69, v69
	v_mul_f32_e32 v58, v71, v71
	v_pk_add_f32 v[34:35], v[60:61], v[34:35]
	v_pk_add_f32 v[32:33], v[32:33], v[42:43]
	v_mov_b32_e32 v41, v63
	v_mov_b32_e32 v45, v64
	v_pk_add_f32 v[42:43], v[46:47], v[50:51]
	v_pk_add_f32 v[46:47], v[48:49], v[54:55]
	v_mul_f32_e32 v62, v81, v81
	v_mul_f32_e32 v65, v36, v36
	v_mul_f32_e32 v66, v37, v37
	v_mul_f32_e32 v67, v38, v38
	v_mul_f32_e32 v102, v39, v39
	v_pk_fma_f32 v[52:53], v[68:69], v[68:69], v[56:57] op_sel_hi:[1, 1, 0]
	v_pk_fma_f32 v[56:57], v[70:71], v[70:71], v[58:59] op_sel_hi:[1, 1, 0]
	v_pk_add_f32 v[34:35], v[34:35], v[34:35] op_sel:[0, 1] op_sel_hi:[1, 0]
	v_pk_add_f32 v[32:33], v[32:33], v[32:33] op_sel:[0, 1] op_sel_hi:[1, 0]
	v_pk_add_f32 v[40:41], v[40:41], v[44:45]
	v_pk_add_f32 v[42:43], v[42:43], v[42:43] op_sel:[0, 1] op_sel_hi:[1, 0]
	v_pk_add_f32 v[44:45], v[46:47], v[46:47] op_sel:[0, 1] op_sel_hi:[1, 0]
	v_mov_b32_e32 v53, v67
	v_mov_b32_e32 v57, v102
	v_mov_b32_e32 v35, v59
	v_mov_b32_e32 v33, v62
	v_mov_b32_e32 v43, v65
	v_mov_b32_e32 v45, v66
	v_pk_add_f32 v[46:47], v[52:53], v[56:57]
	v_pk_add_f32 v[32:33], v[34:35], v[32:33]
	v_pk_add_f32 v[34:35], v[42:43], v[44:45]
	v_pk_add_f32 v[32:33], v[32:33], v[40:41]
	v_pk_add_f32 v[34:35], v[34:35], v[46:47]
	v_mov_b32_e32 v41, v32
	v_mov_b32_e32 v40, v34
	v_mov_b32_e32 v32, v35
	v_pk_add_f32 v[32:33], v[40:41], v[32:33]
	v_lshl_add_u64 v[40:41], v[140:141], 0, s[50:51]
	v_lshl_add_u64 v[102:103], v[140:141], 0, s[52:53]
	global_load_dwordx4 v[64:67], v[40:41], off
	global_load_dwordx4 v[60:63], v[40:41], off offset:1024
	global_load_dwordx4 v[56:59], v[40:41], off offset:2048
	global_load_dwordx4 v[52:55], v[40:41], off offset:3072
	s_waitcnt lgkmcnt(0)
	s_nop 1
	v_add_f32_dpp v32, v32, v32 quad_perm:[1,0,3,2] row_mask:0xf bank_mask:0xf
	v_add_f32_dpp v33, v33, v33 quad_perm:[1,0,3,2] row_mask:0xf bank_mask:0xf
	s_waitcnt lgkmcnt(0)
	s_nop 1
	v_add_f32_dpp v32, v32, v32 quad_perm:[2,3,0,1] row_mask:0xf bank_mask:0xf
	v_add_f32_dpp v33, v33, v33 quad_perm:[2,3,0,1] row_mask:0xf bank_mask:0xf
	s_waitcnt lgkmcnt(0)
	s_nop 1
	v_add_f32_dpp v32, v32, v32 row_half_mirror row_mask:0xf bank_mask:0xf
	v_add_f32_dpp v33, v33, v33 row_half_mirror row_mask:0xf bank_mask:0xf
	s_waitcnt lgkmcnt(0)
	s_nop 1
	v_add_f32_dpp v32, v32, v32 row_mirror row_mask:0xf bank_mask:0xf
	v_add_f32_dpp v33, v33, v33 row_mirror row_mask:0xf bank_mask:0xf
	ds_bpermute_b32 v35, v188, v33
	ds_bpermute_b32 v34, v188, v32
	s_waitcnt lgkmcnt(0)
	v_pk_add_f32 v[32:33], v[32:33], v[34:35]
	s_waitcnt lgkmcnt(0)
	v_mov_b32_e32 v34, v32
	v_mov_b32_e32 v35, v33
	s_nop 1
	v_permlane32_swap_b32_e32 v34, v32
	v_permlane32_swap_b32_e32 v35, v33
	v_pk_add_f32 v[32:33], v[32:33], v[34:35]
	s_nop 0
	v_pk_fma_f32 v[106:107], v[32:33], s[28:29], v[84:85] op_sel_hi:[1, 0, 0]
	s_nop 0
	v_mul_f32_e32 v32, 0x4b800000, v107
	v_cmp_gt_f32_e32 vcc, s79, v107
	s_nop 1
	v_cndmask_b32_e32 v32, v107, v32, vcc
	v_rsq_f32_e32 v107, v32
	global_load_dwordx4 v[48:51], v[102:103], off
	global_load_dwordx4 v[44:47], v[102:103], off offset:1024
	global_load_dwordx4 v[40:43], v[102:103], off offset:2048
	global_load_dwordx4 v[32:35], v[102:103], off offset:3072
	v_mul_f32_e32 v102, 0x45800000, v107
	v_cndmask_b32_e32 v102, v107, v102, vcc
	v_pk_mul_f32 v[88:89], v[88:89], v[102:103] op_sel_hi:[1, 0]
	v_pk_mul_f32 v[86:87], v[86:87], v[102:103] op_sel_hi:[1, 0]
	v_pk_mul_f32 v[88:89], v[110:111], v[88:89]
	v_pk_mul_f32 v[86:87], v[108:109], v[86:87]
	v_pk_fma_f32 v[88:89], v[14:15], v[88:89], v[10:11]
	v_pk_fma_f32 v[86:87], v[12:13], v[86:87], v[8:9]
	v_pk_mul_f32 v[92:93], v[92:93], v[102:103] op_sel_hi:[1, 0]
	v_cvt_pk_bf16_f32 v86, v86, v87
	v_cvt_pk_bf16_f32 v87, v88, v89
	global_store_dwordx2 v[104:105], v[86:87], off sc1
	v_pk_mul_f32 v[90:91], v[90:91], v[102:103] op_sel_hi:[1, 0]
	v_pk_mul_f32 v[82:83], v[82:83], v[102:103] op_sel_hi:[1, 0]
	v_pk_mul_f32 v[80:81], v[80:81], v[102:103] op_sel_hi:[1, 0]
	v_cmp_gt_f32_e32 vcc, s79, v106
	s_waitcnt vmcnt(5)
	v_mul_f32_e32 v99, v53, v53
	s_waitcnt vmcnt(2)
	v_mul_f32_e32 v98, v43, v43
	s_waitcnt vmcnt(1)
	v_mul_f32_e32 v104, v32, v32
	v_mul_f32_e32 v105, v33, v33
	v_mul_f32_e32 v107, v35, v35
	v_pk_mul_f32 v[86:87], v[112:113], v[90:91]
	v_pk_mul_f32 v[88:89], v[114:115], v[92:93]
	v_pk_fma_f32 v[86:87], v[20:21], v[86:87], v[16:17]
	v_pk_fma_f32 v[88:89], v[22:23], v[88:89], v[18:19]
	v_cvt_pk_bf16_f32 v86, v86, v87
	v_cvt_pk_bf16_f32 v87, v88, v89
	global_store_dwordx2 v200, v[86:87], s[48:49] sc1
	v_pk_mul_f32 v[90:91], v[96:97], v[102:103] op_sel_hi:[1, 0]
	v_pk_mul_f32 v[92:93], v[94:95], v[102:103] op_sel_hi:[1, 0]
	v_pk_mul_f32 v[94:95], v[44:45], v[44:45]
	v_mul_f32_e32 v96, v41, v41
	v_mul_f32_e32 v102, v54, v54
	v_mul_f32_e32 v103, v55, v55
	v_pk_mul_f32 v[86:87], v[116:117], v[92:93]
	v_pk_mul_f32 v[88:89], v[118:119], v[90:91]
	v_pk_fma_f32 v[86:87], v[28:29], v[86:87], v[24:25]
	v_pk_fma_f32 v[88:89], v[30:31], v[88:89], v[26:27]
	v_cvt_pk_bf16_f32 v86, v86, v87
	v_cvt_pk_bf16_f32 v87, v88, v89
	global_store_dwordx2 v201, v[86:87], s[48:49] sc1
	v_pk_mul_f32 v[90:91], v[48:49], v[48:49]
	v_pk_mul_f32 v[92:93], v[46:47], v[46:47]
	v_pk_mul_f32 v[80:81], v[120:121], v[80:81]
	v_pk_mul_f32 v[82:83], v[122:123], v[82:83]
	v_pk_fma_f32 v[80:81], v[4:5], v[80:81], v[0:1]
	v_pk_fma_f32 v[82:83], v[6:7], v[82:83], v[2:3]
	v_cvt_pk_bf16_f32 v80, v80, v81
	v_cvt_pk_bf16_f32 v81, v82, v83
	global_store_dwordx2 v210, v[80:81], s[48:49] sc1
	v_mul_f32_e32 v86, 0x4b800000, v106
	v_cndmask_b32_e32 v86, v106, v86, vcc
	v_rsq_f32_e32 v88, v86
	v_lshl_add_u64 v[86:87], v[144:145], 0, s[46:47]
	s_add_u32 s46, s12, s46
	s_addc_u32 s47, s13, s47
	v_mul_f32_e32 v89, 0x45800000, v88
	v_cndmask_b32_e32 v88, v88, v89, vcc
	v_pk_mul_f32 v[78:79], v[78:79], v[88:89] op_sel_hi:[1, 0]
	v_pk_mul_f32 v[76:77], v[76:77], v[88:89] op_sel_hi:[1, 0]
	v_pk_mul_f32 v[74:75], v[74:75], v[88:89] op_sel_hi:[1, 0]
	v_pk_mul_f32 v[72:73], v[72:73], v[88:89] op_sel_hi:[1, 0]
	v_pk_mul_f32 v[70:71], v[70:71], v[88:89] op_sel_hi:[1, 0]
	v_pk_mul_f32 v[68:69], v[68:69], v[88:89] op_sel_hi:[1, 0]
	v_mul_f32_e32 v89, v52, v52
	v_pk_mul_f32 v[38:39], v[38:39], v[88:89] op_sel_hi:[1, 0]
	v_pk_mul_f32 v[36:37], v[36:37], v[88:89] op_sel_hi:[1, 0]
	v_mul_f32_e32 v106, v34, v34
	s_lshl_b64 s[44:45], s[44:45], 11
	v_pk_mul_f32 v[76:77], v[108:109], v[76:77]
	v_pk_mul_f32 v[78:79], v[110:111], v[78:79]
	v_pk_fma_f32 v[76:77], v[12:13], v[76:77], v[8:9]
	v_pk_fma_f32 v[78:79], v[14:15], v[78:79], v[10:11]
	v_cvt_pk_bf16_f32 v76, v76, v77
	v_cvt_pk_bf16_f32 v77, v78, v79
	global_store_dwordx2 v[86:87], v[76:77], off sc1
	v_mul_f32_e32 v80, v57, v57
	v_mul_f32_e32 v82, v59, v59
	v_pk_mul_f32 v[86:87], v[50:51], v[50:51]
	v_pk_mul_f32 v[72:73], v[112:113], v[72:73]
	v_pk_mul_f32 v[74:75], v[114:115], v[74:75]
	v_pk_fma_f32 v[72:73], v[20:21], v[72:73], v[16:17]
	v_pk_fma_f32 v[74:75], v[22:23], v[74:75], v[18:19]
	v_cvt_pk_bf16_f32 v72, v72, v73
	v_cvt_pk_bf16_f32 v73, v74, v75
	global_store_dwordx2 v200, v[72:73], s[46:47] sc1
	v_pk_mul_f32 v[76:77], v[62:63], v[62:63]
	v_pk_mul_f32 v[78:79], v[60:61], v[60:61]
	v_pk_mul_f32 v[68:69], v[116:117], v[68:69]
	v_pk_mul_f32 v[70:71], v[118:119], v[70:71]
	v_pk_fma_f32 v[68:69], v[28:29], v[68:69], v[24:25]
	v_pk_fma_f32 v[70:71], v[30:31], v[70:71], v[26:27]
	v_cvt_pk_bf16_f32 v68, v68, v69
	v_cvt_pk_bf16_f32 v69, v70, v71
	global_store_dwordx2 v201, v[68:69], s[46:47] sc1
	v_pk_mul_f32 v[72:73], v[66:67], v[66:67]
	v_pk_mul_f32 v[74:75], v[64:65], v[64:65]
	v_pk_mul_f32 v[36:37], v[120:121], v[36:37]
	v_pk_mul_f32 v[38:39], v[122:123], v[38:39]
	v_pk_fma_f32 v[36:37], v[4:5], v[36:37], v[0:1]
	v_pk_fma_f32 v[38:39], v[6:7], v[38:39], v[2:3]
	v_cvt_pk_bf16_f32 v36, v36, v37
	v_cvt_pk_bf16_f32 v37, v38, v39
	global_store_dwordx2 v210, v[36:37], s[46:47] sc1
	v_pk_mov_b32 v[100:101], v[74:75], v[72:73] op_sel:[1, 0]
	v_mov_b32_e32 v75, v73
	v_pk_mov_b32 v[72:73], v[78:79], v[76:77] op_sel:[1, 0]
	v_mov_b32_e32 v79, v77
	v_pk_fma_f32 v[76:77], v[56:57], v[56:57], v[80:81] op_sel_hi:[1, 1, 0]
	v_pk_fma_f32 v[80:81], v[58:59], v[58:59], v[82:83] op_sel_hi:[1, 1, 0]
	v_pk_mov_b32 v[82:83], v[90:91], v[86:87] op_sel:[1, 0]
	v_mov_b32_e32 v91, v87
	v_pk_mov_b32 v[86:87], v[94:95], v[92:93] op_sel:[1, 0]
	v_mov_b32_e32 v95, v93
	v_pk_add_f32 v[74:75], v[100:101], v[74:75]
	v_pk_add_f32 v[68:69], v[72:73], v[78:79]
	v_pk_add_f32 v[70:71], v[82:83], v[90:91]
	v_pk_add_f32 v[72:73], v[86:87], v[94:95]
	v_pk_fma_f32 v[92:93], v[40:41], v[40:41], v[96:97] op_sel_hi:[1, 1, 0]
	v_pk_fma_f32 v[96:97], v[42:43], v[42:43], v[98:99] op_sel_hi:[1, 1, 0]
	v_pk_add_f32 v[74:75], v[74:75], v[74:75] op_sel:[0, 1] op_sel_hi:[1, 0]
	v_pk_add_f32 v[68:69], v[68:69], v[68:69] op_sel:[0, 1] op_sel_hi:[1, 0]
	v_pk_add_f32 v[70:71], v[70:71], v[70:71] op_sel:[0, 1] op_sel_hi:[1, 0]
	v_pk_add_f32 v[72:73], v[72:73], v[72:73] op_sel:[0, 1] op_sel_hi:[1, 0]
	v_mov_b32_e32 v77, v102
	v_mov_b32_e32 v81, v103
	v_mov_b32_e32 v93, v106
	v_mov_b32_e32 v97, v107
	v_mov_b32_e32 v75, v89
	v_mov_b32_e32 v69, v99
	v_mov_b32_e32 v71, v104
	v_mov_b32_e32 v73, v105
	v_pk_add_f32 v[76:77], v[76:77], v[80:81]
	v_pk_add_f32 v[78:79], v[92:93], v[96:97]
	v_pk_add_f32 v[68:69], v[74:75], v[68:69]
	v_pk_add_f32 v[70:71], v[70:71], v[72:73]
	v_pk_add_f32 v[68:69], v[68:69], v[76:77]
	v_pk_add_f32 v[70:71], v[70:71], v[78:79]
	v_mov_b32_e32 v73, v68
	v_mov_b32_e32 v72, v70
	v_mov_b32_e32 v68, v71
	v_pk_add_f32 v[68:69], v[72:73], v[68:69]
	s_waitcnt lgkmcnt(0)
	s_nop 1
	v_add_f32_dpp v68, v68, v68 quad_perm:[1,0,3,2] row_mask:0xf bank_mask:0xf
	v_add_f32_dpp v69, v69, v69 quad_perm:[1,0,3,2] row_mask:0xf bank_mask:0xf
	s_waitcnt lgkmcnt(0)
	s_nop 1
	v_add_f32_dpp v68, v68, v68 quad_perm:[2,3,0,1] row_mask:0xf bank_mask:0xf
	v_add_f32_dpp v69, v69, v69 quad_perm:[2,3,0,1] row_mask:0xf bank_mask:0xf
	s_waitcnt lgkmcnt(0)
	s_nop 1
	v_add_f32_dpp v68, v68, v68 row_half_mirror row_mask:0xf bank_mask:0xf
	v_add_f32_dpp v69, v69, v69 row_half_mirror row_mask:0xf bank_mask:0xf
	s_waitcnt lgkmcnt(0)
	s_nop 1
	v_add_f32_dpp v68, v68, v68 row_mirror row_mask:0xf bank_mask:0xf
	v_add_f32_dpp v69, v69, v69 row_mirror row_mask:0xf bank_mask:0xf
	ds_bpermute_b32 v71, v188, v69
	ds_bpermute_b32 v70, v188, v68
	s_waitcnt lgkmcnt(0)
	v_pk_add_f32 v[68:69], v[68:69], v[70:71]
	s_waitcnt lgkmcnt(0)
	v_mov_b32_e32 v70, v68
	v_mov_b32_e32 v71, v69
	s_nop 1
	v_permlane32_swap_b32_e32 v70, v68
	v_permlane32_swap_b32_e32 v71, v69
	v_pk_add_f32 v[68:69], v[68:69], v[70:71]
	s_nop 0
	v_pk_fma_f32 v[68:69], v[68:69], s[28:29], v[84:85] op_sel_hi:[1, 0, 0]
	s_nop 0
	v_mul_f32_e32 v70, 0x4b800000, v69
	v_cmp_gt_f32_e32 vcc, s79, v69
	s_nop 1
	v_cndmask_b32_e32 v69, v69, v70, vcc
	v_rsq_f32_e32 v69, v69
	v_lshl_add_u64 v[70:71], v[144:145], 0, s[44:45]
	s_add_u32 s44, s12, s44
	s_addc_u32 s45, s13, s45
	v_mul_f32_e32 v72, 0x45800000, v69
	v_cndmask_b32_e32 v72, v69, v72, vcc
	v_pk_mul_f32 v[66:67], v[66:67], v[72:73] op_sel_hi:[1, 0]
	v_pk_mul_f32 v[64:65], v[64:65], v[72:73] op_sel_hi:[1, 0]
	v_pk_mul_f32 v[38:39], v[110:111], v[66:67]
	v_pk_mul_f32 v[36:37], v[108:109], v[64:65]
	v_pk_fma_f32 v[38:39], v[14:15], v[38:39], v[10:11]
	v_pk_fma_f32 v[36:37], v[12:13], v[36:37], v[8:9]
	v_pk_mul_f32 v[62:63], v[62:63], v[72:73] op_sel_hi:[1, 0]
	v_cvt_pk_bf16_f32 v36, v36, v37
	v_cvt_pk_bf16_f32 v37, v38, v39
	global_store_dwordx2 v[70:71], v[36:37], off sc1
	v_pk_mul_f32 v[60:61], v[60:61], v[72:73] op_sel_hi:[1, 0]
	v_pk_mul_f32 v[58:59], v[58:59], v[72:73] op_sel_hi:[1, 0]
	v_pk_mul_f32 v[56:57], v[56:57], v[72:73] op_sel_hi:[1, 0]
	v_pk_mul_f32 v[54:55], v[54:55], v[72:73] op_sel_hi:[1, 0]
	v_pk_mul_f32 v[52:53], v[52:53], v[72:73] op_sel_hi:[1, 0]
	v_cmp_gt_f32_e32 vcc, s79, v68
	s_lshl_b64 s[42:43], s[42:43], 11
	v_pk_mul_f32 v[36:37], v[112:113], v[60:61]
	v_pk_mul_f32 v[38:39], v[114:115], v[62:63]
	v_pk_fma_f32 v[36:37], v[20:21], v[36:37], v[16:17]
	v_pk_fma_f32 v[38:39], v[22:23], v[38:39], v[18:19]
	v_cvt_pk_bf16_f32 v36, v36, v37
	v_cvt_pk_bf16_f32 v37, v38, v39
	global_store_dwordx2 v200, v[36:37], s[44:45] sc1
	v_pk_mul_f32 v[36:37], v[116:117], v[56:57]
	v_pk_mul_f32 v[38:39], v[118:119], v[58:59]
	v_pk_fma_f32 v[36:37], v[28:29], v[36:37], v[24:25]
	v_pk_fma_f32 v[38:39], v[30:31], v[38:39], v[26:27]
	v_cvt_pk_bf16_f32 v36, v36, v37
	v_cvt_pk_bf16_f32 v37, v38, v39
	global_store_dwordx2 v201, v[36:37], s[44:45] sc1
	v_pk_mul_f32 v[36:37], v[120:121], v[52:53]
	v_pk_mul_f32 v[38:39], v[122:123], v[54:55]
	v_pk_fma_f32 v[36:37], v[4:5], v[36:37], v[0:1]
	v_pk_fma_f32 v[38:39], v[6:7], v[38:39], v[2:3]
	v_cvt_pk_bf16_f32 v36, v36, v37
	v_cvt_pk_bf16_f32 v37, v38, v39
	global_store_dwordx2 v210, v[36:37], s[44:45] sc1
	v_mul_f32_e32 v52, 0x4b800000, v68
	v_cndmask_b32_e32 v52, v68, v52, vcc
	v_rsq_f32_e32 v54, v52
	v_lshl_add_u64 v[52:53], v[144:145], 0, s[42:43]
	s_add_u32 s42, s12, s42
	s_addc_u32 s43, s13, s43
	v_mul_f32_e32 v55, 0x45800000, v54
	v_cndmask_b32_e32 v54, v54, v55, vcc
	v_pk_mul_f32 v[50:51], v[50:51], v[54:55] op_sel_hi:[1, 0]
	v_pk_mul_f32 v[48:49], v[48:49], v[54:55] op_sel_hi:[1, 0]
	s_andn2_b64 vcc, exec, s[8:9]
	s_mov_b64 s[8:9], -1
	v_pk_mul_f32 v[36:37], v[108:109], v[48:49]
	v_pk_mul_f32 v[38:39], v[110:111], v[50:51]
	v_pk_fma_f32 v[8:9], v[12:13], v[36:37], v[8:9]
	v_pk_fma_f32 v[10:11], v[14:15], v[38:39], v[10:11]
	v_cvt_pk_bf16_f32 v8, v8, v9
	v_cvt_pk_bf16_f32 v9, v10, v11
	global_store_dwordx2 v[52:53], v[8:9], off sc1
	v_pk_mul_f32 v[12:13], v[46:47], v[54:55] op_sel_hi:[1, 0]
	v_pk_mul_f32 v[14:15], v[44:45], v[54:55] op_sel_hi:[1, 0]
	v_pk_mul_f32 v[10:11], v[114:115], v[12:13]
	v_pk_mul_f32 v[8:9], v[112:113], v[14:15]
	v_pk_fma_f32 v[10:11], v[22:23], v[10:11], v[18:19]
	v_pk_fma_f32 v[8:9], v[20:21], v[8:9], v[16:17]
	v_pk_mul_f32 v[12:13], v[42:43], v[54:55] op_sel_hi:[1, 0]
	v_cvt_pk_bf16_f32 v8, v8, v9
	v_cvt_pk_bf16_f32 v9, v10, v11
	global_store_dwordx2 v200, v[8:9], s[42:43] sc1
	v_pk_mul_f32 v[14:15], v[40:41], v[54:55] op_sel_hi:[1, 0]
	v_pk_mul_f32 v[10:11], v[118:119], v[12:13]
	v_pk_mul_f32 v[8:9], v[116:117], v[14:15]
	v_pk_fma_f32 v[10:11], v[30:31], v[10:11], v[26:27]
	v_pk_fma_f32 v[8:9], v[28:29], v[8:9], v[24:25]
	v_pk_mul_f32 v[12:13], v[34:35], v[54:55] op_sel_hi:[1, 0]
	v_cvt_pk_bf16_f32 v8, v8, v9
	v_cvt_pk_bf16_f32 v9, v10, v11
	global_store_dwordx2 v201, v[8:9], s[42:43] sc1
	v_pk_mul_f32 v[14:15], v[32:33], v[54:55] op_sel_hi:[1, 0]
	v_pk_mul_f32 v[10:11], v[122:123], v[12:13]
	v_pk_mul_f32 v[8:9], v[120:121], v[14:15]
	v_pk_fma_f32 v[2:3], v[6:7], v[10:11], v[2:3]
	v_pk_fma_f32 v[0:1], v[4:5], v[8:9], v[0:1]
	s_nop 0
	v_cvt_pk_bf16_f32 v0, v0, v1
	v_cvt_pk_bf16_f32 v1, v2, v3
	global_store_dwordx2 v210, v[0:1], s[42:43] sc1
	s_cbranch_vccnz .LBB0_2350
	s_andn2_b64 vcc, exec, s[10:11]
	s_cbranch_vccnz .LBB0_2349
	s_barrier
	s_branch .LBB0_2349

.LBB0_2522:
	v_lshl_or_b32 v160, s60, 8, v177
	v_add_u32_e32 v144, 0x2000, v160
	v_ashrrev_i32_e32 v145, 31, v144
	s_ashr_i32 s30, s61, 3
	v_lshlrev_b64 v[148:149], 2, v[144:145]
	s_add_i32 s39, s30, 64
	v_lshl_add_u64 v[152:153], s[2:3], 0, v[148:149]
	v_lshl_add_u64 v[144:145], s[16:17], 0, v[148:149]
	v_mad_i64_i32 v[148:149], s[64:65], s39, v181, v[152:153]
	global_load_dwordx4 v[144:147], v[144:145], off
	s_add_i32 s38, s30, 0x48
	s_add_i32 s37, s30, 0x50
	s_add_i32 s36, s30, 0x58
	s_add_i32 s35, s30, 0x60
	s_add_i32 s34, s30, 0x68
	s_add_i32 s31, s30, 0x70
	s_addk_i32 s30, 0x78
	s_lshl_b32 s62, s61, 8
	global_load_dwordx4 v[148:151], v[148:149], off
	v_mad_i64_i32 v[182:183], s[64:65], s38, v181, v[152:153]
	global_load_dwordx4 v[182:185], v[182:183], off
	v_mad_i64_i32 v[186:187], s[64:65], s37, v181, v[152:153]
	global_load_dwordx4 v[186:189], v[186:187], off
	v_mad_i64_i32 v[190:191], s[64:65], s36, v181, v[152:153]
	global_load_dwordx4 v[190:193], v[190:191], off
	v_mad_i64_i32 v[200:201], s[64:65], s35, v181, v[152:153]
	global_load_dwordx4 v[200:203], v[200:201], off
	v_mad_i64_i32 v[204:205], s[64:65], s34, v181, v[152:153]
	global_load_dwordx4 v[204:207], v[204:205], off
	v_mad_i64_i32 v[208:209], s[64:65], s31, v181, v[152:153]
	global_load_dwordx4 v[208:211], v[208:209], off
	v_mad_i64_i32 v[216:217], s[64:65], s30, v181, v[152:153]
	global_load_dwordx4 v[216:219], v[216:217], off
	v_ashrrev_i32_e32 v161, 31, v160
	v_readfirstlane_b32 s63, v168
	s_waitcnt vmcnt(7)
	v_pk_add_f32 v[148:149], v[144:145], v[148:149]
	v_pk_add_f32 v[150:151], v[146:147], v[150:151]
	s_waitcnt vmcnt(6)
	v_pk_add_f32 v[148:149], v[148:149], v[182:183]
	v_pk_add_f32 v[150:151], v[150:151], v[184:185]
	s_waitcnt vmcnt(5)
	v_pk_add_f32 v[148:149], v[148:149], v[186:187]
	v_pk_add_f32 v[150:151], v[150:151], v[188:189]
	s_waitcnt vmcnt(4)
	v_pk_add_f32 v[148:149], v[148:149], v[190:191]
	v_pk_add_f32 v[150:151], v[150:151], v[192:193]
	s_waitcnt vmcnt(3)
	v_pk_add_f32 v[148:149], v[148:149], v[200:201]
	v_pk_add_f32 v[150:151], v[150:151], v[202:203]
	s_waitcnt vmcnt(2)
	v_pk_add_f32 v[148:149], v[148:149], v[204:205]
	v_pk_add_f32 v[150:151], v[150:151], v[206:207]
	s_waitcnt vmcnt(1)
	v_pk_add_f32 v[148:149], v[148:149], v[208:209]
	v_pk_add_f32 v[150:151], v[150:151], v[210:211]
	s_waitcnt vmcnt(0)
	v_pk_add_f32 v[146:147], v[150:151], v[218:219]
	v_pk_add_f32 v[148:149], v[148:149], v[216:217]
	v_pk_mul_f32 v[144:145], v[146:147], 0.5 op_sel_hi:[1, 0]
	v_pk_mul_f32 v[146:147], v[148:149], 0.5 op_sel_hi:[1, 0]
	v_add_u32_e32 v148, 0x2010, v160
	v_ashrrev_i32_e32 v149, 31, v148
	v_lshlrev_b64 v[152:153], 2, v[148:149]
	v_lshl_add_u64 v[156:157], s[2:3], 0, v[152:153]
	v_lshl_add_u64 v[148:149], s[16:17], 0, v[152:153]
	v_mad_i64_i32 v[152:153], s[64:65], s39, v181, v[156:157]
	global_load_dwordx4 v[148:151], v[148:149], off
	global_load_dwordx4 v[152:155], v[152:153], off
	v_mad_i64_i32 v[182:183], s[64:65], s38, v181, v[156:157]
	global_load_dwordx4 v[182:185], v[182:183], off
	v_mad_i64_i32 v[186:187], s[64:65], s37, v181, v[156:157]
	global_load_dwordx4 v[186:189], v[186:187], off
	v_mad_i64_i32 v[190:191], s[64:65], s36, v181, v[156:157]
	global_load_dwordx4 v[190:193], v[190:191], off
	v_mad_i64_i32 v[200:201], s[64:65], s35, v181, v[156:157]
	global_load_dwordx4 v[200:203], v[200:201], off
	v_mad_i64_i32 v[204:205], s[64:65], s34, v181, v[156:157]
	global_load_dwordx4 v[204:207], v[204:205], off
	v_mad_i64_i32 v[208:209], s[64:65], s31, v181, v[156:157]
	global_load_dwordx4 v[208:211], v[208:209], off
	v_mad_i64_i32 v[216:217], s[64:65], s30, v181, v[156:157]
	global_load_dwordx4 v[216:219], v[216:217], off
	s_waitcnt vmcnt(7)
	v_pk_add_f32 v[152:153], v[148:149], v[152:153]
	v_pk_add_f32 v[154:155], v[150:151], v[154:155]
	s_waitcnt vmcnt(6)
	v_pk_add_f32 v[152:153], v[152:153], v[182:183]
	v_pk_add_f32 v[154:155], v[154:155], v[184:185]
	s_waitcnt vmcnt(5)
	v_pk_add_f32 v[152:153], v[152:153], v[186:187]
	v_pk_add_f32 v[154:155], v[154:155], v[188:189]
	s_waitcnt vmcnt(4)
	v_pk_add_f32 v[152:153], v[152:153], v[190:191]
	v_pk_add_f32 v[154:155], v[154:155], v[192:193]
	s_waitcnt vmcnt(3)
	v_pk_add_f32 v[152:153], v[152:153], v[200:201]
	v_pk_add_f32 v[154:155], v[154:155], v[202:203]
	s_waitcnt vmcnt(2)
	v_pk_add_f32 v[152:153], v[152:153], v[204:205]
	v_pk_add_f32 v[154:155], v[154:155], v[206:207]
	s_waitcnt vmcnt(1)
	v_pk_add_f32 v[152:153], v[152:153], v[208:209]
	v_pk_add_f32 v[154:155], v[154:155], v[210:211]
	s_waitcnt vmcnt(0)
	v_pk_add_f32 v[150:151], v[154:155], v[218:219]
	v_pk_add_f32 v[152:153], v[152:153], v[216:217]
	v_pk_mul_f32 v[148:149], v[150:151], 0.5 op_sel_hi:[1, 0]
	v_pk_mul_f32 v[150:151], v[152:153], 0.5 op_sel_hi:[1, 0]
	v_add_u32_e32 v152, 0x2080, v160
	v_ashrrev_i32_e32 v153, 31, v152
	v_lshlrev_b64 v[156:157], 2, v[152:153]
	v_lshl_add_u64 v[162:163], s[2:3], 0, v[156:157]
	v_lshl_add_u64 v[152:153], s[16:17], 0, v[156:157]
	v_mad_i64_i32 v[156:157], s[64:65], s39, v181, v[162:163]
	global_load_dwordx4 v[152:155], v[152:153], off
	global_load_dwordx4 v[156:159], v[156:157], off
	v_mad_i64_i32 v[182:183], s[64:65], s38, v181, v[162:163]
	global_load_dwordx4 v[182:185], v[182:183], off
	v_mad_i64_i32 v[186:187], s[64:65], s37, v181, v[162:163]
	global_load_dwordx4 v[186:189], v[186:187], off
	v_mad_i64_i32 v[190:191], s[64:65], s36, v181, v[162:163]
	global_load_dwordx4 v[190:193], v[190:191], off
	v_mad_i64_i32 v[200:201], s[64:65], s35, v181, v[162:163]
	global_load_dwordx4 v[200:203], v[200:201], off
	v_mad_i64_i32 v[204:205], s[64:65], s34, v181, v[162:163]
	global_load_dwordx4 v[204:207], v[204:205], off
	v_mad_i64_i32 v[208:209], s[64:65], s31, v181, v[162:163]
	global_load_dwordx4 v[208:211], v[208:209], off
	v_mad_i64_i32 v[216:217], s[64:65], s30, v181, v[162:163]
	global_load_dwordx4 v[216:219], v[216:217], off
	s_waitcnt vmcnt(7)
	v_pk_add_f32 v[156:157], v[152:153], v[156:157]
	v_pk_add_f32 v[158:159], v[154:155], v[158:159]
	s_waitcnt vmcnt(6)
	v_pk_add_f32 v[156:157], v[156:157], v[182:183]
	v_pk_add_f32 v[158:159], v[158:159], v[184:185]
	s_waitcnt vmcnt(5)
	v_pk_add_f32 v[156:157], v[156:157], v[186:187]
	v_pk_add_f32 v[158:159], v[158:159], v[188:189]
	s_waitcnt vmcnt(4)
	v_pk_add_f32 v[156:157], v[156:157], v[190:191]
	v_pk_add_f32 v[158:159], v[158:159], v[192:193]
	s_waitcnt vmcnt(3)
	v_pk_add_f32 v[156:157], v[156:157], v[200:201]
	v_pk_add_f32 v[158:159], v[158:159], v[202:203]
	s_waitcnt vmcnt(2)
	v_pk_add_f32 v[156:157], v[156:157], v[204:205]
	v_pk_add_f32 v[158:159], v[158:159], v[206:207]
	s_waitcnt vmcnt(1)
	v_pk_add_f32 v[156:157], v[156:157], v[208:209]
	v_pk_add_f32 v[158:159], v[158:159], v[210:211]
	s_waitcnt vmcnt(0)
	v_pk_add_f32 v[154:155], v[158:159], v[218:219]
	v_pk_add_f32 v[156:157], v[156:157], v[216:217]
	v_pk_mul_f32 v[152:153], v[154:155], 0.5 op_sel_hi:[1, 0]
	v_pk_mul_f32 v[154:155], v[156:157], 0.5 op_sel_hi:[1, 0]
	v_add_u32_e32 v156, 0x2090, v160
	v_ashrrev_i32_e32 v157, 31, v156
	v_lshlrev_b64 v[162:163], 2, v[156:157]
	v_lshl_add_u64 v[166:167], s[2:3], 0, v[162:163]
	v_lshl_add_u64 v[156:157], s[16:17], 0, v[162:163]
	v_mad_i64_i32 v[162:163], s[64:65], s39, v181, v[166:167]
	global_load_dwordx4 v[156:159], v[156:157], off
	global_load_dwordx4 v[162:165], v[162:163], off
	v_mad_i64_i32 v[182:183], s[38:39], s38, v181, v[166:167]
	global_load_dwordx4 v[182:185], v[182:183], off
	v_mad_i64_i32 v[186:187], s[38:39], s37, v181, v[166:167]
	global_load_dwordx4 v[186:189], v[186:187], off
	v_mad_i64_i32 v[190:191], s[36:37], s36, v181, v[166:167]
	global_load_dwordx4 v[190:193], v[190:191], off
	v_mad_i64_i32 v[200:201], s[36:37], s35, v181, v[166:167]
	global_load_dwordx4 v[200:203], v[200:201], off
	v_mad_i64_i32 v[204:205], s[34:35], s34, v181, v[166:167]
	global_load_dwordx4 v[204:207], v[204:205], off
	v_mad_i64_i32 v[208:209], s[34:35], s31, v181, v[166:167]
	global_load_dwordx4 v[208:211], v[208:209], off
	v_mad_i64_i32 v[216:217], s[30:31], s30, v181, v[166:167]
	global_load_dwordx4 v[216:219], v[216:217], off
	v_lshlrev_b64 v[160:161], 2, v[160:161]
	s_waitcnt vmcnt(7)
	v_pk_add_f32 v[162:163], v[156:157], v[162:163]
	v_pk_add_f32 v[164:165], v[158:159], v[164:165]
	s_waitcnt vmcnt(6)
	v_pk_add_f32 v[162:163], v[162:163], v[182:183]
	v_pk_add_f32 v[164:165], v[164:165], v[184:185]
	s_waitcnt vmcnt(5)
	v_pk_add_f32 v[162:163], v[162:163], v[186:187]
	v_pk_add_f32 v[164:165], v[164:165], v[188:189]
	s_waitcnt vmcnt(4)
	v_pk_add_f32 v[162:163], v[162:163], v[190:191]
	v_pk_add_f32 v[164:165], v[164:165], v[192:193]
	s_waitcnt vmcnt(3)
	v_pk_add_f32 v[162:163], v[162:163], v[200:201]
	v_pk_add_f32 v[164:165], v[164:165], v[202:203]
	s_waitcnt vmcnt(2)
	v_pk_add_f32 v[162:163], v[162:163], v[204:205]
	v_pk_add_f32 v[164:165], v[164:165], v[206:207]
	s_waitcnt vmcnt(1)
	v_pk_add_f32 v[162:163], v[162:163], v[208:209]
	v_pk_add_f32 v[164:165], v[164:165], v[210:211]
	v_add_u32_e32 v166, s62, v169
	v_ashrrev_i32_e32 v167, 31, v166
	v_or_b32_e32 v198, 16, v166
	v_ashrrev_i32_e32 v199, 31, v198
	v_lshlrev_b64 v[214:215], 12, v[198:199]
	s_waitcnt vmcnt(0)
	v_pk_add_f32 v[158:159], v[164:165], v[218:219]
	v_pk_add_f32 v[162:163], v[162:163], v[216:217]
	v_pk_mul_f32 v[156:157], v[158:159], 0.5 op_sel_hi:[1, 0]
	v_pk_mul_f32 v[158:159], v[162:163], 0.5 op_sel_hi:[1, 0]
	v_lshl_add_u64 v[162:163], s[10:11], 0, v[160:161]
	v_lshlrev_b64 v[164:165], 12, v[166:167]
	v_lshl_add_u64 v[194:195], v[162:163], 0, v[164:165]
	global_load_dwordx4 v[182:185], v[194:195], off
	global_load_dwordx4 v[186:189], v[194:195], off offset:64
	global_load_dwordx4 v[190:193], v[194:195], off offset:512
	s_nop 0
	global_load_dwordx4 v[194:197], v[194:195], off offset:576
	v_lshl_add_u64 v[210:211], v[162:163], 0, v[214:215]
	global_load_dwordx4 v[198:201], v[210:211], off
	global_load_dwordx4 v[202:205], v[210:211], off offset:64
	global_load_dwordx4 v[206:209], v[210:211], off offset:512
	s_nop 0
	global_load_dwordx4 v[210:213], v[210:211], off offset:576
	s_waitcnt vmcnt(7)
	v_pk_fma_f32 v[124:125], v[124:125], v[146:147], v[182:183]
	v_lshl_add_u64 v[182:183], s[10:11], 0, v[164:165]
	v_lshl_add_u64 v[182:183], v[182:183], 0, v[160:161]
	s_waitcnt vmcnt(5)
	v_pk_fma_f32 v[110:111], v[110:111], v[152:153], v[192:193]
	v_pk_fma_f32 v[108:109], v[108:109], v[154:155], v[190:191]
	global_store_dwordx4 v[182:183], v[108:111], off offset:512 sc1
	s_waitcnt vmcnt(1)
	v_pk_fma_f32 v[98:99], v[98:99], v[156:157], v[212:213]
	v_pk_fma_f32 v[96:97], v[96:97], v[158:159], v[210:211]
	v_lshl_add_u64 v[108:109], s[10:11], 0, v[214:215]
	v_lshl_add_u64 v[108:109], v[108:109], 0, v[160:161]
	v_pk_fma_f32 v[106:107], v[106:107], v[156:157], v[196:197]
	v_pk_fma_f32 v[104:105], v[104:105], v[158:159], v[194:195]
	global_store_dwordx4 v[108:109], v[96:99], off offset:576 sc1
	v_pk_fma_f32 v[126:127], v[126:127], v[144:145], v[184:185]
	v_pk_fma_f32 v[122:123], v[122:123], v[148:149], v[188:189]
	v_or_b32_e32 v96, 32, v166
	v_pk_fma_f32 v[120:121], v[120:121], v[150:151], v[186:187]
	global_store_dwordx4 v[182:183], v[104:107], off offset:576 sc1
	v_ashrrev_i32_e32 v97, 31, v96
	global_store_dwordx4 v[182:183], v[124:127], off sc1
	v_pk_fma_f32 v[106:107], v[118:119], v[144:145], v[200:201]
	v_pk_fma_f32 v[104:105], v[116:117], v[146:147], v[198:199]
	global_store_dwordx4 v[182:183], v[120:123], off offset:64 sc1
	global_store_dwordx4 v[108:109], v[104:107], off sc1
	v_pk_fma_f32 v[102:103], v[102:103], v[152:153], v[208:209]
	v_pk_fma_f32 v[100:101], v[100:101], v[154:155], v[206:207]
	v_pk_fma_f32 v[106:107], v[114:115], v[148:149], v[204:205]
	v_pk_fma_f32 v[104:105], v[112:113], v[150:151], v[202:203]
	v_lshlrev_b64 v[182:183], 12, v[96:97]
	v_or_b32_e32 v112, 48, v166
	global_store_dwordx4 v[108:109], v[104:107], off offset:64 sc1
	global_store_dwordx4 v[108:109], v[100:103], off offset:512 sc1
	v_lshl_add_u64 v[108:109], v[162:163], 0, v[182:183]
	v_ashrrev_i32_e32 v113, 31, v112
	global_load_dwordx4 v[96:99], v[108:109], off
	global_load_dwordx4 v[100:103], v[108:109], off offset:64
	global_load_dwordx4 v[104:107], v[108:109], off offset:512
	s_nop 0
	global_load_dwordx4 v[108:111], v[108:109], off offset:576
	v_lshlrev_b64 v[166:167], 12, v[112:113]
	v_lshl_add_u64 v[124:125], v[162:163], 0, v[166:167]
	global_load_dwordx4 v[112:115], v[124:125], off
	global_load_dwordx4 v[116:119], v[124:125], off offset:64
	global_load_dwordx4 v[120:123], v[124:125], off offset:512
	s_nop 0
	global_load_dwordx4 v[124:127], v[124:125], off offset:576
	s_waitcnt vmcnt(7)
	v_pk_fma_f32 v[92:93], v[92:93], v[146:147], v[96:97]
	v_lshl_add_u64 v[96:97], s[10:11], 0, v[182:183]
	v_lshl_add_u64 v[96:97], v[96:97], 0, v[160:161]
	s_waitcnt vmcnt(5)
	v_pk_fma_f32 v[78:79], v[78:79], v[152:153], v[106:107]
	v_pk_fma_f32 v[76:77], v[76:77], v[154:155], v[104:105]
	global_store_dwordx4 v[96:97], v[76:79], off offset:512 sc1
	s_waitcnt vmcnt(5)
	v_pk_fma_f32 v[74:75], v[74:75], v[156:157], v[110:111]
	v_pk_fma_f32 v[72:73], v[72:73], v[158:159], v[108:109]
	v_lshl_add_u64 v[76:77], s[10:11], 0, v[166:167]
	v_pk_fma_f32 v[94:95], v[94:95], v[144:145], v[98:99]
	v_pk_fma_f32 v[90:91], v[90:91], v[148:149], v[102:103]
	v_pk_fma_f32 v[88:89], v[88:89], v[150:151], v[100:101]
	global_store_dwordx4 v[96:97], v[72:75], off offset:576 sc1
	v_lshl_add_u64 v[76:77], v[76:77], 0, v[160:161]
	global_store_dwordx4 v[96:97], v[92:95], off sc1
	s_waitcnt vmcnt(6)
	v_pk_fma_f32 v[74:75], v[86:87], v[144:145], v[114:115]
	v_pk_fma_f32 v[72:73], v[84:85], v[146:147], v[112:113]
	global_store_dwordx4 v[96:97], v[88:91], off offset:64 sc1
	global_store_dwordx4 v[76:77], v[72:75], off sc1
	s_waitcnt vmcnt(6)
	v_pk_fma_f32 v[70:71], v[70:71], v[152:153], v[122:123]
	v_pk_fma_f32 v[68:69], v[68:69], v[154:155], v[120:121]
	v_pk_fma_f32 v[74:75], v[82:83], v[148:149], v[118:119]
	v_pk_fma_f32 v[72:73], v[80:81], v[150:151], v[116:117]
	s_waitcnt vmcnt(5)
	v_pk_fma_f32 v[66:67], v[66:67], v[156:157], v[126:127]
	v_pk_fma_f32 v[64:65], v[64:65], v[158:159], v[124:125]
	v_lshl_add_u64 v[96:97], v[164:165], 0, s[8:9]
	global_store_dwordx4 v[76:77], v[72:75], off offset:64 sc1
	global_store_dwordx4 v[76:77], v[68:71], off offset:512 sc1
	global_store_dwordx4 v[76:77], v[64:67], off offset:576 sc1
	v_lshl_add_u64 v[76:77], v[162:163], 0, v[96:97]
	global_load_dwordx4 v[64:67], v[76:77], off
	global_load_dwordx4 v[68:71], v[76:77], off offset:64
	global_load_dwordx4 v[72:75], v[76:77], off offset:512
	s_nop 0
	global_load_dwordx4 v[76:79], v[76:77], off offset:576
	v_lshl_add_u64 v[98:99], v[164:165], 0, s[18:19]
	v_lshl_add_u64 v[92:93], v[162:163], 0, v[98:99]
	global_load_dwordx4 v[80:83], v[92:93], off
	global_load_dwordx4 v[84:87], v[92:93], off offset:64
	global_load_dwordx4 v[88:91], v[92:93], off offset:512
	s_nop 0
	global_load_dwordx4 v[92:95], v[92:93], off offset:576
	s_waitcnt vmcnt(7)
	v_pk_fma_f32 v[60:61], v[60:61], v[146:147], v[64:65]
	v_lshl_add_u64 v[64:65], s[10:11], 0, v[96:97]
	v_lshl_add_u64 v[64:65], v[64:65], 0, v[160:161]
	s_waitcnt vmcnt(5)
	v_pk_fma_f32 v[46:47], v[46:47], v[152:153], v[74:75]
	v_pk_fma_f32 v[44:45], v[44:45], v[154:155], v[72:73]
	global_store_dwordx4 v[64:65], v[44:47], off offset:512 sc1
	s_waitcnt vmcnt(5)
	v_pk_fma_f32 v[42:43], v[42:43], v[156:157], v[78:79]
	v_pk_fma_f32 v[40:41], v[40:41], v[158:159], v[76:77]
	v_lshl_add_u64 v[44:45], s[10:11], 0, v[98:99]
	v_pk_fma_f32 v[62:63], v[62:63], v[144:145], v[66:67]
	v_pk_fma_f32 v[58:59], v[58:59], v[148:149], v[70:71]
	v_pk_fma_f32 v[56:57], v[56:57], v[150:151], v[68:69]
	global_store_dwordx4 v[64:65], v[40:43], off offset:576 sc1
	v_lshl_add_u64 v[44:45], v[44:45], 0, v[160:161]
	global_store_dwordx4 v[64:65], v[60:63], off sc1
	s_waitcnt vmcnt(6)
	v_pk_fma_f32 v[42:43], v[54:55], v[144:145], v[82:83]
	v_pk_fma_f32 v[40:41], v[52:53], v[146:147], v[80:81]
	global_store_dwordx4 v[64:65], v[56:59], off offset:64 sc1
	global_store_dwordx4 v[44:45], v[40:43], off sc1
	s_waitcnt vmcnt(6)
	v_pk_fma_f32 v[38:39], v[38:39], v[152:153], v[90:91]
	v_pk_fma_f32 v[36:37], v[36:37], v[154:155], v[88:89]
	v_pk_fma_f32 v[42:43], v[50:51], v[148:149], v[86:87]
	v_pk_fma_f32 v[40:41], v[48:49], v[150:151], v[84:85]
	s_waitcnt vmcnt(5)
	v_pk_fma_f32 v[34:35], v[34:35], v[156:157], v[94:95]
	v_pk_fma_f32 v[32:33], v[32:33], v[158:159], v[92:93]
	v_lshl_add_u64 v[64:65], v[164:165], 0, s[20:21]
	global_store_dwordx4 v[44:45], v[40:43], off offset:64 sc1
	global_store_dwordx4 v[44:45], v[36:39], off offset:512 sc1
	global_store_dwordx4 v[44:45], v[32:35], off offset:576 sc1
	v_lshl_add_u64 v[44:45], v[162:163], 0, v[64:65]
	global_load_dwordx4 v[32:35], v[44:45], off
	global_load_dwordx4 v[36:39], v[44:45], off offset:64
	global_load_dwordx4 v[40:43], v[44:45], off offset:512
	s_nop 0
	global_load_dwordx4 v[44:47], v[44:45], off offset:576
	v_lshl_add_u64 v[66:67], v[164:165], 0, s[22:23]
	v_lshl_add_u64 v[60:61], v[162:163], 0, v[66:67]
	global_load_dwordx4 v[48:51], v[60:61], off
	global_load_dwordx4 v[52:55], v[60:61], off offset:64
	global_load_dwordx4 v[56:59], v[60:61], off offset:512
	s_nop 0
	global_load_dwordx4 v[60:63], v[60:61], off offset:576
	s_waitcnt vmcnt(7)
	v_pk_fma_f32 v[28:29], v[28:29], v[146:147], v[32:33]
	v_lshl_add_u64 v[32:33], s[10:11], 0, v[64:65]
	v_lshl_add_u64 v[32:33], v[32:33], 0, v[160:161]
	s_waitcnt vmcnt(5)
	v_pk_fma_f32 v[18:19], v[18:19], v[152:153], v[42:43]
	v_pk_fma_f32 v[16:17], v[16:17], v[154:155], v[40:41]
	global_store_dwordx4 v[32:33], v[16:19], off offset:512 sc1
	s_waitcnt vmcnt(5)
	v_pk_fma_f32 v[10:11], v[10:11], v[156:157], v[46:47]
	v_pk_fma_f32 v[8:9], v[8:9], v[158:159], v[44:45]
	v_lshl_add_u64 v[16:17], s[10:11], 0, v[66:67]
	global_store_dwordx4 v[32:33], v[8:11], off offset:576 sc1
	v_lshl_add_u64 v[16:17], v[16:17], 0, v[160:161]
	v_pk_fma_f32 v[30:31], v[30:31], v[144:145], v[34:35]
	s_waitcnt vmcnt(5)
	v_pk_fma_f32 v[10:11], v[22:23], v[144:145], v[50:51]
	v_pk_fma_f32 v[8:9], v[20:21], v[146:147], v[48:49]
	v_pk_fma_f32 v[26:27], v[26:27], v[148:149], v[38:39]
	v_pk_fma_f32 v[24:25], v[24:25], v[150:151], v[36:37]
	global_store_dwordx4 v[16:17], v[8:11], off sc1
	s_waitcnt vmcnt(4)
	v_pk_fma_f32 v[6:7], v[6:7], v[152:153], v[58:59]
	v_pk_fma_f32 v[4:5], v[4:5], v[154:155], v[56:57]
	v_pk_fma_f32 v[10:11], v[14:15], v[148:149], v[54:55]
	v_pk_fma_f32 v[8:9], v[12:13], v[150:151], v[52:53]
	s_waitcnt vmcnt(3)
	v_pk_fma_f32 v[2:3], v[2:3], v[156:157], v[62:63]
	v_pk_fma_f32 v[0:1], v[0:1], v[158:159], v[60:61]
	global_store_dwordx4 v[32:33], v[28:31], off sc1
	global_store_dwordx4 v[32:33], v[24:27], off offset:64 sc1
	global_store_dwordx4 v[16:17], v[8:11], off offset:64 sc1
	global_store_dwordx4 v[16:17], v[4:7], off offset:512 sc1
	global_store_dwordx4 v[16:17], v[0:3], off offset:576 sc1
	s_waitcnt vmcnt(0)
	s_barrier
	s_and_saveexec_b64 s[30:31], s[0:1]
	s_cbranch_execz .LBB0_2536
	s_lshl_b32 s34, s61, 2
	s_ashr_i32 s35, s34, 31
	s_lshl_b64 s[34:35], s[34:35], 2
	s_add_u32 s34, s49, s34
	s_addc_u32 s35, s50, s35
	s_getreg_b32 s36, hwreg(HW_REG_XCC_ID, 0, 4)
	global_load_dwordx4 v[0:3], v129, s[34:35]
	s_and_b32 s34, s36, 15
	s_add_i32 s34, s34, 1
	s_waitcnt vmcnt(0)
	v_cmp_ne_u32_e32 vcc, s34, v2
	s_nop 1
	v_cndmask_b32_e64 v2, 0, 1, vcc
	v_cmp_ne_u32_e32 vcc, s34, v3
	v_lshlrev_b32_e32 v2, 2, v2
	s_nop 0
	v_cndmask_b32_e64 v3, 0, 1, vcc
	v_cmp_ne_u32_e32 vcc, s34, v1
	v_lshlrev_b32_e32 v3, 3, v3
	v_or_b32_e32 v2, v3, v2
	v_cndmask_b32_e64 v1, 0, 1, vcc
	v_cmp_ne_u32_e32 vcc, s34, v0
	v_lshlrev_b32_e32 v1, 1, v1
	s_nop 0
	v_cndmask_b32_e64 v0, 0, 1, vcc
	v_or_b32_e32 v0, v0, v1
	v_and_b32_e32 v0, 3, v0
	v_or_b32_e32 v0, v0, v2
	v_and_b32_e32 v0, 15, v0
	v_cmp_eq_u32_e32 vcc, 0, v0
	s_cbranch_vccnz .LBB0_2525
	buffer_wbl2 sc1
	s_waitcnt vmcnt(0)

.LBB0_2536:
	s_or_b64 exec, exec, s[30:31]
	s_lshl_b32 s30, s60, 6
	s_ashr_i32 s31, s63, 3
	s_add_i32 s30, s62, s30
	s_and_b32 s31, s31, -8
	s_add_i32 s30, s30, s31
	s_ashr_i32 s31, s30, 31
	s_lshl_b64 s[34:35], s[30:31], 12
	v_lshl_add_u64 v[16:17], v[132:133], 0, s[34:35]
	s_barrier
	global_load_dwordx4 v[100:103], v[134:135], off
	global_load_dwordx4 v[104:107], v[134:135], off offset:1024
	global_load_dwordx4 v[108:111], v[134:135], off offset:2048
	global_load_dwordx4 v[112:115], v[134:135], off offset:3072
	global_load_dwordx4 v[18:21], v[16:17], off
	global_load_dwordx4 v[30:33], v[16:17], off offset:1024
	global_load_dwordx4 v[34:37], v[16:17], off offset:3072
	global_load_dwordx4 v[38:41], v[16:17], off offset:2048
	s_or_b32 s34, s30, 1
	s_ashr_i32 s35, s34, 31
	s_lshl_b64 s[34:35], s[34:35], 12
	v_lshl_add_u64 v[28:29], v[132:133], 0, s[34:35]
	global_load_dwordx4 v[8:11], v[28:29], off
	global_load_dwordx4 v[0:3], v[28:29], off offset:1024
	global_load_dwordx4 v[4:7], v[28:29], off offset:3072
	global_load_dwordx4 v[12:15], v[28:29], off offset:2048
	s_or_b32 s34, s30, 2
	s_ashr_i32 s35, s34, 31
	s_lshl_b64 s[34:35], s[34:35], 12
	s_waitcnt vmcnt(7)
	v_pk_mul_f32 v[22:23], v[20:21], v[20:21]
	v_pk_mul_f32 v[24:25], v[18:19], v[18:19]
	s_waitcnt vmcnt(6)
	v_pk_mul_f32 v[26:27], v[32:33], v[32:33]
	v_pk_mul_f32 v[46:47], v[30:31], v[30:31]
	s_waitcnt vmcnt(4)
	v_mul_f32_e32 v48, v39, v39
	v_mul_f32_e32 v50, v41, v41
	v_mul_f32_e32 v64, v36, v36
	v_mul_f32_e32 v65, v37, v37
	v_pk_mov_b32 v[52:53], v[24:25], v[22:23] op_sel:[1, 0]
	v_mov_b32_e32 v25, v23
	v_pk_mov_b32 v[22:23], v[46:47], v[26:27] op_sel:[1, 0]
	v_mov_b32_e32 v47, v27
	v_pk_fma_f32 v[26:27], v[38:39], v[38:39], v[48:49] op_sel_hi:[1, 1, 0]
	v_pk_fma_f32 v[48:49], v[40:41], v[40:41], v[50:51] op_sel_hi:[1, 1, 0]
	s_waitcnt vmcnt(3)
	v_pk_mul_f32 v[50:51], v[10:11], v[10:11]
	v_pk_mul_f32 v[54:55], v[8:9], v[8:9]
	s_waitcnt vmcnt(2)
	v_pk_mul_f32 v[56:57], v[2:3], v[2:3]
	v_pk_mul_f32 v[58:59], v[0:1], v[0:1]
	v_pk_add_f32 v[22:23], v[22:23], v[46:47]
	v_mov_b32_e32 v27, v64
	v_mov_b32_e32 v49, v65
	v_pk_mov_b32 v[46:47], v[54:55], v[50:51] op_sel:[1, 0]
	v_mov_b32_e32 v55, v51
	v_pk_mov_b32 v[50:51], v[58:59], v[56:57] op_sel:[1, 0]
	v_mov_b32_e32 v59, v57
	v_mul_f32_e32 v61, v34, v34
	v_mul_f32_e32 v63, v35, v35
	s_waitcnt vmcnt(0)
	v_mul_f32_e32 v60, v13, v13
	v_mul_f32_e32 v62, v15, v15
	v_pk_add_f32 v[24:25], v[52:53], v[24:25]
	v_pk_add_f32 v[26:27], v[26:27], v[48:49]
	v_pk_add_f32 v[46:47], v[46:47], v[54:55]
	v_pk_add_f32 v[48:49], v[50:51], v[58:59]
	v_mul_f32_e32 v66, v4, v4
	v_mul_f32_e32 v67, v5, v5
	v_mul_f32_e32 v68, v6, v6
	v_mul_f32_e32 v69, v7, v7
	v_pk_fma_f32 v[52:53], v[12:13], v[12:13], v[60:61] op_sel_hi:[1, 1, 0]
	v_pk_fma_f32 v[56:57], v[14:15], v[14:15], v[62:63] op_sel_hi:[1, 1, 0]
	v_pk_add_f32 v[24:25], v[24:25], v[24:25] op_sel:[0, 1] op_sel_hi:[1, 0]
	v_pk_add_f32 v[22:23], v[22:23], v[22:23] op_sel:[0, 1] op_sel_hi:[1, 0]
	v_pk_add_f32 v[46:47], v[46:47], v[46:47] op_sel:[0, 1] op_sel_hi:[1, 0]
	v_pk_add_f32 v[48:49], v[48:49], v[48:49] op_sel:[0, 1] op_sel_hi:[1, 0]
	v_mov_b32_e32 v53, v68
	v_mov_b32_e32 v57, v69
	v_mov_b32_e32 v25, v61
	v_mov_b32_e32 v23, v63
	v_mov_b32_e32 v47, v66
	v_mov_b32_e32 v49, v67
	v_pk_add_f32 v[50:51], v[52:53], v[56:57]
	v_pk_add_f32 v[22:23], v[24:25], v[22:23]
	v_pk_add_f32 v[24:25], v[46:47], v[48:49]
	v_pk_add_f32 v[22:23], v[22:23], v[26:27]
	v_pk_add_f32 v[24:25], v[24:25], v[50:51]
	v_mov_b32_e32 v27, v22
	v_mov_b32_e32 v26, v24
	v_mov_b32_e32 v22, v25
	v_pk_add_f32 v[22:23], v[26:27], v[22:23]
	v_lshl_add_u64 v[52:53], v[132:133], 0, s[34:35]
	s_or_b32 s34, s30, 3
	s_ashr_i32 s35, s34, 31
	s_lshl_b64 s[34:35], s[34:35], 12
	s_waitcnt lgkmcnt(0)
	s_nop 1
	v_add_f32_dpp v22, v22, v22 quad_perm:[1, 0, 3, 2] row_mask:0xf bank_mask:0xf
	v_add_f32_dpp v23, v23, v23 quad_perm:[1, 0, 3, 2] row_mask:0xf bank_mask:0xf
	s_waitcnt lgkmcnt(0)
	s_nop 1
	v_add_f32_dpp v22, v22, v22 quad_perm:[2, 3, 0, 1] row_mask:0xf bank_mask:0xf
	v_add_f32_dpp v23, v23, v23 quad_perm:[2, 3, 0, 1] row_mask:0xf bank_mask:0xf
	s_waitcnt lgkmcnt(0)
	s_nop 1
	v_add_f32_dpp v22, v22, v22 row_half_mirror row_mask:0xf bank_mask:0xf
	v_add_f32_dpp v23, v23, v23 row_half_mirror row_mask:0xf bank_mask:0xf
	s_waitcnt lgkmcnt(0)
	s_nop 1
	v_add_f32_dpp v22, v22, v22 row_mirror row_mask:0xf bank_mask:0xf
	v_add_f32_dpp v23, v23, v23 row_mirror row_mask:0xf bank_mask:0xf
	ds_bpermute_b32 v25, v175, v23
	ds_bpermute_b32 v24, v175, v22
	s_waitcnt lgkmcnt(0)
	v_pk_add_f32 v[22:23], v[22:23], v[24:25]
	v_mov_b64_e32 v[24:25], s[26:27]
	s_waitcnt lgkmcnt(0)
	v_mov_b32_e32 v26, v22
	v_mov_b32_e32 v27, v23
	s_nop 1
	v_permlane32_swap_b32_e32 v26, v22
	v_permlane32_swap_b32_e32 v27, v23
	v_pk_add_f32 v[22:23], v[22:23], v[26:27]
	s_nop 0
	v_pk_fma_f32 v[22:23], v[22:23], s[24:25], v[24:25] op_sel_hi:[1, 0, 0]
	s_nop 0
	v_mul_f32_e32 v26, 0x4b800000, v23
	v_cmp_gt_f32_e32 vcc, s57, v23
	s_nop 1
	v_cndmask_b32_e32 v23, v23, v26, vcc
	v_rsq_f32_e32 v23, v23
	s_nop 0
	v_mul_f32_e32 v26, 0x45800000, v23
	v_cndmask_b32_e32 v26, v23, v26, vcc
	v_pk_mul_f32 v[18:19], v[18:19], v[26:27] op_sel_hi:[1, 0]
	v_pk_mul_f32 v[20:21], v[20:21], v[26:27] op_sel_hi:[1, 0]
	v_pk_mul_f32 v[18:19], v[100:101], v[18:19]
	v_pk_mul_f32 v[20:21], v[102:103], v[20:21]
	global_store_dwordx4 v[16:17], v[18:21], off sc1
	v_pk_mul_f32 v[32:33], v[32:33], v[26:27] op_sel_hi:[1, 0]
	v_pk_mul_f32 v[30:31], v[30:31], v[26:27] op_sel_hi:[1, 0]
	v_cmp_gt_f32_e32 vcc, s57, v22
	v_pk_mul_f32 v[18:19], v[104:105], v[30:31]
	v_pk_mul_f32 v[20:21], v[106:107], v[32:33]
	global_store_dwordx4 v[16:17], v[18:21], off offset:1024 sc1
	v_pk_mul_f32 v[30:31], v[40:41], v[26:27] op_sel_hi:[1, 0]
	v_pk_mul_f32 v[32:33], v[38:39], v[26:27] op_sel_hi:[1, 0]
	s_nop 1
	v_pk_mul_f32 v[20:21], v[110:111], v[30:31]
	v_pk_mul_f32 v[18:19], v[108:109], v[32:33]
	global_store_dwordx4 v[16:17], v[18:21], off offset:2048 sc1
	v_pk_mul_f32 v[30:31], v[36:37], v[26:27] op_sel_hi:[1, 0]
	v_pk_mul_f32 v[26:27], v[34:35], v[26:27] op_sel_hi:[1, 0]
	s_nop 1
	v_pk_mul_f32 v[20:21], v[114:115], v[30:31]
	v_pk_mul_f32 v[18:19], v[112:113], v[26:27]
	global_store_dwordx4 v[16:17], v[18:21], off offset:3072 sc1
	v_lshl_add_u64 v[26:27], v[132:133], 0, s[34:35]
	s_nop 1
	v_mul_f32_e32 v20, 0x4b800000, v22
	s_nop 1
	v_cndmask_b32_e32 v20, v22, v20, vcc
	v_rsq_f32_e32 v20, v20
	s_or_b32 s34, s30, 4
	s_ashr_i32 s35, s34, 31
	s_lshl_b64 s[34:35], s[34:35], 12
	v_mul_f32_e32 v21, 0x45800000, v20
	v_cndmask_b32_e32 v50, v20, v21, vcc
	v_pk_mul_f32 v[10:11], v[10:11], v[50:51] op_sel_hi:[1, 0]
	v_pk_mul_f32 v[8:9], v[8:9], v[50:51] op_sel_hi:[1, 0]
	v_pk_mul_f32 v[2:3], v[2:3], v[50:51] op_sel_hi:[1, 0]
	v_pk_mul_f32 v[0:1], v[0:1], v[50:51] op_sel_hi:[1, 0]
	v_pk_mul_f32 v[14:15], v[14:15], v[50:51] op_sel_hi:[1, 0]
	v_pk_mul_f32 v[12:13], v[12:13], v[50:51] op_sel_hi:[1, 0]
	v_pk_mul_f32 v[8:9], v[100:101], v[8:9]
	v_pk_mul_f32 v[10:11], v[102:103], v[10:11]
	global_store_dwordx4 v[28:29], v[8:11], off sc1
	v_pk_mul_f32 v[0:1], v[104:105], v[0:1]
	v_pk_mul_f32 v[2:3], v[106:107], v[2:3]
	global_store_dwordx4 v[28:29], v[0:3], off offset:1024 sc1
	global_load_dwordx4 v[34:37], v[52:53], off
	global_load_dwordx4 v[38:41], v[52:53], off offset:1024
	global_load_dwordx4 v[42:45], v[52:53], off offset:3072
	global_load_dwordx4 v[46:49], v[52:53], off offset:2048
	global_load_dwordx4 v[20:23], v[26:27], off
	global_load_dwordx4 v[16:19], v[26:27], off offset:1024
	global_load_dwordx4 v[0:3], v[26:27], off offset:3072
	global_load_dwordx4 v[8:11], v[26:27], off offset:2048
	s_waitcnt vmcnt(3)
	v_pk_mul_f32 v[62:63], v[22:23], v[22:23]
	v_pk_mul_f32 v[12:13], v[108:109], v[12:13]
	v_pk_mul_f32 v[14:15], v[110:111], v[14:15]
	global_store_dwordx4 v[28:29], v[12:15], off offset:2048 sc1
	v_mul_f32_e32 v51, v44, v44
	v_pk_mul_f32 v[6:7], v[6:7], v[50:51] op_sel_hi:[1, 0]
	v_pk_mul_f32 v[4:5], v[4:5], v[50:51] op_sel_hi:[1, 0]
	v_pk_mul_f32 v[30:31], v[36:37], v[36:37]
	v_pk_mul_f32 v[32:33], v[34:35], v[34:35]
	v_pk_mul_f32 v[54:55], v[40:41], v[40:41]
	v_pk_mul_f32 v[56:57], v[38:39], v[38:39]
	v_mul_f32_e32 v58, v47, v47
	v_mul_f32_e32 v60, v49, v49
	v_pk_mul_f32 v[64:65], v[20:21], v[20:21]
	s_waitcnt vmcnt(3)
	v_pk_mul_f32 v[66:67], v[18:19], v[18:19]
	v_pk_mul_f32 v[68:69], v[16:17], v[16:17]
	v_pk_mov_b32 v[74:75], v[32:33], v[30:31] op_sel:[1, 0]
	v_mov_b32_e32 v33, v31
	v_pk_mov_b32 v[30:31], v[56:57], v[54:55] op_sel:[1, 0]
	v_mov_b32_e32 v57, v55
	v_pk_fma_f32 v[54:55], v[46:47], v[46:47], v[58:59] op_sel_hi:[1, 1, 0]
	v_pk_fma_f32 v[58:59], v[48:49], v[48:49], v[60:61] op_sel_hi:[1, 1, 0]
	v_pk_mov_b32 v[60:61], v[64:65], v[62:63] op_sel:[1, 0]
	v_mov_b32_e32 v65, v63
	v_pk_mov_b32 v[62:63], v[68:69], v[66:67] op_sel:[1, 0]
	v_mov_b32_e32 v69, v67
	v_mul_f32_e32 v73, v42, v42
	s_waitcnt vmcnt(1)
	v_mul_f32_e32 v70, v9, v9
	v_mul_f32_e32 v72, v11, v11
	v_pk_add_f32 v[32:33], v[74:75], v[32:33]
	v_mul_f32_e32 v76, v43, v43
	v_mul_f32_e32 v77, v45, v45
	v_mul_f32_e32 v78, v0, v0
	v_mul_f32_e32 v79, v1, v1
	v_mul_f32_e32 v80, v2, v2
	v_mul_f32_e32 v81, v3, v3
	v_pk_fma_f32 v[66:67], v[8:9], v[8:9], v[70:71] op_sel_hi:[1, 1, 0]
	v_pk_fma_f32 v[70:71], v[10:11], v[10:11], v[72:73] op_sel_hi:[1, 1, 0]
	v_mov_b32_e32 v55, v51
	v_mov_b32_e32 v59, v77
	v_mov_b32_e32 v67, v80
	v_mov_b32_e32 v71, v81
	v_pk_add_f32 v[50:51], v[66:67], v[70:71]
	v_pk_mul_f32 v[4:5], v[112:113], v[4:5]
	v_pk_mul_f32 v[6:7], v[114:115], v[6:7]
	global_store_dwordx4 v[28:29], v[4:7], off offset:3072 sc1
	v_pk_add_f32 v[12:13], v[30:31], v[56:57]
	v_pk_add_f32 v[14:15], v[60:61], v[64:65]
	v_pk_add_f32 v[28:29], v[62:63], v[68:69]
	v_pk_add_f32 v[30:31], v[32:33], v[32:33] op_sel:[0, 1] op_sel_hi:[1, 0]
	v_pk_add_f32 v[12:13], v[12:13], v[12:13] op_sel:[0, 1] op_sel_hi:[1, 0]
	v_pk_add_f32 v[14:15], v[14:15], v[14:15] op_sel:[0, 1] op_sel_hi:[1, 0]
	v_pk_add_f32 v[28:29], v[28:29], v[28:29] op_sel:[0, 1] op_sel_hi:[1, 0]
	v_mov_b32_e32 v31, v73
	v_mov_b32_e32 v13, v76
	v_mov_b32_e32 v15, v78
	v_mov_b32_e32 v29, v79
	v_pk_add_f32 v[32:33], v[54:55], v[58:59]
	v_pk_add_f32 v[12:13], v[30:31], v[12:13]
	v_pk_add_f32 v[14:15], v[14:15], v[28:29]
	v_pk_add_f32 v[12:13], v[12:13], v[32:33]
	v_pk_add_f32 v[14:15], v[14:15], v[50:51]
	v_mov_b32_e32 v29, v12
	v_mov_b32_e32 v28, v14
	v_mov_b32_e32 v12, v15
	v_pk_add_f32 v[12:13], v[28:29], v[12:13]
	s_waitcnt lgkmcnt(0)
	s_nop 1
	v_add_f32_dpp v12, v12, v12 quad_perm:[1, 0, 3, 2] row_mask:0xf bank_mask:0xf
	v_add_f32_dpp v13, v13, v13 quad_perm:[1, 0, 3, 2] row_mask:0xf bank_mask:0xf
	s_waitcnt lgkmcnt(0)
	s_nop 1
	v_add_f32_dpp v12, v12, v12 quad_perm:[2, 3, 0, 1] row_mask:0xf bank_mask:0xf
	v_add_f32_dpp v13, v13, v13 quad_perm:[2, 3, 0, 1] row_mask:0xf bank_mask:0xf
	s_waitcnt lgkmcnt(0)
	s_nop 1
	v_add_f32_dpp v12, v12, v12 row_half_mirror row_mask:0xf bank_mask:0xf
	v_add_f32_dpp v13, v13, v13 row_half_mirror row_mask:0xf bank_mask:0xf
	s_waitcnt lgkmcnt(0)
	s_nop 1
	v_add_f32_dpp v12, v12, v12 row_mirror row_mask:0xf bank_mask:0xf
	v_add_f32_dpp v13, v13, v13 row_mirror row_mask:0xf bank_mask:0xf
	ds_bpermute_b32 v15, v175, v13
	ds_bpermute_b32 v14, v175, v12
	s_waitcnt lgkmcnt(0)
	v_pk_add_f32 v[12:13], v[12:13], v[14:15]
	s_waitcnt lgkmcnt(0)
	v_mov_b32_e32 v14, v12
	v_mov_b32_e32 v15, v13
	s_nop 1
	v_permlane32_swap_b32_e32 v14, v12
	v_permlane32_swap_b32_e32 v15, v13
	v_pk_add_f32 v[12:13], v[12:13], v[14:15]
	s_nop 0
	v_pk_fma_f32 v[12:13], v[12:13], s[24:25], v[24:25] op_sel_hi:[1, 0, 0]
	s_nop 0
	v_mul_f32_e32 v14, 0x4b800000, v13
	v_cmp_gt_f32_e32 vcc, s57, v13
	s_nop 1
	v_cndmask_b32_e32 v13, v13, v14, vcc
	v_rsq_f32_e32 v13, v13
	s_nop 0
	v_mul_f32_e32 v14, 0x45800000, v13
	v_cndmask_b32_e32 v14, v13, v14, vcc
	v_pk_mul_f32 v[28:29], v[36:37], v[14:15] op_sel_hi:[1, 0]
	v_pk_mul_f32 v[30:31], v[34:35], v[14:15] op_sel_hi:[1, 0]
	v_mul_f32_e32 v13, 0x4b800000, v12
	v_cmp_gt_f32_e32 vcc, s57, v12
	v_pk_mul_f32 v[4:5], v[100:101], v[30:31]
	v_pk_mul_f32 v[6:7], v[102:103], v[28:29]
	global_store_dwordx4 v[52:53], v[4:7], off sc1
	v_pk_mul_f32 v[28:29], v[40:41], v[14:15] op_sel_hi:[1, 0]
	v_pk_mul_f32 v[30:31], v[38:39], v[14:15] op_sel_hi:[1, 0]
	v_cndmask_b32_e32 v12, v12, v13, vcc
	v_rsq_f32_e32 v12, v12
	v_pk_mul_f32 v[4:5], v[104:105], v[30:31]
	v_pk_mul_f32 v[6:7], v[106:107], v[28:29]
	global_store_dwordx4 v[52:53], v[4:7], off offset:1024 sc1
	v_pk_mul_f32 v[28:29], v[48:49], v[14:15] op_sel_hi:[1, 0]
	v_pk_mul_f32 v[30:31], v[46:47], v[14:15] op_sel_hi:[1, 0]
	v_mul_f32_e32 v13, 0x45800000, v12
	v_pk_mul_f32 v[4:5], v[108:109], v[30:31]
	v_pk_mul_f32 v[6:7], v[110:111], v[28:29]
	global_store_dwordx4 v[52:53], v[4:7], off offset:2048 sc1
	v_pk_mul_f32 v[28:29], v[44:45], v[14:15] op_sel_hi:[1, 0]
	v_pk_mul_f32 v[14:15], v[42:43], v[14:15] op_sel_hi:[1, 0]
	v_lshl_add_u64 v[30:31], v[132:133], 0, s[34:35]
	s_or_b32 s34, s30, 5
	s_ashr_i32 s35, s34, 31
	s_lshl_b64 s[34:35], s[34:35], 12
	v_pk_mul_f32 v[4:5], v[112:113], v[14:15]
	v_pk_mul_f32 v[6:7], v[114:115], v[28:29]
	global_store_dwordx4 v[52:53], v[4:7], off offset:3072 sc1
	v_cndmask_b32_e32 v52, v12, v13, vcc
	v_pk_mul_f32 v[12:13], v[22:23], v[52:53] op_sel_hi:[1, 0]
	v_pk_mul_f32 v[14:15], v[20:21], v[52:53] op_sel_hi:[1, 0]
	v_pk_mul_f32 v[10:11], v[10:11], v[52:53] op_sel_hi:[1, 0]
	v_pk_mul_f32 v[8:9], v[8:9], v[52:53] op_sel_hi:[1, 0]
	v_lshl_add_u64 v[28:29], v[132:133], 0, s[34:35]
	s_or_b32 s34, s30, 6
	s_or_b32 s30, s30, 7
	s_ashr_i32 s35, s34, 31
	s_ashr_i32 s31, s30, 31
	s_lshl_b64 s[34:35], s[34:35], 12
	s_lshl_b64 s[30:31], s[30:31], 12
	v_pk_mul_f32 v[4:5], v[100:101], v[14:15]
	v_pk_mul_f32 v[6:7], v[102:103], v[12:13]
	global_store_dwordx4 v[26:27], v[4:7], off sc1
	v_pk_mul_f32 v[12:13], v[18:19], v[52:53] op_sel_hi:[1, 0]
	v_pk_mul_f32 v[14:15], v[16:17], v[52:53] op_sel_hi:[1, 0]
	s_nop 1
	v_pk_mul_f32 v[6:7], v[106:107], v[12:13]
	v_pk_mul_f32 v[4:5], v[104:105], v[14:15]
	global_store_dwordx4 v[26:27], v[4:7], off offset:1024 sc1
	global_load_dwordx4 v[36:39], v[30:31], off
	global_load_dwordx4 v[40:43], v[30:31], off offset:1024
	global_load_dwordx4 v[44:47], v[30:31], off offset:3072
	global_load_dwordx4 v[48:51], v[30:31], off offset:2048
	global_load_dwordx4 v[20:23], v[28:29], off
	global_load_dwordx4 v[16:19], v[28:29], off offset:1024
	global_load_dwordx4 v[4:7], v[28:29], off offset:3072
	global_load_dwordx4 v[12:15], v[28:29], off offset:2048
	s_waitcnt vmcnt(6)
	v_pk_mul_f32 v[54:55], v[42:43], v[42:43]
	v_pk_mul_f32 v[8:9], v[108:109], v[8:9]
	v_pk_mul_f32 v[10:11], v[110:111], v[10:11]
	global_store_dwordx4 v[26:27], v[8:11], off offset:2048 sc1
	s_waitcnt vmcnt(6)
	v_mul_f32_e32 v53, v46, v46
	v_pk_mul_f32 v[2:3], v[2:3], v[52:53] op_sel_hi:[1, 0]
	v_pk_mul_f32 v[0:1], v[0:1], v[52:53] op_sel_hi:[1, 0]
	v_pk_mul_f32 v[32:33], v[38:39], v[38:39]
	v_pk_mul_f32 v[34:35], v[36:37], v[36:37]
	v_pk_mul_f32 v[56:57], v[40:41], v[40:41]
	s_waitcnt vmcnt(5)
	v_mul_f32_e32 v58, v49, v49
	v_mul_f32_e32 v60, v51, v51
	s_waitcnt vmcnt(4)
	v_pk_mul_f32 v[62:63], v[22:23], v[22:23]
	v_pk_mul_f32 v[64:65], v[20:21], v[20:21]
	s_waitcnt vmcnt(3)
	v_pk_mul_f32 v[66:67], v[18:19], v[18:19]
	v_pk_mul_f32 v[68:69], v[16:17], v[16:17]
	v_pk_mov_b32 v[74:75], v[34:35], v[32:33] op_sel:[1, 0]
	v_mov_b32_e32 v35, v33
	v_pk_mov_b32 v[32:33], v[56:57], v[54:55] op_sel:[1, 0]
	v_mov_b32_e32 v57, v55
	v_pk_fma_f32 v[54:55], v[48:49], v[48:49], v[58:59] op_sel_hi:[1, 1, 0]
	v_pk_fma_f32 v[58:59], v[50:51], v[50:51], v[60:61] op_sel_hi:[1, 1, 0]
	v_pk_mov_b32 v[60:61], v[64:65], v[62:63] op_sel:[1, 0]
	v_mov_b32_e32 v65, v63
	v_pk_mov_b32 v[62:63], v[68:69], v[66:67] op_sel:[1, 0]
	v_mov_b32_e32 v69, v67
	v_mul_f32_e32 v73, v44, v44
	s_waitcnt vmcnt(1)
	v_mul_f32_e32 v70, v13, v13
	v_mul_f32_e32 v72, v15, v15
	v_pk_add_f32 v[34:35], v[74:75], v[34:35]
	v_mul_f32_e32 v76, v45, v45
	v_mul_f32_e32 v77, v47, v47
	v_mul_f32_e32 v78, v4, v4
	v_mul_f32_e32 v79, v5, v5
	v_mul_f32_e32 v80, v6, v6
	v_mul_f32_e32 v81, v7, v7
	v_pk_fma_f32 v[66:67], v[12:13], v[12:13], v[70:71] op_sel_hi:[1, 1, 0]
	v_pk_fma_f32 v[70:71], v[14:15], v[14:15], v[72:73] op_sel_hi:[1, 1, 0]
	v_mov_b32_e32 v55, v53
	v_mov_b32_e32 v59, v77
	v_mov_b32_e32 v67, v80
	v_mov_b32_e32 v71, v81
	v_pk_add_f32 v[52:53], v[66:67], v[70:71]
	v_pk_mul_f32 v[0:1], v[112:113], v[0:1]
	v_pk_mul_f32 v[2:3], v[114:115], v[2:3]
	global_store_dwordx4 v[26:27], v[0:3], off offset:3072 sc1
	v_pk_add_f32 v[8:9], v[32:33], v[56:57]
	v_pk_add_f32 v[10:11], v[60:61], v[64:65]
	v_pk_add_f32 v[26:27], v[62:63], v[68:69]
	v_pk_add_f32 v[32:33], v[34:35], v[34:35] op_sel:[0, 1] op_sel_hi:[1, 0]
	v_pk_add_f32 v[8:9], v[8:9], v[8:9] op_sel:[0, 1] op_sel_hi:[1, 0]
	v_pk_add_f32 v[10:11], v[10:11], v[10:11] op_sel:[0, 1] op_sel_hi:[1, 0]
	v_pk_add_f32 v[26:27], v[26:27], v[26:27] op_sel:[0, 1] op_sel_hi:[1, 0]
	v_mov_b32_e32 v33, v73
	v_mov_b32_e32 v9, v76
	v_mov_b32_e32 v11, v78
	v_mov_b32_e32 v27, v79
	v_pk_add_f32 v[34:35], v[54:55], v[58:59]
	v_pk_add_f32 v[8:9], v[32:33], v[8:9]
	v_pk_add_f32 v[10:11], v[10:11], v[26:27]
	v_pk_add_f32 v[8:9], v[8:9], v[34:35]
	v_pk_add_f32 v[10:11], v[10:11], v[52:53]
	v_mov_b32_e32 v27, v8
	v_mov_b32_e32 v26, v10
	v_mov_b32_e32 v8, v11
	v_pk_add_f32 v[8:9], v[26:27], v[8:9]
	v_lshl_add_u64 v[52:53], v[132:133], 0, s[34:35]
	s_waitcnt lgkmcnt(0)
	s_nop 1
	v_add_f32_dpp v8, v8, v8 quad_perm:[1, 0, 3, 2] row_mask:0xf bank_mask:0xf
	v_add_f32_dpp v9, v9, v9 quad_perm:[1, 0, 3, 2] row_mask:0xf bank_mask:0xf
	s_waitcnt lgkmcnt(0)
	s_nop 1
	v_add_f32_dpp v8, v8, v8 quad_perm:[2, 3, 0, 1] row_mask:0xf bank_mask:0xf
	v_add_f32_dpp v9, v9, v9 quad_perm:[2, 3, 0, 1] row_mask:0xf bank_mask:0xf
	s_waitcnt lgkmcnt(0)
	s_nop 1
	v_add_f32_dpp v8, v8, v8 row_half_mirror row_mask:0xf bank_mask:0xf
	v_add_f32_dpp v9, v9, v9 row_half_mirror row_mask:0xf bank_mask:0xf
	s_waitcnt lgkmcnt(0)
	s_nop 1
	v_add_f32_dpp v8, v8, v8 row_mirror row_mask:0xf bank_mask:0xf
	v_add_f32_dpp v9, v9, v9 row_mirror row_mask:0xf bank_mask:0xf
	ds_bpermute_b32 v11, v175, v9
	ds_bpermute_b32 v10, v175, v8
	s_waitcnt lgkmcnt(0)
	v_pk_add_f32 v[8:9], v[8:9], v[10:11]
	s_waitcnt lgkmcnt(0)
	v_mov_b32_e32 v10, v8
	v_mov_b32_e32 v11, v9
	s_nop 1
	v_permlane32_swap_b32_e32 v10, v8
	v_permlane32_swap_b32_e32 v11, v9
	v_pk_add_f32 v[8:9], v[8:9], v[10:11]
	s_nop 0
	v_pk_fma_f32 v[8:9], v[8:9], s[24:25], v[24:25] op_sel_hi:[1, 0, 0]
	s_nop 0
	v_mul_f32_e32 v10, 0x4b800000, v9
	v_cmp_gt_f32_e32 vcc, s57, v9
	s_nop 1
	v_cndmask_b32_e32 v9, v9, v10, vcc
	v_rsq_f32_e32 v9, v9
	s_nop 0
	v_mul_f32_e32 v10, 0x45800000, v9
	v_cndmask_b32_e32 v10, v9, v10, vcc
	v_pk_mul_f32 v[26:27], v[36:37], v[10:11] op_sel_hi:[1, 0]
	v_pk_mul_f32 v[32:33], v[38:39], v[10:11] op_sel_hi:[1, 0]
	v_mul_f32_e32 v9, 0x4b800000, v8
	v_cmp_gt_f32_e32 vcc, s57, v8
	v_pk_mul_f32 v[2:3], v[102:103], v[32:33]
	v_pk_mul_f32 v[0:1], v[100:101], v[26:27]
	global_store_dwordx4 v[30:31], v[0:3], off sc1
	v_pk_mul_f32 v[26:27], v[42:43], v[10:11] op_sel_hi:[1, 0]
	v_pk_mul_f32 v[32:33], v[40:41], v[10:11] op_sel_hi:[1, 0]
	v_cndmask_b32_e32 v8, v8, v9, vcc
	v_rsq_f32_e32 v8, v8
	v_pk_mul_f32 v[0:1], v[104:105], v[32:33]
	v_pk_mul_f32 v[2:3], v[106:107], v[26:27]
	global_store_dwordx4 v[30:31], v[0:3], off offset:1024 sc1
	v_pk_mul_f32 v[26:27], v[50:51], v[10:11] op_sel_hi:[1, 0]
	v_pk_mul_f32 v[32:33], v[48:49], v[10:11] op_sel_hi:[1, 0]
	v_mul_f32_e32 v9, 0x45800000, v8
	v_cndmask_b32_e32 v50, v8, v9, vcc
	v_pk_mul_f32 v[8:9], v[22:23], v[50:51] op_sel_hi:[1, 0]
	v_pk_mul_f32 v[14:15], v[14:15], v[50:51] op_sel_hi:[1, 0]
	v_pk_mul_f32 v[12:13], v[12:13], v[50:51] op_sel_hi:[1, 0]
	v_pk_mul_f32 v[0:1], v[108:109], v[32:33]
	v_pk_mul_f32 v[2:3], v[110:111], v[26:27]
	global_store_dwordx4 v[30:31], v[0:3], off offset:2048 sc1
	v_pk_mul_f32 v[26:27], v[46:47], v[10:11] op_sel_hi:[1, 0]
	v_pk_mul_f32 v[10:11], v[44:45], v[10:11] op_sel_hi:[1, 0]
	s_nop 1
	v_pk_mul_f32 v[2:3], v[114:115], v[26:27]
	v_pk_mul_f32 v[0:1], v[112:113], v[10:11]
	global_store_dwordx4 v[30:31], v[0:3], off offset:3072 sc1
	v_pk_mul_f32 v[10:11], v[20:21], v[50:51] op_sel_hi:[1, 0]
	v_lshl_add_u64 v[26:27], v[132:133], 0, s[30:31]
	s_nop 1
	v_pk_mul_f32 v[0:1], v[100:101], v[10:11]
	v_pk_mul_f32 v[2:3], v[102:103], v[8:9]
	global_store_dwordx4 v[28:29], v[0:3], off sc1
	v_pk_mul_f32 v[8:9], v[18:19], v[50:51] op_sel_hi:[1, 0]
	v_pk_mul_f32 v[10:11], v[16:17], v[50:51] op_sel_hi:[1, 0]
	s_nop 1
	v_pk_mul_f32 v[2:3], v[106:107], v[8:9]
	v_pk_mul_f32 v[0:1], v[104:105], v[10:11]
	global_store_dwordx4 v[28:29], v[0:3], off offset:1024 sc1
	global_load_dwordx4 v[34:37], v[52:53], off
	global_load_dwordx4 v[38:41], v[52:53], off offset:1024
	global_load_dwordx4 v[42:45], v[52:53], off offset:3072
	global_load_dwordx4 v[46:49], v[52:53], off offset:2048
	global_load_dwordx4 v[20:23], v[26:27], off
	global_load_dwordx4 v[16:19], v[26:27], off offset:1024
	global_load_dwordx4 v[0:3], v[26:27], off offset:3072
	global_load_dwordx4 v[8:11], v[26:27], off offset:2048
	s_waitcnt vmcnt(6)
	v_pk_mul_f32 v[54:55], v[40:41], v[40:41]
	v_pk_mul_f32 v[12:13], v[108:109], v[12:13]
	v_pk_mul_f32 v[14:15], v[110:111], v[14:15]
	global_store_dwordx4 v[28:29], v[12:15], off offset:2048 sc1
	s_waitcnt vmcnt(6)
	v_mul_f32_e32 v51, v44, v44
	v_pk_mul_f32 v[6:7], v[6:7], v[50:51] op_sel_hi:[1, 0]
	v_pk_mul_f32 v[4:5], v[4:5], v[50:51] op_sel_hi:[1, 0]
	v_pk_mul_f32 v[30:31], v[36:37], v[36:37]
	v_pk_mul_f32 v[32:33], v[34:35], v[34:35]
	v_pk_mul_f32 v[56:57], v[38:39], v[38:39]
	s_waitcnt vmcnt(5)
	v_mul_f32_e32 v58, v47, v47
	v_mul_f32_e32 v60, v49, v49
	s_waitcnt vmcnt(4)
	v_pk_mul_f32 v[62:63], v[22:23], v[22:23]
	v_pk_mul_f32 v[64:65], v[20:21], v[20:21]
	s_waitcnt vmcnt(3)
	v_pk_mul_f32 v[66:67], v[18:19], v[18:19]
	v_pk_mul_f32 v[68:69], v[16:17], v[16:17]
	v_pk_mov_b32 v[74:75], v[32:33], v[30:31] op_sel:[1, 0]
	v_mov_b32_e32 v33, v31
	v_pk_mov_b32 v[30:31], v[56:57], v[54:55] op_sel:[1, 0]
	v_mov_b32_e32 v57, v55
	v_pk_fma_f32 v[54:55], v[46:47], v[46:47], v[58:59] op_sel_hi:[1, 1, 0]
	v_pk_fma_f32 v[58:59], v[48:49], v[48:49], v[60:61] op_sel_hi:[1, 1, 0]
	v_pk_mov_b32 v[60:61], v[64:65], v[62:63] op_sel:[1, 0]
	v_mov_b32_e32 v65, v63
	v_pk_mov_b32 v[62:63], v[68:69], v[66:67] op_sel:[1, 0]
	v_mov_b32_e32 v69, v67
	v_mul_f32_e32 v73, v42, v42
	s_waitcnt vmcnt(1)
	v_mul_f32_e32 v70, v9, v9
	v_mul_f32_e32 v72, v11, v11
	v_pk_add_f32 v[32:33], v[74:75], v[32:33]
	v_mul_f32_e32 v76, v43, v43
	v_mul_f32_e32 v77, v45, v45
	v_mul_f32_e32 v78, v0, v0
	v_mul_f32_e32 v79, v1, v1
	v_mul_f32_e32 v80, v2, v2
	v_mul_f32_e32 v81, v3, v3
	v_pk_fma_f32 v[66:67], v[8:9], v[8:9], v[70:71] op_sel_hi:[1, 1, 0]
	v_pk_fma_f32 v[70:71], v[10:11], v[10:11], v[72:73] op_sel_hi:[1, 1, 0]
	v_mov_b32_e32 v55, v51
	v_mov_b32_e32 v59, v77
	v_mov_b32_e32 v67, v80
	v_mov_b32_e32 v71, v81
	v_pk_add_f32 v[50:51], v[66:67], v[70:71]
	v_pk_mul_f32 v[4:5], v[112:113], v[4:5]
	v_pk_mul_f32 v[6:7], v[114:115], v[6:7]
	global_store_dwordx4 v[28:29], v[4:7], off offset:3072 sc1
	v_pk_add_f32 v[12:13], v[30:31], v[56:57]
	v_pk_add_f32 v[14:15], v[60:61], v[64:65]
	v_pk_add_f32 v[28:29], v[62:63], v[68:69]
	v_pk_add_f32 v[30:31], v[32:33], v[32:33] op_sel:[0, 1] op_sel_hi:[1, 0]
	v_pk_add_f32 v[12:13], v[12:13], v[12:13] op_sel:[0, 1] op_sel_hi:[1, 0]
	v_pk_add_f32 v[14:15], v[14:15], v[14:15] op_sel:[0, 1] op_sel_hi:[1, 0]
	v_pk_add_f32 v[28:29], v[28:29], v[28:29] op_sel:[0, 1] op_sel_hi:[1, 0]
	v_mov_b32_e32 v31, v73
	v_mov_b32_e32 v13, v76
	v_mov_b32_e32 v15, v78
	v_mov_b32_e32 v29, v79
	v_pk_add_f32 v[32:33], v[54:55], v[58:59]
	v_pk_add_f32 v[12:13], v[30:31], v[12:13]
	v_pk_add_f32 v[14:15], v[14:15], v[28:29]
	v_pk_add_f32 v[12:13], v[12:13], v[32:33]
	v_pk_add_f32 v[14:15], v[14:15], v[50:51]
	v_mov_b32_e32 v29, v12
	v_mov_b32_e32 v28, v14
	v_mov_b32_e32 v12, v15
	v_pk_add_f32 v[12:13], v[28:29], v[12:13]
	s_waitcnt lgkmcnt(0)
	s_nop 1
	v_add_f32_dpp v12, v12, v12 quad_perm:[1, 0, 3, 2] row_mask:0xf bank_mask:0xf
	v_add_f32_dpp v13, v13, v13 quad_perm:[1, 0, 3, 2] row_mask:0xf bank_mask:0xf
	s_waitcnt lgkmcnt(0)
	s_nop 1
	v_add_f32_dpp v12, v12, v12 quad_perm:[2, 3, 0, 1] row_mask:0xf bank_mask:0xf
	v_add_f32_dpp v13, v13, v13 quad_perm:[2, 3, 0, 1] row_mask:0xf bank_mask:0xf
	s_waitcnt lgkmcnt(0)
	s_nop 1
	v_add_f32_dpp v12, v12, v12 row_half_mirror row_mask:0xf bank_mask:0xf
	v_add_f32_dpp v13, v13, v13 row_half_mirror row_mask:0xf bank_mask:0xf
	s_waitcnt lgkmcnt(0)
	s_nop 1
	v_add_f32_dpp v12, v12, v12 row_mirror row_mask:0xf bank_mask:0xf
	v_add_f32_dpp v13, v13, v13 row_mirror row_mask:0xf bank_mask:0xf
	ds_bpermute_b32 v15, v175, v13
	ds_bpermute_b32 v14, v175, v12
	s_waitcnt lgkmcnt(0)
	v_pk_add_f32 v[12:13], v[12:13], v[14:15]
	s_waitcnt lgkmcnt(0)
	v_mov_b32_e32 v14, v12
	v_mov_b32_e32 v15, v13
	s_nop 1
	v_permlane32_swap_b32_e32 v14, v12
	v_permlane32_swap_b32_e32 v15, v13
	v_pk_add_f32 v[12:13], v[12:13], v[14:15]
	s_nop 0
	v_pk_fma_f32 v[12:13], v[12:13], s[24:25], v[24:25] op_sel_hi:[1, 0, 0]
	s_nop 0
	v_mul_f32_e32 v14, 0x4b800000, v13
	v_cmp_gt_f32_e32 vcc, s57, v13
	s_nop 1
	v_cndmask_b32_e32 v13, v13, v14, vcc
	v_rsq_f32_e32 v13, v13
	s_nop 0
	v_mul_f32_e32 v14, 0x45800000, v13
	v_cndmask_b32_e32 v14, v13, v14, vcc
	v_pk_mul_f32 v[24:25], v[36:37], v[14:15] op_sel_hi:[1, 0]
	v_pk_mul_f32 v[28:29], v[34:35], v[14:15] op_sel_hi:[1, 0]
	v_mul_f32_e32 v13, 0x4b800000, v12
	v_cmp_gt_f32_e32 vcc, s57, v12
	v_pk_mul_f32 v[4:5], v[100:101], v[28:29]
	v_pk_mul_f32 v[6:7], v[102:103], v[24:25]
	global_store_dwordx4 v[52:53], v[4:7], off sc1
	v_pk_mul_f32 v[24:25], v[40:41], v[14:15] op_sel_hi:[1, 0]
	v_pk_mul_f32 v[28:29], v[38:39], v[14:15] op_sel_hi:[1, 0]
	v_cndmask_b32_e32 v12, v12, v13, vcc
	v_rsq_f32_e32 v12, v12
	v_pk_mul_f32 v[4:5], v[104:105], v[28:29]
	v_pk_mul_f32 v[6:7], v[106:107], v[24:25]
	global_store_dwordx4 v[52:53], v[4:7], off offset:1024 sc1
	v_pk_mul_f32 v[24:25], v[48:49], v[14:15] op_sel_hi:[1, 0]
	v_pk_mul_f32 v[28:29], v[46:47], v[14:15] op_sel_hi:[1, 0]
	v_mul_f32_e32 v13, 0x45800000, v12
	v_cndmask_b32_e32 v12, v12, v13, vcc
	v_pk_mul_f32 v[20:21], v[20:21], v[12:13] op_sel_hi:[1, 0]
	v_pk_mul_f32 v[16:17], v[16:17], v[12:13] op_sel_hi:[1, 0]
	v_pk_mul_f32 v[10:11], v[10:11], v[12:13] op_sel_hi:[1, 0]
	v_pk_mul_f32 v[8:9], v[8:9], v[12:13] op_sel_hi:[1, 0]
	v_pk_mul_f32 v[2:3], v[2:3], v[12:13] op_sel_hi:[1, 0]
	v_pk_mul_f32 v[0:1], v[0:1], v[12:13] op_sel_hi:[1, 0]
	s_and_b64 vcc, exec, s[6:7]
	s_mov_b64 s[6:7], -1
	v_pk_mul_f32 v[4:5], v[108:109], v[28:29]
	v_pk_mul_f32 v[6:7], v[110:111], v[24:25]
	global_store_dwordx4 v[52:53], v[4:7], off offset:2048 sc1
	v_pk_mul_f32 v[24:25], v[44:45], v[14:15] op_sel_hi:[1, 0]
	v_pk_mul_f32 v[14:15], v[42:43], v[14:15] op_sel_hi:[1, 0]
	s_nop 1
	v_pk_mul_f32 v[6:7], v[114:115], v[24:25]
	v_pk_mul_f32 v[4:5], v[112:113], v[14:15]
	global_store_dwordx4 v[52:53], v[4:7], off offset:3072 sc1
	v_pk_mul_f32 v[14:15], v[22:23], v[12:13] op_sel_hi:[1, 0]
	s_nop 1
	v_pk_mul_f32 v[4:5], v[100:101], v[20:21]
	s_nop 1
	v_pk_mul_f32 v[6:7], v[102:103], v[14:15]
	global_store_dwordx4 v[26:27], v[4:7], off sc1
	v_pk_mul_f32 v[14:15], v[18:19], v[12:13] op_sel_hi:[1, 0]
	s_nop 1
	v_pk_mul_f32 v[4:5], v[104:105], v[16:17]
	s_nop 1
	v_pk_mul_f32 v[6:7], v[106:107], v[14:15]
	global_store_dwordx4 v[26:27], v[4:7], off offset:1024 sc1
	s_nop 1
	v_pk_mul_f32 v[4:5], v[108:109], v[8:9]
	s_nop 1
	v_pk_mul_f32 v[6:7], v[110:111], v[10:11]
	global_store_dwordx4 v[26:27], v[4:7], off offset:2048 sc1
	v_pk_mul_f32 v[0:1], v[112:113], v[0:1]
	v_pk_mul_f32 v[2:3], v[114:115], v[2:3]
	global_store_dwordx4 v[26:27], v[0:3], off offset:3072 sc1
	s_cbranch_vccnz .LBB0_2507
	s_andn2_b64 vcc, exec, s[12:13]
	s_cbranch_vccnz .LBB0_2506
	s_barrier
	s_branch .LBB0_2506
